# GEMM phases: s_setprio 1 moved ahead of the pre-MFMA barrier, s_setprio 0 moved behind the post-MFMA barrier (on top of saddr DMA and redundant wait removal)
# speedup vs baseline: 1.0040x; 1.0014x over previous
;     __host__ __device__ bool next(int i, Unit& u) const { if (!StaticOrder::next(i >> 1, u)) return false; u.seg = i & 1; return true; }
;     ...
;         const bool has_next = S.next(ui + 1, nxt);
;         const char* nA = has_next ? PG8_APTR(nxt) : cA; const char* nB = has_next ? PG8_BPTR(nxt) : cB;
;         const char* pfc = PG8_PFPTR(cA, cB); const char* pfn = PG8_PFPTR(nA, nB);
;         PG8_KITER(0);
.LBB0_248:
	s_ashr_i32 s47, s46, 31
	ds_read_b128 v[2:5], v146
	ds_read_b128 v[6:9], v146 offset:1024
	ds_read_b128 v[10:13], v146 offset:2048
	ds_read_b128 v[14:17], v146 offset:3072
	ds_read_b128 v[18:21], v147
	ds_read_b128 v[22:25], v147 offset:1024
	ds_read_b128 v[26:29], v147 offset:2048
	ds_read_b128 v[30:33], v147 offset:3072
	s_lshl_b64 s[14:15], s[46:47], 21
	s_add_u32 s60, s36, s14
	s_addc_u32 s61, s37, s15
	s_and_b64 s[14:15], s[0:1], exec
	s_cselect_b32 s47, s61, s71
	s_cselect_b32 s93, s60, s70
	s_and_b32 s4, s91, 0x7fffffff
	s_lshl_b64 s[14:15], s[4:5], 21
	s_add_u32 s62, s96, s14
	s_addc_u32 s63, s97, s15
	s_and_b64 s[14:15], s[0:1], exec
	s_cselect_b32 s4, s63, s67
	s_cselect_b32 s94, s62, s66
	s_add_u32 s14, s70, 0x100080
	s_addc_u32 s15, s71, 0
	s_mov_b32 m0, s78
	v_lshl_add_u64 v[66:67], s[14:15], 0, v[136:137]
	ds_read_b128 v[34:37], v148
	ds_read_b128 v[38:41], v148 offset:1024
	ds_read_b128 v[42:45], v148 offset:2048
	ds_read_b128 v[46:49], v148 offset:3072
	ds_read_b128 v[50:53], v148 offset:4096
	ds_read_b128 v[54:57], v148 offset:5120
	ds_read_b128 v[58:61], v148 offset:6144
	ds_read_b128 v[62:65], v148 offset:7168
	global_load_lds_dwordx4 v[66:67], off
	v_lshl_add_u64 v[66:67], s[14:15], 0, v[132:133]
	s_mov_b32 m0, s79
	s_nop 0
	global_load_lds_dwordx4 v[66:67], off
	s_waitcnt vmcnt(8)
	s_waitcnt lgkmcnt(0)
	s_setprio 1
	s_barrier
	v_mfma_f32_16x16x32_bf16 v[90:93], v[2:5], v[58:61], 0
	v_mfma_f32_16x16x32_bf16 v[66:69], v[2:5], v[34:37], 0
	v_mfma_f32_16x16x32_bf16 v[70:73], v[10:13], v[34:37], 0
	v_mfma_f32_16x16x32_bf16 v[74:77], v[2:5], v[42:45], 0
	v_mfma_f32_16x16x32_bf16 v[78:81], v[10:13], v[42:45], 0
	v_mfma_f32_16x16x32_bf16 v[82:85], v[2:5], v[50:53], 0
	v_mfma_f32_16x16x32_bf16 v[86:89], v[10:13], v[50:53], 0
	v_mfma_f32_16x16x32_bf16 v[94:97], v[6:9], v[62:65], v[90:93]
	v_mfma_f32_16x16x32_bf16 v[90:93], v[10:13], v[58:61], 0
	v_mfma_f32_16x16x32_bf16 v[66:69], v[6:9], v[38:41], v[66:69]
	v_mfma_f32_16x16x32_bf16 v[70:73], v[14:17], v[38:41], v[70:73]
	v_mfma_f32_16x16x32_bf16 v[74:77], v[6:9], v[46:49], v[74:77]
	v_mfma_f32_16x16x32_bf16 v[78:81], v[14:17], v[46:49], v[78:81]
	v_mfma_f32_16x16x32_bf16 v[82:85], v[6:9], v[54:57], v[82:85]
	v_mfma_f32_16x16x32_bf16 v[86:89], v[14:17], v[54:57], v[86:89]
	v_mfma_f32_16x16x32_bf16 v[102:105], v[14:17], v[62:65], v[90:93]
	s_setprio 0
	s_setprio 1
	v_mfma_f32_16x16x32_bf16 v[90:93], v[18:21], v[34:37], 0
	v_mfma_f32_16x16x32_bf16 v[34:37], v[26:29], v[34:37], 0
	v_mfma_f32_16x16x32_bf16 v[110:113], v[22:25], v[38:41], v[90:93]
	v_mfma_f32_16x16x32_bf16 v[34:37], v[30:33], v[38:41], v[34:37]
	v_mfma_f32_16x16x32_bf16 v[38:41], v[18:21], v[42:45], 0
	v_mfma_f32_16x16x32_bf16 v[42:45], v[26:29], v[42:45], 0
	v_mfma_f32_16x16x32_bf16 v[38:41], v[22:25], v[46:49], v[38:41]
	v_mfma_f32_16x16x32_bf16 v[42:45], v[30:33], v[46:49], v[42:45]
	v_mfma_f32_16x16x32_bf16 v[46:49], v[18:21], v[50:53], 0
	v_mfma_f32_16x16x32_bf16 v[50:53], v[26:29], v[50:53], 0
	v_mfma_f32_16x16x32_bf16 v[46:49], v[22:25], v[54:57], v[46:49]
	v_mfma_f32_16x16x32_bf16 v[50:53], v[30:33], v[54:57], v[50:53]
	v_mfma_f32_16x16x32_bf16 v[54:57], v[18:21], v[58:61], 0
	v_mfma_f32_16x16x32_bf16 v[58:61], v[26:29], v[58:61], 0
	v_mfma_f32_16x16x32_bf16 v[54:57], v[22:25], v[62:65], v[54:57]
	v_mfma_f32_16x16x32_bf16 v[62:65], v[30:33], v[62:65], v[58:61]
	s_barrier
	s_setprio 0
	v_lshl_add_u64 v[248:249], s[66:67], 0, v[134:135]
	s_mov_b32 m0, s81
	v_lshl_add_u64 v[152:153], v[248:249], 0, s[18:19]
	v_lshl_add_u64 v[250:251], s[66:67], 0, v[130:131]
	s_add_u32 s14, s66, 0x100100
	ds_read_b128 v[58:61], v148 offset:16384
	ds_read_b128 v[90:93], v148 offset:17408
	ds_read_b128 v[98:101], v148 offset:18432
	ds_read_b128 v[106:109], v148 offset:19456
	ds_read_b128 v[114:117], v148 offset:20480
	ds_read_b128 v[118:121], v148 offset:21504
	ds_read_b128 v[122:125], v148 offset:22528
	ds_read_b128 v[126:129], v148 offset:23552
	global_load_lds_dwordx4 v[152:153], off
	v_lshl_add_u64 v[152:153], v[250:251], 0, s[18:19]
	s_mov_b32 m0, s82
	s_addc_u32 s15, s67, 0
	global_load_lds_dwordx4 v[152:153], off
	v_lshl_add_u64 v[152:153], s[14:15], 0, v[134:135]
	s_mov_b32 m0, s83
	v_lshl_add_u64 v[252:253], s[70:71], 0, v[136:137]
	global_load_lds_dwordx4 v[152:153], off
	v_lshl_add_u64 v[152:153], s[14:15], 0, v[130:131]
	s_mov_b32 m0, s86
	v_lshl_add_u64 v[142:143], s[70:71], 0, v[132:133]
	global_load_lds_dwordx4 v[152:153], off
	v_lshl_add_u64 v[152:153], v[252:253], 0, s[18:19]
	s_mov_b32 m0, s29
	s_nop 0
	global_load_lds_dwordx4 v[152:153], off
	v_lshl_add_u64 v[152:153], v[142:143], 0, s[18:19]
	s_mov_b32 m0, s33
	s_nop 0
	global_load_lds_dwordx4 v[152:153], off
	s_waitcnt vmcnt(8)
	s_waitcnt lgkmcnt(0)
	s_setprio 1
	s_barrier
	v_mfma_f32_16x16x32_bf16 v[152:155], v[2:5], v[58:61], 0
	v_mfma_f32_16x16x32_bf16 v[160:163], v[2:5], v[98:101], 0
	v_mfma_f32_16x16x32_bf16 v[168:171], v[2:5], v[114:117], 0
	v_mfma_f32_16x16x32_bf16 v[2:5], v[2:5], v[122:125], 0
	v_mfma_f32_16x16x32_bf16 v[152:155], v[6:9], v[90:93], v[152:155]
	v_mfma_f32_16x16x32_bf16 v[160:163], v[6:9], v[106:109], v[160:163]
	v_mfma_f32_16x16x32_bf16 v[168:171], v[6:9], v[118:121], v[168:171]
	v_mfma_f32_16x16x32_bf16 v[2:5], v[6:9], v[126:129], v[2:5]
	v_mfma_f32_16x16x32_bf16 v[6:9], v[10:13], v[122:125], 0
	v_mfma_f32_16x16x32_bf16 v[156:159], v[10:13], v[58:61], 0
	v_mfma_f32_16x16x32_bf16 v[164:167], v[10:13], v[98:101], 0
	v_mfma_f32_16x16x32_bf16 v[172:175], v[10:13], v[114:117], 0
	v_mfma_f32_16x16x32_bf16 v[6:9], v[14:17], v[126:129], v[6:9]
	v_mfma_f32_16x16x32_bf16 v[156:159], v[14:17], v[90:93], v[156:159]
	v_mfma_f32_16x16x32_bf16 v[164:167], v[14:17], v[106:109], v[164:167]
	v_mfma_f32_16x16x32_bf16 v[172:175], v[14:17], v[118:121], v[172:175]
	s_setprio 0
	s_setprio 1
	v_mfma_f32_16x16x32_bf16 v[10:13], v[18:21], v[58:61], 0
	v_mfma_f32_16x16x32_bf16 v[14:17], v[22:25], v[90:93], v[10:13]
	v_mfma_f32_16x16x32_bf16 v[10:13], v[26:29], v[58:61], 0
	v_mfma_f32_16x16x32_bf16 v[176:179], v[30:33], v[90:93], v[10:13]
	v_mfma_f32_16x16x32_bf16 v[10:13], v[18:21], v[98:101], 0
	v_mfma_f32_16x16x32_bf16 v[180:183], v[22:25], v[106:109], v[10:13]
	v_mfma_f32_16x16x32_bf16 v[10:13], v[26:29], v[98:101], 0
	v_mfma_f32_16x16x32_bf16 v[184:187], v[30:33], v[106:109], v[10:13]
	v_mfma_f32_16x16x32_bf16 v[10:13], v[18:21], v[114:117], 0
	v_mfma_f32_16x16x32_bf16 v[188:191], v[22:25], v[118:121], v[10:13]
	v_mfma_f32_16x16x32_bf16 v[10:13], v[26:29], v[114:117], 0
	v_mfma_f32_16x16x32_bf16 v[192:195], v[30:33], v[118:121], v[10:13]
	v_mfma_f32_16x16x32_bf16 v[10:13], v[18:21], v[122:125], 0
	v_mfma_f32_16x16x32_bf16 v[196:199], v[22:25], v[126:129], v[10:13]
	v_mfma_f32_16x16x32_bf16 v[10:13], v[26:29], v[122:125], 0
	v_mfma_f32_16x16x32_bf16 v[200:203], v[30:33], v[126:129], v[10:13]
	s_barrier
	s_setprio 0
	s_nop 4
	ds_read_b128 v[10:13], v149
	ds_read_b128 v[22:25], v149 offset:1024
	ds_read_b128 v[30:33], v149 offset:2048
	ds_read_b128 v[204:207], v149 offset:3072
	ds_read_b128 v[208:211], v150
	ds_read_b128 v[212:215], v150 offset:1024
	ds_read_b128 v[216:219], v150 offset:2048
	ds_read_b128 v[220:223], v150 offset:3072
	s_add_u32 s14, s70, 0x100100
	s_addc_u32 s15, s71, 0
	s_mov_b32 m0, s58
	v_lshl_add_u64 v[58:59], s[14:15], 0, v[136:137]
	ds_read_b128 v[18:21], v148 offset:32768
	ds_read_b128 v[26:29], v148 offset:33792
	ds_read_b128 v[224:227], v148 offset:34816
	ds_read_b128 v[228:231], v148 offset:35840
	ds_read_b128 v[232:235], v148 offset:36864
	ds_read_b128 v[236:239], v148 offset:37888
	ds_read_b128 v[240:243], v148 offset:38912
	ds_read_b128 v[244:247], v148 offset:39936
	global_load_lds_dwordx4 v[58:59], off
	v_lshl_add_u64 v[58:59], s[14:15], 0, v[132:133]
	s_mov_b32 m0, s59
	s_nop 0
	global_load_lds_dwordx4 v[58:59], off
	s_waitcnt vmcnt(8)
	s_waitcnt lgkmcnt(0)
	s_setprio 1
	s_barrier
	v_mfma_f32_16x16x32_bf16 v[58:61], v[10:13], v[18:21], v[66:69]
	v_mfma_f32_16x16x32_bf16 v[122:125], v[22:25], v[26:29], v[58:61]
	v_mfma_f32_16x16x32_bf16 v[58:61], v[30:33], v[18:21], v[70:73]
	v_mfma_f32_16x16x32_bf16 v[114:117], v[204:207], v[26:29], v[58:61]
	v_mfma_f32_16x16x32_bf16 v[58:61], v[10:13], v[224:227], v[74:77]
	v_mfma_f32_16x16x32_bf16 v[106:109], v[22:25], v[228:231], v[58:61]
	v_mfma_f32_16x16x32_bf16 v[58:61], v[30:33], v[224:227], v[78:81]
	v_mfma_f32_16x16x32_bf16 v[98:101], v[204:207], v[228:231], v[58:61]
	v_mfma_f32_16x16x32_bf16 v[58:61], v[10:13], v[232:235], v[82:85]
	v_mfma_f32_16x16x32_bf16 v[90:93], v[22:25], v[236:239], v[58:61]
	v_mfma_f32_16x16x32_bf16 v[58:61], v[30:33], v[232:235], v[86:89]
	v_mfma_f32_16x16x32_bf16 v[82:85], v[204:207], v[236:239], v[58:61]
	v_mfma_f32_16x16x32_bf16 v[58:61], v[10:13], v[240:243], v[94:97]
	v_mfma_f32_16x16x32_bf16 v[74:77], v[22:25], v[244:247], v[58:61]
	v_mfma_f32_16x16x32_bf16 v[58:61], v[30:33], v[240:243], v[102:105]
	v_mfma_f32_16x16x32_bf16 v[58:61], v[204:207], v[244:247], v[58:61]
	s_setprio 0
	s_setprio 1
	v_mfma_f32_16x16x32_bf16 v[66:69], v[208:211], v[18:21], v[110:113]
	v_mfma_f32_16x16x32_bf16 v[18:21], v[216:219], v[18:21], v[34:37]
	v_mfma_f32_16x16x32_bf16 v[118:121], v[220:223], v[26:29], v[18:21]
	v_mfma_f32_16x16x32_bf16 v[18:21], v[208:211], v[224:227], v[38:41]
	v_mfma_f32_16x16x32_bf16 v[110:113], v[212:215], v[228:231], v[18:21]
	v_mfma_f32_16x16x32_bf16 v[18:21], v[216:219], v[224:227], v[42:45]
	v_mfma_f32_16x16x32_bf16 v[102:105], v[220:223], v[228:231], v[18:21]
	v_mfma_f32_16x16x32_bf16 v[18:21], v[208:211], v[232:235], v[46:49]
	v_mfma_f32_16x16x32_bf16 v[94:97], v[212:215], v[236:239], v[18:21]
	v_mfma_f32_16x16x32_bf16 v[18:21], v[216:219], v[232:235], v[50:53]
	v_mfma_f32_16x16x32_bf16 v[86:89], v[220:223], v[236:239], v[18:21]
	v_mfma_f32_16x16x32_bf16 v[18:21], v[208:211], v[240:243], v[54:57]
	v_mfma_f32_16x16x32_bf16 v[78:81], v[212:215], v[244:247], v[18:21]
	v_mfma_f32_16x16x32_bf16 v[18:21], v[216:219], v[240:243], v[62:65]
	v_mfma_f32_16x16x32_bf16 v[126:129], v[212:215], v[26:29], v[66:69]
	v_mfma_f32_16x16x32_bf16 v[66:69], v[220:223], v[244:247], v[18:21]
	s_barrier
	s_setprio 0
	s_mov_b32 m0, s87
	s_nop 2
	v_lshl_add_u64 v[18:19], v[248:249], 0, s[30:31]
	s_add_u32 s14, s66, 0x100180
	ds_read_b128 v[38:41], v148 offset:49152
	ds_read_b128 v[46:49], v148 offset:50176
	ds_read_b128 v[224:227], v148 offset:51200
	ds_read_b128 v[228:231], v148 offset:52224
	ds_read_b128 v[232:235], v148 offset:53248
	ds_read_b128 v[236:239], v148 offset:54272
	ds_read_b128 v[240:243], v148 offset:55296
	ds_read_b128 v[244:247], v148 offset:56320
	global_load_lds_dwordx4 v[18:19], off
	v_lshl_add_u64 v[18:19], v[250:251], 0, s[30:31]
	s_mov_b32 m0, s88
	s_addc_u32 s15, s67, 0
	global_load_lds_dwordx4 v[18:19], off
	v_lshl_add_u64 v[18:19], s[14:15], 0, v[134:135]
	s_mov_b32 m0, s89
	s_add_i32 s56, s89, 0x2000
	global_load_lds_dwordx4 v[18:19], off
	v_lshl_add_u64 v[18:19], s[14:15], 0, v[130:131]
	s_mov_b32 m0, s56
	s_nop 0
	global_load_lds_dwordx4 v[18:19], off
	v_lshl_add_u64 v[18:19], v[252:253], 0, s[30:31]
	s_mov_b32 m0, s65
	s_nop 0
	global_load_lds_dwordx4 v[18:19], off
	v_lshl_add_u64 v[18:19], v[142:143], 0, s[30:31]
	s_mov_b32 m0, s76
	s_nop 0
	global_load_lds_dwordx4 v[18:19], off
	s_waitcnt vmcnt(8)
	s_waitcnt lgkmcnt(0)
	s_setprio 1
	s_barrier
	v_mfma_f32_16x16x32_bf16 v[18:21], v[10:13], v[38:41], v[152:155]
	v_mfma_f32_16x16x32_bf16 v[62:65], v[22:25], v[46:49], v[18:21]
	v_mfma_f32_16x16x32_bf16 v[18:21], v[30:33], v[38:41], v[156:159]
	v_mfma_f32_16x16x32_bf16 v[50:53], v[204:207], v[46:49], v[18:21]
	v_mfma_f32_16x16x32_bf16 v[18:21], v[10:13], v[224:227], v[160:163]
	v_mfma_f32_16x16x32_bf16 v[42:45], v[22:25], v[228:231], v[18:21]
	v_mfma_f32_16x16x32_bf16 v[18:21], v[30:33], v[224:227], v[164:167]
	v_mfma_f32_16x16x32_bf16 v[34:37], v[204:207], v[228:231], v[18:21]
	v_mfma_f32_16x16x32_bf16 v[18:21], v[10:13], v[232:235], v[168:171]
	v_mfma_f32_16x16x32_bf16 v[2:5], v[10:13], v[240:243], v[2:5]
	v_mfma_f32_16x16x32_bf16 v[26:29], v[22:25], v[236:239], v[18:21]
	v_mfma_f32_16x16x32_bf16 v[18:21], v[30:33], v[232:235], v[172:175]
	v_mfma_f32_16x16x32_bf16 v[10:13], v[22:25], v[244:247], v[2:5]
	v_mfma_f32_16x16x32_bf16 v[2:5], v[30:33], v[240:243], v[6:9]
	v_mfma_f32_16x16x32_bf16 v[18:21], v[204:207], v[236:239], v[18:21]
	v_mfma_f32_16x16x32_bf16 v[2:5], v[204:207], v[244:247], v[2:5]
	s_setprio 0
	s_setprio 1
	v_mfma_f32_16x16x32_bf16 v[6:9], v[208:211], v[38:41], v[14:17]
	v_mfma_f32_16x16x32_bf16 v[70:73], v[212:215], v[46:49], v[6:9]
	v_mfma_f32_16x16x32_bf16 v[6:9], v[216:219], v[38:41], v[176:179]
	v_mfma_f32_16x16x32_bf16 v[54:57], v[220:223], v[46:49], v[6:9]
	v_mfma_f32_16x16x32_bf16 v[6:9], v[208:211], v[224:227], v[180:183]
	v_mfma_f32_16x16x32_bf16 v[46:49], v[212:215], v[228:231], v[6:9]
	v_mfma_f32_16x16x32_bf16 v[6:9], v[216:219], v[224:227], v[184:187]
	v_mfma_f32_16x16x32_bf16 v[38:41], v[220:223], v[228:231], v[6:9]
	v_mfma_f32_16x16x32_bf16 v[6:9], v[208:211], v[232:235], v[188:191]
	v_mfma_f32_16x16x32_bf16 v[30:33], v[212:215], v[236:239], v[6:9]
	v_mfma_f32_16x16x32_bf16 v[6:9], v[216:219], v[232:235], v[192:195]
	v_mfma_f32_16x16x32_bf16 v[22:25], v[220:223], v[236:239], v[6:9]
	v_mfma_f32_16x16x32_bf16 v[6:9], v[208:211], v[240:243], v[196:199]
	v_mfma_f32_16x16x32_bf16 v[14:17], v[212:215], v[244:247], v[6:9]
	v_mfma_f32_16x16x32_bf16 v[6:9], v[216:219], v[240:243], v[200:203]
	v_mfma_f32_16x16x32_bf16 v[6:9], v[220:223], v[244:247], v[6:9]
	s_barrier
	s_setprio 0
	s_add_u32 s70, s70, 0x100180
	s_addc_u32 s71, s71, 0
	s_add_u32 s57, s66, 0x200
	s_addc_u32 s14, s67, 0
	s_mov_b32 s15, 0
.LBB0_249:
	ds_read_b128 v[152:155], v146
	ds_read_b128 v[156:159], v146 offset:1024
	ds_read_b128 v[160:163], v146 offset:2048
	ds_read_b128 v[164:167], v146 offset:3072
	ds_read_b128 v[168:171], v147
	ds_read_b128 v[172:175], v147 offset:1024
	ds_read_b128 v[176:179], v147 offset:2048
	ds_read_b128 v[180:183], v147 offset:3072
	s_add_u32 s16, s70, 0xfff00080
	s_addc_u32 s17, s71, -1
	s_cmp_eq_u32 s15, 60
	s_cselect_b32 s75, s47, s17
	s_cselect_b32 s74, s93, s16
	s_cselect_b32 s67, s4, s14
	s_cselect_b32 s66, s94, s57
	s_mov_b32 m0, s78
	ds_read_b128 v[184:187], v148
	ds_read_b128 v[188:191], v148 offset:1024
	ds_read_b128 v[192:195], v148 offset:2048
	ds_read_b128 v[196:199], v148 offset:3072
	ds_read_b128 v[200:203], v148 offset:4096
	ds_read_b128 v[204:207], v148 offset:5120
	ds_read_b128 v[208:211], v148 offset:6144
	ds_read_b128 v[212:215], v148 offset:7168
	global_load_lds_dwordx4 v138, s[70:71]
	s_mov_b32 m0, s79
	s_nop 0
	global_load_lds_dwordx4 v140, s[70:71]
	s_waitcnt vmcnt(8)
	s_waitcnt lgkmcnt(0)
	s_setprio 1
	s_barrier
	v_mfma_f32_16x16x32_bf16 v[122:125], v[152:155], v[184:187], v[122:125]
	v_mfma_f32_16x16x32_bf16 v[114:117], v[160:163], v[184:187], v[114:117]
	v_mfma_f32_16x16x32_bf16 v[106:109], v[152:155], v[192:195], v[106:109]
	v_mfma_f32_16x16x32_bf16 v[98:101], v[160:163], v[192:195], v[98:101]
	v_mfma_f32_16x16x32_bf16 v[90:93], v[152:155], v[200:203], v[90:93]
	v_mfma_f32_16x16x32_bf16 v[82:85], v[160:163], v[200:203], v[82:85]
	v_mfma_f32_16x16x32_bf16 v[74:77], v[152:155], v[208:211], v[74:77]
	v_mfma_f32_16x16x32_bf16 v[58:61], v[160:163], v[208:211], v[58:61]
	v_mfma_f32_16x16x32_bf16 v[122:125], v[156:159], v[188:191], v[122:125]
	v_mfma_f32_16x16x32_bf16 v[114:117], v[164:167], v[188:191], v[114:117]
	v_mfma_f32_16x16x32_bf16 v[106:109], v[156:159], v[196:199], v[106:109]
	v_mfma_f32_16x16x32_bf16 v[98:101], v[164:167], v[196:199], v[98:101]
	v_mfma_f32_16x16x32_bf16 v[90:93], v[156:159], v[204:207], v[90:93]
	v_mfma_f32_16x16x32_bf16 v[82:85], v[164:167], v[204:207], v[82:85]
	v_mfma_f32_16x16x32_bf16 v[74:77], v[156:159], v[212:215], v[74:77]
	v_mfma_f32_16x16x32_bf16 v[58:61], v[164:167], v[212:215], v[58:61]
	s_setprio 0
	s_setprio 1
	v_mfma_f32_16x16x32_bf16 v[126:129], v[168:171], v[184:187], v[126:129]
	v_mfma_f32_16x16x32_bf16 v[118:121], v[176:179], v[184:187], v[118:121]
	v_mfma_f32_16x16x32_bf16 v[110:113], v[168:171], v[192:195], v[110:113]
	v_mfma_f32_16x16x32_bf16 v[102:105], v[176:179], v[192:195], v[102:105]
	v_mfma_f32_16x16x32_bf16 v[94:97], v[168:171], v[200:203], v[94:97]
	v_mfma_f32_16x16x32_bf16 v[86:89], v[176:179], v[200:203], v[86:89]
	v_mfma_f32_16x16x32_bf16 v[78:81], v[168:171], v[208:211], v[78:81]
	v_mfma_f32_16x16x32_bf16 v[66:69], v[176:179], v[208:211], v[66:69]
	v_mfma_f32_16x16x32_bf16 v[126:129], v[172:175], v[188:191], v[126:129]
	v_mfma_f32_16x16x32_bf16 v[118:121], v[180:183], v[188:191], v[118:121]
	v_mfma_f32_16x16x32_bf16 v[110:113], v[172:175], v[196:199], v[110:113]
	v_mfma_f32_16x16x32_bf16 v[102:105], v[180:183], v[196:199], v[102:105]
	v_mfma_f32_16x16x32_bf16 v[94:97], v[172:175], v[204:207], v[94:97]
	v_mfma_f32_16x16x32_bf16 v[86:89], v[180:183], v[204:207], v[86:89]
	v_mfma_f32_16x16x32_bf16 v[78:81], v[172:175], v[212:215], v[78:81]
	v_mfma_f32_16x16x32_bf16 v[66:69], v[180:183], v[212:215], v[66:69]
	s_barrier
	s_setprio 0
	s_mov_b32 m0, s81
	s_mov_b64 s[98:99], s[66:67]
	s_add_u32 s16, s66, 0x100000
	ds_read_b128 v[184:187], v148 offset:16384
	ds_read_b128 v[188:191], v148 offset:17408
	ds_read_b128 v[192:195], v148 offset:18432
	ds_read_b128 v[196:199], v148 offset:19456
	ds_read_b128 v[200:203], v148 offset:20480
	ds_read_b128 v[204:207], v148 offset:21504
	ds_read_b128 v[208:211], v148 offset:22528
	ds_read_b128 v[212:215], v148 offset:23552
	global_load_lds_dwordx4 v134, s[66:67]
	s_mov_b32 m0, s82
	s_addc_u32 s17, s67, 0
	global_load_lds_dwordx4 v130, s[66:67]
	s_mov_b32 m0, s83
	s_mov_b64 s[100:101], s[74:75]
	global_load_lds_dwordx4 v134, s[16:17]
	s_mov_b32 m0, s86
	s_nop 0
	global_load_lds_dwordx4 v130, s[16:17]
	s_mov_b32 m0, s29
	s_nop 0
	global_load_lds_dwordx4 v136, s[74:75]
	s_mov_b32 m0, s33
	s_nop 0
	global_load_lds_dwordx4 v132, s[74:75]
	s_waitcnt vmcnt(8)
	s_waitcnt lgkmcnt(0)
	s_setprio 1
	s_barrier
	v_mfma_f32_16x16x32_bf16 v[62:65], v[152:155], v[184:187], v[62:65]
	v_mfma_f32_16x16x32_bf16 v[50:53], v[160:163], v[184:187], v[50:53]
	v_mfma_f32_16x16x32_bf16 v[42:45], v[152:155], v[192:195], v[42:45]
	v_mfma_f32_16x16x32_bf16 v[34:37], v[160:163], v[192:195], v[34:37]
	v_mfma_f32_16x16x32_bf16 v[26:29], v[152:155], v[200:203], v[26:29]
	v_mfma_f32_16x16x32_bf16 v[18:21], v[160:163], v[200:203], v[18:21]
	v_mfma_f32_16x16x32_bf16 v[10:13], v[152:155], v[208:211], v[10:13]
	v_mfma_f32_16x16x32_bf16 v[2:5], v[160:163], v[208:211], v[2:5]
	v_mfma_f32_16x16x32_bf16 v[62:65], v[156:159], v[188:191], v[62:65]
	v_mfma_f32_16x16x32_bf16 v[50:53], v[164:167], v[188:191], v[50:53]
	v_mfma_f32_16x16x32_bf16 v[42:45], v[156:159], v[196:199], v[42:45]
	v_mfma_f32_16x16x32_bf16 v[34:37], v[164:167], v[196:199], v[34:37]
	v_mfma_f32_16x16x32_bf16 v[26:29], v[156:159], v[204:207], v[26:29]
	v_mfma_f32_16x16x32_bf16 v[18:21], v[164:167], v[204:207], v[18:21]
	v_mfma_f32_16x16x32_bf16 v[10:13], v[156:159], v[212:215], v[10:13]
	v_mfma_f32_16x16x32_bf16 v[2:5], v[164:167], v[212:215], v[2:5]
	s_setprio 0
	s_setprio 1
	v_mfma_f32_16x16x32_bf16 v[70:73], v[168:171], v[184:187], v[70:73]
	v_mfma_f32_16x16x32_bf16 v[54:57], v[176:179], v[184:187], v[54:57]
	v_mfma_f32_16x16x32_bf16 v[46:49], v[168:171], v[192:195], v[46:49]
	v_mfma_f32_16x16x32_bf16 v[38:41], v[176:179], v[192:195], v[38:41]
	v_mfma_f32_16x16x32_bf16 v[30:33], v[168:171], v[200:203], v[30:33]
	v_mfma_f32_16x16x32_bf16 v[22:25], v[176:179], v[200:203], v[22:25]
	v_mfma_f32_16x16x32_bf16 v[14:17], v[168:171], v[208:211], v[14:17]
	v_mfma_f32_16x16x32_bf16 v[6:9], v[176:179], v[208:211], v[6:9]
	v_mfma_f32_16x16x32_bf16 v[70:73], v[172:175], v[188:191], v[70:73]
	v_mfma_f32_16x16x32_bf16 v[54:57], v[180:183], v[188:191], v[54:57]
	v_mfma_f32_16x16x32_bf16 v[46:49], v[172:175], v[196:199], v[46:49]
	v_mfma_f32_16x16x32_bf16 v[38:41], v[180:183], v[196:199], v[38:41]
	v_mfma_f32_16x16x32_bf16 v[30:33], v[172:175], v[204:207], v[30:33]
	v_mfma_f32_16x16x32_bf16 v[22:25], v[180:183], v[204:207], v[22:25]
	v_mfma_f32_16x16x32_bf16 v[14:17], v[172:175], v[212:215], v[14:17]
	v_mfma_f32_16x16x32_bf16 v[6:9], v[180:183], v[212:215], v[6:9]
	s_barrier
	s_setprio 0
	ds_read_b128 v[152:155], v149
	ds_read_b128 v[156:159], v149 offset:1024
	ds_read_b128 v[160:163], v149 offset:2048
	ds_read_b128 v[164:167], v149 offset:3072
	ds_read_b128 v[168:171], v150
	ds_read_b128 v[172:175], v150 offset:1024
	ds_read_b128 v[176:179], v150 offset:2048
	ds_read_b128 v[180:183], v150 offset:3072
	s_add_u32 s16, s74, 0x100000
	s_addc_u32 s17, s75, 0
	s_mov_b32 m0, s58
	ds_read_b128 v[184:187], v148 offset:32768
	ds_read_b128 v[188:191], v148 offset:33792
	ds_read_b128 v[192:195], v148 offset:34816
	ds_read_b128 v[196:199], v148 offset:35840
	ds_read_b128 v[200:203], v148 offset:36864
	ds_read_b128 v[204:207], v148 offset:37888
	ds_read_b128 v[208:211], v148 offset:38912
	ds_read_b128 v[212:215], v148 offset:39936
	global_load_lds_dwordx4 v136, s[16:17]
	s_mov_b32 m0, s59
	s_nop 0
	global_load_lds_dwordx4 v132, s[16:17]
	s_waitcnt vmcnt(8)
	s_waitcnt lgkmcnt(0)
	s_setprio 1
	s_barrier
	v_mfma_f32_16x16x32_bf16 v[122:125], v[152:155], v[184:187], v[122:125]
	v_mfma_f32_16x16x32_bf16 v[114:117], v[160:163], v[184:187], v[114:117]
	v_mfma_f32_16x16x32_bf16 v[106:109], v[152:155], v[192:195], v[106:109]
	v_mfma_f32_16x16x32_bf16 v[98:101], v[160:163], v[192:195], v[98:101]
	v_mfma_f32_16x16x32_bf16 v[90:93], v[152:155], v[200:203], v[90:93]
	v_mfma_f32_16x16x32_bf16 v[82:85], v[160:163], v[200:203], v[82:85]
	v_mfma_f32_16x16x32_bf16 v[74:77], v[152:155], v[208:211], v[74:77]
	v_mfma_f32_16x16x32_bf16 v[58:61], v[160:163], v[208:211], v[58:61]
	v_mfma_f32_16x16x32_bf16 v[122:125], v[156:159], v[188:191], v[122:125]
	v_mfma_f32_16x16x32_bf16 v[114:117], v[164:167], v[188:191], v[114:117]
	v_mfma_f32_16x16x32_bf16 v[106:109], v[156:159], v[196:199], v[106:109]
	v_mfma_f32_16x16x32_bf16 v[98:101], v[164:167], v[196:199], v[98:101]
	v_mfma_f32_16x16x32_bf16 v[90:93], v[156:159], v[204:207], v[90:93]
	v_mfma_f32_16x16x32_bf16 v[82:85], v[164:167], v[204:207], v[82:85]
	v_mfma_f32_16x16x32_bf16 v[74:77], v[156:159], v[212:215], v[74:77]
	v_mfma_f32_16x16x32_bf16 v[58:61], v[164:167], v[212:215], v[58:61]
	s_setprio 0
	s_setprio 1
	v_mfma_f32_16x16x32_bf16 v[126:129], v[168:171], v[184:187], v[126:129]
	v_mfma_f32_16x16x32_bf16 v[118:121], v[176:179], v[184:187], v[118:121]
	v_mfma_f32_16x16x32_bf16 v[110:113], v[168:171], v[192:195], v[110:113]
	v_mfma_f32_16x16x32_bf16 v[102:105], v[176:179], v[192:195], v[102:105]
	v_mfma_f32_16x16x32_bf16 v[94:97], v[168:171], v[200:203], v[94:97]
	v_mfma_f32_16x16x32_bf16 v[86:89], v[176:179], v[200:203], v[86:89]
	v_mfma_f32_16x16x32_bf16 v[78:81], v[168:171], v[208:211], v[78:81]
	v_mfma_f32_16x16x32_bf16 v[66:69], v[176:179], v[208:211], v[66:69]
	v_mfma_f32_16x16x32_bf16 v[126:129], v[172:175], v[188:191], v[126:129]
	v_mfma_f32_16x16x32_bf16 v[118:121], v[180:183], v[188:191], v[118:121]
	v_mfma_f32_16x16x32_bf16 v[110:113], v[172:175], v[196:199], v[110:113]
	v_mfma_f32_16x16x32_bf16 v[102:105], v[180:183], v[196:199], v[102:105]
	v_mfma_f32_16x16x32_bf16 v[94:97], v[172:175], v[204:207], v[94:97]
	v_mfma_f32_16x16x32_bf16 v[86:89], v[180:183], v[204:207], v[86:89]
	v_mfma_f32_16x16x32_bf16 v[78:81], v[172:175], v[212:215], v[78:81]
	v_mfma_f32_16x16x32_bf16 v[66:69], v[180:183], v[212:215], v[66:69]
	s_barrier
	s_setprio 0
	s_mov_b32 m0, s87
	s_add_u32 s98, s98, 0x80
	s_addc_u32 s99, s99, 0
	s_add_u32 s100, s100, 0x80
	s_addc_u32 s101, s101, 0
	s_add_u32 s16, s66, 0x100080
	ds_read_b128 v[184:187], v148 offset:49152
	ds_read_b128 v[188:191], v148 offset:50176
	ds_read_b128 v[192:195], v148 offset:51200
	ds_read_b128 v[196:199], v148 offset:52224
	ds_read_b128 v[200:203], v148 offset:53248
	ds_read_b128 v[204:207], v148 offset:54272
	ds_read_b128 v[208:211], v148 offset:55296
	ds_read_b128 v[212:215], v148 offset:56320
	global_load_lds_dwordx4 v134, s[98:99]
	s_mov_b32 m0, s88
	s_addc_u32 s17, s67, 0
	global_load_lds_dwordx4 v130, s[98:99]
	s_mov_b32 m0, s89
	s_nop 0
	global_load_lds_dwordx4 v134, s[16:17]
	s_mov_b32 m0, s56
	s_nop 0
	global_load_lds_dwordx4 v130, s[16:17]
	s_mov_b32 m0, s65
	s_nop 0
	global_load_lds_dwordx4 v136, s[100:101]
	s_mov_b32 m0, s76
	s_nop 0
	global_load_lds_dwordx4 v132, s[100:101]
	s_waitcnt vmcnt(8)
	s_waitcnt lgkmcnt(0)
	s_setprio 1
	s_barrier
	v_mfma_f32_16x16x32_bf16 v[62:65], v[152:155], v[184:187], v[62:65]
	v_mfma_f32_16x16x32_bf16 v[50:53], v[160:163], v[184:187], v[50:53]
	v_mfma_f32_16x16x32_bf16 v[42:45], v[152:155], v[192:195], v[42:45]
	v_mfma_f32_16x16x32_bf16 v[34:37], v[160:163], v[192:195], v[34:37]
	v_mfma_f32_16x16x32_bf16 v[26:29], v[152:155], v[200:203], v[26:29]
	v_mfma_f32_16x16x32_bf16 v[18:21], v[160:163], v[200:203], v[18:21]
	v_mfma_f32_16x16x32_bf16 v[10:13], v[152:155], v[208:211], v[10:13]
	v_mfma_f32_16x16x32_bf16 v[2:5], v[160:163], v[208:211], v[2:5]
	v_mfma_f32_16x16x32_bf16 v[62:65], v[156:159], v[188:191], v[62:65]
	v_mfma_f32_16x16x32_bf16 v[50:53], v[164:167], v[188:191], v[50:53]
	v_mfma_f32_16x16x32_bf16 v[42:45], v[156:159], v[196:199], v[42:45]
	v_mfma_f32_16x16x32_bf16 v[34:37], v[164:167], v[196:199], v[34:37]
	v_mfma_f32_16x16x32_bf16 v[26:29], v[156:159], v[204:207], v[26:29]
	v_mfma_f32_16x16x32_bf16 v[18:21], v[164:167], v[204:207], v[18:21]
	v_mfma_f32_16x16x32_bf16 v[10:13], v[156:159], v[212:215], v[10:13]
	v_mfma_f32_16x16x32_bf16 v[2:5], v[164:167], v[212:215], v[2:5]
	s_setprio 0
	s_setprio 1
	v_mfma_f32_16x16x32_bf16 v[70:73], v[168:171], v[184:187], v[70:73]
	v_mfma_f32_16x16x32_bf16 v[54:57], v[176:179], v[184:187], v[54:57]
	v_mfma_f32_16x16x32_bf16 v[46:49], v[168:171], v[192:195], v[46:49]
	v_mfma_f32_16x16x32_bf16 v[38:41], v[176:179], v[192:195], v[38:41]
	v_mfma_f32_16x16x32_bf16 v[30:33], v[168:171], v[200:203], v[30:33]
	v_mfma_f32_16x16x32_bf16 v[22:25], v[176:179], v[200:203], v[22:25]
	v_mfma_f32_16x16x32_bf16 v[14:17], v[168:171], v[208:211], v[14:17]
	v_mfma_f32_16x16x32_bf16 v[6:9], v[176:179], v[208:211], v[6:9]
	v_mfma_f32_16x16x32_bf16 v[70:73], v[172:175], v[188:191], v[70:73]
	v_mfma_f32_16x16x32_bf16 v[54:57], v[180:183], v[188:191], v[54:57]
	v_mfma_f32_16x16x32_bf16 v[46:49], v[172:175], v[196:199], v[46:49]
	v_mfma_f32_16x16x32_bf16 v[38:41], v[180:183], v[196:199], v[38:41]
	v_mfma_f32_16x16x32_bf16 v[30:33], v[172:175], v[204:207], v[30:33]
	v_mfma_f32_16x16x32_bf16 v[22:25], v[180:183], v[204:207], v[22:25]
	v_mfma_f32_16x16x32_bf16 v[14:17], v[172:175], v[212:215], v[14:17]
	v_mfma_f32_16x16x32_bf16 v[6:9], v[180:183], v[212:215], v[6:9]
	s_barrier
	s_setprio 0
	s_add_i32 s15, s15, 2
	s_add_u32 s70, s70, 0x100
	s_addc_u32 s71, s71, 0
	s_add_u32 s57, s57, 0x100
	s_addc_u32 s14, s14, 0
	s_cmp_gt_u32 s15, 61
	s_cbranch_scc0 .LBB0_249
	s_and_b64 vcc, exec, s[12:13]
	s_cbranch_vccz .LBB0_252
	s_barrier

.LBB0_330:
	ds_read_b128 v[2:5], v207
	ds_read_b128 v[6:9], v207 offset:1024
	ds_read_b128 v[10:13], v207 offset:2048
	ds_read_b128 v[14:17], v207 offset:3072
	ds_read_b128 v[18:21], v208
	ds_read_b128 v[22:25], v208 offset:1024
	ds_read_b128 v[26:29], v208 offset:2048
	ds_read_b128 v[30:33], v208 offset:3072
	s_add_u32 s14, s66, 0x2b0080
	s_addc_u32 s15, s67, 0
	s_add_i32 s86, s11, 0xc000
	v_lshl_add_u64 v[66:67], s[14:15], 0, v[178:179]
	s_mov_b32 m0, s86
	s_add_i32 s87, s11, 0xe000
	ds_read_b128 v[34:37], v209
	ds_read_b128 v[38:41], v209 offset:1024
	ds_read_b128 v[42:45], v209 offset:2048
	ds_read_b128 v[46:49], v209 offset:3072
	ds_read_b128 v[50:53], v209 offset:4096
	ds_read_b128 v[54:57], v209 offset:5120
	ds_read_b128 v[58:61], v209 offset:6144
	ds_read_b128 v[62:65], v209 offset:7168
	global_load_lds_dwordx4 v[66:67], off
	v_lshl_add_u64 v[66:67], s[14:15], 0, v[182:183]
	s_mov_b32 m0, s87
	s_nop 0
	global_load_lds_dwordx4 v[66:67], off
	s_waitcnt vmcnt(8)
	s_waitcnt lgkmcnt(0)
	s_setprio 1
	s_barrier
	v_mfma_f32_16x16x32_bf16 v[90:93], v[2:5], v[58:61], 0
	v_mfma_f32_16x16x32_bf16 v[66:69], v[2:5], v[34:37], 0
	v_mfma_f32_16x16x32_bf16 v[70:73], v[10:13], v[34:37], 0
	v_mfma_f32_16x16x32_bf16 v[74:77], v[2:5], v[42:45], 0
	v_mfma_f32_16x16x32_bf16 v[78:81], v[10:13], v[42:45], 0
	v_mfma_f32_16x16x32_bf16 v[82:85], v[2:5], v[50:53], 0
	v_mfma_f32_16x16x32_bf16 v[86:89], v[10:13], v[50:53], 0
	v_mfma_f32_16x16x32_bf16 v[98:101], v[6:9], v[62:65], v[90:93]
	v_mfma_f32_16x16x32_bf16 v[90:93], v[10:13], v[58:61], 0
	v_mfma_f32_16x16x32_bf16 v[66:69], v[6:9], v[38:41], v[66:69]
	v_mfma_f32_16x16x32_bf16 v[70:73], v[14:17], v[38:41], v[70:73]
	v_mfma_f32_16x16x32_bf16 v[74:77], v[6:9], v[46:49], v[74:77]
	v_mfma_f32_16x16x32_bf16 v[78:81], v[14:17], v[46:49], v[78:81]
	v_mfma_f32_16x16x32_bf16 v[82:85], v[6:9], v[54:57], v[82:85]
	v_mfma_f32_16x16x32_bf16 v[86:89], v[14:17], v[54:57], v[86:89]
	v_mfma_f32_16x16x32_bf16 v[102:105], v[14:17], v[62:65], v[90:93]
	s_setprio 0
	s_setprio 1
	v_mfma_f32_16x16x32_bf16 v[90:93], v[18:21], v[34:37], 0
	v_mfma_f32_16x16x32_bf16 v[34:37], v[26:29], v[34:37], 0
	v_mfma_f32_16x16x32_bf16 v[114:117], v[22:25], v[38:41], v[90:93]
	v_mfma_f32_16x16x32_bf16 v[34:37], v[30:33], v[38:41], v[34:37]
	v_mfma_f32_16x16x32_bf16 v[38:41], v[18:21], v[42:45], 0
	v_mfma_f32_16x16x32_bf16 v[42:45], v[26:29], v[42:45], 0
	v_mfma_f32_16x16x32_bf16 v[38:41], v[22:25], v[46:49], v[38:41]
	v_mfma_f32_16x16x32_bf16 v[42:45], v[30:33], v[46:49], v[42:45]
	v_mfma_f32_16x16x32_bf16 v[46:49], v[18:21], v[50:53], 0
	v_mfma_f32_16x16x32_bf16 v[50:53], v[26:29], v[50:53], 0
	v_mfma_f32_16x16x32_bf16 v[46:49], v[22:25], v[54:57], v[46:49]
	v_mfma_f32_16x16x32_bf16 v[50:53], v[30:33], v[54:57], v[50:53]
	v_mfma_f32_16x16x32_bf16 v[54:57], v[18:21], v[58:61], 0
	v_mfma_f32_16x16x32_bf16 v[58:61], v[26:29], v[58:61], 0
	v_mfma_f32_16x16x32_bf16 v[54:57], v[22:25], v[62:65], v[54:57]
	v_mfma_f32_16x16x32_bf16 v[58:61], v[30:33], v[62:65], v[58:61]
	s_barrier
	s_setprio 0
	s_add_i32 s88, s78, s10
	v_lshl_add_u64 v[176:177], s[70:71], 0, v[180:181]
	s_add_i32 s84, s88, 0x2000
	v_lshl_add_u64 v[130:131], v[176:177], 0, s[60:61]
	s_mov_b32 m0, s88
	v_lshl_add_u64 v[250:251], s[70:71], 0, v[184:185]
	s_add_u32 s14, s70, 0x2b0100
	ds_read_b128 v[62:65], v209 offset:16384
	ds_read_b128 v[90:93], v209 offset:17408
	ds_read_b128 v[94:97], v209 offset:18432
	ds_read_b128 v[106:109], v209 offset:19456
	ds_read_b128 v[110:113], v209 offset:20480
	ds_read_b128 v[118:121], v209 offset:21504
	ds_read_b128 v[122:125], v209 offset:22528
	ds_read_b128 v[126:129], v209 offset:23552
	global_load_lds_dwordx4 v[130:131], off
	v_lshl_add_u64 v[130:131], v[250:251], 0, s[60:61]
	s_mov_b32 m0, s84
	s_addc_u32 s15, s71, 0
	s_add_i32 s85, s79, s10
	global_load_lds_dwordx4 v[130:131], off
	v_lshl_add_u64 v[130:131], s[14:15], 0, v[180:181]
	s_mov_b32 m0, s85
	s_add_i32 s46, s85, 0x2000
	global_load_lds_dwordx4 v[130:131], off
	v_lshl_add_u64 v[130:131], s[14:15], 0, v[184:185]
	s_mov_b32 m0, s46
	v_lshl_add_u64 v[252:253], s[66:67], 0, v[178:179]
	global_load_lds_dwordx4 v[130:131], off
	v_lshl_add_u64 v[130:131], v[252:253], 0, s[60:61]
	s_mov_b32 m0, s11
	v_lshl_add_u64 v[190:191], s[66:67], 0, v[182:183]
	global_load_lds_dwordx4 v[130:131], off
	v_lshl_add_u64 v[130:131], v[190:191], 0, s[60:61]
	s_mov_b32 m0, s12
	s_nop 0
	global_load_lds_dwordx4 v[130:131], off
	s_waitcnt vmcnt(8)
	s_waitcnt lgkmcnt(0)
	s_setprio 1
	s_barrier
	v_mfma_f32_16x16x32_bf16 v[130:133], v[2:5], v[62:65], 0
	v_mfma_f32_16x16x32_bf16 v[140:143], v[2:5], v[94:97], 0
	v_mfma_f32_16x16x32_bf16 v[148:151], v[2:5], v[110:113], 0
	v_mfma_f32_16x16x32_bf16 v[2:5], v[2:5], v[122:125], 0
	v_mfma_f32_16x16x32_bf16 v[132:135], v[6:9], v[90:93], v[130:133]
	v_mfma_f32_16x16x32_bf16 v[140:143], v[6:9], v[106:109], v[140:143]
	v_mfma_f32_16x16x32_bf16 v[148:151], v[6:9], v[118:121], v[148:151]
	v_mfma_f32_16x16x32_bf16 v[2:5], v[6:9], v[126:129], v[2:5]
	v_mfma_f32_16x16x32_bf16 v[6:9], v[10:13], v[122:125], 0
	v_mfma_f32_16x16x32_bf16 v[136:139], v[10:13], v[62:65], 0
	v_mfma_f32_16x16x32_bf16 v[144:147], v[10:13], v[94:97], 0
	v_mfma_f32_16x16x32_bf16 v[152:155], v[10:13], v[110:113], 0
	v_mfma_f32_16x16x32_bf16 v[6:9], v[14:17], v[126:129], v[6:9]
	v_mfma_f32_16x16x32_bf16 v[136:139], v[14:17], v[90:93], v[136:139]
	v_mfma_f32_16x16x32_bf16 v[144:147], v[14:17], v[106:109], v[144:147]
	v_mfma_f32_16x16x32_bf16 v[152:155], v[14:17], v[118:121], v[152:155]
	s_setprio 0
	s_setprio 1
	v_mfma_f32_16x16x32_bf16 v[10:13], v[18:21], v[62:65], 0
	v_mfma_f32_16x16x32_bf16 v[156:159], v[22:25], v[90:93], v[10:13]
	v_mfma_f32_16x16x32_bf16 v[10:13], v[26:29], v[62:65], 0
	v_mfma_f32_16x16x32_bf16 v[160:163], v[30:33], v[90:93], v[10:13]
	v_mfma_f32_16x16x32_bf16 v[10:13], v[18:21], v[94:97], 0
	v_mfma_f32_16x16x32_bf16 v[164:167], v[22:25], v[106:109], v[10:13]
	v_mfma_f32_16x16x32_bf16 v[10:13], v[26:29], v[94:97], 0
	v_mfma_f32_16x16x32_bf16 v[168:171], v[30:33], v[106:109], v[10:13]
	v_mfma_f32_16x16x32_bf16 v[10:13], v[18:21], v[110:113], 0
	v_mfma_f32_16x16x32_bf16 v[172:175], v[22:25], v[118:121], v[10:13]
	v_mfma_f32_16x16x32_bf16 v[10:13], v[26:29], v[110:113], 0
	v_mfma_f32_16x16x32_bf16 v[194:197], v[30:33], v[118:121], v[10:13]
	v_mfma_f32_16x16x32_bf16 v[10:13], v[18:21], v[122:125], 0
	v_mfma_f32_16x16x32_bf16 v[198:201], v[22:25], v[126:129], v[10:13]
	v_mfma_f32_16x16x32_bf16 v[10:13], v[26:29], v[122:125], 0
	v_mfma_f32_16x16x32_bf16 v[202:205], v[30:33], v[126:129], v[10:13]
	s_barrier
	s_setprio 0
	s_add_i32 s47, 0, 0x18000
	s_add_i32 s56, 0, 0x1c000
	v_add_u32_e32 v130, s47, v206
	v_add_u32_e32 v131, s56, v206
	s_nop 0
	ds_read_b128 v[10:13], v130
	ds_read_b128 v[14:17], v130 offset:1024
	ds_read_b128 v[18:21], v130 offset:2048
	ds_read_b128 v[22:25], v130 offset:3072
	ds_read_b128 v[210:213], v131
	ds_read_b128 v[214:217], v131 offset:1024
	ds_read_b128 v[218:221], v131 offset:2048
	ds_read_b128 v[222:225], v131 offset:3072
	s_add_u32 s14, s66, 0x2b0100
	s_addc_u32 s15, s67, 0
	s_mov_b32 m0, s13
	v_lshl_add_u64 v[90:91], s[14:15], 0, v[178:179]
	ds_read_b128 v[26:29], v209 offset:32768
	ds_read_b128 v[30:33], v209 offset:33792
	ds_read_b128 v[62:65], v209 offset:34816
	ds_read_b128 v[226:229], v209 offset:35840
	ds_read_b128 v[230:233], v209 offset:36864
	ds_read_b128 v[234:237], v209 offset:37888
	ds_read_b128 v[238:241], v209 offset:38912
	ds_read_b128 v[242:245], v209 offset:39936
	global_load_lds_dwordx4 v[90:91], off
	v_lshl_add_u64 v[90:91], s[14:15], 0, v[182:183]
	s_mov_b32 m0, s29
	s_nop 0
	global_load_lds_dwordx4 v[90:91], off
	s_waitcnt vmcnt(8)
	s_waitcnt lgkmcnt(0)
	s_setprio 1
	s_barrier
	v_mfma_f32_16x16x32_bf16 v[66:69], v[10:13], v[26:29], v[66:69]
	v_mfma_f32_16x16x32_bf16 v[122:125], v[14:17], v[30:33], v[66:69]
	v_mfma_f32_16x16x32_bf16 v[66:69], v[18:21], v[26:29], v[70:73]
	v_mfma_f32_16x16x32_bf16 v[118:121], v[22:25], v[30:33], v[66:69]
	v_mfma_f32_16x16x32_bf16 v[66:69], v[10:13], v[62:65], v[74:77]
	v_mfma_f32_16x16x32_bf16 v[110:113], v[14:17], v[226:229], v[66:69]
	v_mfma_f32_16x16x32_bf16 v[66:69], v[18:21], v[62:65], v[78:81]
	v_mfma_f32_16x16x32_bf16 v[106:109], v[22:25], v[226:229], v[66:69]
	v_mfma_f32_16x16x32_bf16 v[66:69], v[10:13], v[230:233], v[82:85]
	v_mfma_f32_16x16x32_bf16 v[94:97], v[14:17], v[234:237], v[66:69]
	v_mfma_f32_16x16x32_bf16 v[66:69], v[18:21], v[230:233], v[86:89]
	v_mfma_f32_16x16x32_bf16 v[90:93], v[22:25], v[234:237], v[66:69]
	v_mfma_f32_16x16x32_bf16 v[66:69], v[10:13], v[238:241], v[98:101]
	v_mfma_f32_16x16x32_bf16 v[78:81], v[14:17], v[242:245], v[66:69]
	v_mfma_f32_16x16x32_bf16 v[66:69], v[18:21], v[238:241], v[102:105]
	v_mfma_f32_16x16x32_bf16 v[74:77], v[22:25], v[242:245], v[66:69]
	s_setprio 0
	s_setprio 1
	v_mfma_f32_16x16x32_bf16 v[66:69], v[210:213], v[26:29], v[114:117]
	v_mfma_f32_16x16x32_bf16 v[26:29], v[218:221], v[26:29], v[34:37]
	v_mfma_f32_16x16x32_bf16 v[114:117], v[222:225], v[30:33], v[26:29]
	v_mfma_f32_16x16x32_bf16 v[26:29], v[210:213], v[62:65], v[38:41]
	v_mfma_f32_16x16x32_bf16 v[102:105], v[214:217], v[226:229], v[26:29]
	v_mfma_f32_16x16x32_bf16 v[26:29], v[218:221], v[62:65], v[42:45]
	v_mfma_f32_16x16x32_bf16 v[98:101], v[222:225], v[226:229], v[26:29]
	v_mfma_f32_16x16x32_bf16 v[26:29], v[210:213], v[230:233], v[46:49]
	v_mfma_f32_16x16x32_bf16 v[86:89], v[214:217], v[234:237], v[26:29]
	v_mfma_f32_16x16x32_bf16 v[26:29], v[218:221], v[230:233], v[50:53]
	v_mfma_f32_16x16x32_bf16 v[82:85], v[222:225], v[234:237], v[26:29]
	v_mfma_f32_16x16x32_bf16 v[26:29], v[210:213], v[238:241], v[54:57]
	v_mfma_f32_16x16x32_bf16 v[70:73], v[214:217], v[242:245], v[26:29]
	v_mfma_f32_16x16x32_bf16 v[26:29], v[218:221], v[238:241], v[58:61]
	v_mfma_f32_16x16x32_bf16 v[126:129], v[214:217], v[30:33], v[66:69]
	v_mfma_f32_16x16x32_bf16 v[66:69], v[222:225], v[242:245], v[26:29]
	s_barrier
	s_setprio 0
	s_add_i32 s47, s47, s10
	s_add_i32 s89, s47, 0x2000
	s_nop 1
	v_lshl_add_u64 v[26:27], v[176:177], 0, s[62:63]
	s_mov_b32 m0, s47
	s_add_u32 s14, s70, 0x2b0180
	ds_read_b128 v[34:37], v209 offset:49152
	ds_read_b128 v[38:41], v209 offset:50176
	ds_read_b128 v[226:229], v209 offset:51200
	ds_read_b128 v[230:233], v209 offset:52224
	ds_read_b128 v[234:237], v209 offset:53248
	ds_read_b128 v[238:241], v209 offset:54272
	ds_read_b128 v[242:245], v209 offset:55296
	ds_read_b128 v[246:249], v209 offset:56320
	global_load_lds_dwordx4 v[26:27], off
	v_lshl_add_u64 v[26:27], v[250:251], 0, s[62:63]
	s_mov_b32 m0, s89
	s_addc_u32 s15, s71, 0
	s_add_i32 s56, s56, s10
	global_load_lds_dwordx4 v[26:27], off
	v_lshl_add_u64 v[26:27], s[14:15], 0, v[180:181]
	s_mov_b32 m0, s56
	s_add_i32 s57, s56, 0x2000
	global_load_lds_dwordx4 v[26:27], off
	v_lshl_add_u64 v[26:27], s[14:15], 0, v[184:185]
	s_mov_b32 m0, s57
	s_nop 0
	global_load_lds_dwordx4 v[26:27], off
	v_lshl_add_u64 v[26:27], v[252:253], 0, s[62:63]
	s_mov_b32 m0, s58
	s_nop 0
	global_load_lds_dwordx4 v[26:27], off
	v_lshl_add_u64 v[26:27], v[190:191], 0, s[62:63]
	s_mov_b32 m0, s59
	s_nop 0
	global_load_lds_dwordx4 v[26:27], off
	s_waitcnt vmcnt(8)
	s_waitcnt lgkmcnt(0)
	s_setprio 1
	s_barrier
	v_mfma_f32_16x16x32_bf16 v[26:29], v[10:13], v[34:37], v[132:135]
	v_mfma_f32_16x16x32_bf16 v[58:61], v[14:17], v[38:41], v[26:29]
	v_mfma_f32_16x16x32_bf16 v[26:29], v[18:21], v[34:37], v[136:139]
	v_mfma_f32_16x16x32_bf16 v[54:57], v[22:25], v[38:41], v[26:29]
	v_mfma_f32_16x16x32_bf16 v[26:29], v[10:13], v[226:229], v[140:143]
	v_mfma_f32_16x16x32_bf16 v[46:49], v[14:17], v[230:233], v[26:29]
	v_mfma_f32_16x16x32_bf16 v[26:29], v[18:21], v[226:229], v[144:147]
	v_mfma_f32_16x16x32_bf16 v[42:45], v[22:25], v[230:233], v[26:29]
	v_mfma_f32_16x16x32_bf16 v[26:29], v[10:13], v[234:237], v[148:151]
	v_mfma_f32_16x16x32_bf16 v[2:5], v[10:13], v[242:245], v[2:5]
	v_mfma_f32_16x16x32_bf16 v[30:33], v[14:17], v[238:241], v[26:29]
	v_mfma_f32_16x16x32_bf16 v[26:29], v[18:21], v[234:237], v[152:155]
	v_mfma_f32_16x16x32_bf16 v[14:17], v[14:17], v[246:249], v[2:5]
	v_mfma_f32_16x16x32_bf16 v[2:5], v[18:21], v[242:245], v[6:9]
	v_mfma_f32_16x16x32_bf16 v[26:29], v[22:25], v[238:241], v[26:29]
	v_mfma_f32_16x16x32_bf16 v[10:13], v[22:25], v[246:249], v[2:5]
	s_setprio 0
	s_setprio 1
	v_mfma_f32_16x16x32_bf16 v[2:5], v[210:213], v[34:37], v[156:159]
	v_mfma_f32_16x16x32_bf16 v[62:65], v[214:217], v[38:41], v[2:5]
	v_mfma_f32_16x16x32_bf16 v[2:5], v[218:221], v[34:37], v[160:163]
	v_mfma_f32_16x16x32_bf16 v[50:53], v[222:225], v[38:41], v[2:5]
	v_mfma_f32_16x16x32_bf16 v[2:5], v[210:213], v[226:229], v[164:167]
	v_mfma_f32_16x16x32_bf16 v[38:41], v[214:217], v[230:233], v[2:5]
	v_mfma_f32_16x16x32_bf16 v[2:5], v[218:221], v[226:229], v[168:171]
	v_mfma_f32_16x16x32_bf16 v[34:37], v[222:225], v[230:233], v[2:5]
	v_mfma_f32_16x16x32_bf16 v[2:5], v[210:213], v[234:237], v[172:175]
	v_mfma_f32_16x16x32_bf16 v[22:25], v[214:217], v[238:241], v[2:5]
	v_mfma_f32_16x16x32_bf16 v[2:5], v[218:221], v[234:237], v[194:197]
	v_mfma_f32_16x16x32_bf16 v[18:21], v[222:225], v[238:241], v[2:5]
	v_mfma_f32_16x16x32_bf16 v[2:5], v[210:213], v[242:245], v[198:201]
	v_mfma_f32_16x16x32_bf16 v[6:9], v[214:217], v[246:249], v[2:5]
	v_mfma_f32_16x16x32_bf16 v[2:5], v[218:221], v[242:245], v[202:205]
	v_mfma_f32_16x16x32_bf16 v[2:5], v[222:225], v[246:249], v[2:5]
	s_barrier
	s_setprio 0
	s_add_u32 s90, s70, 0x200
	s_addc_u32 s14, s71, 0
	s_mov_b32 s15, 0
.LBB0_331:
	ds_read_b128 v[132:135], v207
	ds_read_b128 v[136:139], v207 offset:1024
	ds_read_b128 v[140:143], v207 offset:2048
	ds_read_b128 v[144:147], v207 offset:3072
	ds_read_b128 v[148:151], v208
	ds_read_b128 v[152:155], v208 offset:1024
	ds_read_b128 v[156:159], v208 offset:2048
	ds_read_b128 v[160:163], v208 offset:3072
	s_add_u32 s16, s66, 0x200
	s_addc_u32 s17, s67, 0
	s_cmpk_eq_i32 s15, 0xa8
	s_cselect_b32 s75, s1, s17
	s_cselect_b32 s74, s0, s16
	s_cselect_b32 s71, s65, s14
	s_cselect_b32 s70, s64, s90
	s_mov_b32 m0, s86
	ds_read_b128 v[164:167], v209
	ds_read_b128 v[168:171], v209 offset:1024
	ds_read_b128 v[172:175], v209 offset:2048
	ds_read_b128 v[194:197], v209 offset:3072
	ds_read_b128 v[198:201], v209 offset:4096
	ds_read_b128 v[202:205], v209 offset:5120
	ds_read_b128 v[210:213], v209 offset:6144
	ds_read_b128 v[214:217], v209 offset:7168
	global_load_lds_dwordx4 v186, s[66:67]
	s_mov_b32 m0, s87
	s_nop 0
	global_load_lds_dwordx4 v188, s[66:67]
	s_waitcnt vmcnt(8)
	s_waitcnt lgkmcnt(0)
	s_setprio 1
	s_barrier
	v_mfma_f32_16x16x32_bf16 v[122:125], v[132:135], v[164:167], v[122:125]
	v_mfma_f32_16x16x32_bf16 v[118:121], v[140:143], v[164:167], v[118:121]
	v_mfma_f32_16x16x32_bf16 v[110:113], v[132:135], v[172:175], v[110:113]
	v_mfma_f32_16x16x32_bf16 v[106:109], v[140:143], v[172:175], v[106:109]
	v_mfma_f32_16x16x32_bf16 v[94:97], v[132:135], v[198:201], v[94:97]
	v_mfma_f32_16x16x32_bf16 v[90:93], v[140:143], v[198:201], v[90:93]
	v_mfma_f32_16x16x32_bf16 v[78:81], v[132:135], v[210:213], v[78:81]
	v_mfma_f32_16x16x32_bf16 v[74:77], v[140:143], v[210:213], v[74:77]
	v_mfma_f32_16x16x32_bf16 v[122:125], v[136:139], v[168:171], v[122:125]
	v_mfma_f32_16x16x32_bf16 v[118:121], v[144:147], v[168:171], v[118:121]
	v_mfma_f32_16x16x32_bf16 v[110:113], v[136:139], v[194:197], v[110:113]
	v_mfma_f32_16x16x32_bf16 v[106:109], v[144:147], v[194:197], v[106:109]
	v_mfma_f32_16x16x32_bf16 v[94:97], v[136:139], v[202:205], v[94:97]
	v_mfma_f32_16x16x32_bf16 v[90:93], v[144:147], v[202:205], v[90:93]
	v_mfma_f32_16x16x32_bf16 v[78:81], v[136:139], v[214:217], v[78:81]
	v_mfma_f32_16x16x32_bf16 v[74:77], v[144:147], v[214:217], v[74:77]
	s_setprio 0
	s_setprio 1
	v_mfma_f32_16x16x32_bf16 v[126:129], v[148:151], v[164:167], v[126:129]
	v_mfma_f32_16x16x32_bf16 v[114:117], v[156:159], v[164:167], v[114:117]
	v_mfma_f32_16x16x32_bf16 v[102:105], v[148:151], v[172:175], v[102:105]
	v_mfma_f32_16x16x32_bf16 v[98:101], v[156:159], v[172:175], v[98:101]
	v_mfma_f32_16x16x32_bf16 v[86:89], v[148:151], v[198:201], v[86:89]
	v_mfma_f32_16x16x32_bf16 v[82:85], v[156:159], v[198:201], v[82:85]
	v_mfma_f32_16x16x32_bf16 v[70:73], v[148:151], v[210:213], v[70:73]
	v_mfma_f32_16x16x32_bf16 v[66:69], v[156:159], v[210:213], v[66:69]
	v_mfma_f32_16x16x32_bf16 v[126:129], v[152:155], v[168:171], v[126:129]
	v_mfma_f32_16x16x32_bf16 v[114:117], v[160:163], v[168:171], v[114:117]
	v_mfma_f32_16x16x32_bf16 v[102:105], v[152:155], v[194:197], v[102:105]
	v_mfma_f32_16x16x32_bf16 v[98:101], v[160:163], v[194:197], v[98:101]
	v_mfma_f32_16x16x32_bf16 v[86:89], v[152:155], v[202:205], v[86:89]
	v_mfma_f32_16x16x32_bf16 v[82:85], v[160:163], v[202:205], v[82:85]
	v_mfma_f32_16x16x32_bf16 v[70:73], v[152:155], v[214:217], v[70:73]
	v_mfma_f32_16x16x32_bf16 v[66:69], v[160:163], v[214:217], v[66:69]
	s_barrier
	s_setprio 0
	s_mov_b32 m0, s88
	s_mov_b64 s[98:99], s[70:71]
	s_add_u32 s16, s70, 0x2b0000
	ds_read_b128 v[164:167], v209 offset:16384
	ds_read_b128 v[168:171], v209 offset:17408
	ds_read_b128 v[172:175], v209 offset:18432
	ds_read_b128 v[194:197], v209 offset:19456
	ds_read_b128 v[198:201], v209 offset:20480
	ds_read_b128 v[202:205], v209 offset:21504
	ds_read_b128 v[210:213], v209 offset:22528
	ds_read_b128 v[214:217], v209 offset:23552
	global_load_lds_dwordx4 v180, s[70:71]
	s_mov_b32 m0, s84
	s_addc_u32 s17, s71, 0
	global_load_lds_dwordx4 v184, s[70:71]
	s_mov_b32 m0, s85
	s_mov_b64 s[100:101], s[74:75]
	global_load_lds_dwordx4 v180, s[16:17]
	s_mov_b32 m0, s46
	s_nop 0
	global_load_lds_dwordx4 v184, s[16:17]
	s_mov_b32 m0, s11
	s_nop 0
	global_load_lds_dwordx4 v178, s[74:75]
	s_mov_b32 m0, s12
	s_nop 0
	global_load_lds_dwordx4 v182, s[74:75]
	s_waitcnt vmcnt(8)
	s_waitcnt lgkmcnt(0)
	s_setprio 1
	s_barrier
	v_mfma_f32_16x16x32_bf16 v[58:61], v[132:135], v[164:167], v[58:61]
	v_mfma_f32_16x16x32_bf16 v[54:57], v[140:143], v[164:167], v[54:57]
	v_mfma_f32_16x16x32_bf16 v[46:49], v[132:135], v[172:175], v[46:49]
	v_mfma_f32_16x16x32_bf16 v[42:45], v[140:143], v[172:175], v[42:45]
	v_mfma_f32_16x16x32_bf16 v[30:33], v[132:135], v[198:201], v[30:33]
	v_mfma_f32_16x16x32_bf16 v[26:29], v[140:143], v[198:201], v[26:29]
	v_mfma_f32_16x16x32_bf16 v[14:17], v[132:135], v[210:213], v[14:17]
	v_mfma_f32_16x16x32_bf16 v[10:13], v[140:143], v[210:213], v[10:13]
	v_mfma_f32_16x16x32_bf16 v[58:61], v[136:139], v[168:171], v[58:61]
	v_mfma_f32_16x16x32_bf16 v[54:57], v[144:147], v[168:171], v[54:57]
	v_mfma_f32_16x16x32_bf16 v[46:49], v[136:139], v[194:197], v[46:49]
	v_mfma_f32_16x16x32_bf16 v[42:45], v[144:147], v[194:197], v[42:45]
	v_mfma_f32_16x16x32_bf16 v[30:33], v[136:139], v[202:205], v[30:33]
	v_mfma_f32_16x16x32_bf16 v[26:29], v[144:147], v[202:205], v[26:29]
	v_mfma_f32_16x16x32_bf16 v[14:17], v[136:139], v[214:217], v[14:17]
	v_mfma_f32_16x16x32_bf16 v[10:13], v[144:147], v[214:217], v[10:13]
	s_setprio 0
	s_setprio 1
	v_mfma_f32_16x16x32_bf16 v[62:65], v[148:151], v[164:167], v[62:65]
	v_mfma_f32_16x16x32_bf16 v[50:53], v[156:159], v[164:167], v[50:53]
	v_mfma_f32_16x16x32_bf16 v[38:41], v[148:151], v[172:175], v[38:41]
	v_mfma_f32_16x16x32_bf16 v[34:37], v[156:159], v[172:175], v[34:37]
	v_mfma_f32_16x16x32_bf16 v[22:25], v[148:151], v[198:201], v[22:25]
	v_mfma_f32_16x16x32_bf16 v[18:21], v[156:159], v[198:201], v[18:21]
	v_mfma_f32_16x16x32_bf16 v[6:9], v[148:151], v[210:213], v[6:9]
	v_mfma_f32_16x16x32_bf16 v[2:5], v[156:159], v[210:213], v[2:5]
	v_mfma_f32_16x16x32_bf16 v[62:65], v[152:155], v[168:171], v[62:65]
	v_mfma_f32_16x16x32_bf16 v[50:53], v[160:163], v[168:171], v[50:53]
	v_mfma_f32_16x16x32_bf16 v[38:41], v[152:155], v[194:197], v[38:41]
	v_mfma_f32_16x16x32_bf16 v[34:37], v[160:163], v[194:197], v[34:37]
	v_mfma_f32_16x16x32_bf16 v[22:25], v[152:155], v[202:205], v[22:25]
	v_mfma_f32_16x16x32_bf16 v[18:21], v[160:163], v[202:205], v[18:21]
	v_mfma_f32_16x16x32_bf16 v[6:9], v[152:155], v[214:217], v[6:9]
	v_mfma_f32_16x16x32_bf16 v[2:5], v[160:163], v[214:217], v[2:5]
	s_barrier
	s_setprio 0
	ds_read_b128 v[132:135], v130
	ds_read_b128 v[136:139], v130 offset:1024
	ds_read_b128 v[140:143], v130 offset:2048
	ds_read_b128 v[144:147], v130 offset:3072
	ds_read_b128 v[148:151], v131
	ds_read_b128 v[152:155], v131 offset:1024
	ds_read_b128 v[156:159], v131 offset:2048
	ds_read_b128 v[160:163], v131 offset:3072
	s_add_u32 s16, s74, 0x2b0000
	s_addc_u32 s17, s75, 0
	s_mov_b32 m0, s13
	ds_read_b128 v[164:167], v209 offset:32768
	ds_read_b128 v[168:171], v209 offset:33792
	ds_read_b128 v[172:175], v209 offset:34816
	ds_read_b128 v[194:197], v209 offset:35840
	ds_read_b128 v[198:201], v209 offset:36864
	ds_read_b128 v[202:205], v209 offset:37888
	ds_read_b128 v[210:213], v209 offset:38912
	ds_read_b128 v[214:217], v209 offset:39936
	global_load_lds_dwordx4 v178, s[16:17]
	s_mov_b32 m0, s29
	s_nop 0
	global_load_lds_dwordx4 v182, s[16:17]
	s_waitcnt vmcnt(8)
	s_waitcnt lgkmcnt(0)
	s_setprio 1
	s_barrier
	v_mfma_f32_16x16x32_bf16 v[122:125], v[132:135], v[164:167], v[122:125]
	v_mfma_f32_16x16x32_bf16 v[118:121], v[140:143], v[164:167], v[118:121]
	v_mfma_f32_16x16x32_bf16 v[110:113], v[132:135], v[172:175], v[110:113]
	v_mfma_f32_16x16x32_bf16 v[106:109], v[140:143], v[172:175], v[106:109]
	v_mfma_f32_16x16x32_bf16 v[94:97], v[132:135], v[198:201], v[94:97]
	v_mfma_f32_16x16x32_bf16 v[90:93], v[140:143], v[198:201], v[90:93]
	v_mfma_f32_16x16x32_bf16 v[78:81], v[132:135], v[210:213], v[78:81]
	v_mfma_f32_16x16x32_bf16 v[74:77], v[140:143], v[210:213], v[74:77]
	v_mfma_f32_16x16x32_bf16 v[122:125], v[136:139], v[168:171], v[122:125]
	v_mfma_f32_16x16x32_bf16 v[118:121], v[144:147], v[168:171], v[118:121]
	v_mfma_f32_16x16x32_bf16 v[110:113], v[136:139], v[194:197], v[110:113]
	v_mfma_f32_16x16x32_bf16 v[106:109], v[144:147], v[194:197], v[106:109]
	v_mfma_f32_16x16x32_bf16 v[94:97], v[136:139], v[202:205], v[94:97]
	v_mfma_f32_16x16x32_bf16 v[90:93], v[144:147], v[202:205], v[90:93]
	v_mfma_f32_16x16x32_bf16 v[78:81], v[136:139], v[214:217], v[78:81]
	v_mfma_f32_16x16x32_bf16 v[74:77], v[144:147], v[214:217], v[74:77]
	s_setprio 0
	s_setprio 1
	v_mfma_f32_16x16x32_bf16 v[126:129], v[148:151], v[164:167], v[126:129]
	v_mfma_f32_16x16x32_bf16 v[114:117], v[156:159], v[164:167], v[114:117]
	v_mfma_f32_16x16x32_bf16 v[102:105], v[148:151], v[172:175], v[102:105]
	v_mfma_f32_16x16x32_bf16 v[98:101], v[156:159], v[172:175], v[98:101]
	v_mfma_f32_16x16x32_bf16 v[86:89], v[148:151], v[198:201], v[86:89]
	v_mfma_f32_16x16x32_bf16 v[82:85], v[156:159], v[198:201], v[82:85]
	v_mfma_f32_16x16x32_bf16 v[70:73], v[148:151], v[210:213], v[70:73]
	v_mfma_f32_16x16x32_bf16 v[66:69], v[156:159], v[210:213], v[66:69]
	v_mfma_f32_16x16x32_bf16 v[126:129], v[152:155], v[168:171], v[126:129]
	v_mfma_f32_16x16x32_bf16 v[114:117], v[160:163], v[168:171], v[114:117]
	v_mfma_f32_16x16x32_bf16 v[102:105], v[152:155], v[194:197], v[102:105]
	v_mfma_f32_16x16x32_bf16 v[98:101], v[160:163], v[194:197], v[98:101]
	v_mfma_f32_16x16x32_bf16 v[86:89], v[152:155], v[202:205], v[86:89]
	v_mfma_f32_16x16x32_bf16 v[82:85], v[160:163], v[202:205], v[82:85]
	v_mfma_f32_16x16x32_bf16 v[70:73], v[152:155], v[214:217], v[70:73]
	v_mfma_f32_16x16x32_bf16 v[66:69], v[160:163], v[214:217], v[66:69]
	s_barrier
	s_setprio 0
	s_mov_b32 m0, s47
	s_add_u32 s98, s98, 0x80
	s_addc_u32 s99, s99, 0
	s_add_u32 s100, s100, 0x80
	s_addc_u32 s101, s101, 0
	s_add_u32 s16, s70, 0x2b0080
	ds_read_b128 v[164:167], v209 offset:49152
	ds_read_b128 v[168:171], v209 offset:50176
	ds_read_b128 v[172:175], v209 offset:51200
	ds_read_b128 v[194:197], v209 offset:52224
	ds_read_b128 v[198:201], v209 offset:53248
	ds_read_b128 v[202:205], v209 offset:54272
	ds_read_b128 v[210:213], v209 offset:55296
	ds_read_b128 v[214:217], v209 offset:56320
	global_load_lds_dwordx4 v180, s[98:99]
	s_mov_b32 m0, s89
	s_addc_u32 s17, s71, 0
	global_load_lds_dwordx4 v184, s[98:99]
	s_mov_b32 m0, s56
	s_nop 0
	global_load_lds_dwordx4 v180, s[16:17]
	s_mov_b32 m0, s57
	s_nop 0
	global_load_lds_dwordx4 v184, s[16:17]
	s_mov_b32 m0, s58
	s_nop 0
	global_load_lds_dwordx4 v178, s[100:101]
	s_mov_b32 m0, s59
	s_nop 0
	global_load_lds_dwordx4 v182, s[100:101]
	s_waitcnt vmcnt(8)
	s_waitcnt lgkmcnt(0)
	s_setprio 1
	s_barrier
	v_mfma_f32_16x16x32_bf16 v[58:61], v[132:135], v[164:167], v[58:61]
	v_mfma_f32_16x16x32_bf16 v[54:57], v[140:143], v[164:167], v[54:57]
	v_mfma_f32_16x16x32_bf16 v[46:49], v[132:135], v[172:175], v[46:49]
	v_mfma_f32_16x16x32_bf16 v[42:45], v[140:143], v[172:175], v[42:45]
	v_mfma_f32_16x16x32_bf16 v[30:33], v[132:135], v[198:201], v[30:33]
	v_mfma_f32_16x16x32_bf16 v[26:29], v[140:143], v[198:201], v[26:29]
	v_mfma_f32_16x16x32_bf16 v[14:17], v[132:135], v[210:213], v[14:17]
	v_mfma_f32_16x16x32_bf16 v[10:13], v[140:143], v[210:213], v[10:13]
	v_mfma_f32_16x16x32_bf16 v[58:61], v[136:139], v[168:171], v[58:61]
	v_mfma_f32_16x16x32_bf16 v[54:57], v[144:147], v[168:171], v[54:57]
	v_mfma_f32_16x16x32_bf16 v[46:49], v[136:139], v[194:197], v[46:49]
	v_mfma_f32_16x16x32_bf16 v[42:45], v[144:147], v[194:197], v[42:45]
	v_mfma_f32_16x16x32_bf16 v[30:33], v[136:139], v[202:205], v[30:33]
	v_mfma_f32_16x16x32_bf16 v[26:29], v[144:147], v[202:205], v[26:29]
	v_mfma_f32_16x16x32_bf16 v[14:17], v[136:139], v[214:217], v[14:17]
	v_mfma_f32_16x16x32_bf16 v[10:13], v[144:147], v[214:217], v[10:13]
	s_setprio 0
	s_setprio 1
	v_mfma_f32_16x16x32_bf16 v[62:65], v[148:151], v[164:167], v[62:65]
	v_mfma_f32_16x16x32_bf16 v[50:53], v[156:159], v[164:167], v[50:53]
	v_mfma_f32_16x16x32_bf16 v[38:41], v[148:151], v[172:175], v[38:41]
	v_mfma_f32_16x16x32_bf16 v[34:37], v[156:159], v[172:175], v[34:37]
	v_mfma_f32_16x16x32_bf16 v[22:25], v[148:151], v[198:201], v[22:25]
	v_mfma_f32_16x16x32_bf16 v[18:21], v[156:159], v[198:201], v[18:21]
	v_mfma_f32_16x16x32_bf16 v[6:9], v[148:151], v[210:213], v[6:9]
	v_mfma_f32_16x16x32_bf16 v[2:5], v[156:159], v[210:213], v[2:5]
	v_mfma_f32_16x16x32_bf16 v[62:65], v[152:155], v[168:171], v[62:65]
	v_mfma_f32_16x16x32_bf16 v[50:53], v[160:163], v[168:171], v[50:53]
	v_mfma_f32_16x16x32_bf16 v[38:41], v[152:155], v[194:197], v[38:41]
	v_mfma_f32_16x16x32_bf16 v[34:37], v[160:163], v[194:197], v[34:37]
	v_mfma_f32_16x16x32_bf16 v[22:25], v[152:155], v[202:205], v[22:25]
	v_mfma_f32_16x16x32_bf16 v[18:21], v[160:163], v[202:205], v[18:21]
	v_mfma_f32_16x16x32_bf16 v[6:9], v[152:155], v[214:217], v[6:9]
	v_mfma_f32_16x16x32_bf16 v[2:5], v[160:163], v[214:217], v[2:5]
	s_barrier
	s_setprio 0
	s_add_i32 s15, s15, 2
	s_add_u32 s66, s66, 0x100
	s_addc_u32 s67, s67, 0
	s_add_u32 s90, s90, 0x100
	s_addc_u32 s14, s14, 0
	s_cmpk_gt_u32 s15, 0xa9
	s_cbranch_scc0 .LBB0_331
	s_and_b64 vcc, exec, s[30:31]
	s_cbranch_vccz .LBB0_334
	s_barrier

;     __host__ __device__ bool next(int i, Unit& u) const { if (!StaticOrder::next(i >> 1, u)) return false; u.seg = i & 1; return true; }
;     ...
;         const bool has_next = S.next(ui + 1, nxt);
;         const char* nA = has_next ? PG8_APTR(nxt) : cA; const char* nB = has_next ? PG8_BPTR(nxt) : cB;
;         const char* pfc = PG8_PFPTR(cA, cB); const char* pfn = PG8_PFPTR(nA, nB);
.LBB0_414:
	s_ashr_i32 s75, s74, 31
	ds_read_b128 v[2:5], v163
	ds_read_b128 v[6:9], v163 offset:1024
	ds_read_b128 v[10:13], v163 offset:2048
	ds_read_b128 v[14:17], v163 offset:3072
	ds_read_b128 v[18:21], v164
	ds_read_b128 v[22:25], v164 offset:1024
	ds_read_b128 v[26:29], v164 offset:2048
	ds_read_b128 v[30:33], v164 offset:3072
	s_lshl_b64 s[14:15], s[74:75], 21
	s_add_u32 s76, s36, s14
	s_addc_u32 s77, s37, s15
	s_and_b64 s[14:15], s[4:5], exec
	s_cselect_b32 s1, s77, s81
	s_cselect_b32 s75, s76, s80
	s_and_b32 s18, s10, 0x7fffffff
	s_lshl_b64 s[14:15], s[18:19], 21
	s_add_u32 s78, s33, s14
	s_addc_u32 s79, s71, s15
	s_and_b64 s[14:15], s[4:5], exec
	s_cselect_b32 s18, s79, s7
	s_cselect_b32 vcc_lo, s78, s6
	s_add_u32 s14, s80, 0x100080
	s_addc_u32 s15, s81, 0
	s_mov_b32 m0, s89
	v_lshl_add_u64 v[66:67], s[14:15], 0, v[136:137]
	ds_read_b128 v[34:37], v165
	ds_read_b128 v[38:41], v165 offset:1024
	ds_read_b128 v[42:45], v165 offset:2048
	ds_read_b128 v[46:49], v165 offset:3072
	ds_read_b128 v[50:53], v165 offset:4096
	ds_read_b128 v[54:57], v165 offset:5120
	ds_read_b128 v[58:61], v165 offset:6144
	ds_read_b128 v[62:65], v165 offset:7168
	global_load_lds_dwordx4 v[66:67], off
	v_lshl_add_u64 v[66:67], s[14:15], 0, v[132:133]
	s_mov_b32 m0, s92
	s_nop 0
	global_load_lds_dwordx4 v[66:67], off
	s_waitcnt vmcnt(8)
	s_waitcnt lgkmcnt(0)
	s_setprio 1
	s_barrier
	v_mfma_f32_16x16x32_bf16 v[86:89], v[10:13], v[50:53], 0
	v_mfma_f32_16x16x32_bf16 v[90:93], v[14:17], v[54:57], v[86:89]
	v_mfma_f32_16x16x32_bf16 v[86:89], v[2:5], v[58:61], 0
	v_mfma_f32_16x16x32_bf16 v[66:69], v[2:5], v[34:37], 0
	v_mfma_f32_16x16x32_bf16 v[70:73], v[10:13], v[34:37], 0
	v_mfma_f32_16x16x32_bf16 v[74:77], v[2:5], v[42:45], 0
	v_mfma_f32_16x16x32_bf16 v[78:81], v[10:13], v[42:45], 0
	v_mfma_f32_16x16x32_bf16 v[82:85], v[2:5], v[50:53], 0
	v_mfma_f32_16x16x32_bf16 v[94:97], v[6:9], v[62:65], v[86:89]
	v_mfma_f32_16x16x32_bf16 v[86:89], v[10:13], v[58:61], 0
	v_mfma_f32_16x16x32_bf16 v[66:69], v[6:9], v[38:41], v[66:69]
	v_mfma_f32_16x16x32_bf16 v[70:73], v[14:17], v[38:41], v[70:73]
	v_mfma_f32_16x16x32_bf16 v[74:77], v[6:9], v[46:49], v[74:77]
	v_mfma_f32_16x16x32_bf16 v[78:81], v[14:17], v[46:49], v[78:81]
	v_mfma_f32_16x16x32_bf16 v[82:85], v[6:9], v[54:57], v[82:85]
	v_mfma_f32_16x16x32_bf16 v[106:109], v[14:17], v[62:65], v[86:89]
	s_setprio 0
	s_setprio 1
	v_mfma_f32_16x16x32_bf16 v[86:89], v[18:21], v[34:37], 0
	v_mfma_f32_16x16x32_bf16 v[34:37], v[26:29], v[34:37], 0
	v_mfma_f32_16x16x32_bf16 v[110:113], v[22:25], v[38:41], v[86:89]
	v_mfma_f32_16x16x32_bf16 v[34:37], v[30:33], v[38:41], v[34:37]
	v_mfma_f32_16x16x32_bf16 v[38:41], v[18:21], v[42:45], 0
	v_mfma_f32_16x16x32_bf16 v[42:45], v[26:29], v[42:45], 0
	v_mfma_f32_16x16x32_bf16 v[38:41], v[22:25], v[46:49], v[38:41]
	v_mfma_f32_16x16x32_bf16 v[42:45], v[30:33], v[46:49], v[42:45]
	v_mfma_f32_16x16x32_bf16 v[46:49], v[18:21], v[50:53], 0
	v_mfma_f32_16x16x32_bf16 v[50:53], v[26:29], v[50:53], 0
	v_mfma_f32_16x16x32_bf16 v[46:49], v[22:25], v[54:57], v[46:49]
	v_mfma_f32_16x16x32_bf16 v[50:53], v[30:33], v[54:57], v[50:53]
	v_mfma_f32_16x16x32_bf16 v[54:57], v[18:21], v[58:61], 0
	v_mfma_f32_16x16x32_bf16 v[58:61], v[26:29], v[58:61], 0
	v_mfma_f32_16x16x32_bf16 v[54:57], v[22:25], v[62:65], v[54:57]
	v_mfma_f32_16x16x32_bf16 v[58:61], v[30:33], v[62:65], v[58:61]
	s_barrier
	s_setprio 0
	s_add_i32 vcc_hi, s59, s29
	v_lshl_add_u64 v[248:249], s[6:7], 0, v[134:135]
	s_add_i32 s84, vcc_hi, 0x2000
	v_lshl_add_u64 v[148:149], v[248:249], 0, s[66:67]
	s_mov_b32 m0, vcc_hi
	v_lshl_add_u64 v[250:251], s[6:7], 0, v[130:131]
	s_add_u32 s14, s6, 0x100100
	ds_read_b128 v[62:65], v165 offset:16384
	ds_read_b128 v[86:89], v165 offset:17408
	ds_read_b128 v[98:101], v165 offset:18432
	ds_read_b128 v[102:105], v165 offset:19456
	ds_read_b128 v[114:117], v165 offset:20480
	ds_read_b128 v[118:121], v165 offset:21504
	ds_read_b128 v[122:125], v165 offset:22528
	ds_read_b128 v[126:129], v165 offset:23552
	global_load_lds_dwordx4 v[148:149], off
	v_lshl_add_u64 v[148:149], v[250:251], 0, s[66:67]
	s_mov_b32 m0, s84
	s_addc_u32 s15, s7, 0
	s_add_i32 s85, s88, s29
	global_load_lds_dwordx4 v[148:149], off
	v_lshl_add_u64 v[148:149], s[14:15], 0, v[134:135]
	s_mov_b32 m0, s85
	s_add_i32 s46, s85, 0x2000
	global_load_lds_dwordx4 v[148:149], off
	v_lshl_add_u64 v[148:149], s[14:15], 0, v[130:131]
	s_mov_b32 m0, s46
	v_lshl_add_u64 v[252:253], s[80:81], 0, v[136:137]
	global_load_lds_dwordx4 v[148:149], off
	v_lshl_add_u64 v[148:149], v[252:253], 0, s[66:67]
	s_mov_b32 m0, s86
	v_lshl_add_u64 v[144:145], s[80:81], 0, v[132:133]
	global_load_lds_dwordx4 v[148:149], off
	v_lshl_add_u64 v[148:149], v[144:145], 0, s[66:67]
	s_mov_b32 m0, s93
	s_nop 0
	global_load_lds_dwordx4 v[148:149], off
	s_waitcnt vmcnt(8)
	s_waitcnt lgkmcnt(0)
	s_setprio 1
	s_barrier
	v_mfma_f32_16x16x32_bf16 v[148:151], v[2:5], v[62:65], 0
	v_mfma_f32_16x16x32_bf16 v[158:161], v[2:5], v[98:101], 0
	v_mfma_f32_16x16x32_bf16 v[172:175], v[2:5], v[114:117], 0
	v_mfma_f32_16x16x32_bf16 v[2:5], v[2:5], v[122:125], 0
	v_mfma_f32_16x16x32_bf16 v[150:153], v[6:9], v[86:89], v[148:151]
	v_mfma_f32_16x16x32_bf16 v[158:161], v[6:9], v[102:105], v[158:161]
	v_mfma_f32_16x16x32_bf16 v[172:175], v[6:9], v[118:121], v[172:175]
	v_mfma_f32_16x16x32_bf16 v[2:5], v[6:9], v[126:129], v[2:5]
	v_mfma_f32_16x16x32_bf16 v[6:9], v[10:13], v[122:125], 0
	v_mfma_f32_16x16x32_bf16 v[154:157], v[10:13], v[62:65], 0
	v_mfma_f32_16x16x32_bf16 v[168:171], v[10:13], v[98:101], 0
	v_mfma_f32_16x16x32_bf16 v[176:179], v[10:13], v[114:117], 0
	v_mfma_f32_16x16x32_bf16 v[10:13], v[14:17], v[126:129], v[6:9]
	v_mfma_f32_16x16x32_bf16 v[154:157], v[14:17], v[86:89], v[154:157]
	v_mfma_f32_16x16x32_bf16 v[168:171], v[14:17], v[102:105], v[168:171]
	v_mfma_f32_16x16x32_bf16 v[176:179], v[14:17], v[118:121], v[176:179]
	s_setprio 0
	s_setprio 1
	v_mfma_f32_16x16x32_bf16 v[6:9], v[18:21], v[62:65], 0
	v_mfma_f32_16x16x32_bf16 v[14:17], v[22:25], v[86:89], v[6:9]
	v_mfma_f32_16x16x32_bf16 v[6:9], v[26:29], v[62:65], 0
	v_mfma_f32_16x16x32_bf16 v[180:183], v[30:33], v[86:89], v[6:9]
	v_mfma_f32_16x16x32_bf16 v[6:9], v[18:21], v[98:101], 0
	v_mfma_f32_16x16x32_bf16 v[184:187], v[22:25], v[102:105], v[6:9]
	v_mfma_f32_16x16x32_bf16 v[6:9], v[26:29], v[98:101], 0
	v_mfma_f32_16x16x32_bf16 v[188:191], v[30:33], v[102:105], v[6:9]
	v_mfma_f32_16x16x32_bf16 v[6:9], v[18:21], v[114:117], 0
	v_mfma_f32_16x16x32_bf16 v[192:195], v[22:25], v[118:121], v[6:9]
	v_mfma_f32_16x16x32_bf16 v[6:9], v[26:29], v[114:117], 0
	v_mfma_f32_16x16x32_bf16 v[196:199], v[30:33], v[118:121], v[6:9]
	v_mfma_f32_16x16x32_bf16 v[6:9], v[18:21], v[122:125], 0
	v_mfma_f32_16x16x32_bf16 v[200:203], v[22:25], v[126:129], v[6:9]
	v_mfma_f32_16x16x32_bf16 v[6:9], v[26:29], v[122:125], 0
	v_mfma_f32_16x16x32_bf16 v[204:207], v[30:33], v[126:129], v[6:9]
	s_barrier
	s_setprio 0
	s_add_i32 s47, 0, 0x18000
	s_add_i32 s56, 0, 0x1c000
	v_add_u32_e32 v138, s47, v162
	v_add_u32_e32 v148, s56, v162
	s_nop 0
	ds_read_b128 v[6:9], v138
	ds_read_b128 v[26:29], v138 offset:1024
	ds_read_b128 v[30:33], v138 offset:2048
	ds_read_b128 v[62:65], v138 offset:3072
	ds_read_b128 v[208:211], v148
	ds_read_b128 v[212:215], v148 offset:1024
	ds_read_b128 v[216:219], v148 offset:2048
	ds_read_b128 v[220:223], v148 offset:3072
	s_add_u32 s14, s80, 0x100100
	s_addc_u32 s15, s81, 0
	s_mov_b32 m0, s94
	v_lshl_add_u64 v[86:87], s[14:15], 0, v[136:137]
	ds_read_b128 v[18:21], v165 offset:32768
	ds_read_b128 v[22:25], v165 offset:33792
	ds_read_b128 v[224:227], v165 offset:34816
	ds_read_b128 v[228:231], v165 offset:35840
	ds_read_b128 v[232:235], v165 offset:36864
	ds_read_b128 v[236:239], v165 offset:37888
	ds_read_b128 v[240:243], v165 offset:38912
	ds_read_b128 v[244:247], v165 offset:39936
	global_load_lds_dwordx4 v[86:87], off
	v_lshl_add_u64 v[86:87], s[14:15], 0, v[132:133]
	s_mov_b32 m0, s95
	s_nop 0
	global_load_lds_dwordx4 v[86:87], off
	s_waitcnt vmcnt(8)
	s_waitcnt lgkmcnt(0)
	s_setprio 1
	s_barrier
	v_mfma_f32_16x16x32_bf16 v[66:69], v[6:9], v[18:21], v[66:69]
	v_mfma_f32_16x16x32_bf16 v[118:121], v[26:29], v[22:25], v[66:69]
	v_mfma_f32_16x16x32_bf16 v[66:69], v[30:33], v[18:21], v[70:73]
	v_mfma_f32_16x16x32_bf16 v[114:117], v[62:65], v[22:25], v[66:69]
	v_mfma_f32_16x16x32_bf16 v[66:69], v[6:9], v[224:227], v[74:77]
	v_mfma_f32_16x16x32_bf16 v[102:105], v[26:29], v[228:231], v[66:69]
	v_mfma_f32_16x16x32_bf16 v[66:69], v[30:33], v[224:227], v[78:81]
	v_mfma_f32_16x16x32_bf16 v[98:101], v[62:65], v[228:231], v[66:69]
	v_mfma_f32_16x16x32_bf16 v[66:69], v[6:9], v[232:235], v[82:85]
	v_mfma_f32_16x16x32_bf16 v[86:89], v[26:29], v[236:239], v[66:69]
	v_mfma_f32_16x16x32_bf16 v[66:69], v[30:33], v[232:235], v[90:93]
	v_mfma_f32_16x16x32_bf16 v[82:85], v[62:65], v[236:239], v[66:69]
	v_mfma_f32_16x16x32_bf16 v[66:69], v[6:9], v[240:243], v[94:97]
	v_mfma_f32_16x16x32_bf16 v[70:73], v[26:29], v[244:247], v[66:69]
	v_mfma_f32_16x16x32_bf16 v[66:69], v[30:33], v[240:243], v[106:109]
	v_mfma_f32_16x16x32_bf16 v[66:69], v[62:65], v[244:247], v[66:69]
	s_setprio 0
	s_setprio 1
	v_mfma_f32_16x16x32_bf16 v[74:77], v[208:211], v[18:21], v[110:113]
	v_mfma_f32_16x16x32_bf16 v[18:21], v[216:219], v[18:21], v[34:37]
	v_mfma_f32_16x16x32_bf16 v[122:125], v[220:223], v[22:25], v[18:21]
	v_mfma_f32_16x16x32_bf16 v[18:21], v[208:211], v[224:227], v[38:41]
	v_mfma_f32_16x16x32_bf16 v[110:113], v[212:215], v[228:231], v[18:21]
	v_mfma_f32_16x16x32_bf16 v[18:21], v[216:219], v[224:227], v[42:45]
	v_mfma_f32_16x16x32_bf16 v[106:109], v[220:223], v[228:231], v[18:21]
	v_mfma_f32_16x16x32_bf16 v[18:21], v[208:211], v[232:235], v[46:49]
	v_mfma_f32_16x16x32_bf16 v[94:97], v[212:215], v[236:239], v[18:21]
	v_mfma_f32_16x16x32_bf16 v[18:21], v[216:219], v[232:235], v[50:53]
	v_mfma_f32_16x16x32_bf16 v[90:93], v[220:223], v[236:239], v[18:21]
	v_mfma_f32_16x16x32_bf16 v[18:21], v[208:211], v[240:243], v[54:57]
	v_mfma_f32_16x16x32_bf16 v[78:81], v[212:215], v[244:247], v[18:21]
	v_mfma_f32_16x16x32_bf16 v[18:21], v[216:219], v[240:243], v[58:61]
	v_mfma_f32_16x16x32_bf16 v[126:129], v[212:215], v[22:25], v[74:77]
	v_mfma_f32_16x16x32_bf16 v[74:77], v[220:223], v[244:247], v[18:21]
	s_barrier
	s_setprio 0
	s_add_i32 s47, s47, s29
	s_add_i32 s91, s47, 0x2000
	s_nop 1
	v_lshl_add_u64 v[18:19], v[248:249], 0, s[68:69]
	s_mov_b32 m0, s47
	s_add_u32 s14, s6, 0x100180
	ds_read_b128 v[42:45], v165 offset:49152
	ds_read_b128 v[46:49], v165 offset:50176
	ds_read_b128 v[224:227], v165 offset:51200
	ds_read_b128 v[228:231], v165 offset:52224
	ds_read_b128 v[232:235], v165 offset:53248
	ds_read_b128 v[236:239], v165 offset:54272
	ds_read_b128 v[240:243], v165 offset:55296
	ds_read_b128 v[244:247], v165 offset:56320
	global_load_lds_dwordx4 v[18:19], off
	v_lshl_add_u64 v[18:19], v[250:251], 0, s[68:69]
	s_mov_b32 m0, s91
	s_addc_u32 s15, s7, 0
	s_add_i32 s56, s56, s29
	global_load_lds_dwordx4 v[18:19], off
	v_lshl_add_u64 v[18:19], s[14:15], 0, v[134:135]
	s_mov_b32 m0, s56
	s_add_i32 s57, s56, 0x2000
	global_load_lds_dwordx4 v[18:19], off
	v_lshl_add_u64 v[18:19], s[14:15], 0, v[130:131]
	s_mov_b32 m0, s57
	s_nop 0
	global_load_lds_dwordx4 v[18:19], off
	v_lshl_add_u64 v[18:19], v[252:253], 0, s[68:69]
	s_mov_b32 m0, s96
	s_nop 0
	global_load_lds_dwordx4 v[18:19], off
	v_lshl_add_u64 v[18:19], v[144:145], 0, s[68:69]
	s_mov_b32 m0, s97
	s_nop 0
	global_load_lds_dwordx4 v[18:19], off
	s_waitcnt vmcnt(8)
	s_waitcnt lgkmcnt(0)
	s_setprio 1
	s_barrier
	v_mfma_f32_16x16x32_bf16 v[18:21], v[6:9], v[42:45], v[150:153]
	v_mfma_f32_16x16x32_bf16 v[54:57], v[26:29], v[46:49], v[18:21]
	v_mfma_f32_16x16x32_bf16 v[18:21], v[30:33], v[42:45], v[154:157]
	v_mfma_f32_16x16x32_bf16 v[50:53], v[62:65], v[46:49], v[18:21]
	v_mfma_f32_16x16x32_bf16 v[18:21], v[6:9], v[224:227], v[158:161]
	v_mfma_f32_16x16x32_bf16 v[38:41], v[26:29], v[228:231], v[18:21]
	v_mfma_f32_16x16x32_bf16 v[18:21], v[30:33], v[224:227], v[168:171]
	v_mfma_f32_16x16x32_bf16 v[34:37], v[62:65], v[228:231], v[18:21]
	v_mfma_f32_16x16x32_bf16 v[18:21], v[6:9], v[232:235], v[172:175]
	v_mfma_f32_16x16x32_bf16 v[2:5], v[6:9], v[240:243], v[2:5]
	v_mfma_f32_16x16x32_bf16 v[22:25], v[26:29], v[236:239], v[18:21]
	v_mfma_f32_16x16x32_bf16 v[18:21], v[30:33], v[232:235], v[176:179]
	v_mfma_f32_16x16x32_bf16 v[6:9], v[26:29], v[244:247], v[2:5]
	v_mfma_f32_16x16x32_bf16 v[2:5], v[30:33], v[240:243], v[10:13]
	v_mfma_f32_16x16x32_bf16 v[18:21], v[62:65], v[236:239], v[18:21]
	v_mfma_f32_16x16x32_bf16 v[2:5], v[62:65], v[244:247], v[2:5]
	s_setprio 0
	s_setprio 1
	v_mfma_f32_16x16x32_bf16 v[10:13], v[208:211], v[42:45], v[14:17]
	v_mfma_f32_16x16x32_bf16 v[62:65], v[212:215], v[46:49], v[10:13]
	v_mfma_f32_16x16x32_bf16 v[10:13], v[216:219], v[42:45], v[180:183]
	v_mfma_f32_16x16x32_bf16 v[58:61], v[220:223], v[46:49], v[10:13]
	v_mfma_f32_16x16x32_bf16 v[10:13], v[208:211], v[224:227], v[184:187]
	v_mfma_f32_16x16x32_bf16 v[46:49], v[212:215], v[228:231], v[10:13]
	v_mfma_f32_16x16x32_bf16 v[10:13], v[216:219], v[224:227], v[188:191]
	v_mfma_f32_16x16x32_bf16 v[42:45], v[220:223], v[228:231], v[10:13]
	v_mfma_f32_16x16x32_bf16 v[10:13], v[208:211], v[232:235], v[192:195]
	v_mfma_f32_16x16x32_bf16 v[30:33], v[212:215], v[236:239], v[10:13]
	v_mfma_f32_16x16x32_bf16 v[10:13], v[216:219], v[232:235], v[196:199]
	v_mfma_f32_16x16x32_bf16 v[26:29], v[220:223], v[236:239], v[10:13]
	v_mfma_f32_16x16x32_bf16 v[10:13], v[208:211], v[240:243], v[200:203]
	v_mfma_f32_16x16x32_bf16 v[14:17], v[212:215], v[244:247], v[10:13]
	v_mfma_f32_16x16x32_bf16 v[10:13], v[216:219], v[240:243], v[204:207]
	v_mfma_f32_16x16x32_bf16 v[10:13], v[220:223], v[244:247], v[10:13]
	s_barrier
	s_setprio 0
	s_add_u32 s80, s80, 0x100180
	s_addc_u32 s81, s81, 0
	s_add_u32 s30, s6, 0x200
	s_addc_u32 s14, s7, 0
	s_mov_b32 s15, 0
.LBB0_415:
	ds_read_b128 v[150:153], v163
	ds_read_b128 v[154:157], v163 offset:1024
	ds_read_b128 v[158:161], v163 offset:2048
	ds_read_b128 v[168:171], v163 offset:3072
	ds_read_b128 v[172:175], v164
	ds_read_b128 v[176:179], v164 offset:1024
	ds_read_b128 v[180:183], v164 offset:2048
	ds_read_b128 v[184:187], v164 offset:3072
	s_add_u32 s6, s80, 0xfff00080
	s_addc_u32 s7, s81, -1
	s_cmp_eq_u32 s15, 60
	s_cselect_b32 s83, s1, s7
	s_cselect_b32 s82, s75, s6
	s_cselect_b32 s7, s18, s14
	s_cselect_b32 s6, vcc_lo, s30
	s_mov_b32 m0, s89
	ds_read_b128 v[188:191], v165
	ds_read_b128 v[192:195], v165 offset:1024
	ds_read_b128 v[196:199], v165 offset:2048
	ds_read_b128 v[200:203], v165 offset:3072
	ds_read_b128 v[204:207], v165 offset:4096
	ds_read_b128 v[208:211], v165 offset:5120
	ds_read_b128 v[212:215], v165 offset:6144
	ds_read_b128 v[216:219], v165 offset:7168
	global_load_lds_dwordx4 v140, s[80:81]
	s_mov_b32 m0, s92
	s_nop 0
	global_load_lds_dwordx4 v142, s[80:81]
	s_waitcnt vmcnt(8)
	s_waitcnt lgkmcnt(0)
	s_setprio 1
	s_barrier
	v_mfma_f32_16x16x32_bf16 v[118:121], v[150:153], v[188:191], v[118:121]
	v_mfma_f32_16x16x32_bf16 v[114:117], v[158:161], v[188:191], v[114:117]
	v_mfma_f32_16x16x32_bf16 v[102:105], v[150:153], v[196:199], v[102:105]
	v_mfma_f32_16x16x32_bf16 v[98:101], v[158:161], v[196:199], v[98:101]
	v_mfma_f32_16x16x32_bf16 v[86:89], v[150:153], v[204:207], v[86:89]
	v_mfma_f32_16x16x32_bf16 v[82:85], v[158:161], v[204:207], v[82:85]
	v_mfma_f32_16x16x32_bf16 v[70:73], v[150:153], v[212:215], v[70:73]
	v_mfma_f32_16x16x32_bf16 v[66:69], v[158:161], v[212:215], v[66:69]
	v_mfma_f32_16x16x32_bf16 v[118:121], v[154:157], v[192:195], v[118:121]
	v_mfma_f32_16x16x32_bf16 v[114:117], v[168:171], v[192:195], v[114:117]
	v_mfma_f32_16x16x32_bf16 v[102:105], v[154:157], v[200:203], v[102:105]
	v_mfma_f32_16x16x32_bf16 v[98:101], v[168:171], v[200:203], v[98:101]
	v_mfma_f32_16x16x32_bf16 v[86:89], v[154:157], v[208:211], v[86:89]
	v_mfma_f32_16x16x32_bf16 v[82:85], v[168:171], v[208:211], v[82:85]
	v_mfma_f32_16x16x32_bf16 v[70:73], v[154:157], v[216:219], v[70:73]
	v_mfma_f32_16x16x32_bf16 v[66:69], v[168:171], v[216:219], v[66:69]
	s_setprio 0
	s_setprio 1
	v_mfma_f32_16x16x32_bf16 v[126:129], v[172:175], v[188:191], v[126:129]
	v_mfma_f32_16x16x32_bf16 v[122:125], v[180:183], v[188:191], v[122:125]
	v_mfma_f32_16x16x32_bf16 v[110:113], v[172:175], v[196:199], v[110:113]
	v_mfma_f32_16x16x32_bf16 v[106:109], v[180:183], v[196:199], v[106:109]
	v_mfma_f32_16x16x32_bf16 v[94:97], v[172:175], v[204:207], v[94:97]
	v_mfma_f32_16x16x32_bf16 v[90:93], v[180:183], v[204:207], v[90:93]
	v_mfma_f32_16x16x32_bf16 v[78:81], v[172:175], v[212:215], v[78:81]
	v_mfma_f32_16x16x32_bf16 v[74:77], v[180:183], v[212:215], v[74:77]
	v_mfma_f32_16x16x32_bf16 v[126:129], v[176:179], v[192:195], v[126:129]
	v_mfma_f32_16x16x32_bf16 v[122:125], v[184:187], v[192:195], v[122:125]
	v_mfma_f32_16x16x32_bf16 v[110:113], v[176:179], v[200:203], v[110:113]
	v_mfma_f32_16x16x32_bf16 v[106:109], v[184:187], v[200:203], v[106:109]
	v_mfma_f32_16x16x32_bf16 v[94:97], v[176:179], v[208:211], v[94:97]
	v_mfma_f32_16x16x32_bf16 v[90:93], v[184:187], v[208:211], v[90:93]
	v_mfma_f32_16x16x32_bf16 v[78:81], v[176:179], v[216:219], v[78:81]
	v_mfma_f32_16x16x32_bf16 v[74:77], v[184:187], v[216:219], v[74:77]
	s_barrier
	s_setprio 0
	s_mov_b32 m0, vcc_hi
	s_mov_b64 s[98:99], s[6:7]
	s_add_u32 s16, s6, 0x100000
	ds_read_b128 v[188:191], v165 offset:16384
	ds_read_b128 v[192:195], v165 offset:17408
	ds_read_b128 v[196:199], v165 offset:18432
	ds_read_b128 v[200:203], v165 offset:19456
	ds_read_b128 v[204:207], v165 offset:20480
	ds_read_b128 v[208:211], v165 offset:21504
	ds_read_b128 v[212:215], v165 offset:22528
	ds_read_b128 v[216:219], v165 offset:23552
	global_load_lds_dwordx4 v134, s[6:7]
	s_mov_b32 m0, s84
	s_addc_u32 s17, s7, 0
	global_load_lds_dwordx4 v130, s[6:7]
	s_mov_b32 m0, s85
	s_mov_b64 s[100:101], s[82:83]
	global_load_lds_dwordx4 v134, s[16:17]
	s_mov_b32 m0, s46
	s_nop 0
	global_load_lds_dwordx4 v130, s[16:17]
	s_mov_b32 m0, s86
	s_nop 0
	global_load_lds_dwordx4 v136, s[82:83]
	s_mov_b32 m0, s93
	s_nop 0
	global_load_lds_dwordx4 v132, s[82:83]
	s_waitcnt vmcnt(8)
	s_waitcnt lgkmcnt(0)
	s_setprio 1
	s_barrier
	v_mfma_f32_16x16x32_bf16 v[54:57], v[150:153], v[188:191], v[54:57]
	v_mfma_f32_16x16x32_bf16 v[50:53], v[158:161], v[188:191], v[50:53]
	v_mfma_f32_16x16x32_bf16 v[38:41], v[150:153], v[196:199], v[38:41]
	v_mfma_f32_16x16x32_bf16 v[34:37], v[158:161], v[196:199], v[34:37]
	v_mfma_f32_16x16x32_bf16 v[22:25], v[150:153], v[204:207], v[22:25]
	v_mfma_f32_16x16x32_bf16 v[18:21], v[158:161], v[204:207], v[18:21]
	v_mfma_f32_16x16x32_bf16 v[6:9], v[150:153], v[212:215], v[6:9]
	v_mfma_f32_16x16x32_bf16 v[2:5], v[158:161], v[212:215], v[2:5]
	v_mfma_f32_16x16x32_bf16 v[54:57], v[154:157], v[192:195], v[54:57]
	v_mfma_f32_16x16x32_bf16 v[50:53], v[168:171], v[192:195], v[50:53]
	v_mfma_f32_16x16x32_bf16 v[38:41], v[154:157], v[200:203], v[38:41]
	v_mfma_f32_16x16x32_bf16 v[34:37], v[168:171], v[200:203], v[34:37]
	v_mfma_f32_16x16x32_bf16 v[22:25], v[154:157], v[208:211], v[22:25]
	v_mfma_f32_16x16x32_bf16 v[18:21], v[168:171], v[208:211], v[18:21]
	v_mfma_f32_16x16x32_bf16 v[6:9], v[154:157], v[216:219], v[6:9]
	v_mfma_f32_16x16x32_bf16 v[2:5], v[168:171], v[216:219], v[2:5]
	s_setprio 0
	s_setprio 1
	v_mfma_f32_16x16x32_bf16 v[62:65], v[172:175], v[188:191], v[62:65]
	v_mfma_f32_16x16x32_bf16 v[58:61], v[180:183], v[188:191], v[58:61]
	v_mfma_f32_16x16x32_bf16 v[46:49], v[172:175], v[196:199], v[46:49]
	v_mfma_f32_16x16x32_bf16 v[42:45], v[180:183], v[196:199], v[42:45]
	v_mfma_f32_16x16x32_bf16 v[30:33], v[172:175], v[204:207], v[30:33]
	v_mfma_f32_16x16x32_bf16 v[26:29], v[180:183], v[204:207], v[26:29]
	v_mfma_f32_16x16x32_bf16 v[14:17], v[172:175], v[212:215], v[14:17]
	v_mfma_f32_16x16x32_bf16 v[10:13], v[180:183], v[212:215], v[10:13]
	v_mfma_f32_16x16x32_bf16 v[62:65], v[176:179], v[192:195], v[62:65]
	v_mfma_f32_16x16x32_bf16 v[58:61], v[184:187], v[192:195], v[58:61]
	v_mfma_f32_16x16x32_bf16 v[46:49], v[176:179], v[200:203], v[46:49]
	v_mfma_f32_16x16x32_bf16 v[42:45], v[184:187], v[200:203], v[42:45]
	v_mfma_f32_16x16x32_bf16 v[30:33], v[176:179], v[208:211], v[30:33]
	v_mfma_f32_16x16x32_bf16 v[26:29], v[184:187], v[208:211], v[26:29]
	v_mfma_f32_16x16x32_bf16 v[14:17], v[176:179], v[216:219], v[14:17]
	v_mfma_f32_16x16x32_bf16 v[10:13], v[184:187], v[216:219], v[10:13]
	s_barrier
;     ...
;         for (int t = 2; t < nt; t += 2) PG8_KITER(t);
	s_setprio 0
	ds_read_b128 v[150:153], v138
	ds_read_b128 v[154:157], v138 offset:1024
	ds_read_b128 v[158:161], v138 offset:2048
	ds_read_b128 v[168:171], v138 offset:3072
	ds_read_b128 v[172:175], v148
	ds_read_b128 v[176:179], v148 offset:1024
	ds_read_b128 v[180:183], v148 offset:2048
	ds_read_b128 v[184:187], v148 offset:3072
	s_add_u32 s16, s82, 0x100000
	s_addc_u32 s17, s83, 0
	s_mov_b32 m0, s94
	ds_read_b128 v[188:191], v165 offset:32768
	ds_read_b128 v[192:195], v165 offset:33792
	ds_read_b128 v[196:199], v165 offset:34816
	ds_read_b128 v[200:203], v165 offset:35840
	ds_read_b128 v[204:207], v165 offset:36864
	ds_read_b128 v[208:211], v165 offset:37888
	ds_read_b128 v[212:215], v165 offset:38912
	ds_read_b128 v[216:219], v165 offset:39936
	global_load_lds_dwordx4 v136, s[16:17]
	s_mov_b32 m0, s95
	s_nop 0
	global_load_lds_dwordx4 v132, s[16:17]
	s_waitcnt vmcnt(8)
	s_waitcnt lgkmcnt(0)
	s_setprio 1
	s_barrier
	v_mfma_f32_16x16x32_bf16 v[118:121], v[150:153], v[188:191], v[118:121]
	v_mfma_f32_16x16x32_bf16 v[114:117], v[158:161], v[188:191], v[114:117]
	v_mfma_f32_16x16x32_bf16 v[102:105], v[150:153], v[196:199], v[102:105]
	v_mfma_f32_16x16x32_bf16 v[98:101], v[158:161], v[196:199], v[98:101]
	v_mfma_f32_16x16x32_bf16 v[86:89], v[150:153], v[204:207], v[86:89]
	v_mfma_f32_16x16x32_bf16 v[82:85], v[158:161], v[204:207], v[82:85]
	v_mfma_f32_16x16x32_bf16 v[70:73], v[150:153], v[212:215], v[70:73]
	v_mfma_f32_16x16x32_bf16 v[66:69], v[158:161], v[212:215], v[66:69]
	v_mfma_f32_16x16x32_bf16 v[118:121], v[154:157], v[192:195], v[118:121]
	v_mfma_f32_16x16x32_bf16 v[114:117], v[168:171], v[192:195], v[114:117]
	v_mfma_f32_16x16x32_bf16 v[102:105], v[154:157], v[200:203], v[102:105]
	v_mfma_f32_16x16x32_bf16 v[98:101], v[168:171], v[200:203], v[98:101]
	v_mfma_f32_16x16x32_bf16 v[86:89], v[154:157], v[208:211], v[86:89]
	v_mfma_f32_16x16x32_bf16 v[82:85], v[168:171], v[208:211], v[82:85]
	v_mfma_f32_16x16x32_bf16 v[70:73], v[154:157], v[216:219], v[70:73]
	v_mfma_f32_16x16x32_bf16 v[66:69], v[168:171], v[216:219], v[66:69]
	s_setprio 0
	s_setprio 1
	v_mfma_f32_16x16x32_bf16 v[126:129], v[172:175], v[188:191], v[126:129]
	v_mfma_f32_16x16x32_bf16 v[122:125], v[180:183], v[188:191], v[122:125]
	v_mfma_f32_16x16x32_bf16 v[110:113], v[172:175], v[196:199], v[110:113]
	v_mfma_f32_16x16x32_bf16 v[106:109], v[180:183], v[196:199], v[106:109]
	v_mfma_f32_16x16x32_bf16 v[94:97], v[172:175], v[204:207], v[94:97]
	v_mfma_f32_16x16x32_bf16 v[90:93], v[180:183], v[204:207], v[90:93]
	v_mfma_f32_16x16x32_bf16 v[78:81], v[172:175], v[212:215], v[78:81]
	v_mfma_f32_16x16x32_bf16 v[74:77], v[180:183], v[212:215], v[74:77]
	v_mfma_f32_16x16x32_bf16 v[126:129], v[176:179], v[192:195], v[126:129]
	v_mfma_f32_16x16x32_bf16 v[122:125], v[184:187], v[192:195], v[122:125]
	v_mfma_f32_16x16x32_bf16 v[110:113], v[176:179], v[200:203], v[110:113]
	v_mfma_f32_16x16x32_bf16 v[106:109], v[184:187], v[200:203], v[106:109]
	v_mfma_f32_16x16x32_bf16 v[94:97], v[176:179], v[208:211], v[94:97]
	v_mfma_f32_16x16x32_bf16 v[90:93], v[184:187], v[208:211], v[90:93]
	v_mfma_f32_16x16x32_bf16 v[78:81], v[176:179], v[216:219], v[78:81]
	v_mfma_f32_16x16x32_bf16 v[74:77], v[184:187], v[216:219], v[74:77]
	s_barrier
	s_setprio 0
	s_mov_b32 m0, s47
	s_add_u32 s98, s98, 0x80
	s_addc_u32 s99, s99, 0
	s_add_u32 s100, s100, 0x80
	s_addc_u32 s101, s101, 0
	s_add_u32 s6, s6, 0x100080
	ds_read_b128 v[188:191], v165 offset:49152
	ds_read_b128 v[192:195], v165 offset:50176
	ds_read_b128 v[196:199], v165 offset:51200
	ds_read_b128 v[200:203], v165 offset:52224
	ds_read_b128 v[204:207], v165 offset:53248
	ds_read_b128 v[208:211], v165 offset:54272
	ds_read_b128 v[212:215], v165 offset:55296
	ds_read_b128 v[216:219], v165 offset:56320
	global_load_lds_dwordx4 v134, s[98:99]
	s_mov_b32 m0, s91
	s_addc_u32 s7, s7, 0
	global_load_lds_dwordx4 v130, s[98:99]
	s_mov_b32 m0, s56
	s_nop 0
	global_load_lds_dwordx4 v134, s[6:7]
	s_mov_b32 m0, s57
	s_nop 0
	global_load_lds_dwordx4 v130, s[6:7]
	s_mov_b32 m0, s96
	s_nop 0
	global_load_lds_dwordx4 v136, s[100:101]
	s_mov_b32 m0, s97
	s_nop 0
	global_load_lds_dwordx4 v132, s[100:101]
	s_waitcnt vmcnt(8)
	s_waitcnt lgkmcnt(0)
	s_setprio 1
	s_barrier
	v_mfma_f32_16x16x32_bf16 v[54:57], v[150:153], v[188:191], v[54:57]
	v_mfma_f32_16x16x32_bf16 v[50:53], v[158:161], v[188:191], v[50:53]
	v_mfma_f32_16x16x32_bf16 v[38:41], v[150:153], v[196:199], v[38:41]
	v_mfma_f32_16x16x32_bf16 v[34:37], v[158:161], v[196:199], v[34:37]
	v_mfma_f32_16x16x32_bf16 v[22:25], v[150:153], v[204:207], v[22:25]
	v_mfma_f32_16x16x32_bf16 v[18:21], v[158:161], v[204:207], v[18:21]
	v_mfma_f32_16x16x32_bf16 v[6:9], v[150:153], v[212:215], v[6:9]
	v_mfma_f32_16x16x32_bf16 v[2:5], v[158:161], v[212:215], v[2:5]
	v_mfma_f32_16x16x32_bf16 v[54:57], v[154:157], v[192:195], v[54:57]
	v_mfma_f32_16x16x32_bf16 v[50:53], v[168:171], v[192:195], v[50:53]
	v_mfma_f32_16x16x32_bf16 v[38:41], v[154:157], v[200:203], v[38:41]
	v_mfma_f32_16x16x32_bf16 v[34:37], v[168:171], v[200:203], v[34:37]
	v_mfma_f32_16x16x32_bf16 v[22:25], v[154:157], v[208:211], v[22:25]
	v_mfma_f32_16x16x32_bf16 v[18:21], v[168:171], v[208:211], v[18:21]
	v_mfma_f32_16x16x32_bf16 v[6:9], v[154:157], v[216:219], v[6:9]
	v_mfma_f32_16x16x32_bf16 v[2:5], v[168:171], v[216:219], v[2:5]
	s_setprio 0
	s_setprio 1
	v_mfma_f32_16x16x32_bf16 v[62:65], v[172:175], v[188:191], v[62:65]
	v_mfma_f32_16x16x32_bf16 v[58:61], v[180:183], v[188:191], v[58:61]
	v_mfma_f32_16x16x32_bf16 v[46:49], v[172:175], v[196:199], v[46:49]
	v_mfma_f32_16x16x32_bf16 v[42:45], v[180:183], v[196:199], v[42:45]
	v_mfma_f32_16x16x32_bf16 v[30:33], v[172:175], v[204:207], v[30:33]
	v_mfma_f32_16x16x32_bf16 v[26:29], v[180:183], v[204:207], v[26:29]
	v_mfma_f32_16x16x32_bf16 v[14:17], v[172:175], v[212:215], v[14:17]
	v_mfma_f32_16x16x32_bf16 v[10:13], v[180:183], v[212:215], v[10:13]
	v_mfma_f32_16x16x32_bf16 v[62:65], v[176:179], v[192:195], v[62:65]
	v_mfma_f32_16x16x32_bf16 v[58:61], v[184:187], v[192:195], v[58:61]
	v_mfma_f32_16x16x32_bf16 v[46:49], v[176:179], v[200:203], v[46:49]
	v_mfma_f32_16x16x32_bf16 v[42:45], v[184:187], v[200:203], v[42:45]
	v_mfma_f32_16x16x32_bf16 v[30:33], v[176:179], v[208:211], v[30:33]
	v_mfma_f32_16x16x32_bf16 v[26:29], v[184:187], v[208:211], v[26:29]
	v_mfma_f32_16x16x32_bf16 v[14:17], v[176:179], v[216:219], v[14:17]
	v_mfma_f32_16x16x32_bf16 v[10:13], v[184:187], v[216:219], v[10:13]
	s_barrier
	s_setprio 0
	s_add_i32 s15, s15, 2
	s_add_u32 s80, s80, 0x100
	s_addc_u32 s81, s81, 0
	s_add_u32 s30, s30, 0x100
	s_addc_u32 s14, s14, 0
	s_cmp_gt_u32 s15, 61
	s_cbranch_scc0 .LBB0_415
	s_and_b64 vcc, exec, s[64:65]
	s_cbranch_vccz .LBB0_418
	s_barrier

;     __host__ __device__ bool next(int i, Unit& u) const { if (!StaticOrder::next(i >> 1, u)) return false; u.seg = i & 1; return true; }
;     ...
;         const bool has_next = S.next(ui + 1, nxt);
;         const char* nA = has_next ? PG8_APTR(nxt) : cA; const char* nB = has_next ? PG8_BPTR(nxt) : cB;
;         const char* pfc = PG8_PFPTR(cA, cB); const char* pfn = PG8_PFPTR(nA, nB);
.LBB0_434:
	s_ashr_i32 s67, s66, 31
	ds_read_b128 v[2:5], v141
	ds_read_b128 v[6:9], v141 offset:1024
	ds_read_b128 v[10:13], v141 offset:2048
	ds_read_b128 v[14:17], v141 offset:3072
	ds_read_b128 v[18:21], v142
	ds_read_b128 v[22:25], v142 offset:1024
	ds_read_b128 v[26:29], v142 offset:2048
	ds_read_b128 v[30:33], v142 offset:3072
	s_lshl_b64 s[14:15], s[66:67], 21
	s_add_u32 s70, s11, s14
	s_addc_u32 s71, s12, s15
	s_and_b64 s[14:15], s[68:69], exec
	s_cselect_b32 s9, s71, s79
	s_cselect_b32 s67, s70, s78
	s_and_b32 s18, s94, 0x7fffffff
	s_lshl_b64 s[14:15], s[18:19], 21
	s_add_u32 s74, s13, s14
	s_addc_u32 s75, s29, s15
	s_and_b64 s[14:15], s[68:69], exec
	s_cselect_b32 s18, s75, s77
	s_cselect_b32 s95, s74, s76
	s_add_u32 s14, s78, 0x100080
	s_addc_u32 s15, s79, 0
	s_add_i32 s96, s59, 0xc000
	v_lshl_add_u64 v[66:67], s[14:15], 0, v[132:133]
	s_mov_b32 m0, s96
	s_add_i32 s97, s59, 0xe000
	ds_read_b128 v[34:37], v143
	ds_read_b128 v[38:41], v143 offset:1024
	ds_read_b128 v[42:45], v143 offset:2048
	ds_read_b128 v[46:49], v143 offset:3072
	ds_read_b128 v[50:53], v143 offset:4096
	ds_read_b128 v[54:57], v143 offset:5120
	ds_read_b128 v[58:61], v143 offset:6144
	ds_read_b128 v[62:65], v143 offset:7168
	global_load_lds_dwordx4 v[66:67], off
	v_lshl_add_u64 v[66:67], s[14:15], 0, v[130:131]
	s_mov_b32 m0, s97
	s_nop 0
	global_load_lds_dwordx4 v[66:67], off
	s_waitcnt vmcnt(8)
	s_waitcnt lgkmcnt(0)
	s_setprio 1
	s_barrier
	v_mfma_f32_16x16x32_bf16 v[66:69], v[2:5], v[34:37], 0
	v_mfma_f32_16x16x32_bf16 v[70:73], v[10:13], v[34:37], 0
	v_mfma_f32_16x16x32_bf16 v[74:77], v[2:5], v[42:45], 0
	v_mfma_f32_16x16x32_bf16 v[78:81], v[10:13], v[42:45], 0
	v_mfma_f32_16x16x32_bf16 v[82:85], v[2:5], v[50:53], 0
	v_mfma_f32_16x16x32_bf16 v[86:89], v[10:13], v[50:53], 0
	v_mfma_f32_16x16x32_bf16 v[90:93], v[2:5], v[58:61], 0
	v_mfma_f32_16x16x32_bf16 v[94:97], v[10:13], v[58:61], 0
	v_mfma_f32_16x16x32_bf16 v[66:69], v[6:9], v[38:41], v[66:69]
	v_mfma_f32_16x16x32_bf16 v[70:73], v[14:17], v[38:41], v[70:73]
	v_mfma_f32_16x16x32_bf16 v[74:77], v[6:9], v[46:49], v[74:77]
	v_mfma_f32_16x16x32_bf16 v[78:81], v[14:17], v[46:49], v[78:81]
	v_mfma_f32_16x16x32_bf16 v[82:85], v[6:9], v[54:57], v[82:85]
	v_mfma_f32_16x16x32_bf16 v[86:89], v[14:17], v[54:57], v[86:89]
	v_mfma_f32_16x16x32_bf16 v[90:93], v[6:9], v[62:65], v[90:93]
	v_mfma_f32_16x16x32_bf16 v[94:97], v[14:17], v[62:65], v[94:97]
	s_setprio 0
	s_setprio 1
	v_mfma_f32_16x16x32_bf16 v[98:101], v[18:21], v[34:37], 0
	v_mfma_f32_16x16x32_bf16 v[34:37], v[26:29], v[34:37], 0
	v_mfma_f32_16x16x32_bf16 v[102:105], v[30:33], v[38:41], v[34:37]
	v_mfma_f32_16x16x32_bf16 v[34:37], v[18:21], v[42:45], 0
	v_mfma_f32_16x16x32_bf16 v[106:109], v[22:25], v[46:49], v[34:37]
	v_mfma_f32_16x16x32_bf16 v[34:37], v[26:29], v[42:45], 0
	v_mfma_f32_16x16x32_bf16 v[42:45], v[30:33], v[46:49], v[34:37]
	v_mfma_f32_16x16x32_bf16 v[34:37], v[18:21], v[50:53], 0
	v_mfma_f32_16x16x32_bf16 v[46:49], v[22:25], v[54:57], v[34:37]
	v_mfma_f32_16x16x32_bf16 v[34:37], v[26:29], v[50:53], 0
	v_mfma_f32_16x16x32_bf16 v[50:53], v[30:33], v[54:57], v[34:37]
	v_mfma_f32_16x16x32_bf16 v[34:37], v[18:21], v[58:61], 0
	v_mfma_f32_16x16x32_bf16 v[110:113], v[22:25], v[62:65], v[34:37]
	v_mfma_f32_16x16x32_bf16 v[34:37], v[26:29], v[58:61], 0
	v_mfma_f32_16x16x32_bf16 v[98:101], v[22:25], v[38:41], v[98:101]
	v_mfma_f32_16x16x32_bf16 v[58:61], v[30:33], v[62:65], v[34:37]
	s_barrier
	s_setprio 0
	s_add_i32 vcc_lo, s91, s33
	v_lshl_add_u64 v[246:247], s[76:77], 0, v[132:133]
	s_add_i32 s84, vcc_lo, 0x2000
	v_lshl_add_u64 v[144:145], v[246:247], 0, s[62:63]
	s_mov_b32 m0, vcc_lo
	v_lshl_add_u64 v[248:249], s[76:77], 0, v[130:131]
	s_add_u32 s14, s76, 0x100100
	ds_read_b128 v[34:37], v143 offset:16384
	ds_read_b128 v[38:41], v143 offset:17408
	ds_read_b128 v[54:57], v143 offset:18432
	ds_read_b128 v[62:65], v143 offset:19456
	ds_read_b128 v[114:117], v143 offset:20480
	ds_read_b128 v[118:121], v143 offset:21504
	ds_read_b128 v[122:125], v143 offset:22528
	ds_read_b128 v[126:129], v143 offset:23552
	global_load_lds_dwordx4 v[144:145], off
	v_lshl_add_u64 v[144:145], v[248:249], 0, s[62:63]
	s_mov_b32 m0, s84
	s_addc_u32 s15, s77, 0
	s_add_i32 s85, s92, s33
	global_load_lds_dwordx4 v[144:145], off
	v_lshl_add_u64 v[144:145], s[14:15], 0, v[132:133]
	s_mov_b32 m0, s85
	s_add_i32 s46, s85, 0x2000
	global_load_lds_dwordx4 v[144:145], off
	v_lshl_add_u64 v[144:145], s[14:15], 0, v[130:131]
	s_mov_b32 m0, s46
	v_lshl_add_u64 v[250:251], s[78:79], 0, v[132:133]
	global_load_lds_dwordx4 v[144:145], off
	v_lshl_add_u64 v[144:145], v[250:251], 0, s[62:63]
	s_mov_b32 m0, s59
	v_lshl_add_u64 v[252:253], s[78:79], 0, v[130:131]
	global_load_lds_dwordx4 v[144:145], off
	v_lshl_add_u64 v[144:145], v[252:253], 0, s[62:63]
	s_mov_b32 m0, s82
	s_nop 0
	global_load_lds_dwordx4 v[144:145], off
	s_waitcnt vmcnt(8)
	s_waitcnt lgkmcnt(0)
	s_setprio 1
	s_barrier
	v_mfma_f32_16x16x32_bf16 v[144:147], v[2:5], v[34:37], 0
	v_mfma_f32_16x16x32_bf16 v[154:157], v[2:5], v[54:57], 0
	v_mfma_f32_16x16x32_bf16 v[162:165], v[2:5], v[114:117], 0
	v_mfma_f32_16x16x32_bf16 v[2:5], v[2:5], v[122:125], 0
	v_mfma_f32_16x16x32_bf16 v[150:153], v[10:13], v[34:37], 0
	v_mfma_f32_16x16x32_bf16 v[158:161], v[10:13], v[54:57], 0
	v_mfma_f32_16x16x32_bf16 v[166:169], v[10:13], v[114:117], 0
	v_mfma_f32_16x16x32_bf16 v[170:173], v[6:9], v[126:129], v[2:5]
	v_mfma_f32_16x16x32_bf16 v[2:5], v[10:13], v[122:125], 0
	v_mfma_f32_16x16x32_bf16 v[146:149], v[6:9], v[38:41], v[144:147]
	v_mfma_f32_16x16x32_bf16 v[150:153], v[14:17], v[38:41], v[150:153]
	v_mfma_f32_16x16x32_bf16 v[154:157], v[6:9], v[62:65], v[154:157]
	v_mfma_f32_16x16x32_bf16 v[158:161], v[14:17], v[62:65], v[158:161]
	v_mfma_f32_16x16x32_bf16 v[162:165], v[6:9], v[118:121], v[162:165]
	v_mfma_f32_16x16x32_bf16 v[166:169], v[14:17], v[118:121], v[166:169]
	v_mfma_f32_16x16x32_bf16 v[174:177], v[14:17], v[126:129], v[2:5]
	s_setprio 0
	s_setprio 1
	v_mfma_f32_16x16x32_bf16 v[2:5], v[18:21], v[34:37], 0
	v_mfma_f32_16x16x32_bf16 v[178:181], v[22:25], v[38:41], v[2:5]
	v_mfma_f32_16x16x32_bf16 v[2:5], v[26:29], v[34:37], 0
	v_mfma_f32_16x16x32_bf16 v[182:185], v[30:33], v[38:41], v[2:5]
	v_mfma_f32_16x16x32_bf16 v[2:5], v[18:21], v[54:57], 0
	v_mfma_f32_16x16x32_bf16 v[186:189], v[22:25], v[62:65], v[2:5]
	v_mfma_f32_16x16x32_bf16 v[2:5], v[26:29], v[54:57], 0
	v_mfma_f32_16x16x32_bf16 v[190:193], v[30:33], v[62:65], v[2:5]
	v_mfma_f32_16x16x32_bf16 v[2:5], v[18:21], v[114:117], 0
	v_mfma_f32_16x16x32_bf16 v[194:197], v[22:25], v[118:121], v[2:5]
	v_mfma_f32_16x16x32_bf16 v[2:5], v[26:29], v[114:117], 0
	v_mfma_f32_16x16x32_bf16 v[198:201], v[30:33], v[118:121], v[2:5]
	v_mfma_f32_16x16x32_bf16 v[2:5], v[18:21], v[122:125], 0
	v_mfma_f32_16x16x32_bf16 v[202:205], v[22:25], v[126:129], v[2:5]
	v_mfma_f32_16x16x32_bf16 v[2:5], v[26:29], v[122:125], 0
	v_mfma_f32_16x16x32_bf16 v[206:209], v[30:33], v[126:129], v[2:5]
	s_barrier
	s_setprio 0
	s_add_i32 s47, 0, 0x18000
	s_add_i32 s56, 0, 0x1c000
	v_add_u32_e32 v134, s47, v140
	v_add_u32_e32 v144, s56, v140
	ds_read_b128 v[114:117], v134
	ds_read_b128 v[118:121], v134 offset:1024
	ds_read_b128 v[122:125], v134 offset:2048
	ds_read_b128 v[126:129], v134 offset:3072
	ds_read_b128 v[210:213], v144
	ds_read_b128 v[214:217], v144 offset:1024
	ds_read_b128 v[218:221], v144 offset:2048
	ds_read_b128 v[222:225], v144 offset:3072
	s_add_u32 s14, s78, 0x100100
	s_addc_u32 s15, s79, 0
	s_mov_b32 m0, s83
	v_lshl_add_u64 v[2:3], s[14:15], 0, v[132:133]
	ds_read_b128 v[26:29], v143 offset:32768
	ds_read_b128 v[30:33], v143 offset:33792
	ds_read_b128 v[62:65], v143 offset:34816
	ds_read_b128 v[226:229], v143 offset:35840
	ds_read_b128 v[230:233], v143 offset:36864
	ds_read_b128 v[234:237], v143 offset:37888
	ds_read_b128 v[238:241], v143 offset:38912
	ds_read_b128 v[242:245], v143 offset:39936
	global_load_lds_dwordx4 v[2:3], off
	v_lshl_add_u64 v[2:3], s[14:15], 0, v[130:131]
	s_mov_b32 m0, s86
	s_nop 0
	global_load_lds_dwordx4 v[2:3], off
	s_waitcnt vmcnt(8)
	s_waitcnt lgkmcnt(0)
	s_setprio 1
	s_barrier
	v_mfma_f32_16x16x32_bf16 v[2:5], v[114:117], v[26:29], v[66:69]
	v_mfma_f32_16x16x32_bf16 v[34:37], v[118:121], v[30:33], v[2:5]
	v_mfma_f32_16x16x32_bf16 v[2:5], v[122:125], v[26:29], v[70:73]
	v_mfma_f32_16x16x32_bf16 v[38:41], v[126:129], v[30:33], v[2:5]
	v_mfma_f32_16x16x32_bf16 v[2:5], v[114:117], v[62:65], v[74:77]
	v_mfma_f32_16x16x32_bf16 v[18:21], v[118:121], v[226:229], v[2:5]
	v_mfma_f32_16x16x32_bf16 v[2:5], v[122:125], v[62:65], v[78:81]
	v_mfma_f32_16x16x32_bf16 v[22:25], v[126:129], v[226:229], v[2:5]
	v_mfma_f32_16x16x32_bf16 v[2:5], v[114:117], v[230:233], v[82:85]
	v_mfma_f32_16x16x32_bf16 v[10:13], v[118:121], v[234:237], v[2:5]
	v_mfma_f32_16x16x32_bf16 v[2:5], v[122:125], v[230:233], v[86:89]
	v_mfma_f32_16x16x32_bf16 v[14:17], v[126:129], v[234:237], v[2:5]
	v_mfma_f32_16x16x32_bf16 v[2:5], v[114:117], v[238:241], v[90:93]
	v_mfma_f32_16x16x32_bf16 v[6:9], v[122:125], v[238:241], v[94:97]
	v_mfma_f32_16x16x32_bf16 v[2:5], v[118:121], v[242:245], v[2:5]
	v_mfma_f32_16x16x32_bf16 v[6:9], v[126:129], v[242:245], v[6:9]
	s_setprio 0
	s_setprio 1
	v_mfma_f32_16x16x32_bf16 v[54:57], v[210:213], v[26:29], v[98:101]
	v_mfma_f32_16x16x32_bf16 v[26:29], v[218:221], v[26:29], v[102:105]
	v_mfma_f32_16x16x32_bf16 v[70:73], v[222:225], v[30:33], v[26:29]
	v_mfma_f32_16x16x32_bf16 v[26:29], v[210:213], v[62:65], v[106:109]
	v_mfma_f32_16x16x32_bf16 v[66:69], v[214:217], v[30:33], v[54:57]
	v_mfma_f32_16x16x32_bf16 v[54:57], v[214:217], v[226:229], v[26:29]
	v_mfma_f32_16x16x32_bf16 v[26:29], v[218:221], v[62:65], v[42:45]
	v_mfma_f32_16x16x32_bf16 v[62:65], v[222:225], v[226:229], v[26:29]
	v_mfma_f32_16x16x32_bf16 v[26:29], v[210:213], v[230:233], v[46:49]
	v_mfma_f32_16x16x32_bf16 v[42:45], v[214:217], v[234:237], v[26:29]
	v_mfma_f32_16x16x32_bf16 v[26:29], v[218:221], v[230:233], v[50:53]
	v_mfma_f32_16x16x32_bf16 v[46:49], v[222:225], v[234:237], v[26:29]
	v_mfma_f32_16x16x32_bf16 v[26:29], v[210:213], v[238:241], v[110:113]
	v_mfma_f32_16x16x32_bf16 v[30:33], v[218:221], v[238:241], v[58:61]
	v_mfma_f32_16x16x32_bf16 v[26:29], v[214:217], v[242:245], v[26:29]
	v_mfma_f32_16x16x32_bf16 v[30:33], v[222:225], v[242:245], v[30:33]
	s_barrier
	s_setprio 0
	s_add_i32 s47, s47, s33
	s_add_i32 vcc_hi, s47, 0x2000
	v_lshl_add_u64 v[50:51], v[246:247], 0, s[64:65]
	s_mov_b32 m0, s47
	s_add_u32 s14, s76, 0x100180
	ds_read_b128 v[82:85], v143 offset:49152
	ds_read_b128 v[86:89], v143 offset:50176
	ds_read_b128 v[98:101], v143 offset:51200
	ds_read_b128 v[106:109], v143 offset:52224
	ds_read_b128 v[226:229], v143 offset:53248
	ds_read_b128 v[230:233], v143 offset:54272
	ds_read_b128 v[234:237], v143 offset:55296
	ds_read_b128 v[238:241], v143 offset:56320
	global_load_lds_dwordx4 v[50:51], off
	v_lshl_add_u64 v[50:51], v[248:249], 0, s[64:65]
	s_mov_b32 m0, vcc_hi
	s_addc_u32 s15, s77, 0
	s_add_i32 s56, s56, s33
	global_load_lds_dwordx4 v[50:51], off
	v_lshl_add_u64 v[50:51], s[14:15], 0, v[132:133]
	s_mov_b32 m0, s56
	s_add_i32 s57, s56, 0x2000
	global_load_lds_dwordx4 v[50:51], off
	v_lshl_add_u64 v[50:51], s[14:15], 0, v[130:131]
	s_mov_b32 m0, s57
	s_nop 0
	global_load_lds_dwordx4 v[50:51], off
	v_lshl_add_u64 v[50:51], v[250:251], 0, s[64:65]
	s_mov_b32 m0, s88
	s_nop 0
	global_load_lds_dwordx4 v[50:51], off
	v_lshl_add_u64 v[50:51], v[252:253], 0, s[64:65]
	s_mov_b32 m0, s89
	s_nop 0
	global_load_lds_dwordx4 v[50:51], off
	s_waitcnt vmcnt(8)
	s_waitcnt lgkmcnt(0)
	s_setprio 1
	s_barrier
	v_mfma_f32_16x16x32_bf16 v[50:53], v[114:117], v[82:85], v[146:149]
	v_mfma_f32_16x16x32_bf16 v[102:105], v[118:121], v[86:89], v[50:53]
	v_mfma_f32_16x16x32_bf16 v[50:53], v[122:125], v[82:85], v[150:153]
	v_mfma_f32_16x16x32_bf16 v[110:113], v[126:129], v[86:89], v[50:53]
	v_mfma_f32_16x16x32_bf16 v[50:53], v[114:117], v[98:101], v[154:157]
	v_mfma_f32_16x16x32_bf16 v[90:93], v[118:121], v[106:109], v[50:53]
	v_mfma_f32_16x16x32_bf16 v[50:53], v[122:125], v[98:101], v[158:161]
	v_mfma_f32_16x16x32_bf16 v[94:97], v[126:129], v[106:109], v[50:53]
	v_mfma_f32_16x16x32_bf16 v[50:53], v[114:117], v[226:229], v[162:165]
	v_mfma_f32_16x16x32_bf16 v[74:77], v[118:121], v[230:233], v[50:53]
	v_mfma_f32_16x16x32_bf16 v[50:53], v[122:125], v[226:229], v[166:169]
	v_mfma_f32_16x16x32_bf16 v[78:81], v[126:129], v[230:233], v[50:53]
	v_mfma_f32_16x16x32_bf16 v[50:53], v[114:117], v[234:237], v[170:173]
	v_mfma_f32_16x16x32_bf16 v[58:61], v[122:125], v[234:237], v[174:177]
	v_mfma_f32_16x16x32_bf16 v[50:53], v[118:121], v[238:241], v[50:53]
	v_mfma_f32_16x16x32_bf16 v[58:61], v[126:129], v[238:241], v[58:61]
	s_setprio 0
	s_setprio 1
	v_mfma_f32_16x16x32_bf16 v[114:117], v[210:213], v[82:85], v[178:181]
	v_mfma_f32_16x16x32_bf16 v[82:85], v[218:221], v[82:85], v[182:185]
	v_mfma_f32_16x16x32_bf16 v[126:129], v[222:225], v[86:89], v[82:85]
	v_mfma_f32_16x16x32_bf16 v[82:85], v[210:213], v[98:101], v[186:189]
	v_mfma_f32_16x16x32_bf16 v[122:125], v[214:217], v[86:89], v[114:117]
	v_mfma_f32_16x16x32_bf16 v[114:117], v[214:217], v[106:109], v[82:85]
	v_mfma_f32_16x16x32_bf16 v[82:85], v[218:221], v[98:101], v[190:193]
	v_mfma_f32_16x16x32_bf16 v[118:121], v[222:225], v[106:109], v[82:85]
	v_mfma_f32_16x16x32_bf16 v[82:85], v[210:213], v[226:229], v[194:197]
	v_mfma_f32_16x16x32_bf16 v[98:101], v[214:217], v[230:233], v[82:85]
	v_mfma_f32_16x16x32_bf16 v[82:85], v[218:221], v[226:229], v[198:201]
	v_mfma_f32_16x16x32_bf16 v[106:109], v[222:225], v[230:233], v[82:85]
	v_mfma_f32_16x16x32_bf16 v[82:85], v[210:213], v[234:237], v[202:205]
	v_mfma_f32_16x16x32_bf16 v[86:89], v[218:221], v[234:237], v[206:209]
	v_mfma_f32_16x16x32_bf16 v[82:85], v[214:217], v[238:241], v[82:85]
	v_mfma_f32_16x16x32_bf16 v[86:89], v[222:225], v[238:241], v[86:89]
	s_barrier
	s_setprio 0
	s_add_u32 s78, s78, 0x100180
	s_addc_u32 s79, s79, 0
	s_add_u32 s14, s76, 0x200
	s_addc_u32 s15, s77, 0
	s_mov_b32 s16, 0
.LBB0_435:
	ds_read_b128 v[146:149], v141
	ds_read_b128 v[150:153], v141 offset:1024
	ds_read_b128 v[154:157], v141 offset:2048
	ds_read_b128 v[158:161], v141 offset:3072
	ds_read_b128 v[162:165], v142
	ds_read_b128 v[166:169], v142 offset:1024
	ds_read_b128 v[170:173], v142 offset:2048
	ds_read_b128 v[174:177], v142 offset:3072
	s_add_u32 s17, s78, 0xfff00080
	s_addc_u32 s20, s79, -1
	s_cmp_eq_u32 s16, 60
	s_cselect_b32 s81, s9, s20
	s_cselect_b32 s80, s67, s17
	s_cselect_b32 s77, s18, s15
	s_cselect_b32 s76, s95, s14
	s_mov_b32 m0, s96
	ds_read_b128 v[178:181], v143
	ds_read_b128 v[182:185], v143 offset:1024
	ds_read_b128 v[186:189], v143 offset:2048
	ds_read_b128 v[190:193], v143 offset:3072
	ds_read_b128 v[194:197], v143 offset:4096
	ds_read_b128 v[198:201], v143 offset:5120
	ds_read_b128 v[202:205], v143 offset:6144
	ds_read_b128 v[206:209], v143 offset:7168
	global_load_lds_dwordx4 v136, s[78:79]
	s_mov_b32 m0, s97
	s_nop 0
	global_load_lds_dwordx4 v138, s[78:79]
	s_waitcnt vmcnt(8)
	s_waitcnt lgkmcnt(0)
	s_setprio 1
	s_barrier
	v_mfma_f32_16x16x32_bf16 v[34:37], v[146:149], v[178:181], v[34:37]
	v_mfma_f32_16x16x32_bf16 v[38:41], v[154:157], v[178:181], v[38:41]
	v_mfma_f32_16x16x32_bf16 v[18:21], v[146:149], v[186:189], v[18:21]
	v_mfma_f32_16x16x32_bf16 v[22:25], v[154:157], v[186:189], v[22:25]
	v_mfma_f32_16x16x32_bf16 v[10:13], v[146:149], v[194:197], v[10:13]
	v_mfma_f32_16x16x32_bf16 v[14:17], v[154:157], v[194:197], v[14:17]
	v_mfma_f32_16x16x32_bf16 v[2:5], v[146:149], v[202:205], v[2:5]
	v_mfma_f32_16x16x32_bf16 v[6:9], v[154:157], v[202:205], v[6:9]
	v_mfma_f32_16x16x32_bf16 v[34:37], v[150:153], v[182:185], v[34:37]
	v_mfma_f32_16x16x32_bf16 v[38:41], v[158:161], v[182:185], v[38:41]
	v_mfma_f32_16x16x32_bf16 v[18:21], v[150:153], v[190:193], v[18:21]
	v_mfma_f32_16x16x32_bf16 v[22:25], v[158:161], v[190:193], v[22:25]
	v_mfma_f32_16x16x32_bf16 v[10:13], v[150:153], v[198:201], v[10:13]
	v_mfma_f32_16x16x32_bf16 v[14:17], v[158:161], v[198:201], v[14:17]
	v_mfma_f32_16x16x32_bf16 v[2:5], v[150:153], v[206:209], v[2:5]
	v_mfma_f32_16x16x32_bf16 v[6:9], v[158:161], v[206:209], v[6:9]
	s_setprio 0
	s_setprio 1
	v_mfma_f32_16x16x32_bf16 v[66:69], v[162:165], v[178:181], v[66:69]
	v_mfma_f32_16x16x32_bf16 v[70:73], v[170:173], v[178:181], v[70:73]
	v_mfma_f32_16x16x32_bf16 v[54:57], v[162:165], v[186:189], v[54:57]
	v_mfma_f32_16x16x32_bf16 v[62:65], v[170:173], v[186:189], v[62:65]
	v_mfma_f32_16x16x32_bf16 v[42:45], v[162:165], v[194:197], v[42:45]
	v_mfma_f32_16x16x32_bf16 v[46:49], v[170:173], v[194:197], v[46:49]
	v_mfma_f32_16x16x32_bf16 v[26:29], v[162:165], v[202:205], v[26:29]
	v_mfma_f32_16x16x32_bf16 v[30:33], v[170:173], v[202:205], v[30:33]
	v_mfma_f32_16x16x32_bf16 v[66:69], v[166:169], v[182:185], v[66:69]
	v_mfma_f32_16x16x32_bf16 v[70:73], v[174:177], v[182:185], v[70:73]
	v_mfma_f32_16x16x32_bf16 v[54:57], v[166:169], v[190:193], v[54:57]
	v_mfma_f32_16x16x32_bf16 v[62:65], v[174:177], v[190:193], v[62:65]
	v_mfma_f32_16x16x32_bf16 v[42:45], v[166:169], v[198:201], v[42:45]
	v_mfma_f32_16x16x32_bf16 v[46:49], v[174:177], v[198:201], v[46:49]
	v_mfma_f32_16x16x32_bf16 v[26:29], v[166:169], v[206:209], v[26:29]
	v_mfma_f32_16x16x32_bf16 v[30:33], v[174:177], v[206:209], v[30:33]
	s_barrier
	s_setprio 0
	s_mov_b32 m0, vcc_lo
	s_mov_b64 s[98:99], s[76:77]
	s_add_u32 s20, s76, 0x100000
	ds_read_b128 v[178:181], v143 offset:16384
	ds_read_b128 v[182:185], v143 offset:17408
	ds_read_b128 v[186:189], v143 offset:18432
	ds_read_b128 v[190:193], v143 offset:19456
	ds_read_b128 v[194:197], v143 offset:20480
	ds_read_b128 v[198:201], v143 offset:21504
	ds_read_b128 v[202:205], v143 offset:22528
	ds_read_b128 v[206:209], v143 offset:23552
	global_load_lds_dwordx4 v132, s[76:77]
	s_mov_b32 m0, s84
	s_addc_u32 s21, s77, 0
	global_load_lds_dwordx4 v130, s[76:77]
	s_mov_b32 m0, s85
	s_mov_b64 s[100:101], s[80:81]
	global_load_lds_dwordx4 v132, s[20:21]
	s_mov_b32 m0, s46
	s_nop 0
	global_load_lds_dwordx4 v130, s[20:21]
	s_mov_b32 m0, s59
	s_nop 0
	global_load_lds_dwordx4 v132, s[80:81]
	s_mov_b32 m0, s82
	s_nop 0
	global_load_lds_dwordx4 v130, s[80:81]
	s_waitcnt vmcnt(8)
	s_waitcnt lgkmcnt(0)
	s_setprio 1
	s_barrier
	v_mfma_f32_16x16x32_bf16 v[102:105], v[146:149], v[178:181], v[102:105]
	v_mfma_f32_16x16x32_bf16 v[110:113], v[154:157], v[178:181], v[110:113]
	v_mfma_f32_16x16x32_bf16 v[90:93], v[146:149], v[186:189], v[90:93]
	v_mfma_f32_16x16x32_bf16 v[94:97], v[154:157], v[186:189], v[94:97]
	v_mfma_f32_16x16x32_bf16 v[74:77], v[146:149], v[194:197], v[74:77]
	v_mfma_f32_16x16x32_bf16 v[78:81], v[154:157], v[194:197], v[78:81]
	v_mfma_f32_16x16x32_bf16 v[50:53], v[146:149], v[202:205], v[50:53]
	v_mfma_f32_16x16x32_bf16 v[58:61], v[154:157], v[202:205], v[58:61]
	v_mfma_f32_16x16x32_bf16 v[102:105], v[150:153], v[182:185], v[102:105]
	v_mfma_f32_16x16x32_bf16 v[110:113], v[158:161], v[182:185], v[110:113]
	v_mfma_f32_16x16x32_bf16 v[90:93], v[150:153], v[190:193], v[90:93]
	v_mfma_f32_16x16x32_bf16 v[94:97], v[158:161], v[190:193], v[94:97]
	v_mfma_f32_16x16x32_bf16 v[74:77], v[150:153], v[198:201], v[74:77]
	v_mfma_f32_16x16x32_bf16 v[78:81], v[158:161], v[198:201], v[78:81]
	v_mfma_f32_16x16x32_bf16 v[50:53], v[150:153], v[206:209], v[50:53]
	v_mfma_f32_16x16x32_bf16 v[58:61], v[158:161], v[206:209], v[58:61]
	s_setprio 0
	s_setprio 1
	v_mfma_f32_16x16x32_bf16 v[122:125], v[162:165], v[178:181], v[122:125]
	v_mfma_f32_16x16x32_bf16 v[126:129], v[170:173], v[178:181], v[126:129]
	v_mfma_f32_16x16x32_bf16 v[114:117], v[162:165], v[186:189], v[114:117]
	v_mfma_f32_16x16x32_bf16 v[118:121], v[170:173], v[186:189], v[118:121]
	v_mfma_f32_16x16x32_bf16 v[98:101], v[162:165], v[194:197], v[98:101]
	v_mfma_f32_16x16x32_bf16 v[106:109], v[170:173], v[194:197], v[106:109]
	v_mfma_f32_16x16x32_bf16 v[82:85], v[162:165], v[202:205], v[82:85]
	v_mfma_f32_16x16x32_bf16 v[86:89], v[170:173], v[202:205], v[86:89]
	v_mfma_f32_16x16x32_bf16 v[122:125], v[166:169], v[182:185], v[122:125]
	v_mfma_f32_16x16x32_bf16 v[126:129], v[174:177], v[182:185], v[126:129]
	v_mfma_f32_16x16x32_bf16 v[114:117], v[166:169], v[190:193], v[114:117]
	v_mfma_f32_16x16x32_bf16 v[118:121], v[174:177], v[190:193], v[118:121]
	v_mfma_f32_16x16x32_bf16 v[98:101], v[166:169], v[198:201], v[98:101]
	v_mfma_f32_16x16x32_bf16 v[106:109], v[174:177], v[198:201], v[106:109]
	v_mfma_f32_16x16x32_bf16 v[82:85], v[166:169], v[206:209], v[82:85]
	v_mfma_f32_16x16x32_bf16 v[86:89], v[174:177], v[206:209], v[86:89]
	s_barrier
;     ...
;         for (int t = 2; t < nt; t += 2) PG8_KITER(t);
	s_setprio 0
	ds_read_b128 v[146:149], v134
	ds_read_b128 v[150:153], v134 offset:1024
	ds_read_b128 v[154:157], v134 offset:2048
	ds_read_b128 v[158:161], v134 offset:3072
	ds_read_b128 v[162:165], v144
	ds_read_b128 v[166:169], v144 offset:1024
	ds_read_b128 v[170:173], v144 offset:2048
	ds_read_b128 v[174:177], v144 offset:3072
	s_add_u32 s20, s80, 0x100000
	s_addc_u32 s21, s81, 0
	s_mov_b32 m0, s83
	ds_read_b128 v[178:181], v143 offset:32768
	ds_read_b128 v[182:185], v143 offset:33792
	ds_read_b128 v[186:189], v143 offset:34816
	ds_read_b128 v[190:193], v143 offset:35840
	ds_read_b128 v[194:197], v143 offset:36864
	ds_read_b128 v[198:201], v143 offset:37888
	ds_read_b128 v[202:205], v143 offset:38912
	ds_read_b128 v[206:209], v143 offset:39936
	global_load_lds_dwordx4 v132, s[20:21]
	s_mov_b32 m0, s86
	s_nop 0
	global_load_lds_dwordx4 v130, s[20:21]
	s_waitcnt vmcnt(8)
	s_waitcnt lgkmcnt(0)
	s_setprio 1
	s_barrier
	v_mfma_f32_16x16x32_bf16 v[34:37], v[146:149], v[178:181], v[34:37]
	v_mfma_f32_16x16x32_bf16 v[38:41], v[154:157], v[178:181], v[38:41]
	v_mfma_f32_16x16x32_bf16 v[18:21], v[146:149], v[186:189], v[18:21]
	v_mfma_f32_16x16x32_bf16 v[22:25], v[154:157], v[186:189], v[22:25]
	v_mfma_f32_16x16x32_bf16 v[10:13], v[146:149], v[194:197], v[10:13]
	v_mfma_f32_16x16x32_bf16 v[14:17], v[154:157], v[194:197], v[14:17]
	v_mfma_f32_16x16x32_bf16 v[2:5], v[146:149], v[202:205], v[2:5]
	v_mfma_f32_16x16x32_bf16 v[6:9], v[154:157], v[202:205], v[6:9]
	v_mfma_f32_16x16x32_bf16 v[34:37], v[150:153], v[182:185], v[34:37]
	v_mfma_f32_16x16x32_bf16 v[38:41], v[158:161], v[182:185], v[38:41]
	v_mfma_f32_16x16x32_bf16 v[18:21], v[150:153], v[190:193], v[18:21]
	v_mfma_f32_16x16x32_bf16 v[22:25], v[158:161], v[190:193], v[22:25]
	v_mfma_f32_16x16x32_bf16 v[10:13], v[150:153], v[198:201], v[10:13]
	v_mfma_f32_16x16x32_bf16 v[14:17], v[158:161], v[198:201], v[14:17]
	v_mfma_f32_16x16x32_bf16 v[2:5], v[150:153], v[206:209], v[2:5]
	v_mfma_f32_16x16x32_bf16 v[6:9], v[158:161], v[206:209], v[6:9]
	s_setprio 0
	s_setprio 1
	v_mfma_f32_16x16x32_bf16 v[66:69], v[162:165], v[178:181], v[66:69]
	v_mfma_f32_16x16x32_bf16 v[70:73], v[170:173], v[178:181], v[70:73]
	v_mfma_f32_16x16x32_bf16 v[54:57], v[162:165], v[186:189], v[54:57]
	v_mfma_f32_16x16x32_bf16 v[62:65], v[170:173], v[186:189], v[62:65]
	v_mfma_f32_16x16x32_bf16 v[42:45], v[162:165], v[194:197], v[42:45]
	v_mfma_f32_16x16x32_bf16 v[46:49], v[170:173], v[194:197], v[46:49]
	v_mfma_f32_16x16x32_bf16 v[26:29], v[162:165], v[202:205], v[26:29]
	v_mfma_f32_16x16x32_bf16 v[30:33], v[170:173], v[202:205], v[30:33]
	v_mfma_f32_16x16x32_bf16 v[66:69], v[166:169], v[182:185], v[66:69]
	v_mfma_f32_16x16x32_bf16 v[70:73], v[174:177], v[182:185], v[70:73]
	v_mfma_f32_16x16x32_bf16 v[54:57], v[166:169], v[190:193], v[54:57]
	v_mfma_f32_16x16x32_bf16 v[62:65], v[174:177], v[190:193], v[62:65]
	v_mfma_f32_16x16x32_bf16 v[42:45], v[166:169], v[198:201], v[42:45]
	v_mfma_f32_16x16x32_bf16 v[46:49], v[174:177], v[198:201], v[46:49]
	v_mfma_f32_16x16x32_bf16 v[26:29], v[166:169], v[206:209], v[26:29]
	v_mfma_f32_16x16x32_bf16 v[30:33], v[174:177], v[206:209], v[30:33]
	s_barrier
	s_setprio 0
	s_mov_b32 m0, s47
	s_add_u32 s98, s98, 0x80
	s_addc_u32 s99, s99, 0
	s_add_u32 s100, s100, 0x80
	s_addc_u32 s101, s101, 0
	s_add_u32 s20, s76, 0x100080
	ds_read_b128 v[178:181], v143 offset:49152
	ds_read_b128 v[182:185], v143 offset:50176
	ds_read_b128 v[186:189], v143 offset:51200
	ds_read_b128 v[190:193], v143 offset:52224
	ds_read_b128 v[194:197], v143 offset:53248
	ds_read_b128 v[198:201], v143 offset:54272
	ds_read_b128 v[202:205], v143 offset:55296
	ds_read_b128 v[206:209], v143 offset:56320
	global_load_lds_dwordx4 v132, s[98:99]
	s_mov_b32 m0, vcc_hi
	s_addc_u32 s21, s77, 0
	global_load_lds_dwordx4 v130, s[98:99]
	s_mov_b32 m0, s56
	s_nop 0
	global_load_lds_dwordx4 v132, s[20:21]
	s_mov_b32 m0, s57
	s_nop 0
	global_load_lds_dwordx4 v130, s[20:21]
	s_mov_b32 m0, s88
	s_nop 0
	global_load_lds_dwordx4 v132, s[100:101]
	s_mov_b32 m0, s89
	s_nop 0
	global_load_lds_dwordx4 v130, s[100:101]
	s_waitcnt vmcnt(8)
	s_waitcnt lgkmcnt(0)
	s_setprio 1
	s_barrier
	v_mfma_f32_16x16x32_bf16 v[102:105], v[146:149], v[178:181], v[102:105]
	v_mfma_f32_16x16x32_bf16 v[110:113], v[154:157], v[178:181], v[110:113]
	v_mfma_f32_16x16x32_bf16 v[90:93], v[146:149], v[186:189], v[90:93]
	v_mfma_f32_16x16x32_bf16 v[94:97], v[154:157], v[186:189], v[94:97]
	v_mfma_f32_16x16x32_bf16 v[74:77], v[146:149], v[194:197], v[74:77]
	v_mfma_f32_16x16x32_bf16 v[78:81], v[154:157], v[194:197], v[78:81]
	v_mfma_f32_16x16x32_bf16 v[50:53], v[146:149], v[202:205], v[50:53]
	v_mfma_f32_16x16x32_bf16 v[58:61], v[154:157], v[202:205], v[58:61]
	v_mfma_f32_16x16x32_bf16 v[102:105], v[150:153], v[182:185], v[102:105]
	v_mfma_f32_16x16x32_bf16 v[110:113], v[158:161], v[182:185], v[110:113]
	v_mfma_f32_16x16x32_bf16 v[90:93], v[150:153], v[190:193], v[90:93]
	v_mfma_f32_16x16x32_bf16 v[94:97], v[158:161], v[190:193], v[94:97]
	v_mfma_f32_16x16x32_bf16 v[74:77], v[150:153], v[198:201], v[74:77]
	v_mfma_f32_16x16x32_bf16 v[78:81], v[158:161], v[198:201], v[78:81]
	v_mfma_f32_16x16x32_bf16 v[50:53], v[150:153], v[206:209], v[50:53]
	v_mfma_f32_16x16x32_bf16 v[58:61], v[158:161], v[206:209], v[58:61]
	s_setprio 0
	s_setprio 1
	v_mfma_f32_16x16x32_bf16 v[122:125], v[162:165], v[178:181], v[122:125]
	v_mfma_f32_16x16x32_bf16 v[126:129], v[170:173], v[178:181], v[126:129]
	v_mfma_f32_16x16x32_bf16 v[114:117], v[162:165], v[186:189], v[114:117]
	v_mfma_f32_16x16x32_bf16 v[118:121], v[170:173], v[186:189], v[118:121]
	v_mfma_f32_16x16x32_bf16 v[98:101], v[162:165], v[194:197], v[98:101]
	v_mfma_f32_16x16x32_bf16 v[106:109], v[170:173], v[194:197], v[106:109]
	v_mfma_f32_16x16x32_bf16 v[82:85], v[162:165], v[202:205], v[82:85]
	v_mfma_f32_16x16x32_bf16 v[86:89], v[170:173], v[202:205], v[86:89]
	v_mfma_f32_16x16x32_bf16 v[122:125], v[166:169], v[182:185], v[122:125]
	v_mfma_f32_16x16x32_bf16 v[126:129], v[174:177], v[182:185], v[126:129]
	v_mfma_f32_16x16x32_bf16 v[114:117], v[166:169], v[190:193], v[114:117]
	v_mfma_f32_16x16x32_bf16 v[118:121], v[174:177], v[190:193], v[118:121]
	v_mfma_f32_16x16x32_bf16 v[98:101], v[166:169], v[198:201], v[98:101]
	v_mfma_f32_16x16x32_bf16 v[106:109], v[174:177], v[198:201], v[106:109]
	v_mfma_f32_16x16x32_bf16 v[82:85], v[166:169], v[206:209], v[82:85]
	v_mfma_f32_16x16x32_bf16 v[86:89], v[174:177], v[206:209], v[86:89]
	s_barrier
	s_setprio 0
	s_add_i32 s16, s16, 2
	s_add_u32 s78, s78, 0x100
	s_addc_u32 s79, s79, 0
	s_add_u32 s14, s14, 0x100
	s_addc_u32 s15, s15, 0
	s_cmp_gt_u32 s16, 61
	s_cbranch_scc0 .LBB0_435
	s_and_b64 vcc, exec, s[30:31]
	s_cbranch_vccz .LBB0_438
	s_barrier

;     __host__ __device__ bool next(int i, Unit& u) const { if (!StaticOrder::next(i >> 1, u)) return false; u.seg = i & 1; return true; }
;     ...
;         const bool has_next = S.next(ui + 1, nxt);
;         const char* nA = has_next ? PG8_APTR(nxt) : cA; const char* nB = has_next ? PG8_BPTR(nxt) : cB;
;         const char* pfc = PG8_PFPTR(cA, cB); const char* pfn = PG8_PFPTR(nA, nB);
.LBB0_643:
	s_ashr_i32 s23, s22, 31
	ds_read_b128 v[2:5], v1
	ds_read_b128 v[6:9], v1 offset:1024
	ds_read_b128 v[10:13], v1 offset:2048
	ds_read_b128 v[14:17], v1 offset:3072
	ds_read_b128 v[18:21], v150
	ds_read_b128 v[22:25], v150 offset:1024
	ds_read_b128 v[26:29], v150 offset:2048
	ds_read_b128 v[30:33], v150 offset:3072
	s_lshl_b64 s[14:15], s[22:23], 19
	s_add_u32 s28, s24, s14
	s_addc_u32 s29, s25, s15
	s_and_b64 s[14:15], s[4:5], exec
	s_cselect_b32 s23, s29, s63
	s_cselect_b32 s83, s28, s62
	s_and_b32 s0, s81, 0x7fffffff
	s_lshl_b64 s[14:15], s[0:1], 19
	s_add_u32 s30, s10, s14
	s_addc_u32 s31, s11, s15
	s_and_b64 s[14:15], s[4:5], exec
	s_cselect_b32 s0, s31, s55
	s_cselect_b32 s86, s30, s54
	s_add_u32 s14, s62, 0x40080
	s_addc_u32 s15, s63, 0
	s_mov_b32 m0, s69
	v_lshl_add_u64 v[66:67], s[14:15], 0, v[136:137]
	ds_read_b128 v[34:37], v151
	ds_read_b128 v[38:41], v151 offset:1024
	ds_read_b128 v[42:45], v151 offset:2048
	ds_read_b128 v[46:49], v151 offset:3072
	ds_read_b128 v[50:53], v151 offset:4096
	ds_read_b128 v[54:57], v151 offset:5120
	ds_read_b128 v[58:61], v151 offset:6144
	ds_read_b128 v[62:65], v151 offset:7168
	global_load_lds_dwordx4 v[66:67], off
	v_lshl_add_u64 v[66:67], s[14:15], 0, v[132:133]
	s_mov_b32 m0, s70
	s_nop 0
	global_load_lds_dwordx4 v[66:67], off
	s_waitcnt vmcnt(8)
	s_waitcnt lgkmcnt(0)
	s_setprio 1
	s_barrier
	v_mfma_f32_16x16x32_bf16 v[90:93], v[2:5], v[58:61], 0
	v_mfma_f32_16x16x32_bf16 v[66:69], v[2:5], v[34:37], 0
	v_mfma_f32_16x16x32_bf16 v[70:73], v[10:13], v[34:37], 0
	v_mfma_f32_16x16x32_bf16 v[74:77], v[2:5], v[42:45], 0
	v_mfma_f32_16x16x32_bf16 v[78:81], v[10:13], v[42:45], 0
	v_mfma_f32_16x16x32_bf16 v[82:85], v[2:5], v[50:53], 0
	v_mfma_f32_16x16x32_bf16 v[86:89], v[10:13], v[50:53], 0
	v_mfma_f32_16x16x32_bf16 v[94:97], v[6:9], v[62:65], v[90:93]
	v_mfma_f32_16x16x32_bf16 v[90:93], v[10:13], v[58:61], 0
	v_mfma_f32_16x16x32_bf16 v[66:69], v[6:9], v[38:41], v[66:69]
	v_mfma_f32_16x16x32_bf16 v[70:73], v[14:17], v[38:41], v[70:73]
	v_mfma_f32_16x16x32_bf16 v[74:77], v[6:9], v[46:49], v[74:77]
	v_mfma_f32_16x16x32_bf16 v[78:81], v[14:17], v[46:49], v[78:81]
	v_mfma_f32_16x16x32_bf16 v[82:85], v[6:9], v[54:57], v[82:85]
	v_mfma_f32_16x16x32_bf16 v[86:89], v[14:17], v[54:57], v[86:89]
	v_mfma_f32_16x16x32_bf16 v[102:105], v[14:17], v[62:65], v[90:93]
	s_setprio 0
	s_setprio 1
	v_mfma_f32_16x16x32_bf16 v[90:93], v[18:21], v[34:37], 0
	v_mfma_f32_16x16x32_bf16 v[34:37], v[26:29], v[34:37], 0
	v_mfma_f32_16x16x32_bf16 v[110:113], v[22:25], v[38:41], v[90:93]
	v_mfma_f32_16x16x32_bf16 v[34:37], v[30:33], v[38:41], v[34:37]
	v_mfma_f32_16x16x32_bf16 v[38:41], v[18:21], v[42:45], 0
	v_mfma_f32_16x16x32_bf16 v[42:45], v[26:29], v[42:45], 0
	v_mfma_f32_16x16x32_bf16 v[38:41], v[22:25], v[46:49], v[38:41]
	v_mfma_f32_16x16x32_bf16 v[42:45], v[30:33], v[46:49], v[42:45]
	v_mfma_f32_16x16x32_bf16 v[46:49], v[18:21], v[50:53], 0
	v_mfma_f32_16x16x32_bf16 v[50:53], v[26:29], v[50:53], 0
	v_mfma_f32_16x16x32_bf16 v[46:49], v[22:25], v[54:57], v[46:49]
	v_mfma_f32_16x16x32_bf16 v[54:57], v[30:33], v[54:57], v[50:53]
	v_mfma_f32_16x16x32_bf16 v[50:53], v[18:21], v[58:61], 0
	v_mfma_f32_16x16x32_bf16 v[146:149], v[22:25], v[62:65], v[50:53]
	v_mfma_f32_16x16x32_bf16 v[50:53], v[26:29], v[58:61], 0
	v_mfma_f32_16x16x32_bf16 v[154:157], v[30:33], v[62:65], v[50:53]
	s_barrier
	s_setprio 0
	v_lshl_add_u64 v[250:251], s[54:55], 0, v[134:135]
	s_mov_b32 m0, s72
	v_lshl_add_u64 v[122:123], v[250:251], 0, s[18:19]
	v_lshl_add_u64 v[252:253], s[54:55], 0, v[130:131]
	s_add_u32 s14, s54, 0x40100
	ds_read_b128 v[50:53], v151 offset:16384
	ds_read_b128 v[58:61], v151 offset:17408
	ds_read_b128 v[62:65], v151 offset:18432
	ds_read_b128 v[90:93], v151 offset:19456
	ds_read_b128 v[98:101], v151 offset:20480
	ds_read_b128 v[106:109], v151 offset:21504
	ds_read_b128 v[114:117], v151 offset:22528
	ds_read_b128 v[118:121], v151 offset:23552
	global_load_lds_dwordx4 v[122:123], off
	v_lshl_add_u64 v[122:123], v[252:253], 0, s[18:19]
	s_mov_b32 m0, s73
	s_addc_u32 s15, s55, 0
	global_load_lds_dwordx4 v[122:123], off
	v_lshl_add_u64 v[122:123], s[14:15], 0, v[134:135]
	s_mov_b32 m0, s74
	v_lshl_add_u64 v[142:143], s[62:63], 0, v[136:137]
	global_load_lds_dwordx4 v[122:123], off
	v_lshl_add_u64 v[122:123], s[14:15], 0, v[130:131]
	s_mov_b32 m0, s75
	v_lshl_add_u64 v[144:145], s[62:63], 0, v[132:133]
	global_load_lds_dwordx4 v[122:123], off
	v_lshl_add_u64 v[122:123], v[142:143], 0, s[18:19]
	s_mov_b32 m0, s33
	s_nop 0
	global_load_lds_dwordx4 v[122:123], off
	v_lshl_add_u64 v[122:123], v[144:145], 0, s[18:19]
	s_mov_b32 m0, s41
	s_nop 0
	global_load_lds_dwordx4 v[122:123], off
	s_waitcnt vmcnt(8)
	s_waitcnt lgkmcnt(0)
	s_setprio 1
	s_barrier
	v_mfma_f32_16x16x32_bf16 v[122:125], v[2:5], v[50:53], 0
	v_mfma_f32_16x16x32_bf16 v[158:161], v[6:9], v[58:61], v[122:125]
	v_mfma_f32_16x16x32_bf16 v[122:125], v[10:13], v[50:53], 0
	v_mfma_f32_16x16x32_bf16 v[162:165], v[14:17], v[58:61], v[122:125]
	v_mfma_f32_16x16x32_bf16 v[122:125], v[2:5], v[62:65], 0
	v_mfma_f32_16x16x32_bf16 v[166:169], v[6:9], v[90:93], v[122:125]
	v_mfma_f32_16x16x32_bf16 v[122:125], v[10:13], v[62:65], 0
	v_mfma_f32_16x16x32_bf16 v[170:173], v[14:17], v[90:93], v[122:125]
	v_mfma_f32_16x16x32_bf16 v[122:125], v[2:5], v[98:101], 0
	v_mfma_f32_16x16x32_bf16 v[2:5], v[2:5], v[114:117], 0
	v_mfma_f32_16x16x32_bf16 v[174:177], v[6:9], v[106:109], v[122:125]
	v_mfma_f32_16x16x32_bf16 v[2:5], v[6:9], v[118:121], v[2:5]
	v_mfma_f32_16x16x32_bf16 v[6:9], v[10:13], v[114:117], 0
	v_mfma_f32_16x16x32_bf16 v[122:125], v[10:13], v[98:101], 0
	v_mfma_f32_16x16x32_bf16 v[6:9], v[14:17], v[118:121], v[6:9]
	v_mfma_f32_16x16x32_bf16 v[178:181], v[14:17], v[106:109], v[122:125]
	s_setprio 0
	s_setprio 1
	v_mfma_f32_16x16x32_bf16 v[10:13], v[18:21], v[50:53], 0
	v_mfma_f32_16x16x32_bf16 v[14:17], v[22:25], v[58:61], v[10:13]
	v_mfma_f32_16x16x32_bf16 v[10:13], v[26:29], v[50:53], 0
	v_mfma_f32_16x16x32_bf16 v[182:185], v[30:33], v[58:61], v[10:13]
	v_mfma_f32_16x16x32_bf16 v[10:13], v[18:21], v[62:65], 0
	v_mfma_f32_16x16x32_bf16 v[186:189], v[22:25], v[90:93], v[10:13]
	v_mfma_f32_16x16x32_bf16 v[10:13], v[26:29], v[62:65], 0
	v_mfma_f32_16x16x32_bf16 v[190:193], v[30:33], v[90:93], v[10:13]
	v_mfma_f32_16x16x32_bf16 v[10:13], v[18:21], v[98:101], 0
	v_mfma_f32_16x16x32_bf16 v[194:197], v[22:25], v[106:109], v[10:13]
	v_mfma_f32_16x16x32_bf16 v[10:13], v[26:29], v[98:101], 0
	v_mfma_f32_16x16x32_bf16 v[198:201], v[30:33], v[106:109], v[10:13]
	v_mfma_f32_16x16x32_bf16 v[10:13], v[18:21], v[114:117], 0
	v_mfma_f32_16x16x32_bf16 v[202:205], v[22:25], v[118:121], v[10:13]
	v_mfma_f32_16x16x32_bf16 v[10:13], v[26:29], v[114:117], 0
	v_mfma_f32_16x16x32_bf16 v[206:209], v[30:33], v[118:121], v[10:13]
	s_barrier
	s_setprio 0
	s_nop 4
	ds_read_b128 v[10:13], v152
	ds_read_b128 v[22:25], v152 offset:1024
	ds_read_b128 v[30:33], v152 offset:2048
	ds_read_b128 v[210:213], v152 offset:3072
	ds_read_b128 v[214:217], v153
	ds_read_b128 v[218:221], v153 offset:1024
	ds_read_b128 v[222:225], v153 offset:2048
	ds_read_b128 v[226:229], v153 offset:3072
	s_add_u32 s14, s62, 0x40100
	s_addc_u32 s15, s63, 0
	s_mov_b32 m0, s58
	v_lshl_add_u64 v[50:51], s[14:15], 0, v[136:137]
	ds_read_b128 v[18:21], v151 offset:32768
	ds_read_b128 v[26:29], v151 offset:33792
	ds_read_b128 v[62:65], v151 offset:34816
	ds_read_b128 v[230:233], v151 offset:35840
	ds_read_b128 v[234:237], v151 offset:36864
	ds_read_b128 v[238:241], v151 offset:37888
	ds_read_b128 v[242:245], v151 offset:38912
	ds_read_b128 v[246:249], v151 offset:39936
	global_load_lds_dwordx4 v[50:51], off
	v_lshl_add_u64 v[50:51], s[14:15], 0, v[132:133]
	s_mov_b32 m0, s59
	s_nop 0
	global_load_lds_dwordx4 v[50:51], off
	s_waitcnt vmcnt(8)
	s_waitcnt lgkmcnt(0)
	s_setprio 1
	s_barrier
	v_mfma_f32_16x16x32_bf16 v[50:53], v[10:13], v[18:21], v[66:69]
	v_mfma_f32_16x16x32_bf16 v[122:125], v[22:25], v[26:29], v[50:53]
	v_mfma_f32_16x16x32_bf16 v[50:53], v[30:33], v[18:21], v[70:73]
	v_mfma_f32_16x16x32_bf16 v[114:117], v[210:213], v[26:29], v[50:53]
	v_mfma_f32_16x16x32_bf16 v[50:53], v[10:13], v[62:65], v[74:77]
	v_mfma_f32_16x16x32_bf16 v[106:109], v[22:25], v[230:233], v[50:53]
	v_mfma_f32_16x16x32_bf16 v[50:53], v[30:33], v[62:65], v[78:81]
	v_mfma_f32_16x16x32_bf16 v[98:101], v[210:213], v[230:233], v[50:53]
	v_mfma_f32_16x16x32_bf16 v[50:53], v[10:13], v[234:237], v[82:85]
	v_mfma_f32_16x16x32_bf16 v[90:93], v[22:25], v[238:241], v[50:53]
	v_mfma_f32_16x16x32_bf16 v[50:53], v[30:33], v[234:237], v[86:89]
	v_mfma_f32_16x16x32_bf16 v[82:85], v[210:213], v[238:241], v[50:53]
	v_mfma_f32_16x16x32_bf16 v[50:53], v[10:13], v[242:245], v[94:97]
	v_mfma_f32_16x16x32_bf16 v[58:61], v[22:25], v[246:249], v[50:53]
	v_mfma_f32_16x16x32_bf16 v[50:53], v[30:33], v[242:245], v[102:105]
	v_mfma_f32_16x16x32_bf16 v[50:53], v[210:213], v[246:249], v[50:53]
	s_setprio 0
	s_setprio 1
	v_mfma_f32_16x16x32_bf16 v[66:69], v[214:217], v[18:21], v[110:113]
	v_mfma_f32_16x16x32_bf16 v[18:21], v[222:225], v[18:21], v[34:37]
	v_mfma_f32_16x16x32_bf16 v[118:121], v[226:229], v[26:29], v[18:21]
	v_mfma_f32_16x16x32_bf16 v[18:21], v[214:217], v[62:65], v[38:41]
	v_mfma_f32_16x16x32_bf16 v[110:113], v[218:221], v[230:233], v[18:21]
	v_mfma_f32_16x16x32_bf16 v[18:21], v[222:225], v[62:65], v[42:45]
	v_mfma_f32_16x16x32_bf16 v[102:105], v[226:229], v[230:233], v[18:21]
	v_mfma_f32_16x16x32_bf16 v[18:21], v[214:217], v[234:237], v[46:49]
	v_mfma_f32_16x16x32_bf16 v[94:97], v[218:221], v[238:241], v[18:21]
	v_mfma_f32_16x16x32_bf16 v[18:21], v[222:225], v[234:237], v[54:57]
	v_mfma_f32_16x16x32_bf16 v[86:89], v[226:229], v[238:241], v[18:21]
	v_mfma_f32_16x16x32_bf16 v[18:21], v[214:217], v[242:245], v[146:149]
	v_mfma_f32_16x16x32_bf16 v[62:65], v[218:221], v[246:249], v[18:21]
	v_mfma_f32_16x16x32_bf16 v[18:21], v[222:225], v[242:245], v[154:157]
	v_mfma_f32_16x16x32_bf16 v[126:129], v[218:221], v[26:29], v[66:69]
	v_mfma_f32_16x16x32_bf16 v[54:57], v[226:229], v[246:249], v[18:21]
	s_barrier
	s_setprio 0
	s_mov_b32 m0, s76
	s_nop 2
	v_lshl_add_u64 v[18:19], v[250:251], 0, s[20:21]
	s_add_u32 s14, s54, 0x40180
	ds_read_b128 v[38:41], v151 offset:49152
	ds_read_b128 v[46:49], v151 offset:50176
	ds_read_b128 v[146:149], v151 offset:51200
	ds_read_b128 v[154:157], v151 offset:52224
	ds_read_b128 v[230:233], v151 offset:53248
	ds_read_b128 v[234:237], v151 offset:54272
	ds_read_b128 v[238:241], v151 offset:55296
	ds_read_b128 v[242:245], v151 offset:56320
	global_load_lds_dwordx4 v[18:19], off
	v_lshl_add_u64 v[18:19], v[252:253], 0, s[20:21]
	s_mov_b32 m0, s77
	s_addc_u32 s15, s55, 0
	global_load_lds_dwordx4 v[18:19], off
	v_lshl_add_u64 v[18:19], s[14:15], 0, v[134:135]
	s_mov_b32 m0, s78
	s_nop 0
	global_load_lds_dwordx4 v[18:19], off
	v_lshl_add_u64 v[18:19], s[14:15], 0, v[130:131]
	s_mov_b32 m0, s79
	s_nop 0
	global_load_lds_dwordx4 v[18:19], off
	v_lshl_add_u64 v[18:19], v[142:143], 0, s[20:21]
	s_mov_b32 m0, s66
	s_nop 0
	global_load_lds_dwordx4 v[18:19], off
	v_lshl_add_u64 v[18:19], v[144:145], 0, s[20:21]
	s_mov_b32 m0, s67
	s_nop 0
	global_load_lds_dwordx4 v[18:19], off
	s_waitcnt vmcnt(8)
	s_waitcnt lgkmcnt(0)
	s_setprio 1
	s_barrier
	v_mfma_f32_16x16x32_bf16 v[18:21], v[10:13], v[38:41], v[158:161]
	v_mfma_f32_16x16x32_bf16 v[74:77], v[22:25], v[46:49], v[18:21]
	v_mfma_f32_16x16x32_bf16 v[18:21], v[30:33], v[38:41], v[162:165]
	v_mfma_f32_16x16x32_bf16 v[66:69], v[210:213], v[46:49], v[18:21]
	v_mfma_f32_16x16x32_bf16 v[18:21], v[10:13], v[146:149], v[166:169]
	v_mfma_f32_16x16x32_bf16 v[42:45], v[22:25], v[154:157], v[18:21]
	v_mfma_f32_16x16x32_bf16 v[18:21], v[30:33], v[146:149], v[170:173]
	v_mfma_f32_16x16x32_bf16 v[34:37], v[210:213], v[154:157], v[18:21]
	v_mfma_f32_16x16x32_bf16 v[18:21], v[10:13], v[230:233], v[174:177]
	v_mfma_f32_16x16x32_bf16 v[2:5], v[10:13], v[238:241], v[2:5]
	v_mfma_f32_16x16x32_bf16 v[26:29], v[22:25], v[234:237], v[18:21]
	v_mfma_f32_16x16x32_bf16 v[18:21], v[30:33], v[230:233], v[178:181]
	v_mfma_f32_16x16x32_bf16 v[10:13], v[22:25], v[242:245], v[2:5]
	v_mfma_f32_16x16x32_bf16 v[2:5], v[30:33], v[238:241], v[6:9]
	v_mfma_f32_16x16x32_bf16 v[18:21], v[210:213], v[234:237], v[18:21]
	v_mfma_f32_16x16x32_bf16 v[2:5], v[210:213], v[242:245], v[2:5]
	s_setprio 0
	s_setprio 1
	v_mfma_f32_16x16x32_bf16 v[6:9], v[214:217], v[38:41], v[14:17]
	v_mfma_f32_16x16x32_bf16 v[78:81], v[218:221], v[46:49], v[6:9]
	v_mfma_f32_16x16x32_bf16 v[6:9], v[222:225], v[38:41], v[182:185]
	v_mfma_f32_16x16x32_bf16 v[70:73], v[226:229], v[46:49], v[6:9]
	v_mfma_f32_16x16x32_bf16 v[6:9], v[214:217], v[146:149], v[186:189]
	v_mfma_f32_16x16x32_bf16 v[46:49], v[218:221], v[154:157], v[6:9]
	v_mfma_f32_16x16x32_bf16 v[6:9], v[222:225], v[146:149], v[190:193]
	v_mfma_f32_16x16x32_bf16 v[38:41], v[226:229], v[154:157], v[6:9]
	v_mfma_f32_16x16x32_bf16 v[6:9], v[214:217], v[230:233], v[194:197]
	v_mfma_f32_16x16x32_bf16 v[30:33], v[218:221], v[234:237], v[6:9]
	v_mfma_f32_16x16x32_bf16 v[6:9], v[222:225], v[230:233], v[198:201]
	v_mfma_f32_16x16x32_bf16 v[22:25], v[226:229], v[234:237], v[6:9]
	v_mfma_f32_16x16x32_bf16 v[6:9], v[214:217], v[238:241], v[202:205]
	v_mfma_f32_16x16x32_bf16 v[14:17], v[218:221], v[242:245], v[6:9]
	v_mfma_f32_16x16x32_bf16 v[6:9], v[222:225], v[238:241], v[206:209]
	v_mfma_f32_16x16x32_bf16 v[6:9], v[226:229], v[242:245], v[6:9]
	s_barrier
	s_setprio 0
	s_add_u32 s62, s62, 0x40180
	s_addc_u32 s63, s63, 0
	s_add_u32 s14, s54, 0x200
	s_addc_u32 s15, s55, 0
	s_mov_b32 s26, 0
.LBB0_644:
	ds_read_b128 v[146:149], v1
	ds_read_b128 v[154:157], v1 offset:1024
	ds_read_b128 v[158:161], v1 offset:2048
	ds_read_b128 v[162:165], v1 offset:3072
	ds_read_b128 v[166:169], v150
	ds_read_b128 v[170:173], v150 offset:1024
	ds_read_b128 v[174:177], v150 offset:2048
	ds_read_b128 v[178:181], v150 offset:3072
	s_add_u32 s27, s62, 0xfffc0080
	s_addc_u32 s46, s63, -1
	s_cmp_eq_u32 s26, 12
	s_cselect_b32 s65, s23, s46
	s_cselect_b32 s64, s83, s27
	s_cselect_b32 s55, s0, s15
	s_cselect_b32 s54, s86, s14
	s_mov_b32 m0, s69
	ds_read_b128 v[182:185], v151
	ds_read_b128 v[186:189], v151 offset:1024
	ds_read_b128 v[190:193], v151 offset:2048
	ds_read_b128 v[194:197], v151 offset:3072
	ds_read_b128 v[198:201], v151 offset:4096
	ds_read_b128 v[202:205], v151 offset:5120
	ds_read_b128 v[206:209], v151 offset:6144
	ds_read_b128 v[210:213], v151 offset:7168
	global_load_lds_dwordx4 v138, s[62:63]
	s_mov_b32 m0, s70
	s_nop 0
	global_load_lds_dwordx4 v140, s[62:63]
	s_waitcnt vmcnt(8)
	s_waitcnt lgkmcnt(0)
	s_setprio 1
	s_barrier
	v_mfma_f32_16x16x32_bf16 v[122:125], v[146:149], v[182:185], v[122:125]
	v_mfma_f32_16x16x32_bf16 v[114:117], v[158:161], v[182:185], v[114:117]
	v_mfma_f32_16x16x32_bf16 v[106:109], v[146:149], v[190:193], v[106:109]
	v_mfma_f32_16x16x32_bf16 v[98:101], v[158:161], v[190:193], v[98:101]
	v_mfma_f32_16x16x32_bf16 v[90:93], v[146:149], v[198:201], v[90:93]
	v_mfma_f32_16x16x32_bf16 v[82:85], v[158:161], v[198:201], v[82:85]
	v_mfma_f32_16x16x32_bf16 v[58:61], v[146:149], v[206:209], v[58:61]
	v_mfma_f32_16x16x32_bf16 v[50:53], v[158:161], v[206:209], v[50:53]
	v_mfma_f32_16x16x32_bf16 v[122:125], v[154:157], v[186:189], v[122:125]
	v_mfma_f32_16x16x32_bf16 v[114:117], v[162:165], v[186:189], v[114:117]
	v_mfma_f32_16x16x32_bf16 v[106:109], v[154:157], v[194:197], v[106:109]
	v_mfma_f32_16x16x32_bf16 v[98:101], v[162:165], v[194:197], v[98:101]
	v_mfma_f32_16x16x32_bf16 v[90:93], v[154:157], v[202:205], v[90:93]
	v_mfma_f32_16x16x32_bf16 v[82:85], v[162:165], v[202:205], v[82:85]
	v_mfma_f32_16x16x32_bf16 v[58:61], v[154:157], v[210:213], v[58:61]
	v_mfma_f32_16x16x32_bf16 v[50:53], v[162:165], v[210:213], v[50:53]
	s_setprio 0
	s_setprio 1
	v_mfma_f32_16x16x32_bf16 v[126:129], v[166:169], v[182:185], v[126:129]
	v_mfma_f32_16x16x32_bf16 v[118:121], v[174:177], v[182:185], v[118:121]
	v_mfma_f32_16x16x32_bf16 v[110:113], v[166:169], v[190:193], v[110:113]
	v_mfma_f32_16x16x32_bf16 v[102:105], v[174:177], v[190:193], v[102:105]
	v_mfma_f32_16x16x32_bf16 v[94:97], v[166:169], v[198:201], v[94:97]
	v_mfma_f32_16x16x32_bf16 v[86:89], v[174:177], v[198:201], v[86:89]
	v_mfma_f32_16x16x32_bf16 v[62:65], v[166:169], v[206:209], v[62:65]
	v_mfma_f32_16x16x32_bf16 v[54:57], v[174:177], v[206:209], v[54:57]
	v_mfma_f32_16x16x32_bf16 v[126:129], v[170:173], v[186:189], v[126:129]
	v_mfma_f32_16x16x32_bf16 v[118:121], v[178:181], v[186:189], v[118:121]
	v_mfma_f32_16x16x32_bf16 v[110:113], v[170:173], v[194:197], v[110:113]
	v_mfma_f32_16x16x32_bf16 v[102:105], v[178:181], v[194:197], v[102:105]
	v_mfma_f32_16x16x32_bf16 v[94:97], v[170:173], v[202:205], v[94:97]
	v_mfma_f32_16x16x32_bf16 v[86:89], v[178:181], v[202:205], v[86:89]
	v_mfma_f32_16x16x32_bf16 v[62:65], v[170:173], v[210:213], v[62:65]
	v_mfma_f32_16x16x32_bf16 v[54:57], v[178:181], v[210:213], v[54:57]
	s_barrier
	s_setprio 0
	s_mov_b32 m0, s72
	s_mov_b64 s[98:99], s[54:55]
	s_add_u32 s46, s54, 0x40000
	ds_read_b128 v[182:185], v151 offset:16384
	ds_read_b128 v[186:189], v151 offset:17408
	ds_read_b128 v[190:193], v151 offset:18432
	ds_read_b128 v[194:197], v151 offset:19456
	ds_read_b128 v[198:201], v151 offset:20480
	ds_read_b128 v[202:205], v151 offset:21504
	ds_read_b128 v[206:209], v151 offset:22528
	ds_read_b128 v[210:213], v151 offset:23552
	global_load_lds_dwordx4 v134, s[54:55]
	s_mov_b32 m0, s73
	s_addc_u32 s47, s55, 0
	global_load_lds_dwordx4 v130, s[54:55]
	s_mov_b32 m0, s74
	s_mov_b64 s[100:101], s[64:65]
	global_load_lds_dwordx4 v134, s[46:47]
	s_mov_b32 m0, s75
	s_nop 0
	global_load_lds_dwordx4 v130, s[46:47]
	s_mov_b32 m0, s33
	s_nop 0
	global_load_lds_dwordx4 v136, s[64:65]
	s_mov_b32 m0, s41
	s_nop 0
	global_load_lds_dwordx4 v132, s[64:65]
	s_waitcnt vmcnt(8)
	s_waitcnt lgkmcnt(0)
	s_setprio 1
	s_barrier
	v_mfma_f32_16x16x32_bf16 v[74:77], v[146:149], v[182:185], v[74:77]
	v_mfma_f32_16x16x32_bf16 v[66:69], v[158:161], v[182:185], v[66:69]
	v_mfma_f32_16x16x32_bf16 v[42:45], v[146:149], v[190:193], v[42:45]
	v_mfma_f32_16x16x32_bf16 v[34:37], v[158:161], v[190:193], v[34:37]
	v_mfma_f32_16x16x32_bf16 v[26:29], v[146:149], v[198:201], v[26:29]
	v_mfma_f32_16x16x32_bf16 v[18:21], v[158:161], v[198:201], v[18:21]
	v_mfma_f32_16x16x32_bf16 v[10:13], v[146:149], v[206:209], v[10:13]
	v_mfma_f32_16x16x32_bf16 v[2:5], v[158:161], v[206:209], v[2:5]
	v_mfma_f32_16x16x32_bf16 v[74:77], v[154:157], v[186:189], v[74:77]
	v_mfma_f32_16x16x32_bf16 v[66:69], v[162:165], v[186:189], v[66:69]
	v_mfma_f32_16x16x32_bf16 v[42:45], v[154:157], v[194:197], v[42:45]
	v_mfma_f32_16x16x32_bf16 v[34:37], v[162:165], v[194:197], v[34:37]
	v_mfma_f32_16x16x32_bf16 v[26:29], v[154:157], v[202:205], v[26:29]
	v_mfma_f32_16x16x32_bf16 v[18:21], v[162:165], v[202:205], v[18:21]
	v_mfma_f32_16x16x32_bf16 v[10:13], v[154:157], v[210:213], v[10:13]
	v_mfma_f32_16x16x32_bf16 v[2:5], v[162:165], v[210:213], v[2:5]
	s_setprio 0
	s_setprio 1
	v_mfma_f32_16x16x32_bf16 v[78:81], v[166:169], v[182:185], v[78:81]
	v_mfma_f32_16x16x32_bf16 v[70:73], v[174:177], v[182:185], v[70:73]
	v_mfma_f32_16x16x32_bf16 v[46:49], v[166:169], v[190:193], v[46:49]
	v_mfma_f32_16x16x32_bf16 v[38:41], v[174:177], v[190:193], v[38:41]
	v_mfma_f32_16x16x32_bf16 v[30:33], v[166:169], v[198:201], v[30:33]
	v_mfma_f32_16x16x32_bf16 v[22:25], v[174:177], v[198:201], v[22:25]
	v_mfma_f32_16x16x32_bf16 v[14:17], v[166:169], v[206:209], v[14:17]
	v_mfma_f32_16x16x32_bf16 v[6:9], v[174:177], v[206:209], v[6:9]
	v_mfma_f32_16x16x32_bf16 v[78:81], v[170:173], v[186:189], v[78:81]
	v_mfma_f32_16x16x32_bf16 v[70:73], v[178:181], v[186:189], v[70:73]
	v_mfma_f32_16x16x32_bf16 v[46:49], v[170:173], v[194:197], v[46:49]
	v_mfma_f32_16x16x32_bf16 v[38:41], v[178:181], v[194:197], v[38:41]
	v_mfma_f32_16x16x32_bf16 v[30:33], v[170:173], v[202:205], v[30:33]
	v_mfma_f32_16x16x32_bf16 v[22:25], v[178:181], v[202:205], v[22:25]
	v_mfma_f32_16x16x32_bf16 v[14:17], v[170:173], v[210:213], v[14:17]
	v_mfma_f32_16x16x32_bf16 v[6:9], v[178:181], v[210:213], v[6:9]
	s_barrier
;     ...
;         for (int t = 2; t < nt; t += 2) PG8_KITER(t);
	s_setprio 0
	ds_read_b128 v[146:149], v152
	ds_read_b128 v[154:157], v152 offset:1024
	ds_read_b128 v[158:161], v152 offset:2048
	ds_read_b128 v[162:165], v152 offset:3072
	ds_read_b128 v[166:169], v153
	ds_read_b128 v[170:173], v153 offset:1024
	ds_read_b128 v[174:177], v153 offset:2048
	ds_read_b128 v[178:181], v153 offset:3072
	s_add_u32 s46, s64, 0x40000
	s_addc_u32 s47, s65, 0
	s_mov_b32 m0, s58
	ds_read_b128 v[182:185], v151 offset:32768
	ds_read_b128 v[186:189], v151 offset:33792
	ds_read_b128 v[190:193], v151 offset:34816
	ds_read_b128 v[194:197], v151 offset:35840
	ds_read_b128 v[198:201], v151 offset:36864
	ds_read_b128 v[202:205], v151 offset:37888
	ds_read_b128 v[206:209], v151 offset:38912
	ds_read_b128 v[210:213], v151 offset:39936
	global_load_lds_dwordx4 v136, s[46:47]
	s_mov_b32 m0, s59
	s_nop 0
	global_load_lds_dwordx4 v132, s[46:47]
	s_waitcnt vmcnt(8)
	s_waitcnt lgkmcnt(0)
	s_setprio 1
	s_barrier
	v_mfma_f32_16x16x32_bf16 v[122:125], v[146:149], v[182:185], v[122:125]
	v_mfma_f32_16x16x32_bf16 v[114:117], v[158:161], v[182:185], v[114:117]
	v_mfma_f32_16x16x32_bf16 v[106:109], v[146:149], v[190:193], v[106:109]
	v_mfma_f32_16x16x32_bf16 v[98:101], v[158:161], v[190:193], v[98:101]
	v_mfma_f32_16x16x32_bf16 v[90:93], v[146:149], v[198:201], v[90:93]
	v_mfma_f32_16x16x32_bf16 v[82:85], v[158:161], v[198:201], v[82:85]
	v_mfma_f32_16x16x32_bf16 v[58:61], v[146:149], v[206:209], v[58:61]
	v_mfma_f32_16x16x32_bf16 v[50:53], v[158:161], v[206:209], v[50:53]
	v_mfma_f32_16x16x32_bf16 v[122:125], v[154:157], v[186:189], v[122:125]
	v_mfma_f32_16x16x32_bf16 v[114:117], v[162:165], v[186:189], v[114:117]
	v_mfma_f32_16x16x32_bf16 v[106:109], v[154:157], v[194:197], v[106:109]
	v_mfma_f32_16x16x32_bf16 v[98:101], v[162:165], v[194:197], v[98:101]
	v_mfma_f32_16x16x32_bf16 v[90:93], v[154:157], v[202:205], v[90:93]
	v_mfma_f32_16x16x32_bf16 v[82:85], v[162:165], v[202:205], v[82:85]
	v_mfma_f32_16x16x32_bf16 v[58:61], v[154:157], v[210:213], v[58:61]
	v_mfma_f32_16x16x32_bf16 v[50:53], v[162:165], v[210:213], v[50:53]
	s_setprio 0
	s_setprio 1
	v_mfma_f32_16x16x32_bf16 v[126:129], v[166:169], v[182:185], v[126:129]
	v_mfma_f32_16x16x32_bf16 v[118:121], v[174:177], v[182:185], v[118:121]
	v_mfma_f32_16x16x32_bf16 v[110:113], v[166:169], v[190:193], v[110:113]
	v_mfma_f32_16x16x32_bf16 v[102:105], v[174:177], v[190:193], v[102:105]
	v_mfma_f32_16x16x32_bf16 v[94:97], v[166:169], v[198:201], v[94:97]
	v_mfma_f32_16x16x32_bf16 v[86:89], v[174:177], v[198:201], v[86:89]
	v_mfma_f32_16x16x32_bf16 v[62:65], v[166:169], v[206:209], v[62:65]
	v_mfma_f32_16x16x32_bf16 v[54:57], v[174:177], v[206:209], v[54:57]
	v_mfma_f32_16x16x32_bf16 v[126:129], v[170:173], v[186:189], v[126:129]
	v_mfma_f32_16x16x32_bf16 v[118:121], v[178:181], v[186:189], v[118:121]
	v_mfma_f32_16x16x32_bf16 v[110:113], v[170:173], v[194:197], v[110:113]
	v_mfma_f32_16x16x32_bf16 v[102:105], v[178:181], v[194:197], v[102:105]
	v_mfma_f32_16x16x32_bf16 v[94:97], v[170:173], v[202:205], v[94:97]
	v_mfma_f32_16x16x32_bf16 v[86:89], v[178:181], v[202:205], v[86:89]
	v_mfma_f32_16x16x32_bf16 v[62:65], v[170:173], v[210:213], v[62:65]
	v_mfma_f32_16x16x32_bf16 v[54:57], v[178:181], v[210:213], v[54:57]
	s_barrier
	s_setprio 0
	s_mov_b32 m0, s76
	s_add_u32 s98, s98, 0x80
	s_addc_u32 s99, s99, 0
	s_add_u32 s100, s100, 0x80
	s_addc_u32 s101, s101, 0
	s_add_u32 s46, s54, 0x40080
	ds_read_b128 v[182:185], v151 offset:49152
	ds_read_b128 v[186:189], v151 offset:50176
	ds_read_b128 v[190:193], v151 offset:51200
	ds_read_b128 v[194:197], v151 offset:52224
	ds_read_b128 v[198:201], v151 offset:53248
	ds_read_b128 v[202:205], v151 offset:54272
	ds_read_b128 v[206:209], v151 offset:55296
	ds_read_b128 v[210:213], v151 offset:56320
	global_load_lds_dwordx4 v134, s[98:99]
	s_mov_b32 m0, s77
	s_addc_u32 s47, s55, 0
	global_load_lds_dwordx4 v130, s[98:99]
	s_mov_b32 m0, s78
	s_nop 0
	global_load_lds_dwordx4 v134, s[46:47]
	s_mov_b32 m0, s79
	s_nop 0
	global_load_lds_dwordx4 v130, s[46:47]
	s_mov_b32 m0, s66
	s_nop 0
	global_load_lds_dwordx4 v136, s[100:101]
	s_mov_b32 m0, s67
	s_nop 0
	global_load_lds_dwordx4 v132, s[100:101]
	s_waitcnt vmcnt(8)
	s_waitcnt lgkmcnt(0)
	s_setprio 1
	s_barrier
	v_mfma_f32_16x16x32_bf16 v[74:77], v[146:149], v[182:185], v[74:77]
	v_mfma_f32_16x16x32_bf16 v[66:69], v[158:161], v[182:185], v[66:69]
	v_mfma_f32_16x16x32_bf16 v[42:45], v[146:149], v[190:193], v[42:45]
	v_mfma_f32_16x16x32_bf16 v[34:37], v[158:161], v[190:193], v[34:37]
	v_mfma_f32_16x16x32_bf16 v[26:29], v[146:149], v[198:201], v[26:29]
	v_mfma_f32_16x16x32_bf16 v[18:21], v[158:161], v[198:201], v[18:21]
	v_mfma_f32_16x16x32_bf16 v[10:13], v[146:149], v[206:209], v[10:13]
	v_mfma_f32_16x16x32_bf16 v[2:5], v[158:161], v[206:209], v[2:5]
	v_mfma_f32_16x16x32_bf16 v[74:77], v[154:157], v[186:189], v[74:77]
	v_mfma_f32_16x16x32_bf16 v[66:69], v[162:165], v[186:189], v[66:69]
	v_mfma_f32_16x16x32_bf16 v[42:45], v[154:157], v[194:197], v[42:45]
	v_mfma_f32_16x16x32_bf16 v[34:37], v[162:165], v[194:197], v[34:37]
	v_mfma_f32_16x16x32_bf16 v[26:29], v[154:157], v[202:205], v[26:29]
	v_mfma_f32_16x16x32_bf16 v[18:21], v[162:165], v[202:205], v[18:21]
	v_mfma_f32_16x16x32_bf16 v[10:13], v[154:157], v[210:213], v[10:13]
	v_mfma_f32_16x16x32_bf16 v[2:5], v[162:165], v[210:213], v[2:5]
	s_setprio 0
	s_setprio 1
	v_mfma_f32_16x16x32_bf16 v[78:81], v[166:169], v[182:185], v[78:81]
	v_mfma_f32_16x16x32_bf16 v[70:73], v[174:177], v[182:185], v[70:73]
	v_mfma_f32_16x16x32_bf16 v[46:49], v[166:169], v[190:193], v[46:49]
	v_mfma_f32_16x16x32_bf16 v[38:41], v[174:177], v[190:193], v[38:41]
	v_mfma_f32_16x16x32_bf16 v[30:33], v[166:169], v[198:201], v[30:33]
	v_mfma_f32_16x16x32_bf16 v[22:25], v[174:177], v[198:201], v[22:25]
	v_mfma_f32_16x16x32_bf16 v[14:17], v[166:169], v[206:209], v[14:17]
	v_mfma_f32_16x16x32_bf16 v[6:9], v[174:177], v[206:209], v[6:9]
	v_mfma_f32_16x16x32_bf16 v[78:81], v[170:173], v[186:189], v[78:81]
	v_mfma_f32_16x16x32_bf16 v[70:73], v[178:181], v[186:189], v[70:73]
	v_mfma_f32_16x16x32_bf16 v[46:49], v[170:173], v[194:197], v[46:49]
	v_mfma_f32_16x16x32_bf16 v[38:41], v[178:181], v[194:197], v[38:41]
	v_mfma_f32_16x16x32_bf16 v[30:33], v[170:173], v[202:205], v[30:33]
	v_mfma_f32_16x16x32_bf16 v[22:25], v[178:181], v[202:205], v[22:25]
	v_mfma_f32_16x16x32_bf16 v[14:17], v[170:173], v[210:213], v[14:17]
	v_mfma_f32_16x16x32_bf16 v[6:9], v[178:181], v[210:213], v[6:9]
	s_barrier
	s_setprio 0
	s_add_i32 s26, s26, 2
	s_add_u32 s62, s62, 0x100
	s_addc_u32 s63, s63, 0
	s_add_u32 s14, s14, 0x100
	s_addc_u32 s15, s15, 0
	s_cmp_gt_u32 s26, 13
	s_cbranch_scc0 .LBB0_644
	s_and_b64 vcc, exec, s[16:17]
	s_cbranch_vccz .LBB0_647
	s_barrier

;     __host__ __device__ bool next(int i, Unit& u) const { if (!StaticOrder::next(i >> 1, u)) return false; u.seg = i & 1; return true; }
;     ...
;         const bool has_next = S.next(ui + 1, nxt);
;         const char* nA = has_next ? PG8_APTR(nxt) : cA; const char* nB = has_next ? PG8_BPTR(nxt) : cB;
;         const char* pfc = PG8_PFPTR(cA, cB); const char* pfn = PG8_PFPTR(nA, nB);
.LBB0_669:
	s_ashr_i32 s29, s28, 31
	ds_read_b128 v[2:5], v158
	ds_read_b128 v[6:9], v158 offset:1024
	ds_read_b128 v[10:13], v158 offset:2048
	ds_read_b128 v[14:17], v158 offset:3072
	ds_read_b128 v[18:21], v159
	ds_read_b128 v[22:25], v159 offset:1024
	ds_read_b128 v[26:29], v159 offset:2048
	ds_read_b128 v[30:33], v159 offset:3072
	s_lshl_b64 s[14:15], s[28:29], 18
	s_add_u32 s30, s10, s14
	s_addc_u32 s31, s11, s15
	s_and_b64 s[14:15], s[4:5], exec
	s_cselect_b32 s29, s31, s65
	s_cselect_b32 s79, s30, s64
	s_and_b32 s0, s77, 0x7fffffff
	s_lshl_b64 s[14:15], s[0:1], 18
	s_add_u32 s40, s12, s14
	s_addc_u32 s41, s13, s15
	s_and_b64 s[14:15], s[4:5], exec
	s_cselect_b32 s0, s41, s7
	s_cselect_b32 s80, s40, s6
	s_add_u32 s14, s64, 0x20080
	s_addc_u32 s15, s65, 0
	s_add_i32 s81, s58, 0xc000
	v_lshl_add_u64 v[66:67], s[14:15], 0, v[138:139]
	s_mov_b32 m0, s81
	s_add_i32 s82, s58, 0xe000
	ds_read_b128 v[34:37], v160
	ds_read_b128 v[38:41], v160 offset:1024
	ds_read_b128 v[42:45], v160 offset:2048
	ds_read_b128 v[46:49], v160 offset:3072
	ds_read_b128 v[50:53], v160 offset:4096
	ds_read_b128 v[54:57], v160 offset:5120
	ds_read_b128 v[58:61], v160 offset:6144
	ds_read_b128 v[62:65], v160 offset:7168
	global_load_lds_dwordx4 v[66:67], off
	v_lshl_add_u64 v[66:67], s[14:15], 0, v[142:143]
	s_mov_b32 m0, s82
	s_nop 0
	global_load_lds_dwordx4 v[66:67], off
	s_waitcnt vmcnt(8)
	s_waitcnt lgkmcnt(0)
	s_setprio 1
	s_barrier
	v_mfma_f32_16x16x32_bf16 v[90:93], v[2:5], v[58:61], 0
	v_mfma_f32_16x16x32_bf16 v[66:69], v[2:5], v[34:37], 0
	v_mfma_f32_16x16x32_bf16 v[70:73], v[10:13], v[34:37], 0
	v_mfma_f32_16x16x32_bf16 v[74:77], v[2:5], v[42:45], 0
	v_mfma_f32_16x16x32_bf16 v[78:81], v[10:13], v[42:45], 0
	v_mfma_f32_16x16x32_bf16 v[82:85], v[2:5], v[50:53], 0
	v_mfma_f32_16x16x32_bf16 v[86:89], v[10:13], v[50:53], 0
	v_mfma_f32_16x16x32_bf16 v[102:105], v[6:9], v[62:65], v[90:93]
	v_mfma_f32_16x16x32_bf16 v[90:93], v[10:13], v[58:61], 0
	v_mfma_f32_16x16x32_bf16 v[66:69], v[6:9], v[38:41], v[66:69]
	v_mfma_f32_16x16x32_bf16 v[70:73], v[14:17], v[38:41], v[70:73]
	v_mfma_f32_16x16x32_bf16 v[74:77], v[6:9], v[46:49], v[74:77]
	v_mfma_f32_16x16x32_bf16 v[78:81], v[14:17], v[46:49], v[78:81]
	v_mfma_f32_16x16x32_bf16 v[82:85], v[6:9], v[54:57], v[82:85]
	v_mfma_f32_16x16x32_bf16 v[86:89], v[14:17], v[54:57], v[86:89]
	v_mfma_f32_16x16x32_bf16 v[106:109], v[14:17], v[62:65], v[90:93]
	s_setprio 0
	s_setprio 1
	v_mfma_f32_16x16x32_bf16 v[90:93], v[18:21], v[34:37], 0
	v_mfma_f32_16x16x32_bf16 v[34:37], v[26:29], v[34:37], 0
	v_mfma_f32_16x16x32_bf16 v[122:125], v[22:25], v[38:41], v[90:93]
	v_mfma_f32_16x16x32_bf16 v[34:37], v[30:33], v[38:41], v[34:37]
	v_mfma_f32_16x16x32_bf16 v[38:41], v[18:21], v[42:45], 0
	v_mfma_f32_16x16x32_bf16 v[42:45], v[26:29], v[42:45], 0
	v_mfma_f32_16x16x32_bf16 v[38:41], v[22:25], v[46:49], v[38:41]
	v_mfma_f32_16x16x32_bf16 v[42:45], v[30:33], v[46:49], v[42:45]
	v_mfma_f32_16x16x32_bf16 v[46:49], v[18:21], v[50:53], 0
	v_mfma_f32_16x16x32_bf16 v[50:53], v[26:29], v[50:53], 0
	v_mfma_f32_16x16x32_bf16 v[46:49], v[22:25], v[54:57], v[46:49]
	v_mfma_f32_16x16x32_bf16 v[50:53], v[30:33], v[54:57], v[50:53]
	v_mfma_f32_16x16x32_bf16 v[54:57], v[18:21], v[58:61], 0
	v_mfma_f32_16x16x32_bf16 v[58:61], v[26:29], v[58:61], 0
	v_mfma_f32_16x16x32_bf16 v[54:57], v[22:25], v[62:65], v[54:57]
	v_mfma_f32_16x16x32_bf16 v[58:61], v[30:33], v[62:65], v[58:61]
	s_barrier
	s_setprio 0
	s_add_i32 s83, s73, s33
	v_lshl_add_u64 v[136:137], s[6:7], 0, v[140:141]
	s_add_i32 s84, s83, 0x2000
	v_lshl_add_u64 v[130:131], v[136:137], 0, s[20:21]
	s_mov_b32 m0, s83
	v_lshl_add_u64 v[250:251], s[6:7], 0, v[144:145]
	s_add_u32 s14, s6, 0x20100
	ds_read_b128 v[62:65], v160 offset:16384
	ds_read_b128 v[90:93], v160 offset:17408
	ds_read_b128 v[94:97], v160 offset:18432
	ds_read_b128 v[98:101], v160 offset:19456
	ds_read_b128 v[110:113], v160 offset:20480
	ds_read_b128 v[114:117], v160 offset:21504
	ds_read_b128 v[118:121], v160 offset:22528
	ds_read_b128 v[126:129], v160 offset:23552
	global_load_lds_dwordx4 v[130:131], off
	v_lshl_add_u64 v[130:131], v[250:251], 0, s[20:21]
	s_mov_b32 m0, s84
	s_addc_u32 s15, s7, 0
	s_add_i32 s85, s74, s33
	global_load_lds_dwordx4 v[130:131], off
	v_lshl_add_u64 v[130:131], s[14:15], 0, v[140:141]
	s_mov_b32 m0, s85
	s_add_i32 s46, s85, 0x2000
	global_load_lds_dwordx4 v[130:131], off
	v_lshl_add_u64 v[130:131], s[14:15], 0, v[144:145]
	s_mov_b32 m0, s46
	v_lshl_add_u64 v[252:253], s[64:65], 0, v[138:139]
	global_load_lds_dwordx4 v[130:131], off
	v_lshl_add_u64 v[130:131], v[252:253], 0, s[20:21]
	s_mov_b32 m0, s58
	v_lshl_add_u64 v[150:151], s[64:65], 0, v[142:143]
	global_load_lds_dwordx4 v[130:131], off
	v_lshl_add_u64 v[130:131], v[150:151], 0, s[20:21]
	s_mov_b32 m0, s59
	s_nop 0
	global_load_lds_dwordx4 v[130:131], off
	s_waitcnt vmcnt(8)
	s_waitcnt lgkmcnt(0)
	s_setprio 1
	s_barrier
	v_mfma_f32_16x16x32_bf16 v[130:133], v[2:5], v[62:65], 0
	v_mfma_f32_16x16x32_bf16 v[162:165], v[2:5], v[94:97], 0
	v_mfma_f32_16x16x32_bf16 v[170:173], v[2:5], v[110:113], 0
	v_mfma_f32_16x16x32_bf16 v[2:5], v[2:5], v[118:121], 0
	v_mfma_f32_16x16x32_bf16 v[132:135], v[6:9], v[90:93], v[130:133]
	v_mfma_f32_16x16x32_bf16 v[162:165], v[6:9], v[98:101], v[162:165]
	v_mfma_f32_16x16x32_bf16 v[170:173], v[6:9], v[114:117], v[170:173]
	v_mfma_f32_16x16x32_bf16 v[2:5], v[6:9], v[126:129], v[2:5]
	v_mfma_f32_16x16x32_bf16 v[6:9], v[10:13], v[118:121], 0
	v_mfma_f32_16x16x32_bf16 v[154:157], v[10:13], v[62:65], 0
	v_mfma_f32_16x16x32_bf16 v[166:169], v[10:13], v[94:97], 0
	v_mfma_f32_16x16x32_bf16 v[174:177], v[10:13], v[110:113], 0
	v_mfma_f32_16x16x32_bf16 v[6:9], v[14:17], v[126:129], v[6:9]
	v_mfma_f32_16x16x32_bf16 v[154:157], v[14:17], v[90:93], v[154:157]
	v_mfma_f32_16x16x32_bf16 v[166:169], v[14:17], v[98:101], v[166:169]
	v_mfma_f32_16x16x32_bf16 v[174:177], v[14:17], v[114:117], v[174:177]
	s_setprio 0
	s_setprio 1
	v_mfma_f32_16x16x32_bf16 v[10:13], v[18:21], v[62:65], 0
	v_mfma_f32_16x16x32_bf16 v[178:181], v[22:25], v[90:93], v[10:13]
	v_mfma_f32_16x16x32_bf16 v[10:13], v[26:29], v[62:65], 0
	v_mfma_f32_16x16x32_bf16 v[182:185], v[30:33], v[90:93], v[10:13]
	v_mfma_f32_16x16x32_bf16 v[10:13], v[18:21], v[94:97], 0
	v_mfma_f32_16x16x32_bf16 v[186:189], v[22:25], v[98:101], v[10:13]
	v_mfma_f32_16x16x32_bf16 v[10:13], v[26:29], v[94:97], 0
	v_mfma_f32_16x16x32_bf16 v[190:193], v[30:33], v[98:101], v[10:13]
	v_mfma_f32_16x16x32_bf16 v[10:13], v[18:21], v[110:113], 0
	v_mfma_f32_16x16x32_bf16 v[194:197], v[22:25], v[114:117], v[10:13]
	v_mfma_f32_16x16x32_bf16 v[10:13], v[26:29], v[110:113], 0
	v_mfma_f32_16x16x32_bf16 v[198:201], v[30:33], v[114:117], v[10:13]
	v_mfma_f32_16x16x32_bf16 v[10:13], v[18:21], v[118:121], 0
	v_mfma_f32_16x16x32_bf16 v[202:205], v[22:25], v[126:129], v[10:13]
	v_mfma_f32_16x16x32_bf16 v[10:13], v[26:29], v[118:121], 0
	v_mfma_f32_16x16x32_bf16 v[206:209], v[30:33], v[126:129], v[10:13]
	s_barrier
	s_setprio 0
	s_add_i32 s47, 0, 0x18000
	s_add_i32 s56, 0, 0x1c000
	v_add_u32_e32 v130, s47, v1
	v_add_u32_e32 v131, s56, v1
	s_nop 0
	ds_read_b128 v[10:13], v130
	ds_read_b128 v[14:17], v130 offset:1024
	ds_read_b128 v[18:21], v130 offset:2048
	ds_read_b128 v[22:25], v130 offset:3072
	ds_read_b128 v[210:213], v131
	ds_read_b128 v[214:217], v131 offset:1024
	ds_read_b128 v[218:221], v131 offset:2048
	ds_read_b128 v[222:225], v131 offset:3072
	s_add_u32 s14, s64, 0x20100
	s_addc_u32 s15, s65, 0
	s_mov_b32 m0, s63
	v_lshl_add_u64 v[90:91], s[14:15], 0, v[138:139]
	ds_read_b128 v[26:29], v160 offset:32768
	ds_read_b128 v[30:33], v160 offset:33792
	ds_read_b128 v[62:65], v160 offset:34816
	ds_read_b128 v[226:229], v160 offset:35840
	ds_read_b128 v[230:233], v160 offset:36864
	ds_read_b128 v[234:237], v160 offset:37888
	ds_read_b128 v[238:241], v160 offset:38912
	ds_read_b128 v[242:245], v160 offset:39936
	global_load_lds_dwordx4 v[90:91], off
	v_lshl_add_u64 v[90:91], s[14:15], 0, v[142:143]
	s_mov_b32 m0, s68
	s_nop 0
	global_load_lds_dwordx4 v[90:91], off
	s_waitcnt vmcnt(8)
	s_waitcnt lgkmcnt(0)
	s_setprio 1
	s_barrier
	v_mfma_f32_16x16x32_bf16 v[66:69], v[10:13], v[26:29], v[66:69]
	v_mfma_f32_16x16x32_bf16 v[118:121], v[14:17], v[30:33], v[66:69]
	v_mfma_f32_16x16x32_bf16 v[66:69], v[18:21], v[26:29], v[70:73]
	v_mfma_f32_16x16x32_bf16 v[114:117], v[22:25], v[30:33], v[66:69]
	v_mfma_f32_16x16x32_bf16 v[66:69], v[10:13], v[62:65], v[74:77]
	v_mfma_f32_16x16x32_bf16 v[110:113], v[14:17], v[226:229], v[66:69]
	v_mfma_f32_16x16x32_bf16 v[66:69], v[18:21], v[62:65], v[78:81]
	v_mfma_f32_16x16x32_bf16 v[98:101], v[22:25], v[226:229], v[66:69]
	v_mfma_f32_16x16x32_bf16 v[66:69], v[10:13], v[230:233], v[82:85]
	v_mfma_f32_16x16x32_bf16 v[94:97], v[14:17], v[234:237], v[66:69]
	v_mfma_f32_16x16x32_bf16 v[66:69], v[18:21], v[230:233], v[86:89]
	v_mfma_f32_16x16x32_bf16 v[90:93], v[22:25], v[234:237], v[66:69]
	v_mfma_f32_16x16x32_bf16 v[66:69], v[10:13], v[238:241], v[102:105]
	v_mfma_f32_16x16x32_bf16 v[78:81], v[14:17], v[242:245], v[66:69]
	v_mfma_f32_16x16x32_bf16 v[66:69], v[18:21], v[238:241], v[106:109]
	v_mfma_f32_16x16x32_bf16 v[70:73], v[22:25], v[242:245], v[66:69]
	s_setprio 0
	s_setprio 1
	v_mfma_f32_16x16x32_bf16 v[66:69], v[210:213], v[26:29], v[122:125]
	v_mfma_f32_16x16x32_bf16 v[26:29], v[218:221], v[26:29], v[34:37]
	v_mfma_f32_16x16x32_bf16 v[122:125], v[222:225], v[30:33], v[26:29]
	v_mfma_f32_16x16x32_bf16 v[26:29], v[210:213], v[62:65], v[38:41]
	v_mfma_f32_16x16x32_bf16 v[106:109], v[214:217], v[226:229], v[26:29]
	v_mfma_f32_16x16x32_bf16 v[26:29], v[218:221], v[62:65], v[42:45]
	v_mfma_f32_16x16x32_bf16 v[102:105], v[222:225], v[226:229], v[26:29]
	v_mfma_f32_16x16x32_bf16 v[26:29], v[210:213], v[230:233], v[46:49]
	v_mfma_f32_16x16x32_bf16 v[86:89], v[214:217], v[234:237], v[26:29]
	v_mfma_f32_16x16x32_bf16 v[26:29], v[218:221], v[230:233], v[50:53]
	v_mfma_f32_16x16x32_bf16 v[82:85], v[222:225], v[234:237], v[26:29]
	v_mfma_f32_16x16x32_bf16 v[26:29], v[210:213], v[238:241], v[54:57]
	v_mfma_f32_16x16x32_bf16 v[62:65], v[214:217], v[242:245], v[26:29]
	v_mfma_f32_16x16x32_bf16 v[26:29], v[218:221], v[238:241], v[58:61]
	v_mfma_f32_16x16x32_bf16 v[126:129], v[214:217], v[30:33], v[66:69]
	v_mfma_f32_16x16x32_bf16 v[58:61], v[222:225], v[242:245], v[26:29]
	s_barrier
	s_setprio 0
	s_add_i32 s47, s47, s33
	s_add_i32 s86, s47, 0x2000
	s_nop 1
	v_lshl_add_u64 v[26:27], v[136:137], 0, s[22:23]
	s_mov_b32 m0, s47
	s_add_u32 s14, s6, 0x20180
	ds_read_b128 v[34:37], v160 offset:49152
	ds_read_b128 v[38:41], v160 offset:50176
	ds_read_b128 v[226:229], v160 offset:51200
	ds_read_b128 v[230:233], v160 offset:52224
	ds_read_b128 v[234:237], v160 offset:53248
	ds_read_b128 v[238:241], v160 offset:54272
	ds_read_b128 v[242:245], v160 offset:55296
	ds_read_b128 v[246:249], v160 offset:56320
	global_load_lds_dwordx4 v[26:27], off
	v_lshl_add_u64 v[26:27], v[250:251], 0, s[22:23]
	s_mov_b32 m0, s86
	s_addc_u32 s15, s7, 0
	s_add_i32 s56, s56, s33
	global_load_lds_dwordx4 v[26:27], off
	v_lshl_add_u64 v[26:27], s[14:15], 0, v[140:141]
	s_mov_b32 m0, s56
	s_add_i32 s57, s56, 0x2000
	global_load_lds_dwordx4 v[26:27], off
	v_lshl_add_u64 v[26:27], s[14:15], 0, v[144:145]
	s_mov_b32 m0, s57
	s_nop 0
	global_load_lds_dwordx4 v[26:27], off
	v_lshl_add_u64 v[26:27], v[252:253], 0, s[22:23]
	s_mov_b32 m0, s69
	s_nop 0
	global_load_lds_dwordx4 v[26:27], off
	v_lshl_add_u64 v[26:27], v[150:151], 0, s[22:23]
	s_mov_b32 m0, s70
	s_nop 0
	global_load_lds_dwordx4 v[26:27], off
	s_waitcnt vmcnt(8)
	s_waitcnt lgkmcnt(0)
	s_setprio 1
	s_barrier
	v_mfma_f32_16x16x32_bf16 v[26:29], v[10:13], v[34:37], v[132:135]
	v_mfma_f32_16x16x32_bf16 v[74:77], v[14:17], v[38:41], v[26:29]
	v_mfma_f32_16x16x32_bf16 v[26:29], v[18:21], v[34:37], v[154:157]
	v_mfma_f32_16x16x32_bf16 v[66:69], v[22:25], v[38:41], v[26:29]
	v_mfma_f32_16x16x32_bf16 v[26:29], v[10:13], v[226:229], v[162:165]
	v_mfma_f32_16x16x32_bf16 v[46:49], v[14:17], v[230:233], v[26:29]
	v_mfma_f32_16x16x32_bf16 v[26:29], v[18:21], v[226:229], v[166:169]
	v_mfma_f32_16x16x32_bf16 v[42:45], v[22:25], v[230:233], v[26:29]
	v_mfma_f32_16x16x32_bf16 v[26:29], v[10:13], v[234:237], v[170:173]
	v_mfma_f32_16x16x32_bf16 v[2:5], v[10:13], v[242:245], v[2:5]
	v_mfma_f32_16x16x32_bf16 v[30:33], v[14:17], v[238:241], v[26:29]
	v_mfma_f32_16x16x32_bf16 v[26:29], v[18:21], v[234:237], v[174:177]
	v_mfma_f32_16x16x32_bf16 v[14:17], v[14:17], v[246:249], v[2:5]
	v_mfma_f32_16x16x32_bf16 v[2:5], v[18:21], v[242:245], v[6:9]
	v_mfma_f32_16x16x32_bf16 v[26:29], v[22:25], v[238:241], v[26:29]
	v_mfma_f32_16x16x32_bf16 v[10:13], v[22:25], v[246:249], v[2:5]
	s_setprio 0
	s_setprio 1
	v_mfma_f32_16x16x32_bf16 v[2:5], v[210:213], v[34:37], v[178:181]
	v_mfma_f32_16x16x32_bf16 v[54:57], v[214:217], v[38:41], v[2:5]
	v_mfma_f32_16x16x32_bf16 v[2:5], v[218:221], v[34:37], v[182:185]
	v_mfma_f32_16x16x32_bf16 v[50:53], v[222:225], v[38:41], v[2:5]
	v_mfma_f32_16x16x32_bf16 v[2:5], v[210:213], v[226:229], v[186:189]
	v_mfma_f32_16x16x32_bf16 v[38:41], v[214:217], v[230:233], v[2:5]
	v_mfma_f32_16x16x32_bf16 v[2:5], v[218:221], v[226:229], v[190:193]
	v_mfma_f32_16x16x32_bf16 v[34:37], v[222:225], v[230:233], v[2:5]
	v_mfma_f32_16x16x32_bf16 v[2:5], v[210:213], v[234:237], v[194:197]
	v_mfma_f32_16x16x32_bf16 v[22:25], v[214:217], v[238:241], v[2:5]
	v_mfma_f32_16x16x32_bf16 v[2:5], v[218:221], v[234:237], v[198:201]
	v_mfma_f32_16x16x32_bf16 v[18:21], v[222:225], v[238:241], v[2:5]
	v_mfma_f32_16x16x32_bf16 v[2:5], v[210:213], v[242:245], v[202:205]
	v_mfma_f32_16x16x32_bf16 v[6:9], v[214:217], v[246:249], v[2:5]
	v_mfma_f32_16x16x32_bf16 v[2:5], v[218:221], v[242:245], v[206:209]
	v_mfma_f32_16x16x32_bf16 v[2:5], v[222:225], v[246:249], v[2:5]
	s_barrier
	s_setprio 0
	s_add_u32 s64, s64, 0x20180
	s_addc_u32 s65, s65, 0
	s_add_u32 s14, s6, 0x200
	s_addc_u32 s15, s7, 0
	s_mov_b32 s26, 0
.LBB0_670:
	ds_read_b128 v[132:135], v158
	ds_read_b128 v[154:157], v158 offset:1024
	ds_read_b128 v[162:165], v158 offset:2048
	ds_read_b128 v[166:169], v158 offset:3072
	ds_read_b128 v[170:173], v159
	ds_read_b128 v[174:177], v159 offset:1024
	ds_read_b128 v[178:181], v159 offset:2048
	ds_read_b128 v[182:185], v159 offset:3072
	s_add_u32 s6, s64, 0xfffe0080
	s_addc_u32 s7, s65, -1
	s_cmp_eq_u32 s26, 4
	s_cselect_b32 s67, s29, s7
	s_cselect_b32 s66, s79, s6
	s_cselect_b32 s7, s0, s15
	s_cselect_b32 s6, s80, s14
	s_mov_b32 m0, s81
	ds_read_b128 v[186:189], v160
	ds_read_b128 v[190:193], v160 offset:1024
	ds_read_b128 v[194:197], v160 offset:2048
	ds_read_b128 v[198:201], v160 offset:3072
	ds_read_b128 v[202:205], v160 offset:4096
	ds_read_b128 v[206:209], v160 offset:5120
	ds_read_b128 v[210:213], v160 offset:6144
	ds_read_b128 v[214:217], v160 offset:7168
	global_load_lds_dwordx4 v146, s[64:65]
	s_mov_b32 m0, s82
	s_nop 0
	global_load_lds_dwordx4 v148, s[64:65]
	s_waitcnt vmcnt(8)
	s_waitcnt lgkmcnt(0)
	s_setprio 1
	s_barrier
	v_mfma_f32_16x16x32_bf16 v[118:121], v[132:135], v[186:189], v[118:121]
	v_mfma_f32_16x16x32_bf16 v[114:117], v[162:165], v[186:189], v[114:117]
	v_mfma_f32_16x16x32_bf16 v[110:113], v[132:135], v[194:197], v[110:113]
	v_mfma_f32_16x16x32_bf16 v[98:101], v[162:165], v[194:197], v[98:101]
	v_mfma_f32_16x16x32_bf16 v[94:97], v[132:135], v[202:205], v[94:97]
	v_mfma_f32_16x16x32_bf16 v[90:93], v[162:165], v[202:205], v[90:93]
	v_mfma_f32_16x16x32_bf16 v[78:81], v[132:135], v[210:213], v[78:81]
	v_mfma_f32_16x16x32_bf16 v[70:73], v[162:165], v[210:213], v[70:73]
	v_mfma_f32_16x16x32_bf16 v[118:121], v[154:157], v[190:193], v[118:121]
	v_mfma_f32_16x16x32_bf16 v[114:117], v[166:169], v[190:193], v[114:117]
	v_mfma_f32_16x16x32_bf16 v[110:113], v[154:157], v[198:201], v[110:113]
	v_mfma_f32_16x16x32_bf16 v[98:101], v[166:169], v[198:201], v[98:101]
	v_mfma_f32_16x16x32_bf16 v[94:97], v[154:157], v[206:209], v[94:97]
	v_mfma_f32_16x16x32_bf16 v[90:93], v[166:169], v[206:209], v[90:93]
	v_mfma_f32_16x16x32_bf16 v[78:81], v[154:157], v[214:217], v[78:81]
	v_mfma_f32_16x16x32_bf16 v[70:73], v[166:169], v[214:217], v[70:73]
	s_setprio 0
	s_setprio 1
	v_mfma_f32_16x16x32_bf16 v[126:129], v[170:173], v[186:189], v[126:129]
	v_mfma_f32_16x16x32_bf16 v[122:125], v[178:181], v[186:189], v[122:125]
	v_mfma_f32_16x16x32_bf16 v[106:109], v[170:173], v[194:197], v[106:109]
	v_mfma_f32_16x16x32_bf16 v[102:105], v[178:181], v[194:197], v[102:105]
	v_mfma_f32_16x16x32_bf16 v[86:89], v[170:173], v[202:205], v[86:89]
	v_mfma_f32_16x16x32_bf16 v[82:85], v[178:181], v[202:205], v[82:85]
	v_mfma_f32_16x16x32_bf16 v[62:65], v[170:173], v[210:213], v[62:65]
	v_mfma_f32_16x16x32_bf16 v[58:61], v[178:181], v[210:213], v[58:61]
	v_mfma_f32_16x16x32_bf16 v[126:129], v[174:177], v[190:193], v[126:129]
	v_mfma_f32_16x16x32_bf16 v[122:125], v[182:185], v[190:193], v[122:125]
	v_mfma_f32_16x16x32_bf16 v[106:109], v[174:177], v[198:201], v[106:109]
	v_mfma_f32_16x16x32_bf16 v[102:105], v[182:185], v[198:201], v[102:105]
	v_mfma_f32_16x16x32_bf16 v[86:89], v[174:177], v[206:209], v[86:89]
	v_mfma_f32_16x16x32_bf16 v[82:85], v[182:185], v[206:209], v[82:85]
	v_mfma_f32_16x16x32_bf16 v[62:65], v[174:177], v[214:217], v[62:65]
	v_mfma_f32_16x16x32_bf16 v[58:61], v[182:185], v[214:217], v[58:61]
	s_barrier
	s_setprio 0
	s_mov_b32 m0, s83
	s_mov_b64 s[98:99], s[6:7]
	s_add_u32 s88, s6, 0x20000
	ds_read_b128 v[186:189], v160 offset:16384
	ds_read_b128 v[190:193], v160 offset:17408
	ds_read_b128 v[194:197], v160 offset:18432
	ds_read_b128 v[198:201], v160 offset:19456
	ds_read_b128 v[202:205], v160 offset:20480
	ds_read_b128 v[206:209], v160 offset:21504
	ds_read_b128 v[210:213], v160 offset:22528
	ds_read_b128 v[214:217], v160 offset:23552
	global_load_lds_dwordx4 v140, s[6:7]
	s_mov_b32 m0, s84
	s_addc_u32 s89, s7, 0
	global_load_lds_dwordx4 v144, s[6:7]
	s_mov_b32 m0, s85
	s_mov_b64 s[100:101], s[66:67]
	global_load_lds_dwordx4 v140, s[88:89]
	s_mov_b32 m0, s46
	s_nop 0
	global_load_lds_dwordx4 v144, s[88:89]
	s_mov_b32 m0, s58
	s_nop 0
	global_load_lds_dwordx4 v138, s[66:67]
	s_mov_b32 m0, s59
	s_nop 0
	global_load_lds_dwordx4 v142, s[66:67]
	s_waitcnt vmcnt(8)
	s_waitcnt lgkmcnt(0)
	s_setprio 1
	s_barrier
	v_mfma_f32_16x16x32_bf16 v[74:77], v[132:135], v[186:189], v[74:77]
	v_mfma_f32_16x16x32_bf16 v[66:69], v[162:165], v[186:189], v[66:69]
	v_mfma_f32_16x16x32_bf16 v[46:49], v[132:135], v[194:197], v[46:49]
	v_mfma_f32_16x16x32_bf16 v[42:45], v[162:165], v[194:197], v[42:45]
	v_mfma_f32_16x16x32_bf16 v[30:33], v[132:135], v[202:205], v[30:33]
	v_mfma_f32_16x16x32_bf16 v[26:29], v[162:165], v[202:205], v[26:29]
	v_mfma_f32_16x16x32_bf16 v[14:17], v[132:135], v[210:213], v[14:17]
	v_mfma_f32_16x16x32_bf16 v[10:13], v[162:165], v[210:213], v[10:13]
	v_mfma_f32_16x16x32_bf16 v[74:77], v[154:157], v[190:193], v[74:77]
	v_mfma_f32_16x16x32_bf16 v[66:69], v[166:169], v[190:193], v[66:69]
	v_mfma_f32_16x16x32_bf16 v[46:49], v[154:157], v[198:201], v[46:49]
	v_mfma_f32_16x16x32_bf16 v[42:45], v[166:169], v[198:201], v[42:45]
	v_mfma_f32_16x16x32_bf16 v[30:33], v[154:157], v[206:209], v[30:33]
	v_mfma_f32_16x16x32_bf16 v[26:29], v[166:169], v[206:209], v[26:29]
	v_mfma_f32_16x16x32_bf16 v[14:17], v[154:157], v[214:217], v[14:17]
	v_mfma_f32_16x16x32_bf16 v[10:13], v[166:169], v[214:217], v[10:13]
	s_setprio 0
	s_setprio 1
	v_mfma_f32_16x16x32_bf16 v[54:57], v[170:173], v[186:189], v[54:57]
	v_mfma_f32_16x16x32_bf16 v[50:53], v[178:181], v[186:189], v[50:53]
	v_mfma_f32_16x16x32_bf16 v[38:41], v[170:173], v[194:197], v[38:41]
	v_mfma_f32_16x16x32_bf16 v[34:37], v[178:181], v[194:197], v[34:37]
	v_mfma_f32_16x16x32_bf16 v[22:25], v[170:173], v[202:205], v[22:25]
	v_mfma_f32_16x16x32_bf16 v[18:21], v[178:181], v[202:205], v[18:21]
	v_mfma_f32_16x16x32_bf16 v[6:9], v[170:173], v[210:213], v[6:9]
	v_mfma_f32_16x16x32_bf16 v[2:5], v[178:181], v[210:213], v[2:5]
	v_mfma_f32_16x16x32_bf16 v[54:57], v[174:177], v[190:193], v[54:57]
	v_mfma_f32_16x16x32_bf16 v[50:53], v[182:185], v[190:193], v[50:53]
	v_mfma_f32_16x16x32_bf16 v[38:41], v[174:177], v[198:201], v[38:41]
	v_mfma_f32_16x16x32_bf16 v[34:37], v[182:185], v[198:201], v[34:37]
	v_mfma_f32_16x16x32_bf16 v[22:25], v[174:177], v[206:209], v[22:25]
	v_mfma_f32_16x16x32_bf16 v[18:21], v[182:185], v[206:209], v[18:21]
	v_mfma_f32_16x16x32_bf16 v[6:9], v[174:177], v[214:217], v[6:9]
	v_mfma_f32_16x16x32_bf16 v[2:5], v[182:185], v[214:217], v[2:5]
	s_barrier
;     ...
;         for (int t = 2; t < nt; t += 2) PG8_KITER(t);
	s_setprio 0
	ds_read_b128 v[132:135], v130
	ds_read_b128 v[154:157], v130 offset:1024
	ds_read_b128 v[162:165], v130 offset:2048
	ds_read_b128 v[166:169], v130 offset:3072
	ds_read_b128 v[170:173], v131
	ds_read_b128 v[174:177], v131 offset:1024
	ds_read_b128 v[178:181], v131 offset:2048
	ds_read_b128 v[182:185], v131 offset:3072
	s_add_u32 s66, s66, 0x20000
	s_addc_u32 s67, s67, 0
	s_mov_b32 m0, s63
	ds_read_b128 v[186:189], v160 offset:32768
	ds_read_b128 v[190:193], v160 offset:33792
	ds_read_b128 v[194:197], v160 offset:34816
	ds_read_b128 v[198:201], v160 offset:35840
	ds_read_b128 v[202:205], v160 offset:36864
	ds_read_b128 v[206:209], v160 offset:37888
	ds_read_b128 v[210:213], v160 offset:38912
	ds_read_b128 v[214:217], v160 offset:39936
	global_load_lds_dwordx4 v138, s[66:67]
	s_mov_b32 m0, s68
	s_nop 0
	global_load_lds_dwordx4 v142, s[66:67]
	s_waitcnt vmcnt(8)
	s_waitcnt lgkmcnt(0)
	s_setprio 1
	s_barrier
	v_mfma_f32_16x16x32_bf16 v[118:121], v[132:135], v[186:189], v[118:121]
	v_mfma_f32_16x16x32_bf16 v[114:117], v[162:165], v[186:189], v[114:117]
	v_mfma_f32_16x16x32_bf16 v[110:113], v[132:135], v[194:197], v[110:113]
	v_mfma_f32_16x16x32_bf16 v[98:101], v[162:165], v[194:197], v[98:101]
	v_mfma_f32_16x16x32_bf16 v[94:97], v[132:135], v[202:205], v[94:97]
	v_mfma_f32_16x16x32_bf16 v[90:93], v[162:165], v[202:205], v[90:93]
	v_mfma_f32_16x16x32_bf16 v[78:81], v[132:135], v[210:213], v[78:81]
	v_mfma_f32_16x16x32_bf16 v[70:73], v[162:165], v[210:213], v[70:73]
	v_mfma_f32_16x16x32_bf16 v[118:121], v[154:157], v[190:193], v[118:121]
	v_mfma_f32_16x16x32_bf16 v[114:117], v[166:169], v[190:193], v[114:117]
	v_mfma_f32_16x16x32_bf16 v[110:113], v[154:157], v[198:201], v[110:113]
	v_mfma_f32_16x16x32_bf16 v[98:101], v[166:169], v[198:201], v[98:101]
	v_mfma_f32_16x16x32_bf16 v[94:97], v[154:157], v[206:209], v[94:97]
	v_mfma_f32_16x16x32_bf16 v[90:93], v[166:169], v[206:209], v[90:93]
	v_mfma_f32_16x16x32_bf16 v[78:81], v[154:157], v[214:217], v[78:81]
	v_mfma_f32_16x16x32_bf16 v[70:73], v[166:169], v[214:217], v[70:73]
	s_setprio 0
	s_setprio 1
	v_mfma_f32_16x16x32_bf16 v[126:129], v[170:173], v[186:189], v[126:129]
	v_mfma_f32_16x16x32_bf16 v[122:125], v[178:181], v[186:189], v[122:125]
	v_mfma_f32_16x16x32_bf16 v[106:109], v[170:173], v[194:197], v[106:109]
	v_mfma_f32_16x16x32_bf16 v[102:105], v[178:181], v[194:197], v[102:105]
	v_mfma_f32_16x16x32_bf16 v[86:89], v[170:173], v[202:205], v[86:89]
	v_mfma_f32_16x16x32_bf16 v[82:85], v[178:181], v[202:205], v[82:85]
	v_mfma_f32_16x16x32_bf16 v[62:65], v[170:173], v[210:213], v[62:65]
	v_mfma_f32_16x16x32_bf16 v[58:61], v[178:181], v[210:213], v[58:61]
	v_mfma_f32_16x16x32_bf16 v[126:129], v[174:177], v[190:193], v[126:129]
	v_mfma_f32_16x16x32_bf16 v[122:125], v[182:185], v[190:193], v[122:125]
	v_mfma_f32_16x16x32_bf16 v[106:109], v[174:177], v[198:201], v[106:109]
	v_mfma_f32_16x16x32_bf16 v[102:105], v[182:185], v[198:201], v[102:105]
	v_mfma_f32_16x16x32_bf16 v[86:89], v[174:177], v[206:209], v[86:89]
	v_mfma_f32_16x16x32_bf16 v[82:85], v[182:185], v[206:209], v[82:85]
	v_mfma_f32_16x16x32_bf16 v[62:65], v[174:177], v[214:217], v[62:65]
	v_mfma_f32_16x16x32_bf16 v[58:61], v[182:185], v[214:217], v[58:61]
	s_barrier
	s_setprio 0
	s_mov_b32 m0, s47
	s_add_u32 s98, s98, 0x80
	s_addc_u32 s99, s99, 0
	s_add_u32 s100, s100, 0x80
	s_addc_u32 s101, s101, 0
	s_add_u32 s6, s6, 0x20080
	ds_read_b128 v[186:189], v160 offset:49152
	ds_read_b128 v[190:193], v160 offset:50176
	ds_read_b128 v[194:197], v160 offset:51200
	ds_read_b128 v[198:201], v160 offset:52224
	ds_read_b128 v[202:205], v160 offset:53248
	ds_read_b128 v[206:209], v160 offset:54272
	ds_read_b128 v[210:213], v160 offset:55296
	ds_read_b128 v[214:217], v160 offset:56320
	global_load_lds_dwordx4 v140, s[98:99]
	s_mov_b32 m0, s86
	s_addc_u32 s7, s7, 0
	global_load_lds_dwordx4 v144, s[98:99]
	s_mov_b32 m0, s56
	s_nop 0
	global_load_lds_dwordx4 v140, s[6:7]
	s_mov_b32 m0, s57
	s_nop 0
	global_load_lds_dwordx4 v144, s[6:7]
	s_mov_b32 m0, s69
	s_nop 0
	global_load_lds_dwordx4 v138, s[100:101]
	s_mov_b32 m0, s70
	s_nop 0
	global_load_lds_dwordx4 v142, s[100:101]
	s_waitcnt vmcnt(8)
	s_waitcnt lgkmcnt(0)
	s_setprio 1
	s_barrier
	v_mfma_f32_16x16x32_bf16 v[74:77], v[132:135], v[186:189], v[74:77]
	v_mfma_f32_16x16x32_bf16 v[66:69], v[162:165], v[186:189], v[66:69]
	v_mfma_f32_16x16x32_bf16 v[46:49], v[132:135], v[194:197], v[46:49]
	v_mfma_f32_16x16x32_bf16 v[42:45], v[162:165], v[194:197], v[42:45]
	v_mfma_f32_16x16x32_bf16 v[30:33], v[132:135], v[202:205], v[30:33]
	v_mfma_f32_16x16x32_bf16 v[26:29], v[162:165], v[202:205], v[26:29]
	v_mfma_f32_16x16x32_bf16 v[14:17], v[132:135], v[210:213], v[14:17]
	v_mfma_f32_16x16x32_bf16 v[10:13], v[162:165], v[210:213], v[10:13]
	v_mfma_f32_16x16x32_bf16 v[74:77], v[154:157], v[190:193], v[74:77]
	v_mfma_f32_16x16x32_bf16 v[66:69], v[166:169], v[190:193], v[66:69]
	v_mfma_f32_16x16x32_bf16 v[46:49], v[154:157], v[198:201], v[46:49]
	v_mfma_f32_16x16x32_bf16 v[42:45], v[166:169], v[198:201], v[42:45]
	v_mfma_f32_16x16x32_bf16 v[30:33], v[154:157], v[206:209], v[30:33]
	v_mfma_f32_16x16x32_bf16 v[26:29], v[166:169], v[206:209], v[26:29]
	v_mfma_f32_16x16x32_bf16 v[14:17], v[154:157], v[214:217], v[14:17]
	v_mfma_f32_16x16x32_bf16 v[10:13], v[166:169], v[214:217], v[10:13]
	s_setprio 0
	s_setprio 1
	v_mfma_f32_16x16x32_bf16 v[54:57], v[170:173], v[186:189], v[54:57]
	v_mfma_f32_16x16x32_bf16 v[50:53], v[178:181], v[186:189], v[50:53]
	v_mfma_f32_16x16x32_bf16 v[38:41], v[170:173], v[194:197], v[38:41]
	v_mfma_f32_16x16x32_bf16 v[34:37], v[178:181], v[194:197], v[34:37]
	v_mfma_f32_16x16x32_bf16 v[22:25], v[170:173], v[202:205], v[22:25]
	v_mfma_f32_16x16x32_bf16 v[18:21], v[178:181], v[202:205], v[18:21]
	v_mfma_f32_16x16x32_bf16 v[6:9], v[170:173], v[210:213], v[6:9]
	v_mfma_f32_16x16x32_bf16 v[2:5], v[178:181], v[210:213], v[2:5]
	v_mfma_f32_16x16x32_bf16 v[54:57], v[174:177], v[190:193], v[54:57]
	v_mfma_f32_16x16x32_bf16 v[50:53], v[182:185], v[190:193], v[50:53]
	v_mfma_f32_16x16x32_bf16 v[38:41], v[174:177], v[198:201], v[38:41]
	v_mfma_f32_16x16x32_bf16 v[34:37], v[182:185], v[198:201], v[34:37]
	v_mfma_f32_16x16x32_bf16 v[22:25], v[174:177], v[206:209], v[22:25]
	v_mfma_f32_16x16x32_bf16 v[18:21], v[182:185], v[206:209], v[18:21]
	v_mfma_f32_16x16x32_bf16 v[6:9], v[174:177], v[214:217], v[6:9]
	v_mfma_f32_16x16x32_bf16 v[2:5], v[182:185], v[214:217], v[2:5]
	s_barrier
	s_setprio 0
	s_add_i32 s26, s26, 2
	s_add_u32 s64, s64, 0x100
	s_addc_u32 s65, s65, 0
	s_add_u32 s14, s14, 0x100
	s_addc_u32 s15, s15, 0
	s_cmp_gt_u32 s26, 5
	s_cbranch_scc0 .LBB0_670
	s_and_b64 vcc, exec, s[18:19]
	s_cbranch_vccz .LBB0_673
	s_barrier

.LBB0_715:
	ds_read_b128 v[2:5], v164
	ds_read_b128 v[6:9], v164 offset:1024
	ds_read_b128 v[10:13], v164 offset:2048
	ds_read_b128 v[14:17], v164 offset:3072
	ds_read_b128 v[18:21], v165
	ds_read_b128 v[22:25], v165 offset:1024
	ds_read_b128 v[26:29], v165 offset:2048
	ds_read_b128 v[30:33], v165 offset:3072
	s_add_u32 s14, s62, 0x80080
	s_addc_u32 s15, s63, 0
	s_add_i32 s23, s59, 0xc000
	v_lshl_add_u64 v[66:67], s[14:15], 0, v[146:147]
	s_mov_b32 m0, s23
	s_add_i32 s77, s59, 0xe000
	ds_read_b128 v[34:37], v166
	ds_read_b128 v[38:41], v166 offset:1024
	ds_read_b128 v[42:45], v166 offset:2048
	ds_read_b128 v[46:49], v166 offset:3072
	ds_read_b128 v[50:53], v166 offset:4096
	ds_read_b128 v[54:57], v166 offset:5120
	ds_read_b128 v[58:61], v166 offset:6144
	ds_read_b128 v[62:65], v166 offset:7168
	global_load_lds_dwordx4 v[66:67], off
	v_lshl_add_u64 v[66:67], s[14:15], 0, v[150:151]
	s_mov_b32 m0, s77
	s_nop 0
	global_load_lds_dwordx4 v[66:67], off
	s_waitcnt vmcnt(8)
	s_waitcnt lgkmcnt(0)
	s_setprio 1
	s_barrier
	v_mfma_f32_16x16x32_bf16 v[86:89], v[10:13], v[50:53], 0
	v_mfma_f32_16x16x32_bf16 v[106:109], v[14:17], v[54:57], v[86:89]
	v_mfma_f32_16x16x32_bf16 v[86:89], v[2:5], v[58:61], 0
	v_mfma_f32_16x16x32_bf16 v[66:69], v[2:5], v[34:37], 0
	v_mfma_f32_16x16x32_bf16 v[70:73], v[10:13], v[34:37], 0
	v_mfma_f32_16x16x32_bf16 v[74:77], v[2:5], v[42:45], 0
	v_mfma_f32_16x16x32_bf16 v[78:81], v[10:13], v[42:45], 0
	v_mfma_f32_16x16x32_bf16 v[82:85], v[2:5], v[50:53], 0
	v_mfma_f32_16x16x32_bf16 v[110:113], v[6:9], v[62:65], v[86:89]
	v_mfma_f32_16x16x32_bf16 v[86:89], v[10:13], v[58:61], 0
	v_mfma_f32_16x16x32_bf16 v[66:69], v[6:9], v[38:41], v[66:69]
	v_mfma_f32_16x16x32_bf16 v[70:73], v[14:17], v[38:41], v[70:73]
	v_mfma_f32_16x16x32_bf16 v[74:77], v[6:9], v[46:49], v[74:77]
	v_mfma_f32_16x16x32_bf16 v[78:81], v[14:17], v[46:49], v[78:81]
	v_mfma_f32_16x16x32_bf16 v[82:85], v[6:9], v[54:57], v[82:85]
	v_mfma_f32_16x16x32_bf16 v[114:117], v[14:17], v[62:65], v[86:89]
	s_setprio 0
	s_setprio 1
	v_mfma_f32_16x16x32_bf16 v[86:89], v[18:21], v[34:37], 0
	v_mfma_f32_16x16x32_bf16 v[34:37], v[26:29], v[34:37], 0
	v_mfma_f32_16x16x32_bf16 v[118:121], v[22:25], v[38:41], v[86:89]
	v_mfma_f32_16x16x32_bf16 v[34:37], v[30:33], v[38:41], v[34:37]
	v_mfma_f32_16x16x32_bf16 v[38:41], v[18:21], v[42:45], 0
	v_mfma_f32_16x16x32_bf16 v[42:45], v[26:29], v[42:45], 0
	v_mfma_f32_16x16x32_bf16 v[38:41], v[22:25], v[46:49], v[38:41]
	v_mfma_f32_16x16x32_bf16 v[42:45], v[30:33], v[46:49], v[42:45]
	v_mfma_f32_16x16x32_bf16 v[46:49], v[18:21], v[50:53], 0
	v_mfma_f32_16x16x32_bf16 v[50:53], v[26:29], v[50:53], 0
	v_mfma_f32_16x16x32_bf16 v[46:49], v[22:25], v[54:57], v[46:49]
	v_mfma_f32_16x16x32_bf16 v[50:53], v[30:33], v[54:57], v[50:53]
	v_mfma_f32_16x16x32_bf16 v[54:57], v[18:21], v[58:61], 0
	v_mfma_f32_16x16x32_bf16 v[58:61], v[26:29], v[58:61], 0
	v_mfma_f32_16x16x32_bf16 v[54:57], v[22:25], v[62:65], v[54:57]
	v_mfma_f32_16x16x32_bf16 v[58:61], v[30:33], v[62:65], v[58:61]
	s_barrier
	s_setprio 0
	s_add_i32 s78, s72, s58
	v_lshl_add_u64 v[144:145], s[50:51], 0, v[148:149]
	s_add_i32 s79, s78, 0x2000
	v_lshl_add_u64 v[130:131], v[144:145], 0, s[18:19]
	s_mov_b32 m0, s78
	v_lshl_add_u64 v[162:163], s[50:51], 0, v[152:153]
	s_add_u32 s14, s50, 0x80100
	ds_read_b128 v[62:65], v166 offset:16384
	ds_read_b128 v[86:89], v166 offset:17408
	ds_read_b128 v[90:93], v166 offset:18432
	ds_read_b128 v[94:97], v166 offset:19456
	ds_read_b128 v[98:101], v166 offset:20480
	ds_read_b128 v[102:105], v166 offset:21504
	ds_read_b128 v[122:125], v166 offset:22528
	ds_read_b128 v[126:129], v166 offset:23552
	global_load_lds_dwordx4 v[130:131], off
	v_lshl_add_u64 v[130:131], v[162:163], 0, s[18:19]
	s_mov_b32 m0, s79
	s_addc_u32 s15, s51, 0
	s_add_i32 s80, s73, s58
	global_load_lds_dwordx4 v[130:131], off
	v_lshl_add_u64 v[130:131], s[14:15], 0, v[148:149]
	s_mov_b32 m0, s80
	s_add_i32 s46, s80, 0x2000
	global_load_lds_dwordx4 v[130:131], off
	v_lshl_add_u64 v[130:131], s[14:15], 0, v[152:153]
	s_mov_b32 m0, s46
	v_lshl_add_u64 v[252:253], s[62:63], 0, v[146:147]
	global_load_lds_dwordx4 v[130:131], off
	v_lshl_add_u64 v[130:131], v[252:253], 0, s[18:19]
	s_mov_b32 m0, s59
	v_lshl_add_u64 v[158:159], s[62:63], 0, v[150:151]
	global_load_lds_dwordx4 v[130:131], off
	v_lshl_add_u64 v[130:131], v[158:159], 0, s[18:19]
	s_mov_b32 m0, s31
	s_nop 0
	global_load_lds_dwordx4 v[130:131], off
	s_waitcnt vmcnt(8)
	s_waitcnt lgkmcnt(0)
	s_setprio 1
	s_barrier
	v_mfma_f32_16x16x32_bf16 v[130:133], v[2:5], v[62:65], 0
	v_mfma_f32_16x16x32_bf16 v[140:143], v[2:5], v[90:93], 0
	v_mfma_f32_16x16x32_bf16 v[172:175], v[2:5], v[98:101], 0
	v_mfma_f32_16x16x32_bf16 v[2:5], v[2:5], v[122:125], 0
	v_mfma_f32_16x16x32_bf16 v[132:135], v[6:9], v[86:89], v[130:133]
	v_mfma_f32_16x16x32_bf16 v[140:143], v[6:9], v[94:97], v[140:143]
	v_mfma_f32_16x16x32_bf16 v[172:175], v[6:9], v[102:105], v[172:175]
	v_mfma_f32_16x16x32_bf16 v[2:5], v[6:9], v[126:129], v[2:5]
	v_mfma_f32_16x16x32_bf16 v[6:9], v[10:13], v[122:125], 0
	v_mfma_f32_16x16x32_bf16 v[136:139], v[10:13], v[62:65], 0
	v_mfma_f32_16x16x32_bf16 v[168:171], v[10:13], v[90:93], 0
	v_mfma_f32_16x16x32_bf16 v[176:179], v[10:13], v[98:101], 0
	v_mfma_f32_16x16x32_bf16 v[6:9], v[14:17], v[126:129], v[6:9]
	v_mfma_f32_16x16x32_bf16 v[136:139], v[14:17], v[86:89], v[136:139]
	v_mfma_f32_16x16x32_bf16 v[168:171], v[14:17], v[94:97], v[168:171]
	v_mfma_f32_16x16x32_bf16 v[176:179], v[14:17], v[102:105], v[176:179]
	s_setprio 0
	s_setprio 1
	v_mfma_f32_16x16x32_bf16 v[10:13], v[18:21], v[62:65], 0
	v_mfma_f32_16x16x32_bf16 v[180:183], v[22:25], v[86:89], v[10:13]
	v_mfma_f32_16x16x32_bf16 v[10:13], v[26:29], v[62:65], 0
	v_mfma_f32_16x16x32_bf16 v[184:187], v[30:33], v[86:89], v[10:13]
	v_mfma_f32_16x16x32_bf16 v[10:13], v[18:21], v[90:93], 0
	v_mfma_f32_16x16x32_bf16 v[188:191], v[22:25], v[94:97], v[10:13]
	v_mfma_f32_16x16x32_bf16 v[10:13], v[26:29], v[90:93], 0
	v_mfma_f32_16x16x32_bf16 v[192:195], v[30:33], v[94:97], v[10:13]
	v_mfma_f32_16x16x32_bf16 v[10:13], v[18:21], v[98:101], 0
	v_mfma_f32_16x16x32_bf16 v[196:199], v[22:25], v[102:105], v[10:13]
	v_mfma_f32_16x16x32_bf16 v[10:13], v[26:29], v[98:101], 0
	v_mfma_f32_16x16x32_bf16 v[200:203], v[30:33], v[102:105], v[10:13]
	v_mfma_f32_16x16x32_bf16 v[10:13], v[18:21], v[122:125], 0
	v_mfma_f32_16x16x32_bf16 v[204:207], v[22:25], v[126:129], v[10:13]
	v_mfma_f32_16x16x32_bf16 v[10:13], v[26:29], v[122:125], 0
	v_mfma_f32_16x16x32_bf16 v[208:211], v[30:33], v[126:129], v[10:13]
	s_barrier
	s_setprio 0
	s_add_i32 s47, 0, 0x18000
	s_add_i32 s56, 0, 0x1c000
	v_add_u32_e32 v130, s47, v1
	v_add_u32_e32 v131, s56, v1
	s_nop 0
	ds_read_b128 v[10:13], v130
	ds_read_b128 v[14:17], v130 offset:1024
	ds_read_b128 v[18:21], v130 offset:2048
	ds_read_b128 v[22:25], v130 offset:3072
	ds_read_b128 v[212:215], v131
	ds_read_b128 v[216:219], v131 offset:1024
	ds_read_b128 v[220:223], v131 offset:2048
	ds_read_b128 v[224:227], v131 offset:3072
	s_add_u32 s14, s62, 0x80100
	s_addc_u32 s15, s63, 0
	s_mov_b32 m0, s66
	v_lshl_add_u64 v[62:63], s[14:15], 0, v[146:147]
	ds_read_b128 v[26:29], v166 offset:32768
	ds_read_b128 v[30:33], v166 offset:33792
	ds_read_b128 v[228:231], v166 offset:34816
	ds_read_b128 v[232:235], v166 offset:35840
	ds_read_b128 v[236:239], v166 offset:36864
	ds_read_b128 v[240:243], v166 offset:37888
	ds_read_b128 v[244:247], v166 offset:38912
	ds_read_b128 v[248:251], v166 offset:39936
	global_load_lds_dwordx4 v[62:63], off
	v_lshl_add_u64 v[62:63], s[14:15], 0, v[150:151]
	s_mov_b32 m0, s67
	s_nop 0
	global_load_lds_dwordx4 v[62:63], off
	s_waitcnt vmcnt(8)
	s_waitcnt lgkmcnt(0)
	s_setprio 1
	s_barrier
	v_mfma_f32_16x16x32_bf16 v[62:65], v[10:13], v[26:29], v[66:69]
	v_mfma_f32_16x16x32_bf16 v[102:105], v[14:17], v[30:33], v[62:65]
	v_mfma_f32_16x16x32_bf16 v[62:65], v[18:21], v[26:29], v[70:73]
	v_mfma_f32_16x16x32_bf16 v[98:101], v[22:25], v[30:33], v[62:65]
	v_mfma_f32_16x16x32_bf16 v[62:65], v[10:13], v[228:231], v[74:77]
	v_mfma_f32_16x16x32_bf16 v[94:97], v[14:17], v[232:235], v[62:65]
	v_mfma_f32_16x16x32_bf16 v[62:65], v[18:21], v[228:231], v[78:81]
	v_mfma_f32_16x16x32_bf16 v[90:93], v[22:25], v[232:235], v[62:65]
	v_mfma_f32_16x16x32_bf16 v[62:65], v[10:13], v[236:239], v[82:85]
	v_mfma_f32_16x16x32_bf16 v[86:89], v[14:17], v[240:243], v[62:65]
	v_mfma_f32_16x16x32_bf16 v[62:65], v[18:21], v[236:239], v[106:109]
	v_mfma_f32_16x16x32_bf16 v[82:85], v[22:25], v[240:243], v[62:65]
	v_mfma_f32_16x16x32_bf16 v[62:65], v[10:13], v[244:247], v[110:113]
	v_mfma_f32_16x16x32_bf16 v[78:81], v[14:17], v[248:251], v[62:65]
	v_mfma_f32_16x16x32_bf16 v[62:65], v[18:21], v[244:247], v[114:117]
	v_mfma_f32_16x16x32_bf16 v[62:65], v[22:25], v[248:251], v[62:65]
	s_setprio 0
	s_setprio 1
	v_mfma_f32_16x16x32_bf16 v[66:69], v[212:215], v[26:29], v[118:121]
	v_mfma_f32_16x16x32_bf16 v[26:29], v[220:223], v[26:29], v[34:37]
	v_mfma_f32_16x16x32_bf16 v[122:125], v[224:227], v[30:33], v[26:29]
	v_mfma_f32_16x16x32_bf16 v[26:29], v[212:215], v[228:231], v[38:41]
	v_mfma_f32_16x16x32_bf16 v[118:121], v[216:219], v[232:235], v[26:29]
	v_mfma_f32_16x16x32_bf16 v[26:29], v[220:223], v[228:231], v[42:45]
	v_mfma_f32_16x16x32_bf16 v[114:117], v[224:227], v[232:235], v[26:29]
	v_mfma_f32_16x16x32_bf16 v[26:29], v[212:215], v[236:239], v[46:49]
	v_mfma_f32_16x16x32_bf16 v[110:113], v[216:219], v[240:243], v[26:29]
	v_mfma_f32_16x16x32_bf16 v[26:29], v[220:223], v[236:239], v[50:53]
	v_mfma_f32_16x16x32_bf16 v[106:109], v[224:227], v[240:243], v[26:29]
	v_mfma_f32_16x16x32_bf16 v[26:29], v[212:215], v[244:247], v[54:57]
	v_mfma_f32_16x16x32_bf16 v[54:57], v[216:219], v[248:251], v[26:29]
	v_mfma_f32_16x16x32_bf16 v[26:29], v[220:223], v[244:247], v[58:61]
	v_mfma_f32_16x16x32_bf16 v[126:129], v[216:219], v[30:33], v[66:69]
	v_mfma_f32_16x16x32_bf16 v[50:53], v[224:227], v[248:251], v[26:29]
	s_barrier
	s_setprio 0
	s_add_i32 s47, s47, s58
	s_add_i32 s81, s47, 0x2000
	s_nop 1
	v_lshl_add_u64 v[26:27], v[144:145], 0, s[20:21]
	s_mov_b32 m0, s47
	s_add_u32 s14, s50, 0x80180
	ds_read_b128 v[34:37], v166 offset:49152
	ds_read_b128 v[38:41], v166 offset:50176
	ds_read_b128 v[228:231], v166 offset:51200
	ds_read_b128 v[232:235], v166 offset:52224
	ds_read_b128 v[236:239], v166 offset:53248
	ds_read_b128 v[240:243], v166 offset:54272
	ds_read_b128 v[244:247], v166 offset:55296
	ds_read_b128 v[248:251], v166 offset:56320
	global_load_lds_dwordx4 v[26:27], off
	v_lshl_add_u64 v[26:27], v[162:163], 0, s[20:21]
	s_mov_b32 m0, s81
	s_addc_u32 s15, s51, 0
	s_add_i32 s56, s56, s58
	global_load_lds_dwordx4 v[26:27], off
	v_lshl_add_u64 v[26:27], s[14:15], 0, v[148:149]
	s_mov_b32 m0, s56
	s_add_i32 s57, s56, 0x2000
	global_load_lds_dwordx4 v[26:27], off
	v_lshl_add_u64 v[26:27], s[14:15], 0, v[152:153]
	s_mov_b32 m0, s57
	s_nop 0
	global_load_lds_dwordx4 v[26:27], off
	v_lshl_add_u64 v[26:27], v[252:253], 0, s[20:21]
	s_mov_b32 m0, s69
	s_nop 0
	global_load_lds_dwordx4 v[26:27], off
	v_lshl_add_u64 v[26:27], v[158:159], 0, s[20:21]
	s_mov_b32 m0, s70
	s_nop 0
	global_load_lds_dwordx4 v[26:27], off
	s_waitcnt vmcnt(8)
	s_waitcnt lgkmcnt(0)
	s_setprio 1
	s_barrier
	v_mfma_f32_16x16x32_bf16 v[26:29], v[10:13], v[34:37], v[132:135]
	v_mfma_f32_16x16x32_bf16 v[74:77], v[14:17], v[38:41], v[26:29]
	v_mfma_f32_16x16x32_bf16 v[26:29], v[18:21], v[34:37], v[136:139]
	v_mfma_f32_16x16x32_bf16 v[70:73], v[22:25], v[38:41], v[26:29]
	v_mfma_f32_16x16x32_bf16 v[26:29], v[10:13], v[228:231], v[140:143]
	v_mfma_f32_16x16x32_bf16 v[46:49], v[14:17], v[232:235], v[26:29]
	v_mfma_f32_16x16x32_bf16 v[26:29], v[18:21], v[228:231], v[168:171]
	v_mfma_f32_16x16x32_bf16 v[42:45], v[22:25], v[232:235], v[26:29]
	v_mfma_f32_16x16x32_bf16 v[26:29], v[10:13], v[236:239], v[172:175]
	v_mfma_f32_16x16x32_bf16 v[2:5], v[10:13], v[244:247], v[2:5]
	v_mfma_f32_16x16x32_bf16 v[30:33], v[14:17], v[240:243], v[26:29]
	v_mfma_f32_16x16x32_bf16 v[26:29], v[18:21], v[236:239], v[176:179]
	v_mfma_f32_16x16x32_bf16 v[14:17], v[14:17], v[248:251], v[2:5]
	v_mfma_f32_16x16x32_bf16 v[2:5], v[18:21], v[244:247], v[6:9]
	v_mfma_f32_16x16x32_bf16 v[26:29], v[22:25], v[240:243], v[26:29]
	v_mfma_f32_16x16x32_bf16 v[10:13], v[22:25], v[248:251], v[2:5]
	s_setprio 0
	s_setprio 1
	v_mfma_f32_16x16x32_bf16 v[2:5], v[212:215], v[34:37], v[180:183]
	v_mfma_f32_16x16x32_bf16 v[66:69], v[216:219], v[38:41], v[2:5]
	v_mfma_f32_16x16x32_bf16 v[2:5], v[220:223], v[34:37], v[184:187]
	v_mfma_f32_16x16x32_bf16 v[58:61], v[224:227], v[38:41], v[2:5]
	v_mfma_f32_16x16x32_bf16 v[2:5], v[212:215], v[228:231], v[188:191]
	v_mfma_f32_16x16x32_bf16 v[38:41], v[216:219], v[232:235], v[2:5]
	v_mfma_f32_16x16x32_bf16 v[2:5], v[220:223], v[228:231], v[192:195]
	v_mfma_f32_16x16x32_bf16 v[34:37], v[224:227], v[232:235], v[2:5]
	v_mfma_f32_16x16x32_bf16 v[2:5], v[212:215], v[236:239], v[196:199]
	v_mfma_f32_16x16x32_bf16 v[22:25], v[216:219], v[240:243], v[2:5]
	v_mfma_f32_16x16x32_bf16 v[2:5], v[220:223], v[236:239], v[200:203]
	v_mfma_f32_16x16x32_bf16 v[18:21], v[224:227], v[240:243], v[2:5]
	v_mfma_f32_16x16x32_bf16 v[2:5], v[212:215], v[244:247], v[204:207]
	v_mfma_f32_16x16x32_bf16 v[6:9], v[216:219], v[248:251], v[2:5]
	v_mfma_f32_16x16x32_bf16 v[2:5], v[220:223], v[244:247], v[208:211]
	v_mfma_f32_16x16x32_bf16 v[2:5], v[224:227], v[248:251], v[2:5]
	s_barrier
	s_setprio 0
	s_add_u32 s62, s62, 0x80180
	s_addc_u32 s63, s63, 0
	s_add_u32 s14, s50, 0x200
	s_addc_u32 s15, s51, 0
	s_mov_b32 s26, 0
.LBB0_716:
	ds_read_b128 v[132:135], v164
	ds_read_b128 v[136:139], v164 offset:1024
	ds_read_b128 v[140:143], v164 offset:2048
	ds_read_b128 v[168:171], v164 offset:3072
	ds_read_b128 v[172:175], v165
	ds_read_b128 v[176:179], v165 offset:1024
	ds_read_b128 v[180:183], v165 offset:2048
	ds_read_b128 v[184:187], v165 offset:3072
	s_add_u32 s27, s62, 0xfff80080
	s_addc_u32 s50, s63, -1
	s_cmp_eq_u32 s26, 4
	s_cselect_b32 s65, s1, s50
	s_cselect_b32 s64, s0, s27
	s_cselect_b32 s51, s29, s15
	s_cselect_b32 s50, s28, s14
	s_mov_b32 m0, s23
	ds_read_b128 v[188:191], v166
	ds_read_b128 v[192:195], v166 offset:1024
	ds_read_b128 v[196:199], v166 offset:2048
	ds_read_b128 v[200:203], v166 offset:3072
	ds_read_b128 v[204:207], v166 offset:4096
	ds_read_b128 v[208:211], v166 offset:5120
	ds_read_b128 v[212:215], v166 offset:6144
	ds_read_b128 v[216:219], v166 offset:7168
	global_load_lds_dwordx4 v154, s[62:63]
	s_mov_b32 m0, s77
	s_nop 0
	global_load_lds_dwordx4 v156, s[62:63]
	s_waitcnt vmcnt(8)
	s_waitcnt lgkmcnt(0)
	s_setprio 1
	s_barrier
	v_mfma_f32_16x16x32_bf16 v[102:105], v[132:135], v[188:191], v[102:105]
	v_mfma_f32_16x16x32_bf16 v[98:101], v[140:143], v[188:191], v[98:101]
	v_mfma_f32_16x16x32_bf16 v[94:97], v[132:135], v[196:199], v[94:97]
	v_mfma_f32_16x16x32_bf16 v[90:93], v[140:143], v[196:199], v[90:93]
	v_mfma_f32_16x16x32_bf16 v[86:89], v[132:135], v[204:207], v[86:89]
	v_mfma_f32_16x16x32_bf16 v[82:85], v[140:143], v[204:207], v[82:85]
	v_mfma_f32_16x16x32_bf16 v[78:81], v[132:135], v[212:215], v[78:81]
	v_mfma_f32_16x16x32_bf16 v[62:65], v[140:143], v[212:215], v[62:65]
	v_mfma_f32_16x16x32_bf16 v[102:105], v[136:139], v[192:195], v[102:105]
	v_mfma_f32_16x16x32_bf16 v[98:101], v[168:171], v[192:195], v[98:101]
	v_mfma_f32_16x16x32_bf16 v[94:97], v[136:139], v[200:203], v[94:97]
	v_mfma_f32_16x16x32_bf16 v[90:93], v[168:171], v[200:203], v[90:93]
	v_mfma_f32_16x16x32_bf16 v[86:89], v[136:139], v[208:211], v[86:89]
	v_mfma_f32_16x16x32_bf16 v[82:85], v[168:171], v[208:211], v[82:85]
	v_mfma_f32_16x16x32_bf16 v[78:81], v[136:139], v[216:219], v[78:81]
	v_mfma_f32_16x16x32_bf16 v[62:65], v[168:171], v[216:219], v[62:65]
	s_setprio 0
	s_setprio 1
	v_mfma_f32_16x16x32_bf16 v[126:129], v[172:175], v[188:191], v[126:129]
	v_mfma_f32_16x16x32_bf16 v[122:125], v[180:183], v[188:191], v[122:125]
	v_mfma_f32_16x16x32_bf16 v[118:121], v[172:175], v[196:199], v[118:121]
	v_mfma_f32_16x16x32_bf16 v[114:117], v[180:183], v[196:199], v[114:117]
	v_mfma_f32_16x16x32_bf16 v[110:113], v[172:175], v[204:207], v[110:113]
	v_mfma_f32_16x16x32_bf16 v[106:109], v[180:183], v[204:207], v[106:109]
	v_mfma_f32_16x16x32_bf16 v[54:57], v[172:175], v[212:215], v[54:57]
	v_mfma_f32_16x16x32_bf16 v[50:53], v[180:183], v[212:215], v[50:53]
	v_mfma_f32_16x16x32_bf16 v[126:129], v[176:179], v[192:195], v[126:129]
	v_mfma_f32_16x16x32_bf16 v[122:125], v[184:187], v[192:195], v[122:125]
	v_mfma_f32_16x16x32_bf16 v[118:121], v[176:179], v[200:203], v[118:121]
	v_mfma_f32_16x16x32_bf16 v[114:117], v[184:187], v[200:203], v[114:117]
	v_mfma_f32_16x16x32_bf16 v[110:113], v[176:179], v[208:211], v[110:113]
	v_mfma_f32_16x16x32_bf16 v[106:109], v[184:187], v[208:211], v[106:109]
	v_mfma_f32_16x16x32_bf16 v[54:57], v[176:179], v[216:219], v[54:57]
	v_mfma_f32_16x16x32_bf16 v[50:53], v[184:187], v[216:219], v[50:53]
	s_barrier
	s_setprio 0
	s_mov_b32 m0, s78
	s_mov_b64 s[98:99], s[50:51]
	s_add_u32 s82, s50, 0x80000
	ds_read_b128 v[188:191], v166 offset:16384
	ds_read_b128 v[192:195], v166 offset:17408
	ds_read_b128 v[196:199], v166 offset:18432
	ds_read_b128 v[200:203], v166 offset:19456
	ds_read_b128 v[204:207], v166 offset:20480
	ds_read_b128 v[208:211], v166 offset:21504
	ds_read_b128 v[212:215], v166 offset:22528
	ds_read_b128 v[216:219], v166 offset:23552
	global_load_lds_dwordx4 v148, s[50:51]
	s_mov_b32 m0, s79
	s_addc_u32 s83, s51, 0
	global_load_lds_dwordx4 v152, s[50:51]
	s_mov_b32 m0, s80
	s_mov_b64 s[100:101], s[64:65]
	global_load_lds_dwordx4 v148, s[82:83]
	s_mov_b32 m0, s46
	s_nop 0
	global_load_lds_dwordx4 v152, s[82:83]
	s_mov_b32 m0, s59
	s_nop 0
	global_load_lds_dwordx4 v146, s[64:65]
	s_mov_b32 m0, s31
	s_nop 0
	global_load_lds_dwordx4 v150, s[64:65]
	s_waitcnt vmcnt(8)
	s_waitcnt lgkmcnt(0)
	s_setprio 1
	s_barrier
	v_mfma_f32_16x16x32_bf16 v[74:77], v[132:135], v[188:191], v[74:77]
	v_mfma_f32_16x16x32_bf16 v[70:73], v[140:143], v[188:191], v[70:73]
	v_mfma_f32_16x16x32_bf16 v[46:49], v[132:135], v[196:199], v[46:49]
	v_mfma_f32_16x16x32_bf16 v[42:45], v[140:143], v[196:199], v[42:45]
	v_mfma_f32_16x16x32_bf16 v[30:33], v[132:135], v[204:207], v[30:33]
	v_mfma_f32_16x16x32_bf16 v[26:29], v[140:143], v[204:207], v[26:29]
	v_mfma_f32_16x16x32_bf16 v[14:17], v[132:135], v[212:215], v[14:17]
	v_mfma_f32_16x16x32_bf16 v[10:13], v[140:143], v[212:215], v[10:13]
	v_mfma_f32_16x16x32_bf16 v[74:77], v[136:139], v[192:195], v[74:77]
	v_mfma_f32_16x16x32_bf16 v[70:73], v[168:171], v[192:195], v[70:73]
	v_mfma_f32_16x16x32_bf16 v[46:49], v[136:139], v[200:203], v[46:49]
	v_mfma_f32_16x16x32_bf16 v[42:45], v[168:171], v[200:203], v[42:45]
	v_mfma_f32_16x16x32_bf16 v[30:33], v[136:139], v[208:211], v[30:33]
	v_mfma_f32_16x16x32_bf16 v[26:29], v[168:171], v[208:211], v[26:29]
	v_mfma_f32_16x16x32_bf16 v[14:17], v[136:139], v[216:219], v[14:17]
	v_mfma_f32_16x16x32_bf16 v[10:13], v[168:171], v[216:219], v[10:13]
	s_setprio 0
	s_setprio 1
	v_mfma_f32_16x16x32_bf16 v[66:69], v[172:175], v[188:191], v[66:69]
	v_mfma_f32_16x16x32_bf16 v[58:61], v[180:183], v[188:191], v[58:61]
	v_mfma_f32_16x16x32_bf16 v[38:41], v[172:175], v[196:199], v[38:41]
	v_mfma_f32_16x16x32_bf16 v[34:37], v[180:183], v[196:199], v[34:37]
	v_mfma_f32_16x16x32_bf16 v[22:25], v[172:175], v[204:207], v[22:25]
	v_mfma_f32_16x16x32_bf16 v[18:21], v[180:183], v[204:207], v[18:21]
	v_mfma_f32_16x16x32_bf16 v[6:9], v[172:175], v[212:215], v[6:9]
	v_mfma_f32_16x16x32_bf16 v[2:5], v[180:183], v[212:215], v[2:5]
	v_mfma_f32_16x16x32_bf16 v[66:69], v[176:179], v[192:195], v[66:69]
	v_mfma_f32_16x16x32_bf16 v[58:61], v[184:187], v[192:195], v[58:61]
	v_mfma_f32_16x16x32_bf16 v[38:41], v[176:179], v[200:203], v[38:41]
	v_mfma_f32_16x16x32_bf16 v[34:37], v[184:187], v[200:203], v[34:37]
	v_mfma_f32_16x16x32_bf16 v[22:25], v[176:179], v[208:211], v[22:25]
	v_mfma_f32_16x16x32_bf16 v[18:21], v[184:187], v[208:211], v[18:21]
	v_mfma_f32_16x16x32_bf16 v[6:9], v[176:179], v[216:219], v[6:9]
	v_mfma_f32_16x16x32_bf16 v[2:5], v[184:187], v[216:219], v[2:5]
	s_barrier
; #define PG8_BAR __builtin_amdgcn_s_barrier()
;     ...
;         for (int t = 2; t < nt; t += 2) PG8_KITER(t);
;         if constexpr (ALIGN_EPI) { if (wr == 0) PG8_BAR; }
	s_setprio 0
	ds_read_b128 v[132:135], v130
	ds_read_b128 v[136:139], v130 offset:1024
	ds_read_b128 v[140:143], v130 offset:2048
	ds_read_b128 v[168:171], v130 offset:3072
	ds_read_b128 v[172:175], v131
	ds_read_b128 v[176:179], v131 offset:1024
	ds_read_b128 v[180:183], v131 offset:2048
	ds_read_b128 v[184:187], v131 offset:3072
	s_add_u32 s64, s64, 0x80000
	s_addc_u32 s65, s65, 0
	s_mov_b32 m0, s66
	ds_read_b128 v[188:191], v166 offset:32768
	ds_read_b128 v[192:195], v166 offset:33792
	ds_read_b128 v[196:199], v166 offset:34816
	ds_read_b128 v[200:203], v166 offset:35840
	ds_read_b128 v[204:207], v166 offset:36864
	ds_read_b128 v[208:211], v166 offset:37888
	ds_read_b128 v[212:215], v166 offset:38912
	ds_read_b128 v[216:219], v166 offset:39936
	global_load_lds_dwordx4 v146, s[64:65]
	s_mov_b32 m0, s67
	s_nop 0
	global_load_lds_dwordx4 v150, s[64:65]
	s_waitcnt vmcnt(8)
	s_waitcnt lgkmcnt(0)
	s_setprio 1
	s_barrier
	v_mfma_f32_16x16x32_bf16 v[102:105], v[132:135], v[188:191], v[102:105]
	v_mfma_f32_16x16x32_bf16 v[98:101], v[140:143], v[188:191], v[98:101]
	v_mfma_f32_16x16x32_bf16 v[94:97], v[132:135], v[196:199], v[94:97]
	v_mfma_f32_16x16x32_bf16 v[90:93], v[140:143], v[196:199], v[90:93]
	v_mfma_f32_16x16x32_bf16 v[86:89], v[132:135], v[204:207], v[86:89]
	v_mfma_f32_16x16x32_bf16 v[82:85], v[140:143], v[204:207], v[82:85]
	v_mfma_f32_16x16x32_bf16 v[78:81], v[132:135], v[212:215], v[78:81]
	v_mfma_f32_16x16x32_bf16 v[62:65], v[140:143], v[212:215], v[62:65]
	v_mfma_f32_16x16x32_bf16 v[102:105], v[136:139], v[192:195], v[102:105]
	v_mfma_f32_16x16x32_bf16 v[98:101], v[168:171], v[192:195], v[98:101]
	v_mfma_f32_16x16x32_bf16 v[94:97], v[136:139], v[200:203], v[94:97]
	v_mfma_f32_16x16x32_bf16 v[90:93], v[168:171], v[200:203], v[90:93]
	v_mfma_f32_16x16x32_bf16 v[86:89], v[136:139], v[208:211], v[86:89]
	v_mfma_f32_16x16x32_bf16 v[82:85], v[168:171], v[208:211], v[82:85]
	v_mfma_f32_16x16x32_bf16 v[78:81], v[136:139], v[216:219], v[78:81]
	v_mfma_f32_16x16x32_bf16 v[62:65], v[168:171], v[216:219], v[62:65]
	s_setprio 0
	s_setprio 1
	v_mfma_f32_16x16x32_bf16 v[126:129], v[172:175], v[188:191], v[126:129]
	v_mfma_f32_16x16x32_bf16 v[122:125], v[180:183], v[188:191], v[122:125]
	v_mfma_f32_16x16x32_bf16 v[118:121], v[172:175], v[196:199], v[118:121]
	v_mfma_f32_16x16x32_bf16 v[114:117], v[180:183], v[196:199], v[114:117]
	v_mfma_f32_16x16x32_bf16 v[110:113], v[172:175], v[204:207], v[110:113]
	v_mfma_f32_16x16x32_bf16 v[106:109], v[180:183], v[204:207], v[106:109]
	v_mfma_f32_16x16x32_bf16 v[54:57], v[172:175], v[212:215], v[54:57]
	v_mfma_f32_16x16x32_bf16 v[50:53], v[180:183], v[212:215], v[50:53]
	v_mfma_f32_16x16x32_bf16 v[126:129], v[176:179], v[192:195], v[126:129]
	v_mfma_f32_16x16x32_bf16 v[122:125], v[184:187], v[192:195], v[122:125]
	v_mfma_f32_16x16x32_bf16 v[118:121], v[176:179], v[200:203], v[118:121]
	v_mfma_f32_16x16x32_bf16 v[114:117], v[184:187], v[200:203], v[114:117]
	v_mfma_f32_16x16x32_bf16 v[110:113], v[176:179], v[208:211], v[110:113]
	v_mfma_f32_16x16x32_bf16 v[106:109], v[184:187], v[208:211], v[106:109]
	v_mfma_f32_16x16x32_bf16 v[54:57], v[176:179], v[216:219], v[54:57]
	v_mfma_f32_16x16x32_bf16 v[50:53], v[184:187], v[216:219], v[50:53]
	s_barrier
	s_setprio 0
	s_mov_b32 m0, s47
	s_add_u32 s98, s98, 0x80
	s_addc_u32 s99, s99, 0
	s_add_u32 s100, s100, 0x80
	s_addc_u32 s101, s101, 0
	s_add_u32 s50, s50, 0x80080
	ds_read_b128 v[188:191], v166 offset:49152
	ds_read_b128 v[192:195], v166 offset:50176
	ds_read_b128 v[196:199], v166 offset:51200
	ds_read_b128 v[200:203], v166 offset:52224
	ds_read_b128 v[204:207], v166 offset:53248
	ds_read_b128 v[208:211], v166 offset:54272
	ds_read_b128 v[212:215], v166 offset:55296
	ds_read_b128 v[216:219], v166 offset:56320
	global_load_lds_dwordx4 v148, s[98:99]
	s_mov_b32 m0, s81
	s_addc_u32 s51, s51, 0
	global_load_lds_dwordx4 v152, s[98:99]
	s_mov_b32 m0, s56
	s_nop 0
	global_load_lds_dwordx4 v148, s[50:51]
	s_mov_b32 m0, s57
	s_nop 0
	global_load_lds_dwordx4 v152, s[50:51]
	s_mov_b32 m0, s69
	s_nop 0
	global_load_lds_dwordx4 v146, s[100:101]
	s_mov_b32 m0, s70
	s_nop 0
	global_load_lds_dwordx4 v150, s[100:101]
	s_waitcnt vmcnt(8)
	s_waitcnt lgkmcnt(0)
	s_setprio 1
	s_barrier
	v_mfma_f32_16x16x32_bf16 v[74:77], v[132:135], v[188:191], v[74:77]
	v_mfma_f32_16x16x32_bf16 v[70:73], v[140:143], v[188:191], v[70:73]
	v_mfma_f32_16x16x32_bf16 v[46:49], v[132:135], v[196:199], v[46:49]
	v_mfma_f32_16x16x32_bf16 v[42:45], v[140:143], v[196:199], v[42:45]
	v_mfma_f32_16x16x32_bf16 v[30:33], v[132:135], v[204:207], v[30:33]
	v_mfma_f32_16x16x32_bf16 v[26:29], v[140:143], v[204:207], v[26:29]
	v_mfma_f32_16x16x32_bf16 v[14:17], v[132:135], v[212:215], v[14:17]
	v_mfma_f32_16x16x32_bf16 v[10:13], v[140:143], v[212:215], v[10:13]
	v_mfma_f32_16x16x32_bf16 v[74:77], v[136:139], v[192:195], v[74:77]
	v_mfma_f32_16x16x32_bf16 v[70:73], v[168:171], v[192:195], v[70:73]
	v_mfma_f32_16x16x32_bf16 v[46:49], v[136:139], v[200:203], v[46:49]
	v_mfma_f32_16x16x32_bf16 v[42:45], v[168:171], v[200:203], v[42:45]
	v_mfma_f32_16x16x32_bf16 v[30:33], v[136:139], v[208:211], v[30:33]
	v_mfma_f32_16x16x32_bf16 v[26:29], v[168:171], v[208:211], v[26:29]
	v_mfma_f32_16x16x32_bf16 v[14:17], v[136:139], v[216:219], v[14:17]
	v_mfma_f32_16x16x32_bf16 v[10:13], v[168:171], v[216:219], v[10:13]
	s_setprio 0
	s_setprio 1
	v_mfma_f32_16x16x32_bf16 v[66:69], v[172:175], v[188:191], v[66:69]
	v_mfma_f32_16x16x32_bf16 v[58:61], v[180:183], v[188:191], v[58:61]
	v_mfma_f32_16x16x32_bf16 v[38:41], v[172:175], v[196:199], v[38:41]
	v_mfma_f32_16x16x32_bf16 v[34:37], v[180:183], v[196:199], v[34:37]
	v_mfma_f32_16x16x32_bf16 v[22:25], v[172:175], v[204:207], v[22:25]
	v_mfma_f32_16x16x32_bf16 v[18:21], v[180:183], v[204:207], v[18:21]
	v_mfma_f32_16x16x32_bf16 v[6:9], v[172:175], v[212:215], v[6:9]
	v_mfma_f32_16x16x32_bf16 v[2:5], v[180:183], v[212:215], v[2:5]
	v_mfma_f32_16x16x32_bf16 v[66:69], v[176:179], v[192:195], v[66:69]
	v_mfma_f32_16x16x32_bf16 v[58:61], v[184:187], v[192:195], v[58:61]
	v_mfma_f32_16x16x32_bf16 v[38:41], v[176:179], v[200:203], v[38:41]
	v_mfma_f32_16x16x32_bf16 v[34:37], v[184:187], v[200:203], v[34:37]
	v_mfma_f32_16x16x32_bf16 v[22:25], v[176:179], v[208:211], v[22:25]
	v_mfma_f32_16x16x32_bf16 v[18:21], v[184:187], v[208:211], v[18:21]
	v_mfma_f32_16x16x32_bf16 v[6:9], v[176:179], v[216:219], v[6:9]
	v_mfma_f32_16x16x32_bf16 v[2:5], v[184:187], v[216:219], v[2:5]
	s_barrier
	s_setprio 0
	s_add_i32 s26, s26, 2
	s_add_u32 s62, s62, 0x100
	s_addc_u32 s63, s63, 0
	s_add_u32 s14, s14, 0x100
	s_addc_u32 s15, s15, 0
	s_cmp_gt_u32 s26, 5
	s_cbranch_scc0 .LBB0_716
	s_and_b64 vcc, exec, s[16:17]
	s_cbranch_vccz .LBB0_719
	s_barrier

;     __host__ __device__ bool next(int i, Unit& u) const { if (!StaticOrder::next(i >> 1, u)) return false; u.seg = i & 1; return true; }
;     ...
;         const bool has_next = S.next(ui + 1, nxt);
;         const char* nA = has_next ? PG8_APTR(nxt) : cA; const char* nB = has_next ? PG8_BPTR(nxt) : cB;
;         const char* pfc = PG8_PFPTR(cA, cB); const char* pfn = PG8_PFPTR(nA, nB);
;         PG8_KITER(0);
.LBB0_929:
	v_add_u32_e32 v130, s79, v1
	v_add_u32_e32 v131, s80, v1
	ds_read_b128 v[132:135], v130
	ds_read_b128 v[136:139], v130 offset:1024
	ds_read_b128 v[140:143], v130 offset:2048
	ds_read_b128 v[144:147], v130 offset:3072
	ds_read_b128 v[168:171], v131
	ds_read_b128 v[174:177], v131 offset:1024
	ds_read_b128 v[178:181], v131 offset:2048
	ds_read_b128 v[182:185], v131 offset:3072
	s_add_u32 s12, s62, 0x80080
	s_addc_u32 s13, s63, 0
	s_add_i32 s0, s69, 0xc000
	v_lshl_add_u64 v[148:149], s[12:13], 0, v[150:151]
	s_mov_b32 m0, s0
	s_add_i32 s11, s69, 0xe000
	ds_read_b128 v[186:189], v172
	ds_read_b128 v[190:193], v172 offset:1024
	ds_read_b128 v[194:197], v172 offset:2048
	ds_read_b128 v[198:201], v172 offset:3072
	ds_read_b128 v[202:205], v172 offset:4096
	ds_read_b128 v[206:209], v172 offset:5120
	ds_read_b128 v[210:213], v172 offset:6144
	ds_read_b128 v[214:217], v172 offset:7168
	global_load_lds_dwordx4 v[148:149], off
	v_lshl_add_u64 v[148:149], s[12:13], 0, v[154:155]
	s_mov_b32 m0, s11
	s_nop 0
	global_load_lds_dwordx4 v[148:149], off
	s_waitcnt vmcnt(8)
	s_waitcnt lgkmcnt(0)
	s_setprio 1
	s_barrier
	v_mfma_f32_16x16x32_bf16 v[126:129], v[132:135], v[186:189], v[126:129]
	v_mfma_f32_16x16x32_bf16 v[122:125], v[140:143], v[186:189], v[122:125]
	v_mfma_f32_16x16x32_bf16 v[118:121], v[132:135], v[194:197], v[118:121]
	v_mfma_f32_16x16x32_bf16 v[114:117], v[140:143], v[194:197], v[114:117]
	v_mfma_f32_16x16x32_bf16 v[110:113], v[132:135], v[202:205], v[110:113]
	v_mfma_f32_16x16x32_bf16 v[106:109], v[140:143], v[202:205], v[106:109]
	v_mfma_f32_16x16x32_bf16 v[102:105], v[132:135], v[210:213], v[102:105]
	v_mfma_f32_16x16x32_bf16 v[98:101], v[140:143], v[210:213], v[98:101]
	v_mfma_f32_16x16x32_bf16 v[126:129], v[136:139], v[190:193], v[126:129]
	v_mfma_f32_16x16x32_bf16 v[122:125], v[144:147], v[190:193], v[122:125]
	v_mfma_f32_16x16x32_bf16 v[118:121], v[136:139], v[198:201], v[118:121]
	v_mfma_f32_16x16x32_bf16 v[114:117], v[144:147], v[198:201], v[114:117]
	v_mfma_f32_16x16x32_bf16 v[110:113], v[136:139], v[206:209], v[110:113]
	v_mfma_f32_16x16x32_bf16 v[106:109], v[144:147], v[206:209], v[106:109]
	v_mfma_f32_16x16x32_bf16 v[102:105], v[136:139], v[214:217], v[102:105]
	v_mfma_f32_16x16x32_bf16 v[98:101], v[144:147], v[214:217], v[98:101]
	s_setprio 0
	s_setprio 1
	v_mfma_f32_16x16x32_bf16 v[94:97], v[168:171], v[186:189], v[94:97]
	v_mfma_f32_16x16x32_bf16 v[90:93], v[178:181], v[186:189], v[90:93]
	v_mfma_f32_16x16x32_bf16 v[86:89], v[168:171], v[194:197], v[86:89]
	v_mfma_f32_16x16x32_bf16 v[82:85], v[178:181], v[194:197], v[82:85]
	v_mfma_f32_16x16x32_bf16 v[78:81], v[168:171], v[202:205], v[78:81]
	v_mfma_f32_16x16x32_bf16 v[74:77], v[178:181], v[202:205], v[74:77]
	v_mfma_f32_16x16x32_bf16 v[70:73], v[168:171], v[210:213], v[70:73]
	v_mfma_f32_16x16x32_bf16 v[66:69], v[178:181], v[210:213], v[66:69]
	v_mfma_f32_16x16x32_bf16 v[94:97], v[174:177], v[190:193], v[94:97]
	v_mfma_f32_16x16x32_bf16 v[90:93], v[182:185], v[190:193], v[90:93]
	v_mfma_f32_16x16x32_bf16 v[86:89], v[174:177], v[198:201], v[86:89]
	v_mfma_f32_16x16x32_bf16 v[82:85], v[182:185], v[198:201], v[82:85]
	v_mfma_f32_16x16x32_bf16 v[78:81], v[174:177], v[206:209], v[78:81]
	v_mfma_f32_16x16x32_bf16 v[74:77], v[182:185], v[206:209], v[74:77]
	v_mfma_f32_16x16x32_bf16 v[70:73], v[174:177], v[214:217], v[70:73]
	v_mfma_f32_16x16x32_bf16 v[66:69], v[182:185], v[214:217], v[66:69]
	s_barrier
	s_setprio 0
	s_add_i32 s12, s79, s68
	v_lshl_add_u64 v[218:219], s[50:51], 0, v[152:153]
	s_add_i32 s13, s12, 0x2000
	v_lshl_add_u64 v[148:149], v[218:219], 0, s[22:23]
	s_mov_b32 m0, s12
	v_lshl_add_u64 v[220:221], s[50:51], 0, v[156:157]
	s_add_u32 s14, s50, 0x80100
	ds_read_b128 v[186:189], v172 offset:16384
	ds_read_b128 v[190:193], v172 offset:17408
	ds_read_b128 v[194:197], v172 offset:18432
	ds_read_b128 v[198:201], v172 offset:19456
	ds_read_b128 v[202:205], v172 offset:20480
	ds_read_b128 v[206:209], v172 offset:21504
	ds_read_b128 v[210:213], v172 offset:22528
	ds_read_b128 v[214:217], v172 offset:23552
	global_load_lds_dwordx4 v[148:149], off
	v_lshl_add_u64 v[148:149], v[220:221], 0, s[22:23]
	s_mov_b32 m0, s13
	s_addc_u32 s15, s51, 0
	s_add_i32 s43, s80, s68
	global_load_lds_dwordx4 v[148:149], off
	v_lshl_add_u64 v[148:149], s[14:15], 0, v[152:153]
	s_mov_b32 m0, s43
	s_add_i32 s46, s43, 0x2000
	global_load_lds_dwordx4 v[148:149], off
	v_lshl_add_u64 v[148:149], s[14:15], 0, v[156:157]
	s_mov_b32 m0, s46
	v_lshl_add_u64 v[222:223], s[62:63], 0, v[150:151]
	global_load_lds_dwordx4 v[148:149], off
	v_lshl_add_u64 v[148:149], v[222:223], 0, s[22:23]
	s_mov_b32 m0, s69
	v_lshl_add_u64 v[224:225], s[62:63], 0, v[154:155]
	global_load_lds_dwordx4 v[148:149], off
	v_lshl_add_u64 v[148:149], v[224:225], 0, s[22:23]
	s_mov_b32 m0, s70
	s_nop 0
	global_load_lds_dwordx4 v[148:149], off
	s_waitcnt vmcnt(8)
	s_waitcnt lgkmcnt(0)
	s_setprio 1
	s_barrier
	v_mfma_f32_16x16x32_bf16 v[62:65], v[132:135], v[186:189], v[62:65]
	v_mfma_f32_16x16x32_bf16 v[58:61], v[140:143], v[186:189], v[58:61]
	v_mfma_f32_16x16x32_bf16 v[54:57], v[132:135], v[194:197], v[54:57]
	v_mfma_f32_16x16x32_bf16 v[50:53], v[140:143], v[194:197], v[50:53]
	v_mfma_f32_16x16x32_bf16 v[46:49], v[132:135], v[202:205], v[46:49]
	v_mfma_f32_16x16x32_bf16 v[42:45], v[140:143], v[202:205], v[42:45]
	v_mfma_f32_16x16x32_bf16 v[38:41], v[132:135], v[210:213], v[38:41]
	v_mfma_f32_16x16x32_bf16 v[34:37], v[140:143], v[210:213], v[34:37]
	v_mfma_f32_16x16x32_bf16 v[62:65], v[136:139], v[190:193], v[62:65]
	v_mfma_f32_16x16x32_bf16 v[58:61], v[144:147], v[190:193], v[58:61]
	v_mfma_f32_16x16x32_bf16 v[54:57], v[136:139], v[198:201], v[54:57]
	v_mfma_f32_16x16x32_bf16 v[50:53], v[144:147], v[198:201], v[50:53]
	v_mfma_f32_16x16x32_bf16 v[46:49], v[136:139], v[206:209], v[46:49]
	v_mfma_f32_16x16x32_bf16 v[42:45], v[144:147], v[206:209], v[42:45]
	v_mfma_f32_16x16x32_bf16 v[38:41], v[136:139], v[214:217], v[38:41]
	v_mfma_f32_16x16x32_bf16 v[34:37], v[144:147], v[214:217], v[34:37]
	s_setprio 0
	s_setprio 1
	v_mfma_f32_16x16x32_bf16 v[30:33], v[168:171], v[186:189], v[30:33]
	v_mfma_f32_16x16x32_bf16 v[26:29], v[178:181], v[186:189], v[26:29]
	v_mfma_f32_16x16x32_bf16 v[22:25], v[168:171], v[194:197], v[22:25]
	v_mfma_f32_16x16x32_bf16 v[18:21], v[178:181], v[194:197], v[18:21]
	v_mfma_f32_16x16x32_bf16 v[14:17], v[168:171], v[202:205], v[14:17]
	v_mfma_f32_16x16x32_bf16 v[10:13], v[178:181], v[202:205], v[10:13]
	v_mfma_f32_16x16x32_bf16 v[6:9], v[168:171], v[210:213], v[6:9]
	v_mfma_f32_16x16x32_bf16 v[2:5], v[178:181], v[210:213], v[2:5]
	v_mfma_f32_16x16x32_bf16 v[30:33], v[174:177], v[190:193], v[30:33]
	v_mfma_f32_16x16x32_bf16 v[26:29], v[182:185], v[190:193], v[26:29]
	v_mfma_f32_16x16x32_bf16 v[22:25], v[174:177], v[198:201], v[22:25]
	v_mfma_f32_16x16x32_bf16 v[18:21], v[182:185], v[198:201], v[18:21]
	v_mfma_f32_16x16x32_bf16 v[14:17], v[174:177], v[206:209], v[14:17]
	v_mfma_f32_16x16x32_bf16 v[10:13], v[182:185], v[206:209], v[10:13]
	v_mfma_f32_16x16x32_bf16 v[6:9], v[174:177], v[214:217], v[6:9]
	v_mfma_f32_16x16x32_bf16 v[2:5], v[182:185], v[214:217], v[2:5]
	s_barrier
	s_setprio 0
	s_add_i32 s47, 0, 0x18000
	s_add_i32 s55, 0, 0x1c000
	v_add_u32_e32 v132, s47, v1
	v_add_u32_e32 v133, s55, v1
	ds_read_b128 v[134:137], v132
	ds_read_b128 v[138:141], v132 offset:1024
	ds_read_b128 v[142:145], v132 offset:2048
	ds_read_b128 v[146:149], v132 offset:3072
	ds_read_b128 v[168:171], v133
	ds_read_b128 v[174:177], v133 offset:1024
	ds_read_b128 v[178:181], v133 offset:2048
	ds_read_b128 v[182:185], v133 offset:3072
	s_add_u32 s14, s62, 0x80100
	s_addc_u32 s15, s63, 0
	s_mov_b32 m0, s71
	v_lshl_add_u64 v[226:227], s[14:15], 0, v[150:151]
	ds_read_b128 v[186:189], v172 offset:32768
	ds_read_b128 v[190:193], v172 offset:33792
	ds_read_b128 v[194:197], v172 offset:34816
	ds_read_b128 v[198:201], v172 offset:35840
	ds_read_b128 v[202:205], v172 offset:36864
	ds_read_b128 v[206:209], v172 offset:37888
	ds_read_b128 v[210:213], v172 offset:38912
	ds_read_b128 v[214:217], v172 offset:39936
	global_load_lds_dwordx4 v[226:227], off
	v_lshl_add_u64 v[226:227], s[14:15], 0, v[154:155]
	s_mov_b32 m0, s72
	s_nop 0
	global_load_lds_dwordx4 v[226:227], off
	s_waitcnt vmcnt(8)
	s_waitcnt lgkmcnt(0)
	s_setprio 1
	s_barrier
	v_mfma_f32_16x16x32_bf16 v[126:129], v[134:137], v[186:189], v[126:129]
	v_mfma_f32_16x16x32_bf16 v[122:125], v[142:145], v[186:189], v[122:125]
	v_mfma_f32_16x16x32_bf16 v[118:121], v[134:137], v[194:197], v[118:121]
	v_mfma_f32_16x16x32_bf16 v[114:117], v[142:145], v[194:197], v[114:117]
	v_mfma_f32_16x16x32_bf16 v[110:113], v[134:137], v[202:205], v[110:113]
	v_mfma_f32_16x16x32_bf16 v[106:109], v[142:145], v[202:205], v[106:109]
	v_mfma_f32_16x16x32_bf16 v[102:105], v[134:137], v[210:213], v[102:105]
	v_mfma_f32_16x16x32_bf16 v[98:101], v[142:145], v[210:213], v[98:101]
	v_mfma_f32_16x16x32_bf16 v[126:129], v[138:141], v[190:193], v[126:129]
	v_mfma_f32_16x16x32_bf16 v[122:125], v[146:149], v[190:193], v[122:125]
	v_mfma_f32_16x16x32_bf16 v[118:121], v[138:141], v[198:201], v[118:121]
	v_mfma_f32_16x16x32_bf16 v[114:117], v[146:149], v[198:201], v[114:117]
	v_mfma_f32_16x16x32_bf16 v[110:113], v[138:141], v[206:209], v[110:113]
	v_mfma_f32_16x16x32_bf16 v[106:109], v[146:149], v[206:209], v[106:109]
	v_mfma_f32_16x16x32_bf16 v[102:105], v[138:141], v[214:217], v[102:105]
	v_mfma_f32_16x16x32_bf16 v[98:101], v[146:149], v[214:217], v[98:101]
	s_setprio 0
	s_setprio 1
	v_mfma_f32_16x16x32_bf16 v[94:97], v[168:171], v[186:189], v[94:97]
	v_mfma_f32_16x16x32_bf16 v[90:93], v[178:181], v[186:189], v[90:93]
	v_mfma_f32_16x16x32_bf16 v[86:89], v[168:171], v[194:197], v[86:89]
	v_mfma_f32_16x16x32_bf16 v[82:85], v[178:181], v[194:197], v[82:85]
	v_mfma_f32_16x16x32_bf16 v[78:81], v[168:171], v[202:205], v[78:81]
	v_mfma_f32_16x16x32_bf16 v[74:77], v[178:181], v[202:205], v[74:77]
	v_mfma_f32_16x16x32_bf16 v[70:73], v[168:171], v[210:213], v[70:73]
	v_mfma_f32_16x16x32_bf16 v[66:69], v[178:181], v[210:213], v[66:69]
	v_mfma_f32_16x16x32_bf16 v[94:97], v[174:177], v[190:193], v[94:97]
	v_mfma_f32_16x16x32_bf16 v[90:93], v[182:185], v[190:193], v[90:93]
	v_mfma_f32_16x16x32_bf16 v[86:89], v[174:177], v[198:201], v[86:89]
	v_mfma_f32_16x16x32_bf16 v[82:85], v[182:185], v[198:201], v[82:85]
	v_mfma_f32_16x16x32_bf16 v[78:81], v[174:177], v[206:209], v[78:81]
	v_mfma_f32_16x16x32_bf16 v[74:77], v[182:185], v[206:209], v[74:77]
	v_mfma_f32_16x16x32_bf16 v[70:73], v[174:177], v[214:217], v[70:73]
	v_mfma_f32_16x16x32_bf16 v[66:69], v[182:185], v[214:217], v[66:69]
	s_barrier
;     __host__ __device__ bool next(int i, Unit& u) const { if (!StaticOrder::next(i >> 1, u)) return false; u.seg = i & 1; return true; }
;     ...
;         const bool has_next = S.next(ui + 1, nxt);
;         const char* nA = has_next ? PG8_APTR(nxt) : cA; const char* nB = has_next ? PG8_BPTR(nxt) : cB;
;         const char* pfc = PG8_PFPTR(cA, cB); const char* pfn = PG8_PFPTR(nA, nB);
;         PG8_KITER(0);
;         for (int t = 2; t < nt; t += 2) PG8_KITER(t);
	s_setprio 0
	s_add_i32 s47, s47, s68
	s_add_i32 s53, s47, 0x2000
	v_lshl_add_u64 v[218:219], v[218:219], 0, s[28:29]
	s_mov_b32 m0, s47
	s_add_u32 s14, s50, 0x80180
	ds_read_b128 v[186:189], v172 offset:49152
	ds_read_b128 v[190:193], v172 offset:50176
	ds_read_b128 v[194:197], v172 offset:51200
	ds_read_b128 v[198:201], v172 offset:52224
	ds_read_b128 v[202:205], v172 offset:53248
	ds_read_b128 v[206:209], v172 offset:54272
	ds_read_b128 v[210:213], v172 offset:55296
	ds_read_b128 v[214:217], v172 offset:56320
	global_load_lds_dwordx4 v[218:219], off
	v_lshl_add_u64 v[218:219], v[220:221], 0, s[28:29]
	s_mov_b32 m0, s53
	s_addc_u32 s15, s51, 0
	s_add_i32 s55, s55, s68
	global_load_lds_dwordx4 v[218:219], off
	v_lshl_add_u64 v[218:219], s[14:15], 0, v[152:153]
	s_mov_b32 m0, s55
	s_add_i32 s56, s55, 0x2000
	global_load_lds_dwordx4 v[218:219], off
	v_lshl_add_u64 v[218:219], s[14:15], 0, v[156:157]
	s_mov_b32 m0, s56
	s_nop 0
	global_load_lds_dwordx4 v[218:219], off
	v_lshl_add_u64 v[218:219], v[222:223], 0, s[28:29]
	s_mov_b32 m0, s77
	s_nop 0
	global_load_lds_dwordx4 v[218:219], off
	v_lshl_add_u64 v[218:219], v[224:225], 0, s[28:29]
	s_mov_b32 m0, s78
	s_nop 0
	global_load_lds_dwordx4 v[218:219], off
	s_waitcnt vmcnt(8)
	s_waitcnt lgkmcnt(0)
	s_setprio 1
	s_barrier
	v_mfma_f32_16x16x32_bf16 v[62:65], v[134:137], v[186:189], v[62:65]
	v_mfma_f32_16x16x32_bf16 v[58:61], v[142:145], v[186:189], v[58:61]
	v_mfma_f32_16x16x32_bf16 v[54:57], v[134:137], v[194:197], v[54:57]
	v_mfma_f32_16x16x32_bf16 v[50:53], v[142:145], v[194:197], v[50:53]
	v_mfma_f32_16x16x32_bf16 v[46:49], v[134:137], v[202:205], v[46:49]
	v_mfma_f32_16x16x32_bf16 v[42:45], v[142:145], v[202:205], v[42:45]
	v_mfma_f32_16x16x32_bf16 v[38:41], v[134:137], v[210:213], v[38:41]
	v_mfma_f32_16x16x32_bf16 v[34:37], v[142:145], v[210:213], v[34:37]
	v_mfma_f32_16x16x32_bf16 v[62:65], v[138:141], v[190:193], v[62:65]
	v_mfma_f32_16x16x32_bf16 v[58:61], v[146:149], v[190:193], v[58:61]
	v_mfma_f32_16x16x32_bf16 v[54:57], v[138:141], v[198:201], v[54:57]
	v_mfma_f32_16x16x32_bf16 v[50:53], v[146:149], v[198:201], v[50:53]
	v_mfma_f32_16x16x32_bf16 v[46:49], v[138:141], v[206:209], v[46:49]
	v_mfma_f32_16x16x32_bf16 v[42:45], v[146:149], v[206:209], v[42:45]
	v_mfma_f32_16x16x32_bf16 v[38:41], v[138:141], v[214:217], v[38:41]
	v_mfma_f32_16x16x32_bf16 v[34:37], v[146:149], v[214:217], v[34:37]
	s_setprio 0
	s_setprio 1
	v_mfma_f32_16x16x32_bf16 v[30:33], v[168:171], v[186:189], v[30:33]
	v_mfma_f32_16x16x32_bf16 v[26:29], v[178:181], v[186:189], v[26:29]
	v_mfma_f32_16x16x32_bf16 v[22:25], v[168:171], v[194:197], v[22:25]
	v_mfma_f32_16x16x32_bf16 v[18:21], v[178:181], v[194:197], v[18:21]
	v_mfma_f32_16x16x32_bf16 v[14:17], v[168:171], v[202:205], v[14:17]
	v_mfma_f32_16x16x32_bf16 v[10:13], v[178:181], v[202:205], v[10:13]
	v_mfma_f32_16x16x32_bf16 v[6:9], v[168:171], v[210:213], v[6:9]
	v_mfma_f32_16x16x32_bf16 v[2:5], v[178:181], v[210:213], v[2:5]
	v_mfma_f32_16x16x32_bf16 v[30:33], v[174:177], v[190:193], v[30:33]
	v_mfma_f32_16x16x32_bf16 v[26:29], v[182:185], v[190:193], v[26:29]
	v_mfma_f32_16x16x32_bf16 v[22:25], v[174:177], v[198:201], v[22:25]
	v_mfma_f32_16x16x32_bf16 v[18:21], v[182:185], v[198:201], v[18:21]
	v_mfma_f32_16x16x32_bf16 v[14:17], v[174:177], v[206:209], v[14:17]
	v_mfma_f32_16x16x32_bf16 v[10:13], v[182:185], v[206:209], v[10:13]
	v_mfma_f32_16x16x32_bf16 v[6:9], v[174:177], v[214:217], v[6:9]
	v_mfma_f32_16x16x32_bf16 v[2:5], v[182:185], v[214:217], v[2:5]
	s_barrier
	s_setprio 0
	s_add_u32 s62, s62, 0x80180
	s_addc_u32 s63, s63, 0
	s_add_u32 s14, s50, 0x200
	s_addc_u32 s15, s51, 0
	s_mov_b32 s26, 0
.LBB0_930:
	ds_read_b128 v[134:137], v130
	ds_read_b128 v[138:141], v130 offset:1024
	ds_read_b128 v[142:145], v130 offset:2048
	ds_read_b128 v[146:149], v130 offset:3072
	ds_read_b128 v[168:171], v131
	ds_read_b128 v[174:177], v131 offset:1024
	ds_read_b128 v[178:181], v131 offset:2048
	ds_read_b128 v[182:185], v131 offset:3072
	s_add_u32 s27, s62, 0xfff80080
	s_addc_u32 s50, s63, -1
	s_cmp_eq_u32 s26, 28
	s_cselect_b32 s65, s7, s50
	s_cselect_b32 s64, s6, s27
	s_cselect_b32 s51, s49, s15
	s_cselect_b32 s50, s48, s14
	s_mov_b32 m0, s0
	ds_read_b128 v[186:189], v172
	ds_read_b128 v[190:193], v172 offset:1024
	ds_read_b128 v[194:197], v172 offset:2048
	ds_read_b128 v[198:201], v172 offset:3072
	ds_read_b128 v[202:205], v172 offset:4096
	ds_read_b128 v[206:209], v172 offset:5120
	ds_read_b128 v[210:213], v172 offset:6144
	ds_read_b128 v[214:217], v172 offset:7168
	global_load_lds_dwordx4 v160, s[62:63]
	s_mov_b32 m0, s11
	s_nop 0
	global_load_lds_dwordx4 v162, s[62:63]
	s_waitcnt vmcnt(8)
	s_waitcnt lgkmcnt(0)
	s_setprio 1
	s_barrier
	v_mfma_f32_16x16x32_bf16 v[126:129], v[134:137], v[186:189], v[126:129]
	v_mfma_f32_16x16x32_bf16 v[122:125], v[142:145], v[186:189], v[122:125]
	v_mfma_f32_16x16x32_bf16 v[118:121], v[134:137], v[194:197], v[118:121]
	v_mfma_f32_16x16x32_bf16 v[114:117], v[142:145], v[194:197], v[114:117]
	v_mfma_f32_16x16x32_bf16 v[110:113], v[134:137], v[202:205], v[110:113]
	v_mfma_f32_16x16x32_bf16 v[106:109], v[142:145], v[202:205], v[106:109]
	v_mfma_f32_16x16x32_bf16 v[102:105], v[134:137], v[210:213], v[102:105]
	v_mfma_f32_16x16x32_bf16 v[98:101], v[142:145], v[210:213], v[98:101]
	v_mfma_f32_16x16x32_bf16 v[126:129], v[138:141], v[190:193], v[126:129]
	v_mfma_f32_16x16x32_bf16 v[122:125], v[146:149], v[190:193], v[122:125]
	v_mfma_f32_16x16x32_bf16 v[118:121], v[138:141], v[198:201], v[118:121]
	v_mfma_f32_16x16x32_bf16 v[114:117], v[146:149], v[198:201], v[114:117]
	v_mfma_f32_16x16x32_bf16 v[110:113], v[138:141], v[206:209], v[110:113]
	v_mfma_f32_16x16x32_bf16 v[106:109], v[146:149], v[206:209], v[106:109]
	v_mfma_f32_16x16x32_bf16 v[102:105], v[138:141], v[214:217], v[102:105]
	v_mfma_f32_16x16x32_bf16 v[98:101], v[146:149], v[214:217], v[98:101]
	s_setprio 0
	s_setprio 1
	v_mfma_f32_16x16x32_bf16 v[94:97], v[168:171], v[186:189], v[94:97]
	v_mfma_f32_16x16x32_bf16 v[90:93], v[178:181], v[186:189], v[90:93]
	v_mfma_f32_16x16x32_bf16 v[86:89], v[168:171], v[194:197], v[86:89]
	v_mfma_f32_16x16x32_bf16 v[82:85], v[178:181], v[194:197], v[82:85]
	v_mfma_f32_16x16x32_bf16 v[78:81], v[168:171], v[202:205], v[78:81]
	v_mfma_f32_16x16x32_bf16 v[74:77], v[178:181], v[202:205], v[74:77]
	v_mfma_f32_16x16x32_bf16 v[70:73], v[168:171], v[210:213], v[70:73]
	v_mfma_f32_16x16x32_bf16 v[66:69], v[178:181], v[210:213], v[66:69]
	v_mfma_f32_16x16x32_bf16 v[94:97], v[174:177], v[190:193], v[94:97]
	v_mfma_f32_16x16x32_bf16 v[90:93], v[182:185], v[190:193], v[90:93]
	v_mfma_f32_16x16x32_bf16 v[86:89], v[174:177], v[198:201], v[86:89]
	v_mfma_f32_16x16x32_bf16 v[82:85], v[182:185], v[198:201], v[82:85]
	v_mfma_f32_16x16x32_bf16 v[78:81], v[174:177], v[206:209], v[78:81]
	v_mfma_f32_16x16x32_bf16 v[74:77], v[182:185], v[206:209], v[74:77]
	v_mfma_f32_16x16x32_bf16 v[70:73], v[174:177], v[214:217], v[70:73]
	v_mfma_f32_16x16x32_bf16 v[66:69], v[182:185], v[214:217], v[66:69]
	s_barrier
	s_setprio 0
	s_mov_b32 m0, s12
	s_mov_b64 s[98:99], s[50:51]
	s_add_u32 s58, s50, 0x80000
	ds_read_b128 v[186:189], v172 offset:16384
	ds_read_b128 v[190:193], v172 offset:17408
	ds_read_b128 v[194:197], v172 offset:18432
	ds_read_b128 v[198:201], v172 offset:19456
	ds_read_b128 v[202:205], v172 offset:20480
	ds_read_b128 v[206:209], v172 offset:21504
	ds_read_b128 v[210:213], v172 offset:22528
	ds_read_b128 v[214:217], v172 offset:23552
	global_load_lds_dwordx4 v152, s[50:51]
	s_mov_b32 m0, s13
	s_addc_u32 s59, s51, 0
	global_load_lds_dwordx4 v156, s[50:51]
	s_mov_b32 m0, s43
	s_mov_b64 s[100:101], s[64:65]
	global_load_lds_dwordx4 v152, s[58:59]
	s_mov_b32 m0, s46
	s_nop 0
	global_load_lds_dwordx4 v156, s[58:59]
	s_mov_b32 m0, s69
	s_nop 0
	global_load_lds_dwordx4 v150, s[64:65]
	s_mov_b32 m0, s70
	s_nop 0
	global_load_lds_dwordx4 v154, s[64:65]
	s_waitcnt vmcnt(8)
	s_waitcnt lgkmcnt(0)
	s_setprio 1
	s_barrier
	v_mfma_f32_16x16x32_bf16 v[62:65], v[134:137], v[186:189], v[62:65]
	v_mfma_f32_16x16x32_bf16 v[58:61], v[142:145], v[186:189], v[58:61]
	v_mfma_f32_16x16x32_bf16 v[54:57], v[134:137], v[194:197], v[54:57]
	v_mfma_f32_16x16x32_bf16 v[50:53], v[142:145], v[194:197], v[50:53]
	v_mfma_f32_16x16x32_bf16 v[46:49], v[134:137], v[202:205], v[46:49]
	v_mfma_f32_16x16x32_bf16 v[42:45], v[142:145], v[202:205], v[42:45]
	v_mfma_f32_16x16x32_bf16 v[38:41], v[134:137], v[210:213], v[38:41]
	v_mfma_f32_16x16x32_bf16 v[34:37], v[142:145], v[210:213], v[34:37]
	v_mfma_f32_16x16x32_bf16 v[62:65], v[138:141], v[190:193], v[62:65]
	v_mfma_f32_16x16x32_bf16 v[58:61], v[146:149], v[190:193], v[58:61]
	v_mfma_f32_16x16x32_bf16 v[54:57], v[138:141], v[198:201], v[54:57]
	v_mfma_f32_16x16x32_bf16 v[50:53], v[146:149], v[198:201], v[50:53]
	v_mfma_f32_16x16x32_bf16 v[46:49], v[138:141], v[206:209], v[46:49]
	v_mfma_f32_16x16x32_bf16 v[42:45], v[146:149], v[206:209], v[42:45]
	v_mfma_f32_16x16x32_bf16 v[38:41], v[138:141], v[214:217], v[38:41]
	v_mfma_f32_16x16x32_bf16 v[34:37], v[146:149], v[214:217], v[34:37]
	s_setprio 0
	s_setprio 1
	v_mfma_f32_16x16x32_bf16 v[30:33], v[168:171], v[186:189], v[30:33]
	v_mfma_f32_16x16x32_bf16 v[26:29], v[178:181], v[186:189], v[26:29]
	v_mfma_f32_16x16x32_bf16 v[22:25], v[168:171], v[194:197], v[22:25]
	v_mfma_f32_16x16x32_bf16 v[18:21], v[178:181], v[194:197], v[18:21]
	v_mfma_f32_16x16x32_bf16 v[14:17], v[168:171], v[202:205], v[14:17]
	v_mfma_f32_16x16x32_bf16 v[10:13], v[178:181], v[202:205], v[10:13]
	v_mfma_f32_16x16x32_bf16 v[6:9], v[168:171], v[210:213], v[6:9]
	v_mfma_f32_16x16x32_bf16 v[2:5], v[178:181], v[210:213], v[2:5]
	v_mfma_f32_16x16x32_bf16 v[30:33], v[174:177], v[190:193], v[30:33]
	v_mfma_f32_16x16x32_bf16 v[26:29], v[182:185], v[190:193], v[26:29]
	v_mfma_f32_16x16x32_bf16 v[22:25], v[174:177], v[198:201], v[22:25]
	v_mfma_f32_16x16x32_bf16 v[18:21], v[182:185], v[198:201], v[18:21]
	v_mfma_f32_16x16x32_bf16 v[14:17], v[174:177], v[206:209], v[14:17]
	v_mfma_f32_16x16x32_bf16 v[10:13], v[182:185], v[206:209], v[10:13]
	v_mfma_f32_16x16x32_bf16 v[6:9], v[174:177], v[214:217], v[6:9]
	v_mfma_f32_16x16x32_bf16 v[2:5], v[182:185], v[214:217], v[2:5]
	s_barrier
; #define PG8_BAR __builtin_amdgcn_s_barrier()
;     ...
;         for (int t = 2; t < nt; t += 2) PG8_KITER(t);
;         if constexpr (ALIGN_EPI) { if (wr == 0) PG8_BAR; }
	s_setprio 0
	ds_read_b128 v[134:137], v132
	ds_read_b128 v[138:141], v132 offset:1024
	ds_read_b128 v[142:145], v132 offset:2048
	ds_read_b128 v[146:149], v132 offset:3072
	ds_read_b128 v[168:171], v133
	ds_read_b128 v[174:177], v133 offset:1024
	ds_read_b128 v[178:181], v133 offset:2048
	ds_read_b128 v[182:185], v133 offset:3072
	s_add_u32 s58, s64, 0x80000
	s_addc_u32 s59, s65, 0
	s_mov_b32 m0, s71
	ds_read_b128 v[186:189], v172 offset:32768
	ds_read_b128 v[190:193], v172 offset:33792
	ds_read_b128 v[194:197], v172 offset:34816
	ds_read_b128 v[198:201], v172 offset:35840
	ds_read_b128 v[202:205], v172 offset:36864
	ds_read_b128 v[206:209], v172 offset:37888
	ds_read_b128 v[210:213], v172 offset:38912
	ds_read_b128 v[214:217], v172 offset:39936
	global_load_lds_dwordx4 v150, s[58:59]
	s_mov_b32 m0, s72
	s_nop 0
	global_load_lds_dwordx4 v154, s[58:59]
	s_waitcnt vmcnt(8)
	s_waitcnt lgkmcnt(0)
	s_setprio 1
	s_barrier
	v_mfma_f32_16x16x32_bf16 v[126:129], v[134:137], v[186:189], v[126:129]
	v_mfma_f32_16x16x32_bf16 v[122:125], v[142:145], v[186:189], v[122:125]
	v_mfma_f32_16x16x32_bf16 v[118:121], v[134:137], v[194:197], v[118:121]
	v_mfma_f32_16x16x32_bf16 v[114:117], v[142:145], v[194:197], v[114:117]
	v_mfma_f32_16x16x32_bf16 v[110:113], v[134:137], v[202:205], v[110:113]
	v_mfma_f32_16x16x32_bf16 v[106:109], v[142:145], v[202:205], v[106:109]
	v_mfma_f32_16x16x32_bf16 v[102:105], v[134:137], v[210:213], v[102:105]
	v_mfma_f32_16x16x32_bf16 v[98:101], v[142:145], v[210:213], v[98:101]
	v_mfma_f32_16x16x32_bf16 v[126:129], v[138:141], v[190:193], v[126:129]
	v_mfma_f32_16x16x32_bf16 v[122:125], v[146:149], v[190:193], v[122:125]
	v_mfma_f32_16x16x32_bf16 v[118:121], v[138:141], v[198:201], v[118:121]
	v_mfma_f32_16x16x32_bf16 v[114:117], v[146:149], v[198:201], v[114:117]
	v_mfma_f32_16x16x32_bf16 v[110:113], v[138:141], v[206:209], v[110:113]
	v_mfma_f32_16x16x32_bf16 v[106:109], v[146:149], v[206:209], v[106:109]
	v_mfma_f32_16x16x32_bf16 v[102:105], v[138:141], v[214:217], v[102:105]
	v_mfma_f32_16x16x32_bf16 v[98:101], v[146:149], v[214:217], v[98:101]
	s_setprio 0
	s_setprio 1
	v_mfma_f32_16x16x32_bf16 v[94:97], v[168:171], v[186:189], v[94:97]
	v_mfma_f32_16x16x32_bf16 v[90:93], v[178:181], v[186:189], v[90:93]
	v_mfma_f32_16x16x32_bf16 v[86:89], v[168:171], v[194:197], v[86:89]
	v_mfma_f32_16x16x32_bf16 v[82:85], v[178:181], v[194:197], v[82:85]
	v_mfma_f32_16x16x32_bf16 v[78:81], v[168:171], v[202:205], v[78:81]
	v_mfma_f32_16x16x32_bf16 v[74:77], v[178:181], v[202:205], v[74:77]
	v_mfma_f32_16x16x32_bf16 v[70:73], v[168:171], v[210:213], v[70:73]
	v_mfma_f32_16x16x32_bf16 v[66:69], v[178:181], v[210:213], v[66:69]
	v_mfma_f32_16x16x32_bf16 v[94:97], v[174:177], v[190:193], v[94:97]
	v_mfma_f32_16x16x32_bf16 v[90:93], v[182:185], v[190:193], v[90:93]
	v_mfma_f32_16x16x32_bf16 v[86:89], v[174:177], v[198:201], v[86:89]
	v_mfma_f32_16x16x32_bf16 v[82:85], v[182:185], v[198:201], v[82:85]
	v_mfma_f32_16x16x32_bf16 v[78:81], v[174:177], v[206:209], v[78:81]
	v_mfma_f32_16x16x32_bf16 v[74:77], v[182:185], v[206:209], v[74:77]
	v_mfma_f32_16x16x32_bf16 v[70:73], v[174:177], v[214:217], v[70:73]
	v_mfma_f32_16x16x32_bf16 v[66:69], v[182:185], v[214:217], v[66:69]
	s_barrier
	s_setprio 0
	s_mov_b32 m0, s47
	s_add_u32 s98, s98, 0x80
	s_addc_u32 s99, s99, 0
	s_add_u32 s100, s100, 0x80
	s_addc_u32 s101, s101, 0
	s_add_u32 s50, s50, 0x80080
	ds_read_b128 v[186:189], v172 offset:49152
	ds_read_b128 v[190:193], v172 offset:50176
	ds_read_b128 v[194:197], v172 offset:51200
	ds_read_b128 v[198:201], v172 offset:52224
	ds_read_b128 v[202:205], v172 offset:53248
	ds_read_b128 v[206:209], v172 offset:54272
	ds_read_b128 v[210:213], v172 offset:55296
	ds_read_b128 v[214:217], v172 offset:56320
	global_load_lds_dwordx4 v152, s[98:99]
	s_mov_b32 m0, s53
	s_addc_u32 s51, s51, 0
	global_load_lds_dwordx4 v156, s[98:99]
	s_mov_b32 m0, s55
	s_nop 0
	global_load_lds_dwordx4 v152, s[50:51]
	s_mov_b32 m0, s56
	s_nop 0
	global_load_lds_dwordx4 v156, s[50:51]
	s_mov_b32 m0, s77
	s_nop 0
	global_load_lds_dwordx4 v150, s[100:101]
	s_mov_b32 m0, s78
	s_nop 0
	global_load_lds_dwordx4 v154, s[100:101]
	s_waitcnt vmcnt(8)
	s_waitcnt lgkmcnt(0)
	s_setprio 1
	s_barrier
	v_mfma_f32_16x16x32_bf16 v[62:65], v[134:137], v[186:189], v[62:65]
	v_mfma_f32_16x16x32_bf16 v[58:61], v[142:145], v[186:189], v[58:61]
	v_mfma_f32_16x16x32_bf16 v[54:57], v[134:137], v[194:197], v[54:57]
	v_mfma_f32_16x16x32_bf16 v[50:53], v[142:145], v[194:197], v[50:53]
	v_mfma_f32_16x16x32_bf16 v[46:49], v[134:137], v[202:205], v[46:49]
	v_mfma_f32_16x16x32_bf16 v[42:45], v[142:145], v[202:205], v[42:45]
	v_mfma_f32_16x16x32_bf16 v[38:41], v[134:137], v[210:213], v[38:41]
	v_mfma_f32_16x16x32_bf16 v[34:37], v[142:145], v[210:213], v[34:37]
	v_mfma_f32_16x16x32_bf16 v[62:65], v[138:141], v[190:193], v[62:65]
	v_mfma_f32_16x16x32_bf16 v[58:61], v[146:149], v[190:193], v[58:61]
	v_mfma_f32_16x16x32_bf16 v[54:57], v[138:141], v[198:201], v[54:57]
	v_mfma_f32_16x16x32_bf16 v[50:53], v[146:149], v[198:201], v[50:53]
	v_mfma_f32_16x16x32_bf16 v[46:49], v[138:141], v[206:209], v[46:49]
	v_mfma_f32_16x16x32_bf16 v[42:45], v[146:149], v[206:209], v[42:45]
	v_mfma_f32_16x16x32_bf16 v[38:41], v[138:141], v[214:217], v[38:41]
	v_mfma_f32_16x16x32_bf16 v[34:37], v[146:149], v[214:217], v[34:37]
	s_setprio 0
	s_setprio 1
	v_mfma_f32_16x16x32_bf16 v[30:33], v[168:171], v[186:189], v[30:33]
	v_mfma_f32_16x16x32_bf16 v[26:29], v[178:181], v[186:189], v[26:29]
	v_mfma_f32_16x16x32_bf16 v[22:25], v[168:171], v[194:197], v[22:25]
	v_mfma_f32_16x16x32_bf16 v[18:21], v[178:181], v[194:197], v[18:21]
	v_mfma_f32_16x16x32_bf16 v[14:17], v[168:171], v[202:205], v[14:17]
	v_mfma_f32_16x16x32_bf16 v[10:13], v[178:181], v[202:205], v[10:13]
	v_mfma_f32_16x16x32_bf16 v[6:9], v[168:171], v[210:213], v[6:9]
	v_mfma_f32_16x16x32_bf16 v[2:5], v[178:181], v[210:213], v[2:5]
	v_mfma_f32_16x16x32_bf16 v[30:33], v[174:177], v[190:193], v[30:33]
	v_mfma_f32_16x16x32_bf16 v[26:29], v[182:185], v[190:193], v[26:29]
	v_mfma_f32_16x16x32_bf16 v[22:25], v[174:177], v[198:201], v[22:25]
	v_mfma_f32_16x16x32_bf16 v[18:21], v[182:185], v[198:201], v[18:21]
	v_mfma_f32_16x16x32_bf16 v[14:17], v[174:177], v[206:209], v[14:17]
	v_mfma_f32_16x16x32_bf16 v[10:13], v[182:185], v[206:209], v[10:13]
	v_mfma_f32_16x16x32_bf16 v[6:9], v[174:177], v[214:217], v[6:9]
	v_mfma_f32_16x16x32_bf16 v[2:5], v[182:185], v[214:217], v[2:5]
	s_barrier
	s_setprio 0
	s_add_i32 s26, s26, 2
	s_add_u32 s62, s62, 0x100
	s_addc_u32 s63, s63, 0
	s_add_u32 s14, s14, 0x100
	s_addc_u32 s15, s15, 0
	s_cmp_gt_u32 s26, 29
	s_cbranch_scc0 .LBB0_930
	s_and_b64 vcc, exec, s[18:19]
	s_cbranch_vccz .LBB0_933
	s_barrier

;     __host__ __device__ bool next(int i, Unit& u) const { if (!StaticOrder::next(i >> 1, u)) return false; u.seg = i & 1; return true; }
;     ...
;         const bool has_next = S.next(ui + 1, nxt);
;         const char* nA = has_next ? PG8_APTR(nxt) : cA; const char* nB = has_next ? PG8_BPTR(nxt) : cB;
;         const char* pfc = PG8_PFPTR(cA, cB); const char* pfn = PG8_PFPTR(nA, nB);
;         PG8_KITER(0);
.LBB0_1013:
	s_ashr_i32 s29, s28, 31
	ds_read_b128 v[2:5], v182
	ds_read_b128 v[6:9], v182 offset:1024
	ds_read_b128 v[10:13], v182 offset:2048
	ds_read_b128 v[14:17], v182 offset:3072
	ds_read_b128 v[18:21], v183
	ds_read_b128 v[22:25], v183 offset:1024
	ds_read_b128 v[26:29], v183 offset:2048
	ds_read_b128 v[30:33], v183 offset:3072
	s_lshl_b64 s[14:15], s[28:29], 21
	s_add_u32 s30, s24, s14
	s_addc_u32 s31, s25, s15
	s_and_b64 s[14:15], s[4:5], exec
	s_cselect_b32 s29, s31, s49
	s_cselect_b32 s41, s30, s48
	s_and_b32 s0, s66, 0x7fffffff
	s_lshl_b64 s[14:15], s[0:1], 21
	s_add_u32 s38, s10, s14
	s_addc_u32 s39, s11, s15
	s_and_b64 s[14:15], s[4:5], exec
	s_cselect_b32 s0, s39, s43
	s_cselect_b32 s68, s38, s42
	s_add_u32 s14, s48, 0x100080
	s_addc_u32 s15, s49, 0
	s_mov_b32 m0, s61
	v_lshl_add_u64 v[66:67], s[14:15], 0, v[154:155]
	ds_read_b128 v[34:37], v184
	ds_read_b128 v[38:41], v184 offset:1024
	ds_read_b128 v[42:45], v184 offset:2048
	ds_read_b128 v[46:49], v184 offset:3072
	ds_read_b128 v[50:53], v184 offset:4096
	ds_read_b128 v[54:57], v184 offset:5120
	ds_read_b128 v[58:61], v184 offset:6144
	ds_read_b128 v[62:65], v184 offset:7168
	global_load_lds_dwordx4 v[66:67], off
	v_lshl_add_u64 v[66:67], s[14:15], 0, v[158:159]
	s_mov_b32 m0, s62
	s_nop 0
	global_load_lds_dwordx4 v[66:67], off
	s_waitcnt vmcnt(8)
	s_waitcnt lgkmcnt(0)
	s_setprio 1
	s_barrier
	v_mfma_f32_16x16x32_bf16 v[90:93], v[2:5], v[58:61], 0
	v_mfma_f32_16x16x32_bf16 v[66:69], v[2:5], v[34:37], 0
	v_mfma_f32_16x16x32_bf16 v[70:73], v[10:13], v[34:37], 0
	v_mfma_f32_16x16x32_bf16 v[74:77], v[2:5], v[42:45], 0
	v_mfma_f32_16x16x32_bf16 v[78:81], v[10:13], v[42:45], 0
	v_mfma_f32_16x16x32_bf16 v[82:85], v[2:5], v[50:53], 0
	v_mfma_f32_16x16x32_bf16 v[86:89], v[10:13], v[50:53], 0
	v_mfma_f32_16x16x32_bf16 v[98:101], v[6:9], v[62:65], v[90:93]
	v_mfma_f32_16x16x32_bf16 v[90:93], v[10:13], v[58:61], 0
	v_mfma_f32_16x16x32_bf16 v[66:69], v[6:9], v[38:41], v[66:69]
	v_mfma_f32_16x16x32_bf16 v[70:73], v[14:17], v[38:41], v[70:73]
	v_mfma_f32_16x16x32_bf16 v[74:77], v[6:9], v[46:49], v[74:77]
	v_mfma_f32_16x16x32_bf16 v[78:81], v[14:17], v[46:49], v[78:81]
	v_mfma_f32_16x16x32_bf16 v[82:85], v[6:9], v[54:57], v[82:85]
	v_mfma_f32_16x16x32_bf16 v[86:89], v[14:17], v[54:57], v[86:89]
	v_mfma_f32_16x16x32_bf16 v[102:105], v[14:17], v[62:65], v[90:93]
	s_setprio 0
	s_setprio 1
	v_mfma_f32_16x16x32_bf16 v[90:93], v[18:21], v[34:37], 0
	v_mfma_f32_16x16x32_bf16 v[34:37], v[26:29], v[34:37], 0
	v_mfma_f32_16x16x32_bf16 v[114:117], v[22:25], v[38:41], v[90:93]
	v_mfma_f32_16x16x32_bf16 v[34:37], v[30:33], v[38:41], v[34:37]
	v_mfma_f32_16x16x32_bf16 v[38:41], v[18:21], v[42:45], 0
	v_mfma_f32_16x16x32_bf16 v[42:45], v[26:29], v[42:45], 0
	v_mfma_f32_16x16x32_bf16 v[38:41], v[22:25], v[46:49], v[38:41]
	v_mfma_f32_16x16x32_bf16 v[42:45], v[30:33], v[46:49], v[42:45]
	v_mfma_f32_16x16x32_bf16 v[46:49], v[18:21], v[50:53], 0
	v_mfma_f32_16x16x32_bf16 v[50:53], v[26:29], v[50:53], 0
	v_mfma_f32_16x16x32_bf16 v[46:49], v[22:25], v[54:57], v[46:49]
	v_mfma_f32_16x16x32_bf16 v[50:53], v[30:33], v[54:57], v[50:53]
	v_mfma_f32_16x16x32_bf16 v[54:57], v[18:21], v[58:61], 0
	v_mfma_f32_16x16x32_bf16 v[58:61], v[26:29], v[58:61], 0
	v_mfma_f32_16x16x32_bf16 v[54:57], v[22:25], v[62:65], v[54:57]
	v_mfma_f32_16x16x32_bf16 v[58:61], v[30:33], v[62:65], v[58:61]
	s_barrier
	s_setprio 0
	v_lshl_add_u64 v[152:153], s[42:43], 0, v[156:157]
	s_mov_b32 m0, s63
	v_lshl_add_u64 v[130:131], v[152:153], 0, s[20:21]
	v_lshl_add_u64 v[250:251], s[42:43], 0, v[160:161]
	s_add_u32 s14, s42, 0x100100
	ds_read_b128 v[62:65], v184 offset:16384
	ds_read_b128 v[90:93], v184 offset:17408
	ds_read_b128 v[94:97], v184 offset:18432
	ds_read_b128 v[106:109], v184 offset:19456
	ds_read_b128 v[110:113], v184 offset:20480
	ds_read_b128 v[118:121], v184 offset:21504
	ds_read_b128 v[122:125], v184 offset:22528
	ds_read_b128 v[126:129], v184 offset:23552
	global_load_lds_dwordx4 v[130:131], off
	v_lshl_add_u64 v[130:131], v[250:251], 0, s[20:21]
	s_mov_b32 m0, s64
	s_addc_u32 s15, s43, 0
	s_add_i32 s69, s60, s12
	global_load_lds_dwordx4 v[130:131], off
	v_lshl_add_u64 v[130:131], s[14:15], 0, v[156:157]
	s_mov_b32 m0, s69
	s_add_i32 s46, s69, 0x2000
	global_load_lds_dwordx4 v[130:131], off
	v_lshl_add_u64 v[130:131], s[14:15], 0, v[160:161]
	s_mov_b32 m0, s46
	v_lshl_add_u64 v[252:253], s[48:49], 0, v[154:155]
	global_load_lds_dwordx4 v[130:131], off
	v_lshl_add_u64 v[130:131], v[252:253], 0, s[20:21]
	s_mov_b32 m0, s13
	v_lshl_add_u64 v[166:167], s[48:49], 0, v[158:159]
	global_load_lds_dwordx4 v[130:131], off
	v_lshl_add_u64 v[130:131], v[166:167], 0, s[20:21]
	s_mov_b32 m0, s33
	s_nop 0
	global_load_lds_dwordx4 v[130:131], off
	s_waitcnt vmcnt(8)
	s_waitcnt lgkmcnt(0)
	s_setprio 1
	s_barrier
	v_mfma_f32_16x16x32_bf16 v[130:133], v[2:5], v[62:65], 0
	v_mfma_f32_16x16x32_bf16 v[140:143], v[2:5], v[94:97], 0
	v_mfma_f32_16x16x32_bf16 v[148:151], v[2:5], v[110:113], 0
	v_mfma_f32_16x16x32_bf16 v[2:5], v[2:5], v[122:125], 0
	v_mfma_f32_16x16x32_bf16 v[132:135], v[6:9], v[90:93], v[130:133]
	v_mfma_f32_16x16x32_bf16 v[140:143], v[6:9], v[106:109], v[140:143]
	v_mfma_f32_16x16x32_bf16 v[148:151], v[6:9], v[118:121], v[148:151]
	v_mfma_f32_16x16x32_bf16 v[2:5], v[6:9], v[126:129], v[2:5]
	v_mfma_f32_16x16x32_bf16 v[6:9], v[10:13], v[122:125], 0
	v_mfma_f32_16x16x32_bf16 v[136:139], v[10:13], v[62:65], 0
	v_mfma_f32_16x16x32_bf16 v[144:147], v[10:13], v[94:97], 0
	v_mfma_f32_16x16x32_bf16 v[170:173], v[10:13], v[110:113], 0
	v_mfma_f32_16x16x32_bf16 v[6:9], v[14:17], v[126:129], v[6:9]
	v_mfma_f32_16x16x32_bf16 v[136:139], v[14:17], v[90:93], v[136:139]
	v_mfma_f32_16x16x32_bf16 v[144:147], v[14:17], v[106:109], v[144:147]
	v_mfma_f32_16x16x32_bf16 v[170:173], v[14:17], v[118:121], v[170:173]
	s_setprio 0
	s_setprio 1
	v_mfma_f32_16x16x32_bf16 v[10:13], v[18:21], v[62:65], 0
	v_mfma_f32_16x16x32_bf16 v[174:177], v[22:25], v[90:93], v[10:13]
	v_mfma_f32_16x16x32_bf16 v[10:13], v[26:29], v[62:65], 0
	v_mfma_f32_16x16x32_bf16 v[178:181], v[30:33], v[90:93], v[10:13]
	v_mfma_f32_16x16x32_bf16 v[10:13], v[18:21], v[94:97], 0
	v_mfma_f32_16x16x32_bf16 v[186:189], v[22:25], v[106:109], v[10:13]
	v_mfma_f32_16x16x32_bf16 v[10:13], v[26:29], v[94:97], 0
	v_mfma_f32_16x16x32_bf16 v[190:193], v[30:33], v[106:109], v[10:13]
	v_mfma_f32_16x16x32_bf16 v[10:13], v[18:21], v[110:113], 0
	v_mfma_f32_16x16x32_bf16 v[194:197], v[22:25], v[118:121], v[10:13]
	v_mfma_f32_16x16x32_bf16 v[10:13], v[26:29], v[110:113], 0
	v_mfma_f32_16x16x32_bf16 v[198:201], v[30:33], v[118:121], v[10:13]
	v_mfma_f32_16x16x32_bf16 v[10:13], v[18:21], v[122:125], 0
	v_mfma_f32_16x16x32_bf16 v[202:205], v[22:25], v[126:129], v[10:13]
	v_mfma_f32_16x16x32_bf16 v[10:13], v[26:29], v[122:125], 0
	v_mfma_f32_16x16x32_bf16 v[206:209], v[30:33], v[126:129], v[10:13]
	s_barrier
	s_setprio 0
	s_add_i32 s47, 0, 0x18000
	s_add_i32 s56, 0, 0x1c000
	v_add_u32_e32 v130, s47, v1
	v_add_u32_e32 v131, s56, v1
	s_nop 0
	ds_read_b128 v[10:13], v130
	ds_read_b128 v[14:17], v130 offset:1024
	ds_read_b128 v[18:21], v130 offset:2048
	ds_read_b128 v[22:25], v130 offset:3072
	ds_read_b128 v[210:213], v131
	ds_read_b128 v[214:217], v131 offset:1024
	ds_read_b128 v[218:221], v131 offset:2048
	ds_read_b128 v[222:225], v131 offset:3072
	s_add_u32 s14, s48, 0x100100
	s_addc_u32 s15, s49, 0
	s_mov_b32 m0, s52
	v_lshl_add_u64 v[90:91], s[14:15], 0, v[154:155]
	ds_read_b128 v[26:29], v184 offset:32768
	ds_read_b128 v[30:33], v184 offset:33792
	ds_read_b128 v[62:65], v184 offset:34816
	ds_read_b128 v[226:229], v184 offset:35840
	ds_read_b128 v[230:233], v184 offset:36864
	ds_read_b128 v[234:237], v184 offset:37888
	ds_read_b128 v[238:241], v184 offset:38912
	ds_read_b128 v[242:245], v184 offset:39936
	global_load_lds_dwordx4 v[90:91], off
	v_lshl_add_u64 v[90:91], s[14:15], 0, v[158:159]
	s_mov_b32 m0, s53
	s_nop 0
	global_load_lds_dwordx4 v[90:91], off
	s_waitcnt vmcnt(8)
	s_waitcnt lgkmcnt(0)
	s_setprio 1
	s_barrier
	v_mfma_f32_16x16x32_bf16 v[66:69], v[10:13], v[26:29], v[66:69]
	v_mfma_f32_16x16x32_bf16 v[122:125], v[14:17], v[30:33], v[66:69]
	v_mfma_f32_16x16x32_bf16 v[66:69], v[18:21], v[26:29], v[70:73]
	v_mfma_f32_16x16x32_bf16 v[118:121], v[22:25], v[30:33], v[66:69]
	v_mfma_f32_16x16x32_bf16 v[66:69], v[10:13], v[62:65], v[74:77]
	v_mfma_f32_16x16x32_bf16 v[110:113], v[14:17], v[226:229], v[66:69]
	v_mfma_f32_16x16x32_bf16 v[66:69], v[18:21], v[62:65], v[78:81]
	v_mfma_f32_16x16x32_bf16 v[106:109], v[22:25], v[226:229], v[66:69]
	v_mfma_f32_16x16x32_bf16 v[66:69], v[10:13], v[230:233], v[82:85]
	v_mfma_f32_16x16x32_bf16 v[94:97], v[14:17], v[234:237], v[66:69]
	v_mfma_f32_16x16x32_bf16 v[66:69], v[18:21], v[230:233], v[86:89]
	v_mfma_f32_16x16x32_bf16 v[90:93], v[22:25], v[234:237], v[66:69]
	v_mfma_f32_16x16x32_bf16 v[66:69], v[10:13], v[238:241], v[98:101]
	v_mfma_f32_16x16x32_bf16 v[78:81], v[14:17], v[242:245], v[66:69]
	v_mfma_f32_16x16x32_bf16 v[66:69], v[18:21], v[238:241], v[102:105]
	v_mfma_f32_16x16x32_bf16 v[74:77], v[22:25], v[242:245], v[66:69]
	s_setprio 0
	s_setprio 1
	v_mfma_f32_16x16x32_bf16 v[66:69], v[210:213], v[26:29], v[114:117]
	v_mfma_f32_16x16x32_bf16 v[26:29], v[218:221], v[26:29], v[34:37]
	v_mfma_f32_16x16x32_bf16 v[114:117], v[222:225], v[30:33], v[26:29]
	v_mfma_f32_16x16x32_bf16 v[26:29], v[210:213], v[62:65], v[38:41]
	v_mfma_f32_16x16x32_bf16 v[102:105], v[214:217], v[226:229], v[26:29]
	v_mfma_f32_16x16x32_bf16 v[26:29], v[218:221], v[62:65], v[42:45]
	v_mfma_f32_16x16x32_bf16 v[98:101], v[222:225], v[226:229], v[26:29]
	v_mfma_f32_16x16x32_bf16 v[26:29], v[210:213], v[230:233], v[46:49]
	v_mfma_f32_16x16x32_bf16 v[86:89], v[214:217], v[234:237], v[26:29]
	v_mfma_f32_16x16x32_bf16 v[26:29], v[218:221], v[230:233], v[50:53]
	v_mfma_f32_16x16x32_bf16 v[82:85], v[222:225], v[234:237], v[26:29]
	v_mfma_f32_16x16x32_bf16 v[26:29], v[210:213], v[238:241], v[54:57]
	v_mfma_f32_16x16x32_bf16 v[70:73], v[214:217], v[242:245], v[26:29]
	v_mfma_f32_16x16x32_bf16 v[26:29], v[218:221], v[238:241], v[58:61]
	v_mfma_f32_16x16x32_bf16 v[126:129], v[214:217], v[30:33], v[66:69]
	v_mfma_f32_16x16x32_bf16 v[66:69], v[222:225], v[242:245], v[26:29]
	s_barrier
;     __host__ __device__ bool next(int i, Unit& u) const { if (!StaticOrder::next(i >> 1, u)) return false; u.seg = i & 1; return true; }
;     ...
;         const bool has_next = S.next(ui + 1, nxt);
;         const char* nA = has_next ? PG8_APTR(nxt) : cA; const char* nB = has_next ? PG8_BPTR(nxt) : cB;
;         const char* pfc = PG8_PFPTR(cA, cB); const char* pfn = PG8_PFPTR(nA, nB);
;         PG8_KITER(0);
;         for (int t = 2; t < nt; t += 2) PG8_KITER(t);
	s_setprio 0
	s_add_i32 s47, s47, s12
	s_add_i32 s70, s47, 0x2000
	s_nop 1
	v_lshl_add_u64 v[26:27], v[152:153], 0, s[22:23]
	s_mov_b32 m0, s47
	s_add_u32 s14, s42, 0x100180
	ds_read_b128 v[34:37], v184 offset:49152
	ds_read_b128 v[38:41], v184 offset:50176
	ds_read_b128 v[226:229], v184 offset:51200
	ds_read_b128 v[230:233], v184 offset:52224
	ds_read_b128 v[234:237], v184 offset:53248
	ds_read_b128 v[238:241], v184 offset:54272
	ds_read_b128 v[242:245], v184 offset:55296
	ds_read_b128 v[246:249], v184 offset:56320
	global_load_lds_dwordx4 v[26:27], off
	v_lshl_add_u64 v[26:27], v[250:251], 0, s[22:23]
	s_mov_b32 m0, s70
	s_addc_u32 s15, s43, 0
	s_add_i32 s56, s56, s12
	global_load_lds_dwordx4 v[26:27], off
	v_lshl_add_u64 v[26:27], s[14:15], 0, v[156:157]
	s_mov_b32 m0, s56
	s_add_i32 s57, s56, 0x2000
	global_load_lds_dwordx4 v[26:27], off
	v_lshl_add_u64 v[26:27], s[14:15], 0, v[160:161]
	s_mov_b32 m0, s57
	s_nop 0
	global_load_lds_dwordx4 v[26:27], off
	v_lshl_add_u64 v[26:27], v[252:253], 0, s[22:23]
	s_mov_b32 m0, s54
	s_nop 0
	global_load_lds_dwordx4 v[26:27], off
	v_lshl_add_u64 v[26:27], v[166:167], 0, s[22:23]
	s_mov_b32 m0, s55
	s_nop 0
	global_load_lds_dwordx4 v[26:27], off
	s_waitcnt vmcnt(8)
	s_waitcnt lgkmcnt(0)
	s_setprio 1
	s_barrier
	v_mfma_f32_16x16x32_bf16 v[26:29], v[10:13], v[34:37], v[132:135]
	v_mfma_f32_16x16x32_bf16 v[58:61], v[14:17], v[38:41], v[26:29]
	v_mfma_f32_16x16x32_bf16 v[26:29], v[18:21], v[34:37], v[136:139]
	v_mfma_f32_16x16x32_bf16 v[54:57], v[22:25], v[38:41], v[26:29]
	v_mfma_f32_16x16x32_bf16 v[26:29], v[10:13], v[226:229], v[140:143]
	v_mfma_f32_16x16x32_bf16 v[46:49], v[14:17], v[230:233], v[26:29]
	v_mfma_f32_16x16x32_bf16 v[26:29], v[18:21], v[226:229], v[144:147]
	v_mfma_f32_16x16x32_bf16 v[42:45], v[22:25], v[230:233], v[26:29]
	v_mfma_f32_16x16x32_bf16 v[26:29], v[10:13], v[234:237], v[148:151]
	v_mfma_f32_16x16x32_bf16 v[2:5], v[10:13], v[242:245], v[2:5]
	v_mfma_f32_16x16x32_bf16 v[30:33], v[14:17], v[238:241], v[26:29]
	v_mfma_f32_16x16x32_bf16 v[26:29], v[18:21], v[234:237], v[170:173]
	v_mfma_f32_16x16x32_bf16 v[14:17], v[14:17], v[246:249], v[2:5]
	v_mfma_f32_16x16x32_bf16 v[2:5], v[18:21], v[242:245], v[6:9]
	v_mfma_f32_16x16x32_bf16 v[26:29], v[22:25], v[238:241], v[26:29]
	v_mfma_f32_16x16x32_bf16 v[10:13], v[22:25], v[246:249], v[2:5]
	s_setprio 0
	s_setprio 1
	v_mfma_f32_16x16x32_bf16 v[2:5], v[210:213], v[34:37], v[174:177]
	v_mfma_f32_16x16x32_bf16 v[62:65], v[214:217], v[38:41], v[2:5]
	v_mfma_f32_16x16x32_bf16 v[2:5], v[218:221], v[34:37], v[178:181]
	v_mfma_f32_16x16x32_bf16 v[50:53], v[222:225], v[38:41], v[2:5]
	v_mfma_f32_16x16x32_bf16 v[2:5], v[210:213], v[226:229], v[186:189]
	v_mfma_f32_16x16x32_bf16 v[38:41], v[214:217], v[230:233], v[2:5]
	v_mfma_f32_16x16x32_bf16 v[2:5], v[218:221], v[226:229], v[190:193]
	v_mfma_f32_16x16x32_bf16 v[34:37], v[222:225], v[230:233], v[2:5]
	v_mfma_f32_16x16x32_bf16 v[2:5], v[210:213], v[234:237], v[194:197]
	v_mfma_f32_16x16x32_bf16 v[22:25], v[214:217], v[238:241], v[2:5]
	v_mfma_f32_16x16x32_bf16 v[2:5], v[218:221], v[234:237], v[198:201]
	v_mfma_f32_16x16x32_bf16 v[18:21], v[222:225], v[238:241], v[2:5]
	v_mfma_f32_16x16x32_bf16 v[2:5], v[210:213], v[242:245], v[202:205]
	v_mfma_f32_16x16x32_bf16 v[6:9], v[214:217], v[246:249], v[2:5]
	v_mfma_f32_16x16x32_bf16 v[2:5], v[218:221], v[242:245], v[206:209]
	v_mfma_f32_16x16x32_bf16 v[2:5], v[222:225], v[246:249], v[2:5]
	s_barrier
	s_setprio 0
	s_add_u32 s48, s48, 0x100180
	s_addc_u32 s49, s49, 0
	s_add_u32 s14, s42, 0x200
	s_addc_u32 s15, s43, 0
	s_mov_b32 s26, 0
.LBB0_1014:
	ds_read_b128 v[132:135], v182
	ds_read_b128 v[136:139], v182 offset:1024
	ds_read_b128 v[140:143], v182 offset:2048
	ds_read_b128 v[144:147], v182 offset:3072
	ds_read_b128 v[148:151], v183
	ds_read_b128 v[170:173], v183 offset:1024
	ds_read_b128 v[174:177], v183 offset:2048
	ds_read_b128 v[178:181], v183 offset:3072
	s_add_u32 s27, s48, 0xfff00080
	s_addc_u32 s42, s49, -1
	s_cmp_eq_u32 s26, 60
	s_cselect_b32 s51, s29, s42
	s_cselect_b32 s50, s41, s27
	s_cselect_b32 s43, s0, s15
	s_cselect_b32 s42, s68, s14
	s_mov_b32 m0, s61
	ds_read_b128 v[186:189], v184
	ds_read_b128 v[190:193], v184 offset:1024
	ds_read_b128 v[194:197], v184 offset:2048
	ds_read_b128 v[198:201], v184 offset:3072
	ds_read_b128 v[202:205], v184 offset:4096
	ds_read_b128 v[206:209], v184 offset:5120
	ds_read_b128 v[210:213], v184 offset:6144
	ds_read_b128 v[214:217], v184 offset:7168
	global_load_lds_dwordx4 v162, s[48:49]
	s_mov_b32 m0, s62
	s_nop 0
	global_load_lds_dwordx4 v164, s[48:49]
	s_waitcnt vmcnt(8)
	s_waitcnt lgkmcnt(0)
	s_setprio 1
	s_barrier
	v_mfma_f32_16x16x32_bf16 v[122:125], v[132:135], v[186:189], v[122:125]
	v_mfma_f32_16x16x32_bf16 v[118:121], v[140:143], v[186:189], v[118:121]
	v_mfma_f32_16x16x32_bf16 v[110:113], v[132:135], v[194:197], v[110:113]
	v_mfma_f32_16x16x32_bf16 v[106:109], v[140:143], v[194:197], v[106:109]
	v_mfma_f32_16x16x32_bf16 v[94:97], v[132:135], v[202:205], v[94:97]
	v_mfma_f32_16x16x32_bf16 v[90:93], v[140:143], v[202:205], v[90:93]
	v_mfma_f32_16x16x32_bf16 v[78:81], v[132:135], v[210:213], v[78:81]
	v_mfma_f32_16x16x32_bf16 v[74:77], v[140:143], v[210:213], v[74:77]
	v_mfma_f32_16x16x32_bf16 v[122:125], v[136:139], v[190:193], v[122:125]
	v_mfma_f32_16x16x32_bf16 v[118:121], v[144:147], v[190:193], v[118:121]
	v_mfma_f32_16x16x32_bf16 v[110:113], v[136:139], v[198:201], v[110:113]
	v_mfma_f32_16x16x32_bf16 v[106:109], v[144:147], v[198:201], v[106:109]
	v_mfma_f32_16x16x32_bf16 v[94:97], v[136:139], v[206:209], v[94:97]
	v_mfma_f32_16x16x32_bf16 v[90:93], v[144:147], v[206:209], v[90:93]
	v_mfma_f32_16x16x32_bf16 v[78:81], v[136:139], v[214:217], v[78:81]
	v_mfma_f32_16x16x32_bf16 v[74:77], v[144:147], v[214:217], v[74:77]
	s_setprio 0
	s_setprio 1
	v_mfma_f32_16x16x32_bf16 v[126:129], v[148:151], v[186:189], v[126:129]
	v_mfma_f32_16x16x32_bf16 v[114:117], v[174:177], v[186:189], v[114:117]
	v_mfma_f32_16x16x32_bf16 v[102:105], v[148:151], v[194:197], v[102:105]
	v_mfma_f32_16x16x32_bf16 v[98:101], v[174:177], v[194:197], v[98:101]
	v_mfma_f32_16x16x32_bf16 v[86:89], v[148:151], v[202:205], v[86:89]
	v_mfma_f32_16x16x32_bf16 v[82:85], v[174:177], v[202:205], v[82:85]
	v_mfma_f32_16x16x32_bf16 v[70:73], v[148:151], v[210:213], v[70:73]
	v_mfma_f32_16x16x32_bf16 v[66:69], v[174:177], v[210:213], v[66:69]
	v_mfma_f32_16x16x32_bf16 v[126:129], v[170:173], v[190:193], v[126:129]
	v_mfma_f32_16x16x32_bf16 v[114:117], v[178:181], v[190:193], v[114:117]
	v_mfma_f32_16x16x32_bf16 v[102:105], v[170:173], v[198:201], v[102:105]
	v_mfma_f32_16x16x32_bf16 v[98:101], v[178:181], v[198:201], v[98:101]
	v_mfma_f32_16x16x32_bf16 v[86:89], v[170:173], v[206:209], v[86:89]
	v_mfma_f32_16x16x32_bf16 v[82:85], v[178:181], v[206:209], v[82:85]
	v_mfma_f32_16x16x32_bf16 v[70:73], v[170:173], v[214:217], v[70:73]
	v_mfma_f32_16x16x32_bf16 v[66:69], v[178:181], v[214:217], v[66:69]
	s_barrier
	s_setprio 0
	s_mov_b32 m0, s63
	s_mov_b64 s[98:99], s[42:43]
	s_add_u32 s72, s42, 0x100000
	ds_read_b128 v[186:189], v184 offset:16384
	ds_read_b128 v[190:193], v184 offset:17408
	ds_read_b128 v[194:197], v184 offset:18432
	ds_read_b128 v[198:201], v184 offset:19456
	ds_read_b128 v[202:205], v184 offset:20480
	ds_read_b128 v[206:209], v184 offset:21504
	ds_read_b128 v[210:213], v184 offset:22528
	ds_read_b128 v[214:217], v184 offset:23552
	global_load_lds_dwordx4 v156, s[42:43]
	s_mov_b32 m0, s64
	s_addc_u32 s73, s43, 0
	global_load_lds_dwordx4 v160, s[42:43]
	s_mov_b32 m0, s69
	s_mov_b64 s[100:101], s[50:51]
	global_load_lds_dwordx4 v156, s[72:73]
	s_mov_b32 m0, s46
	s_nop 0
	global_load_lds_dwordx4 v160, s[72:73]
	s_mov_b32 m0, s13
	s_nop 0
	global_load_lds_dwordx4 v154, s[50:51]
	s_mov_b32 m0, s33
	s_nop 0
	global_load_lds_dwordx4 v158, s[50:51]
	s_waitcnt vmcnt(8)
	s_waitcnt lgkmcnt(0)
	s_setprio 1
	s_barrier
	v_mfma_f32_16x16x32_bf16 v[58:61], v[132:135], v[186:189], v[58:61]
	v_mfma_f32_16x16x32_bf16 v[54:57], v[140:143], v[186:189], v[54:57]
	v_mfma_f32_16x16x32_bf16 v[46:49], v[132:135], v[194:197], v[46:49]
	v_mfma_f32_16x16x32_bf16 v[42:45], v[140:143], v[194:197], v[42:45]
	v_mfma_f32_16x16x32_bf16 v[30:33], v[132:135], v[202:205], v[30:33]
	v_mfma_f32_16x16x32_bf16 v[26:29], v[140:143], v[202:205], v[26:29]
	v_mfma_f32_16x16x32_bf16 v[14:17], v[132:135], v[210:213], v[14:17]
	v_mfma_f32_16x16x32_bf16 v[10:13], v[140:143], v[210:213], v[10:13]
	v_mfma_f32_16x16x32_bf16 v[58:61], v[136:139], v[190:193], v[58:61]
	v_mfma_f32_16x16x32_bf16 v[54:57], v[144:147], v[190:193], v[54:57]
	v_mfma_f32_16x16x32_bf16 v[46:49], v[136:139], v[198:201], v[46:49]
	v_mfma_f32_16x16x32_bf16 v[42:45], v[144:147], v[198:201], v[42:45]
	v_mfma_f32_16x16x32_bf16 v[30:33], v[136:139], v[206:209], v[30:33]
	v_mfma_f32_16x16x32_bf16 v[26:29], v[144:147], v[206:209], v[26:29]
	v_mfma_f32_16x16x32_bf16 v[14:17], v[136:139], v[214:217], v[14:17]
	v_mfma_f32_16x16x32_bf16 v[10:13], v[144:147], v[214:217], v[10:13]
	s_setprio 0
	s_setprio 1
	v_mfma_f32_16x16x32_bf16 v[62:65], v[148:151], v[186:189], v[62:65]
	v_mfma_f32_16x16x32_bf16 v[50:53], v[174:177], v[186:189], v[50:53]
	v_mfma_f32_16x16x32_bf16 v[38:41], v[148:151], v[194:197], v[38:41]
	v_mfma_f32_16x16x32_bf16 v[34:37], v[174:177], v[194:197], v[34:37]
	v_mfma_f32_16x16x32_bf16 v[22:25], v[148:151], v[202:205], v[22:25]
	v_mfma_f32_16x16x32_bf16 v[18:21], v[174:177], v[202:205], v[18:21]
	v_mfma_f32_16x16x32_bf16 v[6:9], v[148:151], v[210:213], v[6:9]
	v_mfma_f32_16x16x32_bf16 v[2:5], v[174:177], v[210:213], v[2:5]
	v_mfma_f32_16x16x32_bf16 v[62:65], v[170:173], v[190:193], v[62:65]
	v_mfma_f32_16x16x32_bf16 v[50:53], v[178:181], v[190:193], v[50:53]
	v_mfma_f32_16x16x32_bf16 v[38:41], v[170:173], v[198:201], v[38:41]
	v_mfma_f32_16x16x32_bf16 v[34:37], v[178:181], v[198:201], v[34:37]
	v_mfma_f32_16x16x32_bf16 v[22:25], v[170:173], v[206:209], v[22:25]
	v_mfma_f32_16x16x32_bf16 v[18:21], v[178:181], v[206:209], v[18:21]
	v_mfma_f32_16x16x32_bf16 v[6:9], v[170:173], v[214:217], v[6:9]
	v_mfma_f32_16x16x32_bf16 v[2:5], v[178:181], v[214:217], v[2:5]
	s_barrier
; #define PG8_BAR __builtin_amdgcn_s_barrier()
;     ...
;         for (int t = 2; t < nt; t += 2) PG8_KITER(t);
;         if constexpr (ALIGN_EPI) { if (wr == 0) PG8_BAR; }
	s_setprio 0
	ds_read_b128 v[132:135], v130
	ds_read_b128 v[136:139], v130 offset:1024
	ds_read_b128 v[140:143], v130 offset:2048
	ds_read_b128 v[144:147], v130 offset:3072
	ds_read_b128 v[148:151], v131
	ds_read_b128 v[170:173], v131 offset:1024
	ds_read_b128 v[174:177], v131 offset:2048
	ds_read_b128 v[178:181], v131 offset:3072
	s_add_u32 s50, s50, 0x100000
	s_addc_u32 s51, s51, 0
	s_mov_b32 m0, s52
	ds_read_b128 v[186:189], v184 offset:32768
	ds_read_b128 v[190:193], v184 offset:33792
	ds_read_b128 v[194:197], v184 offset:34816
	ds_read_b128 v[198:201], v184 offset:35840
	ds_read_b128 v[202:205], v184 offset:36864
	ds_read_b128 v[206:209], v184 offset:37888
	ds_read_b128 v[210:213], v184 offset:38912
	ds_read_b128 v[214:217], v184 offset:39936
	global_load_lds_dwordx4 v154, s[50:51]
	s_mov_b32 m0, s53
	s_nop 0
	global_load_lds_dwordx4 v158, s[50:51]
	s_waitcnt vmcnt(8)
	s_waitcnt lgkmcnt(0)
	s_setprio 1
	s_barrier
	v_mfma_f32_16x16x32_bf16 v[122:125], v[132:135], v[186:189], v[122:125]
	v_mfma_f32_16x16x32_bf16 v[118:121], v[140:143], v[186:189], v[118:121]
	v_mfma_f32_16x16x32_bf16 v[110:113], v[132:135], v[194:197], v[110:113]
	v_mfma_f32_16x16x32_bf16 v[106:109], v[140:143], v[194:197], v[106:109]
	v_mfma_f32_16x16x32_bf16 v[94:97], v[132:135], v[202:205], v[94:97]
	v_mfma_f32_16x16x32_bf16 v[90:93], v[140:143], v[202:205], v[90:93]
	v_mfma_f32_16x16x32_bf16 v[78:81], v[132:135], v[210:213], v[78:81]
	v_mfma_f32_16x16x32_bf16 v[74:77], v[140:143], v[210:213], v[74:77]
	v_mfma_f32_16x16x32_bf16 v[122:125], v[136:139], v[190:193], v[122:125]
	v_mfma_f32_16x16x32_bf16 v[118:121], v[144:147], v[190:193], v[118:121]
	v_mfma_f32_16x16x32_bf16 v[110:113], v[136:139], v[198:201], v[110:113]
	v_mfma_f32_16x16x32_bf16 v[106:109], v[144:147], v[198:201], v[106:109]
	v_mfma_f32_16x16x32_bf16 v[94:97], v[136:139], v[206:209], v[94:97]
	v_mfma_f32_16x16x32_bf16 v[90:93], v[144:147], v[206:209], v[90:93]
	v_mfma_f32_16x16x32_bf16 v[78:81], v[136:139], v[214:217], v[78:81]
	v_mfma_f32_16x16x32_bf16 v[74:77], v[144:147], v[214:217], v[74:77]
	s_setprio 0
	s_setprio 1
	v_mfma_f32_16x16x32_bf16 v[126:129], v[148:151], v[186:189], v[126:129]
	v_mfma_f32_16x16x32_bf16 v[114:117], v[174:177], v[186:189], v[114:117]
	v_mfma_f32_16x16x32_bf16 v[102:105], v[148:151], v[194:197], v[102:105]
	v_mfma_f32_16x16x32_bf16 v[98:101], v[174:177], v[194:197], v[98:101]
	v_mfma_f32_16x16x32_bf16 v[86:89], v[148:151], v[202:205], v[86:89]
	v_mfma_f32_16x16x32_bf16 v[82:85], v[174:177], v[202:205], v[82:85]
	v_mfma_f32_16x16x32_bf16 v[70:73], v[148:151], v[210:213], v[70:73]
	v_mfma_f32_16x16x32_bf16 v[66:69], v[174:177], v[210:213], v[66:69]
	v_mfma_f32_16x16x32_bf16 v[126:129], v[170:173], v[190:193], v[126:129]
	v_mfma_f32_16x16x32_bf16 v[114:117], v[178:181], v[190:193], v[114:117]
	v_mfma_f32_16x16x32_bf16 v[102:105], v[170:173], v[198:201], v[102:105]
	v_mfma_f32_16x16x32_bf16 v[98:101], v[178:181], v[198:201], v[98:101]
	v_mfma_f32_16x16x32_bf16 v[86:89], v[170:173], v[206:209], v[86:89]
	v_mfma_f32_16x16x32_bf16 v[82:85], v[178:181], v[206:209], v[82:85]
	v_mfma_f32_16x16x32_bf16 v[70:73], v[170:173], v[214:217], v[70:73]
	v_mfma_f32_16x16x32_bf16 v[66:69], v[178:181], v[214:217], v[66:69]
	s_barrier
	s_setprio 0
	s_mov_b32 m0, s47
	s_add_u32 s98, s98, 0x80
	s_addc_u32 s99, s99, 0
	s_add_u32 s100, s100, 0x80
	s_addc_u32 s101, s101, 0
	s_add_u32 s42, s42, 0x100080
	ds_read_b128 v[186:189], v184 offset:49152
	ds_read_b128 v[190:193], v184 offset:50176
	ds_read_b128 v[194:197], v184 offset:51200
	ds_read_b128 v[198:201], v184 offset:52224
	ds_read_b128 v[202:205], v184 offset:53248
	ds_read_b128 v[206:209], v184 offset:54272
	ds_read_b128 v[210:213], v184 offset:55296
	ds_read_b128 v[214:217], v184 offset:56320
	global_load_lds_dwordx4 v156, s[98:99]
	s_mov_b32 m0, s70
	s_addc_u32 s43, s43, 0
	global_load_lds_dwordx4 v160, s[98:99]
	s_mov_b32 m0, s56
	s_nop 0
	global_load_lds_dwordx4 v156, s[42:43]
	s_mov_b32 m0, s57
	s_nop 0
	global_load_lds_dwordx4 v160, s[42:43]
	s_mov_b32 m0, s54
	s_nop 0
	global_load_lds_dwordx4 v154, s[100:101]
	s_mov_b32 m0, s55
	s_nop 0
	global_load_lds_dwordx4 v158, s[100:101]
	s_waitcnt vmcnt(8)
	s_waitcnt lgkmcnt(0)
	s_setprio 1
	s_barrier
	v_mfma_f32_16x16x32_bf16 v[58:61], v[132:135], v[186:189], v[58:61]
	v_mfma_f32_16x16x32_bf16 v[54:57], v[140:143], v[186:189], v[54:57]
	v_mfma_f32_16x16x32_bf16 v[46:49], v[132:135], v[194:197], v[46:49]
	v_mfma_f32_16x16x32_bf16 v[42:45], v[140:143], v[194:197], v[42:45]
	v_mfma_f32_16x16x32_bf16 v[30:33], v[132:135], v[202:205], v[30:33]
	v_mfma_f32_16x16x32_bf16 v[26:29], v[140:143], v[202:205], v[26:29]
	v_mfma_f32_16x16x32_bf16 v[14:17], v[132:135], v[210:213], v[14:17]
	v_mfma_f32_16x16x32_bf16 v[10:13], v[140:143], v[210:213], v[10:13]
	v_mfma_f32_16x16x32_bf16 v[58:61], v[136:139], v[190:193], v[58:61]
	v_mfma_f32_16x16x32_bf16 v[54:57], v[144:147], v[190:193], v[54:57]
	v_mfma_f32_16x16x32_bf16 v[46:49], v[136:139], v[198:201], v[46:49]
	v_mfma_f32_16x16x32_bf16 v[42:45], v[144:147], v[198:201], v[42:45]
	v_mfma_f32_16x16x32_bf16 v[30:33], v[136:139], v[206:209], v[30:33]
	v_mfma_f32_16x16x32_bf16 v[26:29], v[144:147], v[206:209], v[26:29]
	v_mfma_f32_16x16x32_bf16 v[14:17], v[136:139], v[214:217], v[14:17]
	v_mfma_f32_16x16x32_bf16 v[10:13], v[144:147], v[214:217], v[10:13]
	s_setprio 0
	s_setprio 1
	v_mfma_f32_16x16x32_bf16 v[62:65], v[148:151], v[186:189], v[62:65]
	v_mfma_f32_16x16x32_bf16 v[50:53], v[174:177], v[186:189], v[50:53]
	v_mfma_f32_16x16x32_bf16 v[38:41], v[148:151], v[194:197], v[38:41]
	v_mfma_f32_16x16x32_bf16 v[34:37], v[174:177], v[194:197], v[34:37]
	v_mfma_f32_16x16x32_bf16 v[22:25], v[148:151], v[202:205], v[22:25]
	v_mfma_f32_16x16x32_bf16 v[18:21], v[174:177], v[202:205], v[18:21]
	v_mfma_f32_16x16x32_bf16 v[6:9], v[148:151], v[210:213], v[6:9]
	v_mfma_f32_16x16x32_bf16 v[2:5], v[174:177], v[210:213], v[2:5]
	v_mfma_f32_16x16x32_bf16 v[62:65], v[170:173], v[190:193], v[62:65]
	v_mfma_f32_16x16x32_bf16 v[50:53], v[178:181], v[190:193], v[50:53]
	v_mfma_f32_16x16x32_bf16 v[38:41], v[170:173], v[198:201], v[38:41]
	v_mfma_f32_16x16x32_bf16 v[34:37], v[178:181], v[198:201], v[34:37]
	v_mfma_f32_16x16x32_bf16 v[22:25], v[170:173], v[206:209], v[22:25]
	v_mfma_f32_16x16x32_bf16 v[18:21], v[178:181], v[206:209], v[18:21]
	v_mfma_f32_16x16x32_bf16 v[6:9], v[170:173], v[214:217], v[6:9]
	v_mfma_f32_16x16x32_bf16 v[2:5], v[178:181], v[214:217], v[2:5]
	s_barrier
	s_setprio 0
	s_add_i32 s26, s26, 2
	s_add_u32 s48, s48, 0x100
	s_addc_u32 s49, s49, 0
	s_add_u32 s14, s14, 0x100
	s_addc_u32 s15, s15, 0
	s_cmp_gt_u32 s26, 61
	s_cbranch_scc0 .LBB0_1014
	s_and_b64 vcc, exec, s[18:19]
	s_cbranch_vccz .LBB0_1017
	s_barrier

;     __host__ __device__ bool next(int i, Unit& u) const { if (!StaticOrder::next(i >> 1, u)) return false; u.seg = i & 1; return true; }
;     ...
;         const bool has_next = S.next(ui + 1, nxt);
;         const char* nA = has_next ? PG8_APTR(nxt) : cA; const char* nB = has_next ? PG8_BPTR(nxt) : cB;
;         const char* pfc = PG8_PFPTR(cA, cB); const char* pfn = PG8_PFPTR(nA, nB);
;         PG8_KITER(0);
.LBB0_1109:
	ds_read_b128 v[2:5], v148
	ds_read_b128 v[6:9], v148 offset:1024
	ds_read_b128 v[10:13], v148 offset:2048
	ds_read_b128 v[14:17], v148 offset:3072
	ds_read_b128 v[18:21], v149
	ds_read_b128 v[22:25], v149 offset:1024
	ds_read_b128 v[26:29], v149 offset:2048
	ds_read_b128 v[30:33], v149 offset:3072
	s_add_u32 s0, s54, 0x100080
	s_addc_u32 s1, s55, 0
	s_add_i32 s41, s33, 0xc000
	v_lshl_add_u64 v[66:67], s[0:1], 0, v[130:131]
	s_mov_b32 m0, s41
	s_add_i32 s73, s33, 0xe000
	ds_read_b128 v[34:37], v150
	ds_read_b128 v[38:41], v150 offset:1024
	ds_read_b128 v[42:45], v150 offset:2048
	ds_read_b128 v[46:49], v150 offset:3072
	ds_read_b128 v[50:53], v150 offset:4096
	ds_read_b128 v[54:57], v150 offset:5120
	ds_read_b128 v[58:61], v150 offset:6144
	ds_read_b128 v[62:65], v150 offset:7168
	global_load_lds_dwordx4 v[66:67], off
	v_lshl_add_u64 v[66:67], s[0:1], 0, v[132:133]
	s_mov_b32 m0, s73
	s_nop 0
	global_load_lds_dwordx4 v[66:67], off
	s_waitcnt vmcnt(8)
	s_waitcnt lgkmcnt(0)
	s_setprio 1
	s_barrier
	v_mfma_f32_16x16x32_bf16 v[86:89], v[10:13], v[50:53], 0
	v_mfma_f32_16x16x32_bf16 v[90:93], v[14:17], v[54:57], v[86:89]
	v_mfma_f32_16x16x32_bf16 v[86:89], v[2:5], v[58:61], 0
	v_mfma_f32_16x16x32_bf16 v[66:69], v[2:5], v[34:37], 0
	v_mfma_f32_16x16x32_bf16 v[70:73], v[10:13], v[34:37], 0
	v_mfma_f32_16x16x32_bf16 v[74:77], v[2:5], v[42:45], 0
	v_mfma_f32_16x16x32_bf16 v[78:81], v[10:13], v[42:45], 0
	v_mfma_f32_16x16x32_bf16 v[82:85], v[2:5], v[50:53], 0
	v_mfma_f32_16x16x32_bf16 v[94:97], v[6:9], v[62:65], v[86:89]
	v_mfma_f32_16x16x32_bf16 v[86:89], v[10:13], v[58:61], 0
	v_mfma_f32_16x16x32_bf16 v[66:69], v[6:9], v[38:41], v[66:69]
	v_mfma_f32_16x16x32_bf16 v[70:73], v[14:17], v[38:41], v[70:73]
	v_mfma_f32_16x16x32_bf16 v[74:77], v[6:9], v[46:49], v[74:77]
	v_mfma_f32_16x16x32_bf16 v[78:81], v[14:17], v[46:49], v[78:81]
	v_mfma_f32_16x16x32_bf16 v[82:85], v[6:9], v[54:57], v[82:85]
	v_mfma_f32_16x16x32_bf16 v[106:109], v[14:17], v[62:65], v[86:89]
	s_setprio 0
	s_setprio 1
	v_mfma_f32_16x16x32_bf16 v[86:89], v[18:21], v[34:37], 0
	v_mfma_f32_16x16x32_bf16 v[34:37], v[26:29], v[34:37], 0
	v_mfma_f32_16x16x32_bf16 v[110:113], v[22:25], v[38:41], v[86:89]
	v_mfma_f32_16x16x32_bf16 v[34:37], v[30:33], v[38:41], v[34:37]
	v_mfma_f32_16x16x32_bf16 v[38:41], v[18:21], v[42:45], 0
	v_mfma_f32_16x16x32_bf16 v[42:45], v[26:29], v[42:45], 0
	v_mfma_f32_16x16x32_bf16 v[38:41], v[22:25], v[46:49], v[38:41]
	v_mfma_f32_16x16x32_bf16 v[42:45], v[30:33], v[46:49], v[42:45]
	v_mfma_f32_16x16x32_bf16 v[46:49], v[18:21], v[50:53], 0
	v_mfma_f32_16x16x32_bf16 v[50:53], v[26:29], v[50:53], 0
	v_mfma_f32_16x16x32_bf16 v[46:49], v[22:25], v[54:57], v[46:49]
	v_mfma_f32_16x16x32_bf16 v[50:53], v[30:33], v[54:57], v[50:53]
	v_mfma_f32_16x16x32_bf16 v[54:57], v[18:21], v[58:61], 0
	v_mfma_f32_16x16x32_bf16 v[152:155], v[22:25], v[62:65], v[54:57]
	v_mfma_f32_16x16x32_bf16 v[54:57], v[26:29], v[58:61], 0
	v_mfma_f32_16x16x32_bf16 v[58:61], v[30:33], v[62:65], v[54:57]
	s_barrier
	s_setprio 0
	s_add_i32 s74, s64, s13
	v_lshl_add_u64 v[146:147], s[52:53], 0, v[130:131]
	s_add_i32 s75, s74, 0x2000
	v_lshl_add_u64 v[126:127], v[146:147], 0, s[20:21]
	s_mov_b32 m0, s74
	v_lshl_add_u64 v[248:249], s[52:53], 0, v[132:133]
	s_add_u32 s0, s52, 0x100100
	ds_read_b128 v[54:57], v150 offset:16384
	ds_read_b128 v[62:65], v150 offset:17408
	ds_read_b128 v[86:89], v150 offset:18432
	ds_read_b128 v[98:101], v150 offset:19456
	ds_read_b128 v[102:105], v150 offset:20480
	ds_read_b128 v[114:117], v150 offset:21504
	ds_read_b128 v[118:121], v150 offset:22528
	ds_read_b128 v[122:125], v150 offset:23552
	global_load_lds_dwordx4 v[126:127], off
	v_lshl_add_u64 v[126:127], v[248:249], 0, s[20:21]
	s_mov_b32 m0, s75
	s_addc_u32 s1, s53, 0
	s_add_i32 s76, s65, s13
	global_load_lds_dwordx4 v[126:127], off
	v_lshl_add_u64 v[126:127], s[0:1], 0, v[130:131]
	s_mov_b32 m0, s76
	s_add_i32 s46, s76, 0x2000
	global_load_lds_dwordx4 v[126:127], off
	v_lshl_add_u64 v[126:127], s[0:1], 0, v[132:133]
	s_mov_b32 m0, s46
	v_lshl_add_u64 v[250:251], s[54:55], 0, v[130:131]
	global_load_lds_dwordx4 v[126:127], off
	v_lshl_add_u64 v[126:127], v[250:251], 0, s[20:21]
	s_mov_b32 m0, s33
	v_lshl_add_u64 v[252:253], s[54:55], 0, v[132:133]
	global_load_lds_dwordx4 v[126:127], off
	v_lshl_add_u64 v[126:127], v[252:253], 0, s[20:21]
	s_mov_b32 m0, s51
	s_nop 0
	global_load_lds_dwordx4 v[126:127], off
	s_waitcnt vmcnt(8)
	s_waitcnt lgkmcnt(0)
	s_setprio 1
	s_barrier
	v_mfma_f32_16x16x32_bf16 v[126:129], v[2:5], v[54:57], 0
	v_mfma_f32_16x16x32_bf16 v[156:159], v[6:9], v[62:65], v[126:129]
	v_mfma_f32_16x16x32_bf16 v[126:129], v[10:13], v[54:57], 0
	v_mfma_f32_16x16x32_bf16 v[160:163], v[14:17], v[62:65], v[126:129]
	v_mfma_f32_16x16x32_bf16 v[126:129], v[2:5], v[86:89], 0
	v_mfma_f32_16x16x32_bf16 v[164:167], v[6:9], v[98:101], v[126:129]
	v_mfma_f32_16x16x32_bf16 v[126:129], v[10:13], v[86:89], 0
	v_mfma_f32_16x16x32_bf16 v[168:171], v[14:17], v[98:101], v[126:129]
	v_mfma_f32_16x16x32_bf16 v[126:129], v[2:5], v[102:105], 0
	v_mfma_f32_16x16x32_bf16 v[2:5], v[2:5], v[118:121], 0
	v_mfma_f32_16x16x32_bf16 v[172:175], v[6:9], v[114:117], v[126:129]
	v_mfma_f32_16x16x32_bf16 v[2:5], v[6:9], v[122:125], v[2:5]
	v_mfma_f32_16x16x32_bf16 v[6:9], v[10:13], v[118:121], 0
	v_mfma_f32_16x16x32_bf16 v[126:129], v[10:13], v[102:105], 0
	v_mfma_f32_16x16x32_bf16 v[10:13], v[14:17], v[122:125], v[6:9]
	v_mfma_f32_16x16x32_bf16 v[176:179], v[14:17], v[114:117], v[126:129]
	s_setprio 0
	s_setprio 1
	v_mfma_f32_16x16x32_bf16 v[6:9], v[18:21], v[54:57], 0
	v_mfma_f32_16x16x32_bf16 v[14:17], v[22:25], v[62:65], v[6:9]
	v_mfma_f32_16x16x32_bf16 v[6:9], v[26:29], v[54:57], 0
	v_mfma_f32_16x16x32_bf16 v[180:183], v[30:33], v[62:65], v[6:9]
	v_mfma_f32_16x16x32_bf16 v[6:9], v[18:21], v[86:89], 0
	v_mfma_f32_16x16x32_bf16 v[184:187], v[22:25], v[98:101], v[6:9]
	v_mfma_f32_16x16x32_bf16 v[6:9], v[26:29], v[86:89], 0
	v_mfma_f32_16x16x32_bf16 v[188:191], v[30:33], v[98:101], v[6:9]
	v_mfma_f32_16x16x32_bf16 v[6:9], v[18:21], v[102:105], 0
	v_mfma_f32_16x16x32_bf16 v[192:195], v[22:25], v[114:117], v[6:9]
	v_mfma_f32_16x16x32_bf16 v[6:9], v[26:29], v[102:105], 0
	v_mfma_f32_16x16x32_bf16 v[196:199], v[30:33], v[114:117], v[6:9]
	v_mfma_f32_16x16x32_bf16 v[6:9], v[18:21], v[118:121], 0
	v_mfma_f32_16x16x32_bf16 v[200:203], v[22:25], v[122:125], v[6:9]
	v_mfma_f32_16x16x32_bf16 v[6:9], v[26:29], v[118:121], 0
	v_mfma_f32_16x16x32_bf16 v[204:207], v[30:33], v[122:125], v[6:9]
	s_barrier
;     __host__ __device__ bool next(int i, Unit& u) const { if (!StaticOrder::next(i >> 1, u)) return false; u.seg = i & 1; return true; }
;     ...
;         const bool has_next = S.next(ui + 1, nxt);
;         const char* nA = has_next ? PG8_APTR(nxt) : cA; const char* nB = has_next ? PG8_BPTR(nxt) : cB;
;         const char* pfc = PG8_PFPTR(cA, cB); const char* pfn = PG8_PFPTR(nA, nB);
;         PG8_KITER(0);
;         for (int t = 2; t < nt; t += 2) PG8_KITER(t);
	s_setprio 0
	s_add_i32 s47, 0, 0x18000
	s_add_i32 s56, 0, 0x1c000
	v_add_u32_e32 v134, s47, v1
	v_add_u32_e32 v144, s56, v1
	s_nop 0
	ds_read_b128 v[6:9], v134
	ds_read_b128 v[18:21], v134 offset:1024
	ds_read_b128 v[30:33], v134 offset:2048
	ds_read_b128 v[208:211], v134 offset:3072
	ds_read_b128 v[212:215], v144
	ds_read_b128 v[216:219], v144 offset:1024
	ds_read_b128 v[220:223], v144 offset:2048
	ds_read_b128 v[224:227], v144 offset:3072
	s_add_u32 s0, s54, 0x100100
	s_addc_u32 s1, s55, 0
	s_mov_b32 m0, s58
	v_lshl_add_u64 v[54:55], s[0:1], 0, v[130:131]
	ds_read_b128 v[22:25], v150 offset:32768
	ds_read_b128 v[26:29], v150 offset:33792
	ds_read_b128 v[62:65], v150 offset:34816
	ds_read_b128 v[228:231], v150 offset:35840
	ds_read_b128 v[232:235], v150 offset:36864
	ds_read_b128 v[236:239], v150 offset:37888
	ds_read_b128 v[240:243], v150 offset:38912
	ds_read_b128 v[244:247], v150 offset:39936
	global_load_lds_dwordx4 v[54:55], off
	v_lshl_add_u64 v[54:55], s[0:1], 0, v[132:133]
	s_mov_b32 m0, s59
	s_nop 0
	global_load_lds_dwordx4 v[54:55], off
	s_waitcnt vmcnt(8)
	s_waitcnt lgkmcnt(0)
	s_setprio 1
	s_barrier
	v_mfma_f32_16x16x32_bf16 v[54:57], v[6:9], v[22:25], v[66:69]
	v_mfma_f32_16x16x32_bf16 v[118:121], v[18:21], v[26:29], v[54:57]
	v_mfma_f32_16x16x32_bf16 v[54:57], v[30:33], v[22:25], v[70:73]
	v_mfma_f32_16x16x32_bf16 v[114:117], v[208:211], v[26:29], v[54:57]
	v_mfma_f32_16x16x32_bf16 v[54:57], v[6:9], v[62:65], v[74:77]
	v_mfma_f32_16x16x32_bf16 v[102:105], v[18:21], v[228:231], v[54:57]
	v_mfma_f32_16x16x32_bf16 v[54:57], v[30:33], v[62:65], v[78:81]
	v_mfma_f32_16x16x32_bf16 v[98:101], v[208:211], v[228:231], v[54:57]
	v_mfma_f32_16x16x32_bf16 v[54:57], v[6:9], v[232:235], v[82:85]
	v_mfma_f32_16x16x32_bf16 v[86:89], v[18:21], v[236:239], v[54:57]
	v_mfma_f32_16x16x32_bf16 v[54:57], v[30:33], v[232:235], v[90:93]
	v_mfma_f32_16x16x32_bf16 v[82:85], v[208:211], v[236:239], v[54:57]
	v_mfma_f32_16x16x32_bf16 v[54:57], v[6:9], v[240:243], v[94:97]
	v_mfma_f32_16x16x32_bf16 v[74:77], v[18:21], v[244:247], v[54:57]
	v_mfma_f32_16x16x32_bf16 v[54:57], v[30:33], v[240:243], v[106:109]
	v_mfma_f32_16x16x32_bf16 v[54:57], v[208:211], v[244:247], v[54:57]
	s_setprio 0
	s_setprio 1
	v_mfma_f32_16x16x32_bf16 v[66:69], v[212:215], v[22:25], v[110:113]
	v_mfma_f32_16x16x32_bf16 v[22:25], v[220:223], v[22:25], v[34:37]
	v_mfma_f32_16x16x32_bf16 v[122:125], v[224:227], v[26:29], v[22:25]
	v_mfma_f32_16x16x32_bf16 v[22:25], v[212:215], v[62:65], v[38:41]
	v_mfma_f32_16x16x32_bf16 v[110:113], v[216:219], v[228:231], v[22:25]
	v_mfma_f32_16x16x32_bf16 v[22:25], v[220:223], v[62:65], v[42:45]
	v_mfma_f32_16x16x32_bf16 v[106:109], v[224:227], v[228:231], v[22:25]
	v_mfma_f32_16x16x32_bf16 v[22:25], v[212:215], v[232:235], v[46:49]
	v_mfma_f32_16x16x32_bf16 v[94:97], v[216:219], v[236:239], v[22:25]
	v_mfma_f32_16x16x32_bf16 v[22:25], v[220:223], v[232:235], v[50:53]
	v_mfma_f32_16x16x32_bf16 v[90:93], v[224:227], v[236:239], v[22:25]
	v_mfma_f32_16x16x32_bf16 v[22:25], v[212:215], v[240:243], v[152:155]
	v_mfma_f32_16x16x32_bf16 v[70:73], v[216:219], v[244:247], v[22:25]
	v_mfma_f32_16x16x32_bf16 v[22:25], v[220:223], v[240:243], v[58:61]
	v_mfma_f32_16x16x32_bf16 v[126:129], v[216:219], v[26:29], v[66:69]
	v_mfma_f32_16x16x32_bf16 v[50:53], v[224:227], v[244:247], v[22:25]
	s_barrier
	s_setprio 0
	s_add_i32 s47, s47, s13
	s_add_i32 s77, s47, 0x2000
	s_nop 1
	v_lshl_add_u64 v[22:23], v[146:147], 0, s[22:23]
	s_mov_b32 m0, s47
	s_add_u32 s0, s52, 0x100180
	ds_read_b128 v[34:37], v150 offset:49152
	ds_read_b128 v[46:49], v150 offset:50176
	ds_read_b128 v[152:155], v150 offset:51200
	ds_read_b128 v[228:231], v150 offset:52224
	ds_read_b128 v[232:235], v150 offset:53248
	ds_read_b128 v[236:239], v150 offset:54272
	ds_read_b128 v[240:243], v150 offset:55296
	ds_read_b128 v[244:247], v150 offset:56320
	global_load_lds_dwordx4 v[22:23], off
	v_lshl_add_u64 v[22:23], v[248:249], 0, s[22:23]
	s_mov_b32 m0, s77
	s_addc_u32 s1, s53, 0
	s_add_i32 s56, s56, s13
	global_load_lds_dwordx4 v[22:23], off
	v_lshl_add_u64 v[22:23], s[0:1], 0, v[130:131]
	s_mov_b32 m0, s56
	s_add_i32 s57, s56, 0x2000
	global_load_lds_dwordx4 v[22:23], off
	v_lshl_add_u64 v[22:23], s[0:1], 0, v[132:133]
	s_mov_b32 m0, s57
	s_nop 0
	global_load_lds_dwordx4 v[22:23], off
	v_lshl_add_u64 v[22:23], v[250:251], 0, s[22:23]
	s_mov_b32 m0, s61
	s_nop 0
	global_load_lds_dwordx4 v[22:23], off
	v_lshl_add_u64 v[22:23], v[252:253], 0, s[22:23]
	s_mov_b32 m0, s62
	s_nop 0
	global_load_lds_dwordx4 v[22:23], off
	s_waitcnt vmcnt(8)
	s_waitcnt lgkmcnt(0)
	s_setprio 1
	s_barrier
	v_mfma_f32_16x16x32_bf16 v[22:25], v[6:9], v[34:37], v[156:159]
	v_mfma_f32_16x16x32_bf16 v[66:69], v[18:21], v[46:49], v[22:25]
	v_mfma_f32_16x16x32_bf16 v[22:25], v[30:33], v[34:37], v[160:163]
	v_mfma_f32_16x16x32_bf16 v[62:65], v[208:211], v[46:49], v[22:25]
	v_mfma_f32_16x16x32_bf16 v[22:25], v[6:9], v[152:155], v[164:167]
	v_mfma_f32_16x16x32_bf16 v[42:45], v[18:21], v[228:231], v[22:25]
	v_mfma_f32_16x16x32_bf16 v[22:25], v[30:33], v[152:155], v[168:171]
	v_mfma_f32_16x16x32_bf16 v[38:41], v[208:211], v[228:231], v[22:25]
	v_mfma_f32_16x16x32_bf16 v[22:25], v[6:9], v[232:235], v[172:175]
	v_mfma_f32_16x16x32_bf16 v[2:5], v[6:9], v[240:243], v[2:5]
	v_mfma_f32_16x16x32_bf16 v[26:29], v[18:21], v[236:239], v[22:25]
	v_mfma_f32_16x16x32_bf16 v[22:25], v[30:33], v[232:235], v[176:179]
	v_mfma_f32_16x16x32_bf16 v[6:9], v[18:21], v[244:247], v[2:5]
	v_mfma_f32_16x16x32_bf16 v[2:5], v[30:33], v[240:243], v[10:13]
	v_mfma_f32_16x16x32_bf16 v[22:25], v[208:211], v[236:239], v[22:25]
	v_mfma_f32_16x16x32_bf16 v[2:5], v[208:211], v[244:247], v[2:5]
	s_setprio 0
	s_setprio 1
	v_mfma_f32_16x16x32_bf16 v[10:13], v[212:215], v[34:37], v[14:17]
	v_mfma_f32_16x16x32_bf16 v[78:81], v[216:219], v[46:49], v[10:13]
	v_mfma_f32_16x16x32_bf16 v[10:13], v[220:223], v[34:37], v[180:183]
	v_mfma_f32_16x16x32_bf16 v[58:61], v[224:227], v[46:49], v[10:13]
	v_mfma_f32_16x16x32_bf16 v[10:13], v[212:215], v[152:155], v[184:187]
	v_mfma_f32_16x16x32_bf16 v[46:49], v[216:219], v[228:231], v[10:13]
	v_mfma_f32_16x16x32_bf16 v[10:13], v[220:223], v[152:155], v[188:191]
	v_mfma_f32_16x16x32_bf16 v[34:37], v[224:227], v[228:231], v[10:13]
	v_mfma_f32_16x16x32_bf16 v[10:13], v[212:215], v[232:235], v[192:195]
	v_mfma_f32_16x16x32_bf16 v[30:33], v[216:219], v[236:239], v[10:13]
	v_mfma_f32_16x16x32_bf16 v[10:13], v[220:223], v[232:235], v[196:199]
	v_mfma_f32_16x16x32_bf16 v[18:21], v[224:227], v[236:239], v[10:13]
	v_mfma_f32_16x16x32_bf16 v[10:13], v[212:215], v[240:243], v[200:203]
	v_mfma_f32_16x16x32_bf16 v[14:17], v[216:219], v[244:247], v[10:13]
	v_mfma_f32_16x16x32_bf16 v[10:13], v[220:223], v[240:243], v[204:207]
	v_mfma_f32_16x16x32_bf16 v[10:13], v[224:227], v[244:247], v[10:13]
	s_barrier
	s_setprio 0
	s_add_u32 s0, s54, 0x100180
	s_addc_u32 s1, s55, 0
	s_add_u32 s14, s52, 0x200
	s_addc_u32 s15, s53, 0
	s_mov_b32 s26, 0
.LBB0_1110:
	ds_read_b128 v[152:155], v148
	ds_read_b128 v[156:159], v148 offset:1024
	ds_read_b128 v[160:163], v148 offset:2048
	ds_read_b128 v[164:167], v148 offset:3072
	ds_read_b128 v[168:171], v149
	ds_read_b128 v[172:175], v149 offset:1024
	ds_read_b128 v[176:179], v149 offset:2048
	ds_read_b128 v[180:183], v149 offset:3072
	s_add_u32 s27, s0, 0xfff00080
	s_addc_u32 s52, s1, -1
	s_cmp_eq_u32 s26, 28
	s_cselect_b32 s55, s43, s52
	s_cselect_b32 s54, s42, s27
	s_cselect_b32 s53, s49, s15
	s_cselect_b32 s52, s48, s14
	s_mov_b32 m0, s41
	ds_read_b128 v[184:187], v150
	ds_read_b128 v[188:191], v150 offset:1024
	ds_read_b128 v[192:195], v150 offset:2048
	ds_read_b128 v[196:199], v150 offset:3072
	ds_read_b128 v[200:203], v150 offset:4096
	ds_read_b128 v[204:207], v150 offset:5120
	ds_read_b128 v[208:211], v150 offset:6144
	ds_read_b128 v[212:215], v150 offset:7168
	global_load_lds_dwordx4 v136, s[0:1]
	s_mov_b32 m0, s73
	s_nop 0
	global_load_lds_dwordx4 v138, s[0:1]
	s_waitcnt vmcnt(8)
	s_waitcnt lgkmcnt(0)
	s_setprio 1
	s_barrier
	v_mfma_f32_16x16x32_bf16 v[118:121], v[152:155], v[184:187], v[118:121]
	v_mfma_f32_16x16x32_bf16 v[114:117], v[160:163], v[184:187], v[114:117]
	v_mfma_f32_16x16x32_bf16 v[102:105], v[152:155], v[192:195], v[102:105]
	v_mfma_f32_16x16x32_bf16 v[98:101], v[160:163], v[192:195], v[98:101]
	v_mfma_f32_16x16x32_bf16 v[86:89], v[152:155], v[200:203], v[86:89]
	v_mfma_f32_16x16x32_bf16 v[82:85], v[160:163], v[200:203], v[82:85]
	v_mfma_f32_16x16x32_bf16 v[74:77], v[152:155], v[208:211], v[74:77]
	v_mfma_f32_16x16x32_bf16 v[54:57], v[160:163], v[208:211], v[54:57]
	v_mfma_f32_16x16x32_bf16 v[118:121], v[156:159], v[188:191], v[118:121]
	v_mfma_f32_16x16x32_bf16 v[114:117], v[164:167], v[188:191], v[114:117]
	v_mfma_f32_16x16x32_bf16 v[102:105], v[156:159], v[196:199], v[102:105]
	v_mfma_f32_16x16x32_bf16 v[98:101], v[164:167], v[196:199], v[98:101]
	v_mfma_f32_16x16x32_bf16 v[86:89], v[156:159], v[204:207], v[86:89]
	v_mfma_f32_16x16x32_bf16 v[82:85], v[164:167], v[204:207], v[82:85]
	v_mfma_f32_16x16x32_bf16 v[74:77], v[156:159], v[212:215], v[74:77]
	v_mfma_f32_16x16x32_bf16 v[54:57], v[164:167], v[212:215], v[54:57]
	s_setprio 0
	s_setprio 1
	v_mfma_f32_16x16x32_bf16 v[126:129], v[168:171], v[184:187], v[126:129]
	v_mfma_f32_16x16x32_bf16 v[122:125], v[176:179], v[184:187], v[122:125]
	v_mfma_f32_16x16x32_bf16 v[110:113], v[168:171], v[192:195], v[110:113]
	v_mfma_f32_16x16x32_bf16 v[106:109], v[176:179], v[192:195], v[106:109]
	v_mfma_f32_16x16x32_bf16 v[94:97], v[168:171], v[200:203], v[94:97]
	v_mfma_f32_16x16x32_bf16 v[90:93], v[176:179], v[200:203], v[90:93]
	v_mfma_f32_16x16x32_bf16 v[70:73], v[168:171], v[208:211], v[70:73]
	v_mfma_f32_16x16x32_bf16 v[50:53], v[176:179], v[208:211], v[50:53]
	v_mfma_f32_16x16x32_bf16 v[126:129], v[172:175], v[188:191], v[126:129]
	v_mfma_f32_16x16x32_bf16 v[122:125], v[180:183], v[188:191], v[122:125]
	v_mfma_f32_16x16x32_bf16 v[110:113], v[172:175], v[196:199], v[110:113]
	v_mfma_f32_16x16x32_bf16 v[106:109], v[180:183], v[196:199], v[106:109]
	v_mfma_f32_16x16x32_bf16 v[94:97], v[172:175], v[204:207], v[94:97]
	v_mfma_f32_16x16x32_bf16 v[90:93], v[180:183], v[204:207], v[90:93]
	v_mfma_f32_16x16x32_bf16 v[70:73], v[172:175], v[212:215], v[70:73]
	v_mfma_f32_16x16x32_bf16 v[50:53], v[180:183], v[212:215], v[50:53]
	s_barrier
	s_setprio 0
	s_mov_b32 m0, s74
	s_mov_b64 s[98:99], s[52:53]
	s_add_u32 s78, s52, 0x100000
	ds_read_b128 v[184:187], v150 offset:16384
	ds_read_b128 v[188:191], v150 offset:17408
	ds_read_b128 v[192:195], v150 offset:18432
	ds_read_b128 v[196:199], v150 offset:19456
	ds_read_b128 v[200:203], v150 offset:20480
	ds_read_b128 v[204:207], v150 offset:21504
	ds_read_b128 v[208:211], v150 offset:22528
	ds_read_b128 v[212:215], v150 offset:23552
	global_load_lds_dwordx4 v130, s[52:53]
	s_mov_b32 m0, s75
	s_addc_u32 s79, s53, 0
	global_load_lds_dwordx4 v132, s[52:53]
	s_mov_b32 m0, s76
	s_mov_b64 s[100:101], s[54:55]
	global_load_lds_dwordx4 v130, s[78:79]
	s_mov_b32 m0, s46
	s_nop 0
	global_load_lds_dwordx4 v132, s[78:79]
	s_mov_b32 m0, s33
	s_nop 0
	global_load_lds_dwordx4 v130, s[54:55]
	s_mov_b32 m0, s51
	s_nop 0
	global_load_lds_dwordx4 v132, s[54:55]
	s_waitcnt vmcnt(8)
	s_waitcnt lgkmcnt(0)
	s_setprio 1
	s_barrier
	v_mfma_f32_16x16x32_bf16 v[66:69], v[152:155], v[184:187], v[66:69]
	v_mfma_f32_16x16x32_bf16 v[62:65], v[160:163], v[184:187], v[62:65]
	v_mfma_f32_16x16x32_bf16 v[42:45], v[152:155], v[192:195], v[42:45]
	v_mfma_f32_16x16x32_bf16 v[38:41], v[160:163], v[192:195], v[38:41]
	v_mfma_f32_16x16x32_bf16 v[26:29], v[152:155], v[200:203], v[26:29]
	v_mfma_f32_16x16x32_bf16 v[22:25], v[160:163], v[200:203], v[22:25]
	v_mfma_f32_16x16x32_bf16 v[6:9], v[152:155], v[208:211], v[6:9]
	v_mfma_f32_16x16x32_bf16 v[2:5], v[160:163], v[208:211], v[2:5]
	v_mfma_f32_16x16x32_bf16 v[66:69], v[156:159], v[188:191], v[66:69]
	v_mfma_f32_16x16x32_bf16 v[62:65], v[164:167], v[188:191], v[62:65]
	v_mfma_f32_16x16x32_bf16 v[42:45], v[156:159], v[196:199], v[42:45]
	v_mfma_f32_16x16x32_bf16 v[38:41], v[164:167], v[196:199], v[38:41]
	v_mfma_f32_16x16x32_bf16 v[26:29], v[156:159], v[204:207], v[26:29]
	v_mfma_f32_16x16x32_bf16 v[22:25], v[164:167], v[204:207], v[22:25]
	v_mfma_f32_16x16x32_bf16 v[6:9], v[156:159], v[212:215], v[6:9]
	v_mfma_f32_16x16x32_bf16 v[2:5], v[164:167], v[212:215], v[2:5]
	s_setprio 0
	s_setprio 1
	v_mfma_f32_16x16x32_bf16 v[78:81], v[168:171], v[184:187], v[78:81]
	v_mfma_f32_16x16x32_bf16 v[58:61], v[176:179], v[184:187], v[58:61]
	v_mfma_f32_16x16x32_bf16 v[46:49], v[168:171], v[192:195], v[46:49]
	v_mfma_f32_16x16x32_bf16 v[34:37], v[176:179], v[192:195], v[34:37]
	v_mfma_f32_16x16x32_bf16 v[30:33], v[168:171], v[200:203], v[30:33]
	v_mfma_f32_16x16x32_bf16 v[18:21], v[176:179], v[200:203], v[18:21]
	v_mfma_f32_16x16x32_bf16 v[14:17], v[168:171], v[208:211], v[14:17]
	v_mfma_f32_16x16x32_bf16 v[10:13], v[176:179], v[208:211], v[10:13]
	v_mfma_f32_16x16x32_bf16 v[78:81], v[172:175], v[188:191], v[78:81]
	v_mfma_f32_16x16x32_bf16 v[58:61], v[180:183], v[188:191], v[58:61]
	v_mfma_f32_16x16x32_bf16 v[46:49], v[172:175], v[196:199], v[46:49]
	v_mfma_f32_16x16x32_bf16 v[34:37], v[180:183], v[196:199], v[34:37]
	v_mfma_f32_16x16x32_bf16 v[30:33], v[172:175], v[204:207], v[30:33]
	v_mfma_f32_16x16x32_bf16 v[18:21], v[180:183], v[204:207], v[18:21]
	v_mfma_f32_16x16x32_bf16 v[14:17], v[172:175], v[212:215], v[14:17]
	v_mfma_f32_16x16x32_bf16 v[10:13], v[180:183], v[212:215], v[10:13]
	s_barrier
; #define PG8_BAR __builtin_amdgcn_s_barrier()
;     ...
;         for (int t = 2; t < nt; t += 2) PG8_KITER(t);
;         if constexpr (ALIGN_EPI) { if (wr == 0) PG8_BAR; }
	s_setprio 0
	ds_read_b128 v[152:155], v134
	ds_read_b128 v[156:159], v134 offset:1024
	ds_read_b128 v[160:163], v134 offset:2048
	ds_read_b128 v[164:167], v134 offset:3072
	ds_read_b128 v[168:171], v144
	ds_read_b128 v[172:175], v144 offset:1024
	ds_read_b128 v[176:179], v144 offset:2048
	ds_read_b128 v[180:183], v144 offset:3072
	s_add_u32 s54, s54, 0x100000
	s_addc_u32 s55, s55, 0
	s_mov_b32 m0, s58
	ds_read_b128 v[184:187], v150 offset:32768
	ds_read_b128 v[188:191], v150 offset:33792
	ds_read_b128 v[192:195], v150 offset:34816
	ds_read_b128 v[196:199], v150 offset:35840
	ds_read_b128 v[200:203], v150 offset:36864
	ds_read_b128 v[204:207], v150 offset:37888
	ds_read_b128 v[208:211], v150 offset:38912
	ds_read_b128 v[212:215], v150 offset:39936
	global_load_lds_dwordx4 v130, s[54:55]
	s_mov_b32 m0, s59
	s_nop 0
	global_load_lds_dwordx4 v132, s[54:55]
	s_waitcnt vmcnt(8)
	s_waitcnt lgkmcnt(0)
	s_setprio 1
	s_barrier
	v_mfma_f32_16x16x32_bf16 v[118:121], v[152:155], v[184:187], v[118:121]
	v_mfma_f32_16x16x32_bf16 v[114:117], v[160:163], v[184:187], v[114:117]
	v_mfma_f32_16x16x32_bf16 v[102:105], v[152:155], v[192:195], v[102:105]
	v_mfma_f32_16x16x32_bf16 v[98:101], v[160:163], v[192:195], v[98:101]
	v_mfma_f32_16x16x32_bf16 v[86:89], v[152:155], v[200:203], v[86:89]
	v_mfma_f32_16x16x32_bf16 v[82:85], v[160:163], v[200:203], v[82:85]
	v_mfma_f32_16x16x32_bf16 v[74:77], v[152:155], v[208:211], v[74:77]
	v_mfma_f32_16x16x32_bf16 v[54:57], v[160:163], v[208:211], v[54:57]
	v_mfma_f32_16x16x32_bf16 v[118:121], v[156:159], v[188:191], v[118:121]
	v_mfma_f32_16x16x32_bf16 v[114:117], v[164:167], v[188:191], v[114:117]
	v_mfma_f32_16x16x32_bf16 v[102:105], v[156:159], v[196:199], v[102:105]
	v_mfma_f32_16x16x32_bf16 v[98:101], v[164:167], v[196:199], v[98:101]
	v_mfma_f32_16x16x32_bf16 v[86:89], v[156:159], v[204:207], v[86:89]
	v_mfma_f32_16x16x32_bf16 v[82:85], v[164:167], v[204:207], v[82:85]
	v_mfma_f32_16x16x32_bf16 v[74:77], v[156:159], v[212:215], v[74:77]
	v_mfma_f32_16x16x32_bf16 v[54:57], v[164:167], v[212:215], v[54:57]
	s_setprio 0
	s_setprio 1
	v_mfma_f32_16x16x32_bf16 v[126:129], v[168:171], v[184:187], v[126:129]
	v_mfma_f32_16x16x32_bf16 v[122:125], v[176:179], v[184:187], v[122:125]
	v_mfma_f32_16x16x32_bf16 v[110:113], v[168:171], v[192:195], v[110:113]
	v_mfma_f32_16x16x32_bf16 v[106:109], v[176:179], v[192:195], v[106:109]
	v_mfma_f32_16x16x32_bf16 v[94:97], v[168:171], v[200:203], v[94:97]
	v_mfma_f32_16x16x32_bf16 v[90:93], v[176:179], v[200:203], v[90:93]
	v_mfma_f32_16x16x32_bf16 v[70:73], v[168:171], v[208:211], v[70:73]
	v_mfma_f32_16x16x32_bf16 v[50:53], v[176:179], v[208:211], v[50:53]
	v_mfma_f32_16x16x32_bf16 v[126:129], v[172:175], v[188:191], v[126:129]
	v_mfma_f32_16x16x32_bf16 v[122:125], v[180:183], v[188:191], v[122:125]
	v_mfma_f32_16x16x32_bf16 v[110:113], v[172:175], v[196:199], v[110:113]
	v_mfma_f32_16x16x32_bf16 v[106:109], v[180:183], v[196:199], v[106:109]
	v_mfma_f32_16x16x32_bf16 v[94:97], v[172:175], v[204:207], v[94:97]
	v_mfma_f32_16x16x32_bf16 v[90:93], v[180:183], v[204:207], v[90:93]
	v_mfma_f32_16x16x32_bf16 v[70:73], v[172:175], v[212:215], v[70:73]
	v_mfma_f32_16x16x32_bf16 v[50:53], v[180:183], v[212:215], v[50:53]
	s_barrier
	s_setprio 0
	s_mov_b32 m0, s47
	s_add_u32 s98, s98, 0x80
	s_addc_u32 s99, s99, 0
	s_add_u32 s100, s100, 0x80
	s_addc_u32 s101, s101, 0
	s_add_u32 s52, s52, 0x100080
	ds_read_b128 v[184:187], v150 offset:49152
	ds_read_b128 v[188:191], v150 offset:50176
	ds_read_b128 v[192:195], v150 offset:51200
	ds_read_b128 v[196:199], v150 offset:52224
	ds_read_b128 v[200:203], v150 offset:53248
	ds_read_b128 v[204:207], v150 offset:54272
	ds_read_b128 v[208:211], v150 offset:55296
	ds_read_b128 v[212:215], v150 offset:56320
	global_load_lds_dwordx4 v130, s[98:99]
	s_mov_b32 m0, s77
	s_addc_u32 s53, s53, 0
	global_load_lds_dwordx4 v132, s[98:99]
	s_mov_b32 m0, s56
	s_nop 0
	global_load_lds_dwordx4 v130, s[52:53]
	s_mov_b32 m0, s57
	s_nop 0
	global_load_lds_dwordx4 v132, s[52:53]
	s_mov_b32 m0, s61
	s_nop 0
	global_load_lds_dwordx4 v130, s[100:101]
	s_mov_b32 m0, s62
	s_nop 0
	global_load_lds_dwordx4 v132, s[100:101]
	s_waitcnt vmcnt(8)
	s_waitcnt lgkmcnt(0)
	s_setprio 1
	s_barrier
	v_mfma_f32_16x16x32_bf16 v[66:69], v[152:155], v[184:187], v[66:69]
	v_mfma_f32_16x16x32_bf16 v[62:65], v[160:163], v[184:187], v[62:65]
	v_mfma_f32_16x16x32_bf16 v[42:45], v[152:155], v[192:195], v[42:45]
	v_mfma_f32_16x16x32_bf16 v[38:41], v[160:163], v[192:195], v[38:41]
	v_mfma_f32_16x16x32_bf16 v[26:29], v[152:155], v[200:203], v[26:29]
	v_mfma_f32_16x16x32_bf16 v[22:25], v[160:163], v[200:203], v[22:25]
	v_mfma_f32_16x16x32_bf16 v[6:9], v[152:155], v[208:211], v[6:9]
	v_mfma_f32_16x16x32_bf16 v[2:5], v[160:163], v[208:211], v[2:5]
	v_mfma_f32_16x16x32_bf16 v[66:69], v[156:159], v[188:191], v[66:69]
	v_mfma_f32_16x16x32_bf16 v[62:65], v[164:167], v[188:191], v[62:65]
	v_mfma_f32_16x16x32_bf16 v[42:45], v[156:159], v[196:199], v[42:45]
	v_mfma_f32_16x16x32_bf16 v[38:41], v[164:167], v[196:199], v[38:41]
	v_mfma_f32_16x16x32_bf16 v[26:29], v[156:159], v[204:207], v[26:29]
	v_mfma_f32_16x16x32_bf16 v[22:25], v[164:167], v[204:207], v[22:25]
	v_mfma_f32_16x16x32_bf16 v[6:9], v[156:159], v[212:215], v[6:9]
	v_mfma_f32_16x16x32_bf16 v[2:5], v[164:167], v[212:215], v[2:5]
	s_setprio 0
	s_setprio 1
	v_mfma_f32_16x16x32_bf16 v[78:81], v[168:171], v[184:187], v[78:81]
	v_mfma_f32_16x16x32_bf16 v[58:61], v[176:179], v[184:187], v[58:61]
	v_mfma_f32_16x16x32_bf16 v[46:49], v[168:171], v[192:195], v[46:49]
	v_mfma_f32_16x16x32_bf16 v[34:37], v[176:179], v[192:195], v[34:37]
	v_mfma_f32_16x16x32_bf16 v[30:33], v[168:171], v[200:203], v[30:33]
	v_mfma_f32_16x16x32_bf16 v[18:21], v[176:179], v[200:203], v[18:21]
	v_mfma_f32_16x16x32_bf16 v[14:17], v[168:171], v[208:211], v[14:17]
	v_mfma_f32_16x16x32_bf16 v[10:13], v[176:179], v[208:211], v[10:13]
	v_mfma_f32_16x16x32_bf16 v[78:81], v[172:175], v[188:191], v[78:81]
	v_mfma_f32_16x16x32_bf16 v[58:61], v[180:183], v[188:191], v[58:61]
	v_mfma_f32_16x16x32_bf16 v[46:49], v[172:175], v[196:199], v[46:49]
	v_mfma_f32_16x16x32_bf16 v[34:37], v[180:183], v[196:199], v[34:37]
	v_mfma_f32_16x16x32_bf16 v[30:33], v[172:175], v[204:207], v[30:33]
	v_mfma_f32_16x16x32_bf16 v[18:21], v[180:183], v[204:207], v[18:21]
	v_mfma_f32_16x16x32_bf16 v[14:17], v[172:175], v[212:215], v[14:17]
	v_mfma_f32_16x16x32_bf16 v[10:13], v[180:183], v[212:215], v[10:13]
	s_barrier
	s_setprio 0
	s_add_i32 s26, s26, 2
	s_add_u32 s0, s0, 0x100
	s_addc_u32 s1, s1, 0
	s_add_u32 s14, s14, 0x100
	s_addc_u32 s15, s15, 0
	s_cmp_gt_u32 s26, 29
	s_cbranch_scc0 .LBB0_1110
	s_and_b64 vcc, exec, s[18:19]
	s_cbranch_vccz .LBB0_1113
	s_barrier

;     __host__ __device__ bool next(int i, Unit& u) const { if (!StaticOrder::next(i >> 1, u)) return false; u.seg = i & 1; return true; }
;     ...
;         const bool has_next = S.next(ui + 1, nxt);
;         const char* nA = has_next ? PG8_APTR(nxt) : cA; const char* nB = has_next ? PG8_BPTR(nxt) : cB;
;         const char* pfc = PG8_PFPTR(cA, cB); const char* pfn = PG8_PFPTR(nA, nB);
;         PG8_KITER(0);
.LBB0_1260:
	s_ashr_i32 s23, s22, 31
	ds_read_b128 v[2:5], v182
	ds_read_b128 v[6:9], v182 offset:1024
	ds_read_b128 v[10:13], v182 offset:2048
	ds_read_b128 v[14:17], v182 offset:3072
	ds_read_b128 v[18:21], v183
	ds_read_b128 v[22:25], v183 offset:1024
	ds_read_b128 v[26:29], v183 offset:2048
	ds_read_b128 v[30:33], v183 offset:3072
	s_lshl_b64 s[24:25], s[22:23], 18
	s_add_u32 s24, s10, s24
	s_addc_u32 s25, s11, s25
	s_and_b64 s[26:27], s[4:5], exec
	s_cselect_b32 s23, s25, s41
	s_cselect_b32 s31, s24, s40
	s_and_b32 s0, s64, 0x7fffffff
	s_lshl_b64 s[26:27], s[0:1], 18
	s_add_u32 s28, s12, s26
	s_addc_u32 s29, s13, s27
	s_and_b64 s[26:27], s[4:5], exec
	s_cselect_b32 s0, s29, s39
	s_cselect_b32 s66, s28, s38
	s_add_u32 s26, s40, 0x20080
	s_addc_u32 s27, s41, 0
	s_mov_b32 m0, s59
	v_lshl_add_u64 v[66:67], s[26:27], 0, v[154:155]
	ds_read_b128 v[34:37], v184
	ds_read_b128 v[38:41], v184 offset:1024
	ds_read_b128 v[42:45], v184 offset:2048
	ds_read_b128 v[46:49], v184 offset:3072
	ds_read_b128 v[50:53], v184 offset:4096
	ds_read_b128 v[54:57], v184 offset:5120
	ds_read_b128 v[58:61], v184 offset:6144
	ds_read_b128 v[62:65], v184 offset:7168
	global_load_lds_dwordx4 v[66:67], off
	v_lshl_add_u64 v[66:67], s[26:27], 0, v[158:159]
	s_mov_b32 m0, s60
	s_nop 0
	global_load_lds_dwordx4 v[66:67], off
	s_waitcnt vmcnt(8)
	s_waitcnt lgkmcnt(0)
	s_setprio 1
	s_barrier
	v_mfma_f32_16x16x32_bf16 v[90:93], v[2:5], v[58:61], 0
	v_mfma_f32_16x16x32_bf16 v[66:69], v[2:5], v[34:37], 0
	v_mfma_f32_16x16x32_bf16 v[70:73], v[10:13], v[34:37], 0
	v_mfma_f32_16x16x32_bf16 v[74:77], v[2:5], v[42:45], 0
	v_mfma_f32_16x16x32_bf16 v[78:81], v[10:13], v[42:45], 0
	v_mfma_f32_16x16x32_bf16 v[82:85], v[2:5], v[50:53], 0
	v_mfma_f32_16x16x32_bf16 v[86:89], v[10:13], v[50:53], 0
	v_mfma_f32_16x16x32_bf16 v[98:101], v[6:9], v[62:65], v[90:93]
	v_mfma_f32_16x16x32_bf16 v[90:93], v[10:13], v[58:61], 0
	v_mfma_f32_16x16x32_bf16 v[66:69], v[6:9], v[38:41], v[66:69]
	v_mfma_f32_16x16x32_bf16 v[70:73], v[14:17], v[38:41], v[70:73]
	v_mfma_f32_16x16x32_bf16 v[74:77], v[6:9], v[46:49], v[74:77]
	v_mfma_f32_16x16x32_bf16 v[78:81], v[14:17], v[46:49], v[78:81]
	v_mfma_f32_16x16x32_bf16 v[82:85], v[6:9], v[54:57], v[82:85]
	v_mfma_f32_16x16x32_bf16 v[86:89], v[14:17], v[54:57], v[86:89]
	v_mfma_f32_16x16x32_bf16 v[102:105], v[14:17], v[62:65], v[90:93]
	s_setprio 0
	s_setprio 1
	v_mfma_f32_16x16x32_bf16 v[90:93], v[18:21], v[34:37], 0
	v_mfma_f32_16x16x32_bf16 v[34:37], v[26:29], v[34:37], 0
	v_mfma_f32_16x16x32_bf16 v[114:117], v[22:25], v[38:41], v[90:93]
	v_mfma_f32_16x16x32_bf16 v[34:37], v[30:33], v[38:41], v[34:37]
	v_mfma_f32_16x16x32_bf16 v[38:41], v[18:21], v[42:45], 0
	v_mfma_f32_16x16x32_bf16 v[42:45], v[26:29], v[42:45], 0
	v_mfma_f32_16x16x32_bf16 v[38:41], v[22:25], v[46:49], v[38:41]
	v_mfma_f32_16x16x32_bf16 v[42:45], v[30:33], v[46:49], v[42:45]
	v_mfma_f32_16x16x32_bf16 v[46:49], v[18:21], v[50:53], 0
	v_mfma_f32_16x16x32_bf16 v[50:53], v[26:29], v[50:53], 0
	v_mfma_f32_16x16x32_bf16 v[46:49], v[22:25], v[54:57], v[46:49]
	v_mfma_f32_16x16x32_bf16 v[50:53], v[30:33], v[54:57], v[50:53]
	v_mfma_f32_16x16x32_bf16 v[54:57], v[18:21], v[58:61], 0
	v_mfma_f32_16x16x32_bf16 v[58:61], v[26:29], v[58:61], 0
	v_mfma_f32_16x16x32_bf16 v[54:57], v[22:25], v[62:65], v[54:57]
	v_mfma_f32_16x16x32_bf16 v[58:61], v[30:33], v[62:65], v[58:61]
	s_barrier
	s_setprio 0
	v_lshl_add_u64 v[152:153], s[38:39], 0, v[156:157]
	s_mov_b32 m0, s61
	v_lshl_add_u64 v[130:131], v[152:153], 0, s[18:19]
	v_lshl_add_u64 v[250:251], s[38:39], 0, v[160:161]
	s_add_u32 s26, s38, 0x20100
	ds_read_b128 v[62:65], v184 offset:16384
	ds_read_b128 v[90:93], v184 offset:17408
	ds_read_b128 v[94:97], v184 offset:18432
	ds_read_b128 v[106:109], v184 offset:19456
	ds_read_b128 v[110:113], v184 offset:20480
	ds_read_b128 v[118:121], v184 offset:21504
	ds_read_b128 v[122:125], v184 offset:22528
	ds_read_b128 v[126:129], v184 offset:23552
	global_load_lds_dwordx4 v[130:131], off
	v_lshl_add_u64 v[130:131], v[250:251], 0, s[18:19]
	s_mov_b32 m0, s62
	s_addc_u32 s27, s39, 0
	s_add_i32 s67, s58, s33
	global_load_lds_dwordx4 v[130:131], off
	v_lshl_add_u64 v[130:131], s[26:27], 0, v[156:157]
	s_mov_b32 m0, s67
	s_add_i32 s46, s67, 0x2000
	global_load_lds_dwordx4 v[130:131], off
	v_lshl_add_u64 v[130:131], s[26:27], 0, v[160:161]
	s_mov_b32 m0, s46
	v_lshl_add_u64 v[252:253], s[40:41], 0, v[154:155]
	global_load_lds_dwordx4 v[130:131], off
	v_lshl_add_u64 v[130:131], v[252:253], 0, s[18:19]
	s_mov_b32 m0, s48
	v_lshl_add_u64 v[166:167], s[40:41], 0, v[158:159]
	global_load_lds_dwordx4 v[130:131], off
	v_lshl_add_u64 v[130:131], v[166:167], 0, s[18:19]
	s_mov_b32 m0, s49
	s_nop 0
	global_load_lds_dwordx4 v[130:131], off
	s_waitcnt vmcnt(8)
	s_waitcnt lgkmcnt(0)
	s_setprio 1
	s_barrier
	v_mfma_f32_16x16x32_bf16 v[130:133], v[2:5], v[62:65], 0
	v_mfma_f32_16x16x32_bf16 v[140:143], v[2:5], v[94:97], 0
	v_mfma_f32_16x16x32_bf16 v[148:151], v[2:5], v[110:113], 0
	v_mfma_f32_16x16x32_bf16 v[2:5], v[2:5], v[122:125], 0
	v_mfma_f32_16x16x32_bf16 v[132:135], v[6:9], v[90:93], v[130:133]
	v_mfma_f32_16x16x32_bf16 v[140:143], v[6:9], v[106:109], v[140:143]
	v_mfma_f32_16x16x32_bf16 v[148:151], v[6:9], v[118:121], v[148:151]
	v_mfma_f32_16x16x32_bf16 v[2:5], v[6:9], v[126:129], v[2:5]
	v_mfma_f32_16x16x32_bf16 v[6:9], v[10:13], v[122:125], 0
	v_mfma_f32_16x16x32_bf16 v[136:139], v[10:13], v[62:65], 0
	v_mfma_f32_16x16x32_bf16 v[144:147], v[10:13], v[94:97], 0
	v_mfma_f32_16x16x32_bf16 v[170:173], v[10:13], v[110:113], 0
	v_mfma_f32_16x16x32_bf16 v[6:9], v[14:17], v[126:129], v[6:9]
	v_mfma_f32_16x16x32_bf16 v[136:139], v[14:17], v[90:93], v[136:139]
	v_mfma_f32_16x16x32_bf16 v[144:147], v[14:17], v[106:109], v[144:147]
	v_mfma_f32_16x16x32_bf16 v[170:173], v[14:17], v[118:121], v[170:173]
	s_setprio 0
	s_setprio 1
	v_mfma_f32_16x16x32_bf16 v[10:13], v[18:21], v[62:65], 0
	v_mfma_f32_16x16x32_bf16 v[174:177], v[22:25], v[90:93], v[10:13]
	v_mfma_f32_16x16x32_bf16 v[10:13], v[26:29], v[62:65], 0
	v_mfma_f32_16x16x32_bf16 v[178:181], v[30:33], v[90:93], v[10:13]
	v_mfma_f32_16x16x32_bf16 v[10:13], v[18:21], v[94:97], 0
	v_mfma_f32_16x16x32_bf16 v[186:189], v[22:25], v[106:109], v[10:13]
	v_mfma_f32_16x16x32_bf16 v[10:13], v[26:29], v[94:97], 0
	v_mfma_f32_16x16x32_bf16 v[190:193], v[30:33], v[106:109], v[10:13]
	v_mfma_f32_16x16x32_bf16 v[10:13], v[18:21], v[110:113], 0
	v_mfma_f32_16x16x32_bf16 v[194:197], v[22:25], v[118:121], v[10:13]
	v_mfma_f32_16x16x32_bf16 v[10:13], v[26:29], v[110:113], 0
	v_mfma_f32_16x16x32_bf16 v[198:201], v[30:33], v[118:121], v[10:13]
	v_mfma_f32_16x16x32_bf16 v[10:13], v[18:21], v[122:125], 0
	v_mfma_f32_16x16x32_bf16 v[202:205], v[22:25], v[126:129], v[10:13]
	v_mfma_f32_16x16x32_bf16 v[10:13], v[26:29], v[122:125], 0
	v_mfma_f32_16x16x32_bf16 v[206:209], v[30:33], v[126:129], v[10:13]
	s_barrier
	s_setprio 0
	s_add_i32 s47, 0, 0x18000
	s_add_i32 s56, 0, 0x1c000
	v_add_u32_e32 v130, s47, v1
	v_add_u32_e32 v131, s56, v1
	s_nop 0
	ds_read_b128 v[10:13], v130
	ds_read_b128 v[14:17], v130 offset:1024
	ds_read_b128 v[18:21], v130 offset:2048
	ds_read_b128 v[22:25], v130 offset:3072
	ds_read_b128 v[210:213], v131
	ds_read_b128 v[214:217], v131 offset:1024
	ds_read_b128 v[218:221], v131 offset:2048
	ds_read_b128 v[222:225], v131 offset:3072
	s_add_u32 s26, s40, 0x20100
	s_addc_u32 s27, s41, 0
	s_mov_b32 m0, s50
	v_lshl_add_u64 v[90:91], s[26:27], 0, v[154:155]
	ds_read_b128 v[26:29], v184 offset:32768
	ds_read_b128 v[30:33], v184 offset:33792
	ds_read_b128 v[62:65], v184 offset:34816
	ds_read_b128 v[226:229], v184 offset:35840
	ds_read_b128 v[230:233], v184 offset:36864
	ds_read_b128 v[234:237], v184 offset:37888
	ds_read_b128 v[238:241], v184 offset:38912
	ds_read_b128 v[242:245], v184 offset:39936
	global_load_lds_dwordx4 v[90:91], off
	v_lshl_add_u64 v[90:91], s[26:27], 0, v[158:159]
	s_mov_b32 m0, s51
	s_nop 0
	global_load_lds_dwordx4 v[90:91], off
	s_waitcnt vmcnt(8)
	s_waitcnt lgkmcnt(0)
	s_setprio 1
	s_barrier
	v_mfma_f32_16x16x32_bf16 v[66:69], v[10:13], v[26:29], v[66:69]
	v_mfma_f32_16x16x32_bf16 v[122:125], v[14:17], v[30:33], v[66:69]
	v_mfma_f32_16x16x32_bf16 v[66:69], v[18:21], v[26:29], v[70:73]
	v_mfma_f32_16x16x32_bf16 v[118:121], v[22:25], v[30:33], v[66:69]
	v_mfma_f32_16x16x32_bf16 v[66:69], v[10:13], v[62:65], v[74:77]
	v_mfma_f32_16x16x32_bf16 v[110:113], v[14:17], v[226:229], v[66:69]
	v_mfma_f32_16x16x32_bf16 v[66:69], v[18:21], v[62:65], v[78:81]
	v_mfma_f32_16x16x32_bf16 v[106:109], v[22:25], v[226:229], v[66:69]
	v_mfma_f32_16x16x32_bf16 v[66:69], v[10:13], v[230:233], v[82:85]
	v_mfma_f32_16x16x32_bf16 v[94:97], v[14:17], v[234:237], v[66:69]
	v_mfma_f32_16x16x32_bf16 v[66:69], v[18:21], v[230:233], v[86:89]
	v_mfma_f32_16x16x32_bf16 v[90:93], v[22:25], v[234:237], v[66:69]
	v_mfma_f32_16x16x32_bf16 v[66:69], v[10:13], v[238:241], v[98:101]
	v_mfma_f32_16x16x32_bf16 v[78:81], v[14:17], v[242:245], v[66:69]
	v_mfma_f32_16x16x32_bf16 v[66:69], v[18:21], v[238:241], v[102:105]
	v_mfma_f32_16x16x32_bf16 v[74:77], v[22:25], v[242:245], v[66:69]
	s_setprio 0
	s_setprio 1
	v_mfma_f32_16x16x32_bf16 v[66:69], v[210:213], v[26:29], v[114:117]
	v_mfma_f32_16x16x32_bf16 v[26:29], v[218:221], v[26:29], v[34:37]
	v_mfma_f32_16x16x32_bf16 v[114:117], v[222:225], v[30:33], v[26:29]
	v_mfma_f32_16x16x32_bf16 v[26:29], v[210:213], v[62:65], v[38:41]
	v_mfma_f32_16x16x32_bf16 v[102:105], v[214:217], v[226:229], v[26:29]
	v_mfma_f32_16x16x32_bf16 v[26:29], v[218:221], v[62:65], v[42:45]
	v_mfma_f32_16x16x32_bf16 v[98:101], v[222:225], v[226:229], v[26:29]
	v_mfma_f32_16x16x32_bf16 v[26:29], v[210:213], v[230:233], v[46:49]
	v_mfma_f32_16x16x32_bf16 v[86:89], v[214:217], v[234:237], v[26:29]
	v_mfma_f32_16x16x32_bf16 v[26:29], v[218:221], v[230:233], v[50:53]
	v_mfma_f32_16x16x32_bf16 v[82:85], v[222:225], v[234:237], v[26:29]
	v_mfma_f32_16x16x32_bf16 v[26:29], v[210:213], v[238:241], v[54:57]
	v_mfma_f32_16x16x32_bf16 v[70:73], v[214:217], v[242:245], v[26:29]
	v_mfma_f32_16x16x32_bf16 v[26:29], v[218:221], v[238:241], v[58:61]
	v_mfma_f32_16x16x32_bf16 v[126:129], v[214:217], v[30:33], v[66:69]
	v_mfma_f32_16x16x32_bf16 v[66:69], v[222:225], v[242:245], v[26:29]
	s_barrier
;     __host__ __device__ bool next(int i, Unit& u) const { if (!StaticOrder::next(i >> 1, u)) return false; u.seg = i & 1; return true; }
;     ...
;         const bool has_next = S.next(ui + 1, nxt);
;         const char* nA = has_next ? PG8_APTR(nxt) : cA; const char* nB = has_next ? PG8_BPTR(nxt) : cB;
;         const char* pfc = PG8_PFPTR(cA, cB); const char* pfn = PG8_PFPTR(nA, nB);
;         PG8_KITER(0);
;         for (int t = 2; t < nt; t += 2) PG8_KITER(t);
	s_setprio 0
	s_add_i32 s47, s47, s33
	s_add_i32 s68, s47, 0x2000
	s_nop 1
	v_lshl_add_u64 v[26:27], v[152:153], 0, s[20:21]
	s_mov_b32 m0, s47
	s_add_u32 s26, s38, 0x20180
	ds_read_b128 v[34:37], v184 offset:49152
	ds_read_b128 v[38:41], v184 offset:50176
	ds_read_b128 v[226:229], v184 offset:51200
	ds_read_b128 v[230:233], v184 offset:52224
	ds_read_b128 v[234:237], v184 offset:53248
	ds_read_b128 v[238:241], v184 offset:54272
	ds_read_b128 v[242:245], v184 offset:55296
	ds_read_b128 v[246:249], v184 offset:56320
	global_load_lds_dwordx4 v[26:27], off
	v_lshl_add_u64 v[26:27], v[250:251], 0, s[20:21]
	s_mov_b32 m0, s68
	s_addc_u32 s27, s39, 0
	s_add_i32 s56, s56, s33
	global_load_lds_dwordx4 v[26:27], off
	v_lshl_add_u64 v[26:27], s[26:27], 0, v[156:157]
	s_mov_b32 m0, s56
	s_add_i32 s57, s56, 0x2000
	global_load_lds_dwordx4 v[26:27], off
	v_lshl_add_u64 v[26:27], s[26:27], 0, v[160:161]
	s_mov_b32 m0, s57
	s_nop 0
	global_load_lds_dwordx4 v[26:27], off
	v_lshl_add_u64 v[26:27], v[252:253], 0, s[20:21]
	s_mov_b32 m0, s52
	s_nop 0
	global_load_lds_dwordx4 v[26:27], off
	v_lshl_add_u64 v[26:27], v[166:167], 0, s[20:21]
	s_mov_b32 m0, s53
	s_nop 0
	global_load_lds_dwordx4 v[26:27], off
	s_waitcnt vmcnt(8)
	s_waitcnt lgkmcnt(0)
	s_setprio 1
	s_barrier
	v_mfma_f32_16x16x32_bf16 v[26:29], v[10:13], v[34:37], v[132:135]
	v_mfma_f32_16x16x32_bf16 v[58:61], v[14:17], v[38:41], v[26:29]
	v_mfma_f32_16x16x32_bf16 v[26:29], v[18:21], v[34:37], v[136:139]
	v_mfma_f32_16x16x32_bf16 v[54:57], v[22:25], v[38:41], v[26:29]
	v_mfma_f32_16x16x32_bf16 v[26:29], v[10:13], v[226:229], v[140:143]
	v_mfma_f32_16x16x32_bf16 v[46:49], v[14:17], v[230:233], v[26:29]
	v_mfma_f32_16x16x32_bf16 v[26:29], v[18:21], v[226:229], v[144:147]
	v_mfma_f32_16x16x32_bf16 v[42:45], v[22:25], v[230:233], v[26:29]
	v_mfma_f32_16x16x32_bf16 v[26:29], v[10:13], v[234:237], v[148:151]
	v_mfma_f32_16x16x32_bf16 v[2:5], v[10:13], v[242:245], v[2:5]
	v_mfma_f32_16x16x32_bf16 v[30:33], v[14:17], v[238:241], v[26:29]
	v_mfma_f32_16x16x32_bf16 v[26:29], v[18:21], v[234:237], v[170:173]
	v_mfma_f32_16x16x32_bf16 v[14:17], v[14:17], v[246:249], v[2:5]
	v_mfma_f32_16x16x32_bf16 v[2:5], v[18:21], v[242:245], v[6:9]
	v_mfma_f32_16x16x32_bf16 v[26:29], v[22:25], v[238:241], v[26:29]
	v_mfma_f32_16x16x32_bf16 v[10:13], v[22:25], v[246:249], v[2:5]
	s_setprio 0
	s_setprio 1
	v_mfma_f32_16x16x32_bf16 v[2:5], v[210:213], v[34:37], v[174:177]
	v_mfma_f32_16x16x32_bf16 v[62:65], v[214:217], v[38:41], v[2:5]
	v_mfma_f32_16x16x32_bf16 v[2:5], v[218:221], v[34:37], v[178:181]
	v_mfma_f32_16x16x32_bf16 v[50:53], v[222:225], v[38:41], v[2:5]
	v_mfma_f32_16x16x32_bf16 v[2:5], v[210:213], v[226:229], v[186:189]
	v_mfma_f32_16x16x32_bf16 v[38:41], v[214:217], v[230:233], v[2:5]
	v_mfma_f32_16x16x32_bf16 v[2:5], v[218:221], v[226:229], v[190:193]
	v_mfma_f32_16x16x32_bf16 v[34:37], v[222:225], v[230:233], v[2:5]
	v_mfma_f32_16x16x32_bf16 v[2:5], v[210:213], v[234:237], v[194:197]
	v_mfma_f32_16x16x32_bf16 v[22:25], v[214:217], v[238:241], v[2:5]
	v_mfma_f32_16x16x32_bf16 v[2:5], v[218:221], v[234:237], v[198:201]
	v_mfma_f32_16x16x32_bf16 v[18:21], v[222:225], v[238:241], v[2:5]
	v_mfma_f32_16x16x32_bf16 v[2:5], v[210:213], v[242:245], v[202:205]
	v_mfma_f32_16x16x32_bf16 v[6:9], v[214:217], v[246:249], v[2:5]
	v_mfma_f32_16x16x32_bf16 v[2:5], v[218:221], v[242:245], v[206:209]
	v_mfma_f32_16x16x32_bf16 v[2:5], v[222:225], v[246:249], v[2:5]
	s_barrier
	s_setprio 0
	s_add_u32 s40, s40, 0x20180
	s_addc_u32 s41, s41, 0
	s_add_u32 s26, s38, 0x200
	s_addc_u32 s27, s39, 0
	s_mov_b32 s69, 0
.LBB0_1261:
	ds_read_b128 v[132:135], v182
	ds_read_b128 v[136:139], v182 offset:1024
	ds_read_b128 v[140:143], v182 offset:2048
	ds_read_b128 v[144:147], v182 offset:3072
	ds_read_b128 v[148:151], v183
	ds_read_b128 v[170:173], v183 offset:1024
	ds_read_b128 v[174:177], v183 offset:2048
	ds_read_b128 v[178:181], v183 offset:3072
	s_add_u32 s38, s40, 0xfffe0080
	s_addc_u32 s39, s41, -1
	s_cmp_eq_u32 s69, 4
	s_cselect_b32 s43, s23, s39
	s_cselect_b32 s42, s31, s38
	s_cselect_b32 s39, s0, s27
	s_cselect_b32 s38, s66, s26
	s_mov_b32 m0, s59
	ds_read_b128 v[186:189], v184
	ds_read_b128 v[190:193], v184 offset:1024
	ds_read_b128 v[194:197], v184 offset:2048
	ds_read_b128 v[198:201], v184 offset:3072
	ds_read_b128 v[202:205], v184 offset:4096
	ds_read_b128 v[206:209], v184 offset:5120
	ds_read_b128 v[210:213], v184 offset:6144
	ds_read_b128 v[214:217], v184 offset:7168
	global_load_lds_dwordx4 v162, s[40:41]
	s_mov_b32 m0, s60
	s_nop 0
	global_load_lds_dwordx4 v164, s[40:41]
	s_waitcnt vmcnt(8)
	s_waitcnt lgkmcnt(0)
	s_setprio 1
	s_barrier
	v_mfma_f32_16x16x32_bf16 v[122:125], v[132:135], v[186:189], v[122:125]
	v_mfma_f32_16x16x32_bf16 v[118:121], v[140:143], v[186:189], v[118:121]
	v_mfma_f32_16x16x32_bf16 v[110:113], v[132:135], v[194:197], v[110:113]
	v_mfma_f32_16x16x32_bf16 v[106:109], v[140:143], v[194:197], v[106:109]
	v_mfma_f32_16x16x32_bf16 v[94:97], v[132:135], v[202:205], v[94:97]
	v_mfma_f32_16x16x32_bf16 v[90:93], v[140:143], v[202:205], v[90:93]
	v_mfma_f32_16x16x32_bf16 v[78:81], v[132:135], v[210:213], v[78:81]
	v_mfma_f32_16x16x32_bf16 v[74:77], v[140:143], v[210:213], v[74:77]
	v_mfma_f32_16x16x32_bf16 v[122:125], v[136:139], v[190:193], v[122:125]
	v_mfma_f32_16x16x32_bf16 v[118:121], v[144:147], v[190:193], v[118:121]
	v_mfma_f32_16x16x32_bf16 v[110:113], v[136:139], v[198:201], v[110:113]
	v_mfma_f32_16x16x32_bf16 v[106:109], v[144:147], v[198:201], v[106:109]
	v_mfma_f32_16x16x32_bf16 v[94:97], v[136:139], v[206:209], v[94:97]
	v_mfma_f32_16x16x32_bf16 v[90:93], v[144:147], v[206:209], v[90:93]
	v_mfma_f32_16x16x32_bf16 v[78:81], v[136:139], v[214:217], v[78:81]
	v_mfma_f32_16x16x32_bf16 v[74:77], v[144:147], v[214:217], v[74:77]
	s_setprio 0
	s_setprio 1
	v_mfma_f32_16x16x32_bf16 v[126:129], v[148:151], v[186:189], v[126:129]
	v_mfma_f32_16x16x32_bf16 v[114:117], v[174:177], v[186:189], v[114:117]
	v_mfma_f32_16x16x32_bf16 v[102:105], v[148:151], v[194:197], v[102:105]
	v_mfma_f32_16x16x32_bf16 v[98:101], v[174:177], v[194:197], v[98:101]
	v_mfma_f32_16x16x32_bf16 v[86:89], v[148:151], v[202:205], v[86:89]
	v_mfma_f32_16x16x32_bf16 v[82:85], v[174:177], v[202:205], v[82:85]
	v_mfma_f32_16x16x32_bf16 v[70:73], v[148:151], v[210:213], v[70:73]
	v_mfma_f32_16x16x32_bf16 v[66:69], v[174:177], v[210:213], v[66:69]
	v_mfma_f32_16x16x32_bf16 v[126:129], v[170:173], v[190:193], v[126:129]
	v_mfma_f32_16x16x32_bf16 v[114:117], v[178:181], v[190:193], v[114:117]
	v_mfma_f32_16x16x32_bf16 v[102:105], v[170:173], v[198:201], v[102:105]
	v_mfma_f32_16x16x32_bf16 v[98:101], v[178:181], v[198:201], v[98:101]
	v_mfma_f32_16x16x32_bf16 v[86:89], v[170:173], v[206:209], v[86:89]
	v_mfma_f32_16x16x32_bf16 v[82:85], v[178:181], v[206:209], v[82:85]
	v_mfma_f32_16x16x32_bf16 v[70:73], v[170:173], v[214:217], v[70:73]
	v_mfma_f32_16x16x32_bf16 v[66:69], v[178:181], v[214:217], v[66:69]
	s_barrier
	s_setprio 0
	s_mov_b32 m0, s61
	s_mov_b64 s[98:99], s[38:39]
	s_add_u32 s70, s38, 0x20000
	ds_read_b128 v[186:189], v184 offset:16384
	ds_read_b128 v[190:193], v184 offset:17408
	ds_read_b128 v[194:197], v184 offset:18432
	ds_read_b128 v[198:201], v184 offset:19456
	ds_read_b128 v[202:205], v184 offset:20480
	ds_read_b128 v[206:209], v184 offset:21504
	ds_read_b128 v[210:213], v184 offset:22528
	ds_read_b128 v[214:217], v184 offset:23552
	global_load_lds_dwordx4 v156, s[38:39]
	s_mov_b32 m0, s62
	s_addc_u32 s71, s39, 0
	global_load_lds_dwordx4 v160, s[38:39]
	s_mov_b32 m0, s67
	s_mov_b64 s[100:101], s[42:43]
	global_load_lds_dwordx4 v156, s[70:71]
	s_mov_b32 m0, s46
	s_nop 0
	global_load_lds_dwordx4 v160, s[70:71]
	s_mov_b32 m0, s48
	s_nop 0
	global_load_lds_dwordx4 v154, s[42:43]
	s_mov_b32 m0, s49
	s_nop 0
	global_load_lds_dwordx4 v158, s[42:43]
	s_waitcnt vmcnt(8)
	s_waitcnt lgkmcnt(0)
	s_setprio 1
	s_barrier
	v_mfma_f32_16x16x32_bf16 v[58:61], v[132:135], v[186:189], v[58:61]
	v_mfma_f32_16x16x32_bf16 v[54:57], v[140:143], v[186:189], v[54:57]
	v_mfma_f32_16x16x32_bf16 v[46:49], v[132:135], v[194:197], v[46:49]
	v_mfma_f32_16x16x32_bf16 v[42:45], v[140:143], v[194:197], v[42:45]
	v_mfma_f32_16x16x32_bf16 v[30:33], v[132:135], v[202:205], v[30:33]
	v_mfma_f32_16x16x32_bf16 v[26:29], v[140:143], v[202:205], v[26:29]
	v_mfma_f32_16x16x32_bf16 v[14:17], v[132:135], v[210:213], v[14:17]
	v_mfma_f32_16x16x32_bf16 v[10:13], v[140:143], v[210:213], v[10:13]
	v_mfma_f32_16x16x32_bf16 v[58:61], v[136:139], v[190:193], v[58:61]
	v_mfma_f32_16x16x32_bf16 v[54:57], v[144:147], v[190:193], v[54:57]
	v_mfma_f32_16x16x32_bf16 v[46:49], v[136:139], v[198:201], v[46:49]
	v_mfma_f32_16x16x32_bf16 v[42:45], v[144:147], v[198:201], v[42:45]
	v_mfma_f32_16x16x32_bf16 v[30:33], v[136:139], v[206:209], v[30:33]
	v_mfma_f32_16x16x32_bf16 v[26:29], v[144:147], v[206:209], v[26:29]
	v_mfma_f32_16x16x32_bf16 v[14:17], v[136:139], v[214:217], v[14:17]
	v_mfma_f32_16x16x32_bf16 v[10:13], v[144:147], v[214:217], v[10:13]
	s_setprio 0
	s_setprio 1
	v_mfma_f32_16x16x32_bf16 v[62:65], v[148:151], v[186:189], v[62:65]
	v_mfma_f32_16x16x32_bf16 v[50:53], v[174:177], v[186:189], v[50:53]
	v_mfma_f32_16x16x32_bf16 v[38:41], v[148:151], v[194:197], v[38:41]
	v_mfma_f32_16x16x32_bf16 v[34:37], v[174:177], v[194:197], v[34:37]
	v_mfma_f32_16x16x32_bf16 v[22:25], v[148:151], v[202:205], v[22:25]
	v_mfma_f32_16x16x32_bf16 v[18:21], v[174:177], v[202:205], v[18:21]
	v_mfma_f32_16x16x32_bf16 v[6:9], v[148:151], v[210:213], v[6:9]
	v_mfma_f32_16x16x32_bf16 v[2:5], v[174:177], v[210:213], v[2:5]
	v_mfma_f32_16x16x32_bf16 v[62:65], v[170:173], v[190:193], v[62:65]
	v_mfma_f32_16x16x32_bf16 v[50:53], v[178:181], v[190:193], v[50:53]
	v_mfma_f32_16x16x32_bf16 v[38:41], v[170:173], v[198:201], v[38:41]
	v_mfma_f32_16x16x32_bf16 v[34:37], v[178:181], v[198:201], v[34:37]
	v_mfma_f32_16x16x32_bf16 v[22:25], v[170:173], v[206:209], v[22:25]
	v_mfma_f32_16x16x32_bf16 v[18:21], v[178:181], v[206:209], v[18:21]
	v_mfma_f32_16x16x32_bf16 v[6:9], v[170:173], v[214:217], v[6:9]
	v_mfma_f32_16x16x32_bf16 v[2:5], v[178:181], v[214:217], v[2:5]
	s_barrier
; #define PG8_BAR __builtin_amdgcn_s_barrier()
;     ...
;         for (int t = 2; t < nt; t += 2) PG8_KITER(t);
;         if constexpr (ALIGN_EPI) { if (wr == 0) PG8_BAR; }
	s_setprio 0
	ds_read_b128 v[132:135], v130
	ds_read_b128 v[136:139], v130 offset:1024
	ds_read_b128 v[140:143], v130 offset:2048
	ds_read_b128 v[144:147], v130 offset:3072
	ds_read_b128 v[148:151], v131
	ds_read_b128 v[170:173], v131 offset:1024
	ds_read_b128 v[174:177], v131 offset:2048
	ds_read_b128 v[178:181], v131 offset:3072
	s_add_u32 s42, s42, 0x20000
	s_addc_u32 s43, s43, 0
	s_mov_b32 m0, s50
	ds_read_b128 v[186:189], v184 offset:32768
	ds_read_b128 v[190:193], v184 offset:33792
	ds_read_b128 v[194:197], v184 offset:34816
	ds_read_b128 v[198:201], v184 offset:35840
	ds_read_b128 v[202:205], v184 offset:36864
	ds_read_b128 v[206:209], v184 offset:37888
	ds_read_b128 v[210:213], v184 offset:38912
	ds_read_b128 v[214:217], v184 offset:39936
	global_load_lds_dwordx4 v154, s[42:43]
	s_mov_b32 m0, s51
	s_nop 0
	global_load_lds_dwordx4 v158, s[42:43]
	s_waitcnt vmcnt(8)
	s_waitcnt lgkmcnt(0)
	s_setprio 1
	s_barrier
	v_mfma_f32_16x16x32_bf16 v[122:125], v[132:135], v[186:189], v[122:125]
	v_mfma_f32_16x16x32_bf16 v[118:121], v[140:143], v[186:189], v[118:121]
	v_mfma_f32_16x16x32_bf16 v[110:113], v[132:135], v[194:197], v[110:113]
	v_mfma_f32_16x16x32_bf16 v[106:109], v[140:143], v[194:197], v[106:109]
	v_mfma_f32_16x16x32_bf16 v[94:97], v[132:135], v[202:205], v[94:97]
	v_mfma_f32_16x16x32_bf16 v[90:93], v[140:143], v[202:205], v[90:93]
	v_mfma_f32_16x16x32_bf16 v[78:81], v[132:135], v[210:213], v[78:81]
	v_mfma_f32_16x16x32_bf16 v[74:77], v[140:143], v[210:213], v[74:77]
	v_mfma_f32_16x16x32_bf16 v[122:125], v[136:139], v[190:193], v[122:125]
	v_mfma_f32_16x16x32_bf16 v[118:121], v[144:147], v[190:193], v[118:121]
	v_mfma_f32_16x16x32_bf16 v[110:113], v[136:139], v[198:201], v[110:113]
	v_mfma_f32_16x16x32_bf16 v[106:109], v[144:147], v[198:201], v[106:109]
	v_mfma_f32_16x16x32_bf16 v[94:97], v[136:139], v[206:209], v[94:97]
	v_mfma_f32_16x16x32_bf16 v[90:93], v[144:147], v[206:209], v[90:93]
	v_mfma_f32_16x16x32_bf16 v[78:81], v[136:139], v[214:217], v[78:81]
	v_mfma_f32_16x16x32_bf16 v[74:77], v[144:147], v[214:217], v[74:77]
	s_setprio 0
	s_setprio 1
	v_mfma_f32_16x16x32_bf16 v[126:129], v[148:151], v[186:189], v[126:129]
	v_mfma_f32_16x16x32_bf16 v[114:117], v[174:177], v[186:189], v[114:117]
	v_mfma_f32_16x16x32_bf16 v[102:105], v[148:151], v[194:197], v[102:105]
	v_mfma_f32_16x16x32_bf16 v[98:101], v[174:177], v[194:197], v[98:101]
	v_mfma_f32_16x16x32_bf16 v[86:89], v[148:151], v[202:205], v[86:89]
	v_mfma_f32_16x16x32_bf16 v[82:85], v[174:177], v[202:205], v[82:85]
	v_mfma_f32_16x16x32_bf16 v[70:73], v[148:151], v[210:213], v[70:73]
	v_mfma_f32_16x16x32_bf16 v[66:69], v[174:177], v[210:213], v[66:69]
	v_mfma_f32_16x16x32_bf16 v[126:129], v[170:173], v[190:193], v[126:129]
	v_mfma_f32_16x16x32_bf16 v[114:117], v[178:181], v[190:193], v[114:117]
	v_mfma_f32_16x16x32_bf16 v[102:105], v[170:173], v[198:201], v[102:105]
	v_mfma_f32_16x16x32_bf16 v[98:101], v[178:181], v[198:201], v[98:101]
	v_mfma_f32_16x16x32_bf16 v[86:89], v[170:173], v[206:209], v[86:89]
	v_mfma_f32_16x16x32_bf16 v[82:85], v[178:181], v[206:209], v[82:85]
	v_mfma_f32_16x16x32_bf16 v[70:73], v[170:173], v[214:217], v[70:73]
	v_mfma_f32_16x16x32_bf16 v[66:69], v[178:181], v[214:217], v[66:69]
	s_barrier
	s_setprio 0
	s_mov_b32 m0, s47
	s_add_u32 s98, s98, 0x80
	s_addc_u32 s99, s99, 0
	s_add_u32 s100, s100, 0x80
	s_addc_u32 s101, s101, 0
	s_add_u32 s38, s38, 0x20080
	ds_read_b128 v[186:189], v184 offset:49152
	ds_read_b128 v[190:193], v184 offset:50176
	ds_read_b128 v[194:197], v184 offset:51200
	ds_read_b128 v[198:201], v184 offset:52224
	ds_read_b128 v[202:205], v184 offset:53248
	ds_read_b128 v[206:209], v184 offset:54272
	ds_read_b128 v[210:213], v184 offset:55296
	ds_read_b128 v[214:217], v184 offset:56320
	global_load_lds_dwordx4 v156, s[98:99]
	s_mov_b32 m0, s68
	s_addc_u32 s39, s39, 0
	global_load_lds_dwordx4 v160, s[98:99]
	s_mov_b32 m0, s56
	s_nop 0
	global_load_lds_dwordx4 v156, s[38:39]
	s_mov_b32 m0, s57
	s_nop 0
	global_load_lds_dwordx4 v160, s[38:39]
	s_mov_b32 m0, s52
	s_nop 0
	global_load_lds_dwordx4 v154, s[100:101]
	s_mov_b32 m0, s53
	s_nop 0
	global_load_lds_dwordx4 v158, s[100:101]
	s_waitcnt vmcnt(8)
	s_waitcnt lgkmcnt(0)
	s_setprio 1
	s_barrier
	v_mfma_f32_16x16x32_bf16 v[58:61], v[132:135], v[186:189], v[58:61]
	v_mfma_f32_16x16x32_bf16 v[54:57], v[140:143], v[186:189], v[54:57]
	v_mfma_f32_16x16x32_bf16 v[46:49], v[132:135], v[194:197], v[46:49]
	v_mfma_f32_16x16x32_bf16 v[42:45], v[140:143], v[194:197], v[42:45]
	v_mfma_f32_16x16x32_bf16 v[30:33], v[132:135], v[202:205], v[30:33]
	v_mfma_f32_16x16x32_bf16 v[26:29], v[140:143], v[202:205], v[26:29]
	v_mfma_f32_16x16x32_bf16 v[14:17], v[132:135], v[210:213], v[14:17]
	v_mfma_f32_16x16x32_bf16 v[10:13], v[140:143], v[210:213], v[10:13]
	v_mfma_f32_16x16x32_bf16 v[58:61], v[136:139], v[190:193], v[58:61]
	v_mfma_f32_16x16x32_bf16 v[54:57], v[144:147], v[190:193], v[54:57]
	v_mfma_f32_16x16x32_bf16 v[46:49], v[136:139], v[198:201], v[46:49]
	v_mfma_f32_16x16x32_bf16 v[42:45], v[144:147], v[198:201], v[42:45]
	v_mfma_f32_16x16x32_bf16 v[30:33], v[136:139], v[206:209], v[30:33]
	v_mfma_f32_16x16x32_bf16 v[26:29], v[144:147], v[206:209], v[26:29]
	v_mfma_f32_16x16x32_bf16 v[14:17], v[136:139], v[214:217], v[14:17]
	v_mfma_f32_16x16x32_bf16 v[10:13], v[144:147], v[214:217], v[10:13]
	s_setprio 0
	s_setprio 1
	v_mfma_f32_16x16x32_bf16 v[62:65], v[148:151], v[186:189], v[62:65]
	v_mfma_f32_16x16x32_bf16 v[50:53], v[174:177], v[186:189], v[50:53]
	v_mfma_f32_16x16x32_bf16 v[38:41], v[148:151], v[194:197], v[38:41]
	v_mfma_f32_16x16x32_bf16 v[34:37], v[174:177], v[194:197], v[34:37]
	v_mfma_f32_16x16x32_bf16 v[22:25], v[148:151], v[202:205], v[22:25]
	v_mfma_f32_16x16x32_bf16 v[18:21], v[174:177], v[202:205], v[18:21]
	v_mfma_f32_16x16x32_bf16 v[6:9], v[148:151], v[210:213], v[6:9]
	v_mfma_f32_16x16x32_bf16 v[2:5], v[174:177], v[210:213], v[2:5]
	v_mfma_f32_16x16x32_bf16 v[62:65], v[170:173], v[190:193], v[62:65]
	v_mfma_f32_16x16x32_bf16 v[50:53], v[178:181], v[190:193], v[50:53]
	v_mfma_f32_16x16x32_bf16 v[38:41], v[170:173], v[198:201], v[38:41]
	v_mfma_f32_16x16x32_bf16 v[34:37], v[178:181], v[198:201], v[34:37]
	v_mfma_f32_16x16x32_bf16 v[22:25], v[170:173], v[206:209], v[22:25]
	v_mfma_f32_16x16x32_bf16 v[18:21], v[178:181], v[206:209], v[18:21]
	v_mfma_f32_16x16x32_bf16 v[6:9], v[170:173], v[214:217], v[6:9]
	v_mfma_f32_16x16x32_bf16 v[2:5], v[178:181], v[214:217], v[2:5]
	s_barrier
	s_setprio 0
	s_add_i32 s69, s69, 2
	s_add_u32 s40, s40, 0x100
	s_addc_u32 s41, s41, 0
	s_add_u32 s26, s26, 0x100
	s_addc_u32 s27, s27, 0
	s_cmp_gt_u32 s69, 5
	s_cbranch_scc0 .LBB0_1261
	s_and_b64 vcc, exec, s[16:17]
	s_cbranch_vccz .LBB0_1264
	s_barrier

;     __host__ __device__ bool next(int i, Unit& u) const { if (!StaticOrder::next(i >> 1, u)) return false; u.seg = i & 1; return true; }
;     ...
;         const bool has_next = S.next(ui + 1, nxt);
;         const char* nA = has_next ? PG8_APTR(nxt) : cA; const char* nB = has_next ? PG8_BPTR(nxt) : cB;
;         const char* pfc = PG8_PFPTR(cA, cB); const char* pfn = PG8_PFPTR(nA, nB);
;         PG8_KITER(0);
.LBB0_1344:
	s_ashr_i32 s25, s24, 31
	ds_read_b128 v[2:5], v150
	ds_read_b128 v[6:9], v150 offset:1024
	ds_read_b128 v[10:13], v150 offset:2048
	ds_read_b128 v[14:17], v150 offset:3072
	ds_read_b128 v[18:21], v151
	ds_read_b128 v[22:25], v151 offset:1024
	ds_read_b128 v[26:29], v151 offset:2048
	ds_read_b128 v[30:33], v151 offset:3072
	s_lshl_b64 s[26:27], s[24:25], 21
	s_add_u32 s28, s36, s26
	s_addc_u32 s29, s37, s27
	s_and_b64 s[26:27], s[4:5], exec
	s_cselect_b32 s1, s29, s41
	s_cselect_b32 s25, s28, s40
	s_and_b32 s8, s65, 0x7fffffff
	s_lshl_b64 s[26:27], s[8:9], 21
	s_add_u32 s30, s96, s26
	s_addc_u32 s31, s97, s27
	s_and_b64 s[26:27], s[4:5], exec
	s_cselect_b32 s8, s31, s39
	s_cselect_b32 s67, s30, s38
	s_add_u32 s26, s40, 0x100080
	s_addc_u32 s27, s41, 0
	s_mov_b32 m0, s53
	v_lshl_add_u64 v[66:67], s[26:27], 0, v[136:137]
	ds_read_b128 v[34:37], v152
	ds_read_b128 v[38:41], v152 offset:1024
	ds_read_b128 v[42:45], v152 offset:2048
	ds_read_b128 v[46:49], v152 offset:3072
	ds_read_b128 v[50:53], v152 offset:4096
	ds_read_b128 v[54:57], v152 offset:5120
	ds_read_b128 v[58:61], v152 offset:6144
	ds_read_b128 v[62:65], v152 offset:7168
	global_load_lds_dwordx4 v[66:67], off
	v_lshl_add_u64 v[66:67], s[26:27], 0, v[132:133]
	s_mov_b32 m0, s54
	s_nop 0
	global_load_lds_dwordx4 v[66:67], off
	s_waitcnt vmcnt(8)
	s_waitcnt lgkmcnt(0)
	s_setprio 1
	s_barrier
	v_mfma_f32_16x16x32_bf16 v[86:89], v[10:13], v[50:53], 0
	v_mfma_f32_16x16x32_bf16 v[90:93], v[14:17], v[54:57], v[86:89]
	v_mfma_f32_16x16x32_bf16 v[86:89], v[2:5], v[58:61], 0
	v_mfma_f32_16x16x32_bf16 v[66:69], v[2:5], v[34:37], 0
	v_mfma_f32_16x16x32_bf16 v[70:73], v[10:13], v[34:37], 0
	v_mfma_f32_16x16x32_bf16 v[74:77], v[2:5], v[42:45], 0
	v_mfma_f32_16x16x32_bf16 v[78:81], v[10:13], v[42:45], 0
	v_mfma_f32_16x16x32_bf16 v[82:85], v[2:5], v[50:53], 0
	v_mfma_f32_16x16x32_bf16 v[94:97], v[6:9], v[62:65], v[86:89]
	v_mfma_f32_16x16x32_bf16 v[86:89], v[10:13], v[58:61], 0
	v_mfma_f32_16x16x32_bf16 v[66:69], v[6:9], v[38:41], v[66:69]
	v_mfma_f32_16x16x32_bf16 v[70:73], v[14:17], v[38:41], v[70:73]
	v_mfma_f32_16x16x32_bf16 v[74:77], v[6:9], v[46:49], v[74:77]
	v_mfma_f32_16x16x32_bf16 v[78:81], v[14:17], v[46:49], v[78:81]
	v_mfma_f32_16x16x32_bf16 v[82:85], v[6:9], v[54:57], v[82:85]
	v_mfma_f32_16x16x32_bf16 v[106:109], v[14:17], v[62:65], v[86:89]
	s_setprio 0
	s_setprio 1
	v_mfma_f32_16x16x32_bf16 v[86:89], v[18:21], v[34:37], 0
	v_mfma_f32_16x16x32_bf16 v[34:37], v[26:29], v[34:37], 0
	v_mfma_f32_16x16x32_bf16 v[110:113], v[22:25], v[38:41], v[86:89]
	v_mfma_f32_16x16x32_bf16 v[34:37], v[30:33], v[38:41], v[34:37]
	v_mfma_f32_16x16x32_bf16 v[38:41], v[18:21], v[42:45], 0
	v_mfma_f32_16x16x32_bf16 v[42:45], v[26:29], v[42:45], 0
	v_mfma_f32_16x16x32_bf16 v[38:41], v[22:25], v[46:49], v[38:41]
	v_mfma_f32_16x16x32_bf16 v[42:45], v[30:33], v[46:49], v[42:45]
	v_mfma_f32_16x16x32_bf16 v[46:49], v[18:21], v[50:53], 0
	v_mfma_f32_16x16x32_bf16 v[50:53], v[26:29], v[50:53], 0
	v_mfma_f32_16x16x32_bf16 v[46:49], v[22:25], v[54:57], v[46:49]
	v_mfma_f32_16x16x32_bf16 v[50:53], v[30:33], v[54:57], v[50:53]
	v_mfma_f32_16x16x32_bf16 v[54:57], v[18:21], v[58:61], 0
	v_mfma_f32_16x16x32_bf16 v[58:61], v[26:29], v[58:61], 0
	v_mfma_f32_16x16x32_bf16 v[54:57], v[22:25], v[62:65], v[54:57]
	v_mfma_f32_16x16x32_bf16 v[58:61], v[30:33], v[62:65], v[58:61]
	s_barrier
	s_setprio 0
	v_lshl_add_u64 v[252:253], s[38:39], 0, v[134:135]
	s_mov_b32 m0, s59
	v_lshl_add_u64 v[146:147], v[252:253], 0, s[20:21]
	v_lshl_add_u64 v[142:143], s[38:39], 0, v[130:131]
	s_add_u32 s26, s38, 0x100100
	ds_read_b128 v[62:65], v152 offset:16384
	ds_read_b128 v[86:89], v152 offset:17408
	ds_read_b128 v[98:101], v152 offset:18432
	ds_read_b128 v[102:105], v152 offset:19456
	ds_read_b128 v[114:117], v152 offset:20480
	ds_read_b128 v[118:121], v152 offset:21504
	ds_read_b128 v[122:125], v152 offset:22528
	ds_read_b128 v[126:129], v152 offset:23552
	global_load_lds_dwordx4 v[146:147], off
	v_lshl_add_u64 v[146:147], v[142:143], 0, s[20:21]
	s_mov_b32 m0, s60
	s_addc_u32 s27, s39, 0
	global_load_lds_dwordx4 v[146:147], off
	v_lshl_add_u64 v[146:147], s[26:27], 0, v[134:135]
	s_mov_b32 m0, s61
	v_lshl_add_u64 v[144:145], s[40:41], 0, v[136:137]
	global_load_lds_dwordx4 v[146:147], off
	v_lshl_add_u64 v[146:147], s[26:27], 0, v[130:131]
	s_mov_b32 m0, s62
	v_lshl_add_u64 v[138:139], s[40:41], 0, v[132:133]
	global_load_lds_dwordx4 v[146:147], off
	v_lshl_add_u64 v[146:147], v[144:145], 0, s[20:21]
	s_mov_b32 m0, s13
	s_nop 0
	global_load_lds_dwordx4 v[146:147], off
	v_lshl_add_u64 v[146:147], v[138:139], 0, s[20:21]
	s_mov_b32 m0, s33
	s_nop 0
	global_load_lds_dwordx4 v[146:147], off
	s_waitcnt vmcnt(8)
	s_waitcnt lgkmcnt(0)
	s_setprio 1
	s_barrier
	v_mfma_f32_16x16x32_bf16 v[146:149], v[2:5], v[62:65], 0
	v_mfma_f32_16x16x32_bf16 v[156:159], v[6:9], v[86:89], v[146:149]
	v_mfma_f32_16x16x32_bf16 v[146:149], v[10:13], v[62:65], 0
	v_mfma_f32_16x16x32_bf16 v[160:163], v[14:17], v[86:89], v[146:149]
	v_mfma_f32_16x16x32_bf16 v[146:149], v[2:5], v[98:101], 0
	v_mfma_f32_16x16x32_bf16 v[164:167], v[6:9], v[102:105], v[146:149]
	v_mfma_f32_16x16x32_bf16 v[146:149], v[10:13], v[98:101], 0
	v_mfma_f32_16x16x32_bf16 v[168:171], v[14:17], v[102:105], v[146:149]
	v_mfma_f32_16x16x32_bf16 v[146:149], v[2:5], v[114:117], 0
	v_mfma_f32_16x16x32_bf16 v[2:5], v[2:5], v[122:125], 0
	v_mfma_f32_16x16x32_bf16 v[172:175], v[6:9], v[118:121], v[146:149]
	v_mfma_f32_16x16x32_bf16 v[2:5], v[6:9], v[126:129], v[2:5]
	v_mfma_f32_16x16x32_bf16 v[6:9], v[10:13], v[122:125], 0
	v_mfma_f32_16x16x32_bf16 v[146:149], v[10:13], v[114:117], 0
	v_mfma_f32_16x16x32_bf16 v[10:13], v[14:17], v[126:129], v[6:9]
	v_mfma_f32_16x16x32_bf16 v[176:179], v[14:17], v[118:121], v[146:149]
	s_setprio 0
	s_setprio 1
	v_mfma_f32_16x16x32_bf16 v[6:9], v[18:21], v[62:65], 0
	v_mfma_f32_16x16x32_bf16 v[14:17], v[22:25], v[86:89], v[6:9]
	v_mfma_f32_16x16x32_bf16 v[6:9], v[26:29], v[62:65], 0
	v_mfma_f32_16x16x32_bf16 v[180:183], v[30:33], v[86:89], v[6:9]
	v_mfma_f32_16x16x32_bf16 v[6:9], v[18:21], v[98:101], 0
	v_mfma_f32_16x16x32_bf16 v[184:187], v[22:25], v[102:105], v[6:9]
	v_mfma_f32_16x16x32_bf16 v[6:9], v[26:29], v[98:101], 0
	v_mfma_f32_16x16x32_bf16 v[188:191], v[30:33], v[102:105], v[6:9]
	v_mfma_f32_16x16x32_bf16 v[6:9], v[18:21], v[114:117], 0
	v_mfma_f32_16x16x32_bf16 v[192:195], v[22:25], v[118:121], v[6:9]
	v_mfma_f32_16x16x32_bf16 v[6:9], v[26:29], v[114:117], 0
	v_mfma_f32_16x16x32_bf16 v[196:199], v[30:33], v[118:121], v[6:9]
	v_mfma_f32_16x16x32_bf16 v[6:9], v[18:21], v[122:125], 0
	v_mfma_f32_16x16x32_bf16 v[200:203], v[22:25], v[126:129], v[6:9]
	v_mfma_f32_16x16x32_bf16 v[6:9], v[26:29], v[122:125], 0
	v_mfma_f32_16x16x32_bf16 v[204:207], v[30:33], v[126:129], v[6:9]
	s_barrier
	s_setprio 0
	s_add_i32 s56, 0, 0x1c000
	v_add_u32_e32 v146, s56, v155
	s_nop 2
	ds_read_b128 v[6:9], v154
	ds_read_b128 v[26:29], v154 offset:1024
	ds_read_b128 v[30:33], v154 offset:2048
	ds_read_b128 v[208:211], v154 offset:3072
	ds_read_b128 v[212:215], v146
	ds_read_b128 v[216:219], v146 offset:1024
	ds_read_b128 v[220:223], v146 offset:2048
	ds_read_b128 v[224:227], v146 offset:3072
	s_add_u32 s26, s40, 0x100100
	s_addc_u32 s27, s41, 0
	s_mov_b32 m0, s48
	v_lshl_add_u64 v[62:63], s[26:27], 0, v[136:137]
	ds_read_b128 v[18:21], v152 offset:32768
	ds_read_b128 v[22:25], v152 offset:33792
	ds_read_b128 v[228:231], v152 offset:34816
	ds_read_b128 v[232:235], v152 offset:35840
	ds_read_b128 v[236:239], v152 offset:36864
	ds_read_b128 v[240:243], v152 offset:37888
	ds_read_b128 v[244:247], v152 offset:38912
	ds_read_b128 v[248:251], v152 offset:39936
	global_load_lds_dwordx4 v[62:63], off
	v_lshl_add_u64 v[62:63], s[26:27], 0, v[132:133]
	s_mov_b32 m0, s49
	s_nop 0
	global_load_lds_dwordx4 v[62:63], off
	s_waitcnt vmcnt(8)
	s_waitcnt lgkmcnt(0)
	s_setprio 1
	s_barrier
	v_mfma_f32_16x16x32_bf16 v[62:65], v[6:9], v[18:21], v[66:69]
	v_mfma_f32_16x16x32_bf16 v[118:121], v[26:29], v[22:25], v[62:65]
	v_mfma_f32_16x16x32_bf16 v[62:65], v[30:33], v[18:21], v[70:73]
	v_mfma_f32_16x16x32_bf16 v[114:117], v[208:211], v[22:25], v[62:65]
	v_mfma_f32_16x16x32_bf16 v[62:65], v[6:9], v[228:231], v[74:77]
	v_mfma_f32_16x16x32_bf16 v[102:105], v[26:29], v[232:235], v[62:65]
	v_mfma_f32_16x16x32_bf16 v[62:65], v[30:33], v[228:231], v[78:81]
	v_mfma_f32_16x16x32_bf16 v[98:101], v[208:211], v[232:235], v[62:65]
	v_mfma_f32_16x16x32_bf16 v[62:65], v[6:9], v[236:239], v[82:85]
	v_mfma_f32_16x16x32_bf16 v[86:89], v[26:29], v[240:243], v[62:65]
	v_mfma_f32_16x16x32_bf16 v[62:65], v[30:33], v[236:239], v[90:93]
	v_mfma_f32_16x16x32_bf16 v[82:85], v[208:211], v[240:243], v[62:65]
	v_mfma_f32_16x16x32_bf16 v[62:65], v[6:9], v[244:247], v[94:97]
	v_mfma_f32_16x16x32_bf16 v[66:69], v[26:29], v[248:251], v[62:65]
	v_mfma_f32_16x16x32_bf16 v[62:65], v[30:33], v[244:247], v[106:109]
	v_mfma_f32_16x16x32_bf16 v[62:65], v[208:211], v[248:251], v[62:65]
	s_setprio 0
	s_setprio 1
	v_mfma_f32_16x16x32_bf16 v[70:73], v[212:215], v[18:21], v[110:113]
	v_mfma_f32_16x16x32_bf16 v[18:21], v[220:223], v[18:21], v[34:37]
	v_mfma_f32_16x16x32_bf16 v[122:125], v[224:227], v[22:25], v[18:21]
	v_mfma_f32_16x16x32_bf16 v[18:21], v[212:215], v[228:231], v[38:41]
	v_mfma_f32_16x16x32_bf16 v[110:113], v[216:219], v[232:235], v[18:21]
	v_mfma_f32_16x16x32_bf16 v[18:21], v[220:223], v[228:231], v[42:45]
	v_mfma_f32_16x16x32_bf16 v[106:109], v[224:227], v[232:235], v[18:21]
	v_mfma_f32_16x16x32_bf16 v[18:21], v[212:215], v[236:239], v[46:49]
	v_mfma_f32_16x16x32_bf16 v[94:97], v[216:219], v[240:243], v[18:21]
	v_mfma_f32_16x16x32_bf16 v[18:21], v[220:223], v[236:239], v[50:53]
	v_mfma_f32_16x16x32_bf16 v[90:93], v[224:227], v[240:243], v[18:21]
	v_mfma_f32_16x16x32_bf16 v[18:21], v[212:215], v[244:247], v[54:57]
	v_mfma_f32_16x16x32_bf16 v[78:81], v[216:219], v[248:251], v[18:21]
	v_mfma_f32_16x16x32_bf16 v[18:21], v[220:223], v[244:247], v[58:61]
	v_mfma_f32_16x16x32_bf16 v[126:129], v[216:219], v[22:25], v[70:73]
	v_mfma_f32_16x16x32_bf16 v[74:77], v[224:227], v[248:251], v[18:21]
	s_barrier
	s_setprio 0
	s_add_i32 s46, s63, s10
	s_add_i32 s47, s46, 0x2000
	s_nop 1
	v_lshl_add_u64 v[18:19], v[252:253], 0, s[22:23]
	s_mov_b32 m0, s46
	s_add_u32 s26, s38, 0x100180
	ds_read_b128 v[42:45], v152 offset:49152
	ds_read_b128 v[46:49], v152 offset:50176
	ds_read_b128 v[228:231], v152 offset:51200
	ds_read_b128 v[232:235], v152 offset:52224
	ds_read_b128 v[236:239], v152 offset:53248
	ds_read_b128 v[240:243], v152 offset:54272
	ds_read_b128 v[244:247], v152 offset:55296
	ds_read_b128 v[248:251], v152 offset:56320
	global_load_lds_dwordx4 v[18:19], off
	v_lshl_add_u64 v[18:19], v[142:143], 0, s[22:23]
	s_mov_b32 m0, s47
	s_addc_u32 s27, s39, 0
	s_add_i32 s56, s56, s10
	global_load_lds_dwordx4 v[18:19], off
	v_lshl_add_u64 v[18:19], s[26:27], 0, v[134:135]
	s_mov_b32 m0, s56
	s_add_i32 s57, s56, 0x2000
	global_load_lds_dwordx4 v[18:19], off
	v_lshl_add_u64 v[18:19], s[26:27], 0, v[130:131]
	s_mov_b32 m0, s57
	s_nop 0
	global_load_lds_dwordx4 v[18:19], off
	v_lshl_add_u64 v[18:19], v[144:145], 0, s[22:23]
	s_mov_b32 m0, s50
	s_nop 0
	global_load_lds_dwordx4 v[18:19], off
	v_lshl_add_u64 v[18:19], v[138:139], 0, s[22:23]
	s_mov_b32 m0, s51
	s_nop 0
	global_load_lds_dwordx4 v[18:19], off
	s_waitcnt vmcnt(8)
	s_waitcnt lgkmcnt(0)
	s_setprio 1
	s_barrier
	v_mfma_f32_16x16x32_bf16 v[18:21], v[6:9], v[42:45], v[156:159]
	v_mfma_f32_16x16x32_bf16 v[54:57], v[26:29], v[46:49], v[18:21]
	v_mfma_f32_16x16x32_bf16 v[18:21], v[30:33], v[42:45], v[160:163]
	v_mfma_f32_16x16x32_bf16 v[50:53], v[208:211], v[46:49], v[18:21]
	v_mfma_f32_16x16x32_bf16 v[18:21], v[6:9], v[228:231], v[164:167]
	v_mfma_f32_16x16x32_bf16 v[38:41], v[26:29], v[232:235], v[18:21]
	v_mfma_f32_16x16x32_bf16 v[18:21], v[30:33], v[228:231], v[168:171]
	v_mfma_f32_16x16x32_bf16 v[34:37], v[208:211], v[232:235], v[18:21]
	v_mfma_f32_16x16x32_bf16 v[18:21], v[6:9], v[236:239], v[172:175]
	v_mfma_f32_16x16x32_bf16 v[2:5], v[6:9], v[244:247], v[2:5]
	v_mfma_f32_16x16x32_bf16 v[22:25], v[26:29], v[240:243], v[18:21]
	v_mfma_f32_16x16x32_bf16 v[18:21], v[30:33], v[236:239], v[176:179]
	v_mfma_f32_16x16x32_bf16 v[6:9], v[26:29], v[248:251], v[2:5]
	v_mfma_f32_16x16x32_bf16 v[2:5], v[30:33], v[244:247], v[10:13]
	v_mfma_f32_16x16x32_bf16 v[18:21], v[208:211], v[240:243], v[18:21]
	v_mfma_f32_16x16x32_bf16 v[2:5], v[208:211], v[248:251], v[2:5]
	s_setprio 0
	s_setprio 1
	v_mfma_f32_16x16x32_bf16 v[10:13], v[212:215], v[42:45], v[14:17]
	v_mfma_f32_16x16x32_bf16 v[70:73], v[216:219], v[46:49], v[10:13]
	v_mfma_f32_16x16x32_bf16 v[10:13], v[220:223], v[42:45], v[180:183]
	v_mfma_f32_16x16x32_bf16 v[58:61], v[224:227], v[46:49], v[10:13]
	v_mfma_f32_16x16x32_bf16 v[10:13], v[212:215], v[228:231], v[184:187]
	v_mfma_f32_16x16x32_bf16 v[46:49], v[216:219], v[232:235], v[10:13]
	v_mfma_f32_16x16x32_bf16 v[10:13], v[220:223], v[228:231], v[188:191]
	v_mfma_f32_16x16x32_bf16 v[42:45], v[224:227], v[232:235], v[10:13]
	v_mfma_f32_16x16x32_bf16 v[10:13], v[212:215], v[236:239], v[192:195]
	v_mfma_f32_16x16x32_bf16 v[30:33], v[216:219], v[240:243], v[10:13]
	v_mfma_f32_16x16x32_bf16 v[10:13], v[220:223], v[236:239], v[196:199]
	v_mfma_f32_16x16x32_bf16 v[26:29], v[224:227], v[240:243], v[10:13]
	v_mfma_f32_16x16x32_bf16 v[10:13], v[212:215], v[244:247], v[200:203]
	v_mfma_f32_16x16x32_bf16 v[14:17], v[216:219], v[248:251], v[10:13]
	v_mfma_f32_16x16x32_bf16 v[10:13], v[220:223], v[244:247], v[204:207]
	v_mfma_f32_16x16x32_bf16 v[10:13], v[224:227], v[248:251], v[10:13]
	s_barrier
	s_setprio 0
	s_add_u32 s40, s40, 0x100180
	s_addc_u32 s41, s41, 0
	s_add_u32 s26, s38, 0x200
	s_addc_u32 s27, s39, 0
	s_mov_b32 s68, 0
.LBB0_1345:
	ds_read_b128 v[156:159], v150
	ds_read_b128 v[160:163], v150 offset:1024
	ds_read_b128 v[164:167], v150 offset:2048
	ds_read_b128 v[168:171], v150 offset:3072
	ds_read_b128 v[172:175], v151
	ds_read_b128 v[176:179], v151 offset:1024
	ds_read_b128 v[180:183], v151 offset:2048
	ds_read_b128 v[184:187], v151 offset:3072
	s_add_u32 s38, s40, 0xfff00080
	s_addc_u32 s39, s41, -1
	s_cmp_eq_u32 s68, 60
	s_cselect_b32 s43, s1, s39
	s_cselect_b32 s42, s25, s38
	s_cselect_b32 s39, s8, s27
	s_cselect_b32 s38, s67, s26
	s_mov_b32 m0, s53
	ds_read_b128 v[188:191], v152
	ds_read_b128 v[192:195], v152 offset:1024
	ds_read_b128 v[196:199], v152 offset:2048
	ds_read_b128 v[200:203], v152 offset:3072
	ds_read_b128 v[204:207], v152 offset:4096
	ds_read_b128 v[208:211], v152 offset:5120
	ds_read_b128 v[212:215], v152 offset:6144
	ds_read_b128 v[216:219], v152 offset:7168
	global_load_lds_dwordx4 v0, s[40:41]
	s_mov_b32 m0, s54
	s_nop 0
	global_load_lds_dwordx4 v140, s[40:41]
	s_waitcnt vmcnt(8)
	s_waitcnt lgkmcnt(0)
	s_setprio 1
	s_barrier
	v_mfma_f32_16x16x32_bf16 v[118:121], v[156:159], v[188:191], v[118:121]
	v_mfma_f32_16x16x32_bf16 v[114:117], v[164:167], v[188:191], v[114:117]
	v_mfma_f32_16x16x32_bf16 v[102:105], v[156:159], v[196:199], v[102:105]
	v_mfma_f32_16x16x32_bf16 v[98:101], v[164:167], v[196:199], v[98:101]
	v_mfma_f32_16x16x32_bf16 v[86:89], v[156:159], v[204:207], v[86:89]
	v_mfma_f32_16x16x32_bf16 v[82:85], v[164:167], v[204:207], v[82:85]
	v_mfma_f32_16x16x32_bf16 v[66:69], v[156:159], v[212:215], v[66:69]
	v_mfma_f32_16x16x32_bf16 v[62:65], v[164:167], v[212:215], v[62:65]
	v_mfma_f32_16x16x32_bf16 v[118:121], v[160:163], v[192:195], v[118:121]
	v_mfma_f32_16x16x32_bf16 v[114:117], v[168:171], v[192:195], v[114:117]
	v_mfma_f32_16x16x32_bf16 v[102:105], v[160:163], v[200:203], v[102:105]
	v_mfma_f32_16x16x32_bf16 v[98:101], v[168:171], v[200:203], v[98:101]
	v_mfma_f32_16x16x32_bf16 v[86:89], v[160:163], v[208:211], v[86:89]
	v_mfma_f32_16x16x32_bf16 v[82:85], v[168:171], v[208:211], v[82:85]
	v_mfma_f32_16x16x32_bf16 v[66:69], v[160:163], v[216:219], v[66:69]
	v_mfma_f32_16x16x32_bf16 v[62:65], v[168:171], v[216:219], v[62:65]
	s_setprio 0
	s_setprio 1
	v_mfma_f32_16x16x32_bf16 v[126:129], v[172:175], v[188:191], v[126:129]
	v_mfma_f32_16x16x32_bf16 v[122:125], v[180:183], v[188:191], v[122:125]
	v_mfma_f32_16x16x32_bf16 v[110:113], v[172:175], v[196:199], v[110:113]
	v_mfma_f32_16x16x32_bf16 v[106:109], v[180:183], v[196:199], v[106:109]
	v_mfma_f32_16x16x32_bf16 v[94:97], v[172:175], v[204:207], v[94:97]
	v_mfma_f32_16x16x32_bf16 v[90:93], v[180:183], v[204:207], v[90:93]
	v_mfma_f32_16x16x32_bf16 v[78:81], v[172:175], v[212:215], v[78:81]
	v_mfma_f32_16x16x32_bf16 v[74:77], v[180:183], v[212:215], v[74:77]
	v_mfma_f32_16x16x32_bf16 v[126:129], v[176:179], v[192:195], v[126:129]
	v_mfma_f32_16x16x32_bf16 v[122:125], v[184:187], v[192:195], v[122:125]
	v_mfma_f32_16x16x32_bf16 v[110:113], v[176:179], v[200:203], v[110:113]
	v_mfma_f32_16x16x32_bf16 v[106:109], v[184:187], v[200:203], v[106:109]
	v_mfma_f32_16x16x32_bf16 v[94:97], v[176:179], v[208:211], v[94:97]
	v_mfma_f32_16x16x32_bf16 v[90:93], v[184:187], v[208:211], v[90:93]
	v_mfma_f32_16x16x32_bf16 v[78:81], v[176:179], v[216:219], v[78:81]
	v_mfma_f32_16x16x32_bf16 v[74:77], v[184:187], v[216:219], v[74:77]
	s_barrier
	s_setprio 0
	s_mov_b32 m0, s59
	s_mov_b64 s[98:99], s[38:39]
	s_add_u32 s70, s38, 0x100000
	ds_read_b128 v[188:191], v152 offset:16384
	ds_read_b128 v[192:195], v152 offset:17408
	ds_read_b128 v[196:199], v152 offset:18432
	ds_read_b128 v[200:203], v152 offset:19456
	ds_read_b128 v[204:207], v152 offset:20480
	ds_read_b128 v[208:211], v152 offset:21504
	ds_read_b128 v[212:215], v152 offset:22528
	ds_read_b128 v[216:219], v152 offset:23552
	global_load_lds_dwordx4 v134, s[38:39]
	s_mov_b32 m0, s60
	s_addc_u32 s71, s39, 0
	global_load_lds_dwordx4 v130, s[38:39]
	s_mov_b32 m0, s61
	s_mov_b64 s[100:101], s[42:43]
	global_load_lds_dwordx4 v134, s[70:71]
	s_mov_b32 m0, s62
	s_nop 0
	global_load_lds_dwordx4 v130, s[70:71]
	s_mov_b32 m0, s13
	s_nop 0
	global_load_lds_dwordx4 v136, s[42:43]
	s_mov_b32 m0, s33
	s_nop 0
	global_load_lds_dwordx4 v132, s[42:43]
	s_waitcnt vmcnt(8)
	s_waitcnt lgkmcnt(0)
	s_setprio 1
	s_barrier
	v_mfma_f32_16x16x32_bf16 v[54:57], v[156:159], v[188:191], v[54:57]
	v_mfma_f32_16x16x32_bf16 v[50:53], v[164:167], v[188:191], v[50:53]
	v_mfma_f32_16x16x32_bf16 v[38:41], v[156:159], v[196:199], v[38:41]
	v_mfma_f32_16x16x32_bf16 v[34:37], v[164:167], v[196:199], v[34:37]
	v_mfma_f32_16x16x32_bf16 v[22:25], v[156:159], v[204:207], v[22:25]
	v_mfma_f32_16x16x32_bf16 v[18:21], v[164:167], v[204:207], v[18:21]
	v_mfma_f32_16x16x32_bf16 v[6:9], v[156:159], v[212:215], v[6:9]
	v_mfma_f32_16x16x32_bf16 v[2:5], v[164:167], v[212:215], v[2:5]
	v_mfma_f32_16x16x32_bf16 v[54:57], v[160:163], v[192:195], v[54:57]
	v_mfma_f32_16x16x32_bf16 v[50:53], v[168:171], v[192:195], v[50:53]
	v_mfma_f32_16x16x32_bf16 v[38:41], v[160:163], v[200:203], v[38:41]
	v_mfma_f32_16x16x32_bf16 v[34:37], v[168:171], v[200:203], v[34:37]
	v_mfma_f32_16x16x32_bf16 v[22:25], v[160:163], v[208:211], v[22:25]
	v_mfma_f32_16x16x32_bf16 v[18:21], v[168:171], v[208:211], v[18:21]
	v_mfma_f32_16x16x32_bf16 v[6:9], v[160:163], v[216:219], v[6:9]
	v_mfma_f32_16x16x32_bf16 v[2:5], v[168:171], v[216:219], v[2:5]
	s_setprio 0
	s_setprio 1
	v_mfma_f32_16x16x32_bf16 v[70:73], v[172:175], v[188:191], v[70:73]
	v_mfma_f32_16x16x32_bf16 v[58:61], v[180:183], v[188:191], v[58:61]
	v_mfma_f32_16x16x32_bf16 v[46:49], v[172:175], v[196:199], v[46:49]
	v_mfma_f32_16x16x32_bf16 v[42:45], v[180:183], v[196:199], v[42:45]
	v_mfma_f32_16x16x32_bf16 v[30:33], v[172:175], v[204:207], v[30:33]
	v_mfma_f32_16x16x32_bf16 v[26:29], v[180:183], v[204:207], v[26:29]
	v_mfma_f32_16x16x32_bf16 v[14:17], v[172:175], v[212:215], v[14:17]
	v_mfma_f32_16x16x32_bf16 v[10:13], v[180:183], v[212:215], v[10:13]
	v_mfma_f32_16x16x32_bf16 v[70:73], v[176:179], v[192:195], v[70:73]
	v_mfma_f32_16x16x32_bf16 v[58:61], v[184:187], v[192:195], v[58:61]
	v_mfma_f32_16x16x32_bf16 v[46:49], v[176:179], v[200:203], v[46:49]
	v_mfma_f32_16x16x32_bf16 v[42:45], v[184:187], v[200:203], v[42:45]
	v_mfma_f32_16x16x32_bf16 v[30:33], v[176:179], v[208:211], v[30:33]
	v_mfma_f32_16x16x32_bf16 v[26:29], v[184:187], v[208:211], v[26:29]
	v_mfma_f32_16x16x32_bf16 v[14:17], v[176:179], v[216:219], v[14:17]
	v_mfma_f32_16x16x32_bf16 v[10:13], v[184:187], v[216:219], v[10:13]
	s_barrier
; #define PG8_BAR __builtin_amdgcn_s_barrier()
;     ...
;         for (int t = 2; t < nt; t += 2) PG8_KITER(t);
;         if constexpr (ALIGN_EPI) { if (wr == 0) PG8_BAR; }
	s_setprio 0
	ds_read_b128 v[156:159], v154
	ds_read_b128 v[160:163], v154 offset:1024
	ds_read_b128 v[164:167], v154 offset:2048
	ds_read_b128 v[168:171], v154 offset:3072
	ds_read_b128 v[172:175], v146
	ds_read_b128 v[176:179], v146 offset:1024
	ds_read_b128 v[180:183], v146 offset:2048
	ds_read_b128 v[184:187], v146 offset:3072
	s_add_u32 s42, s42, 0x100000
	s_addc_u32 s43, s43, 0
	s_mov_b32 m0, s48
	ds_read_b128 v[188:191], v152 offset:32768
	ds_read_b128 v[192:195], v152 offset:33792
	ds_read_b128 v[196:199], v152 offset:34816
	ds_read_b128 v[200:203], v152 offset:35840
	ds_read_b128 v[204:207], v152 offset:36864
	ds_read_b128 v[208:211], v152 offset:37888
	ds_read_b128 v[212:215], v152 offset:38912
	ds_read_b128 v[216:219], v152 offset:39936
	global_load_lds_dwordx4 v136, s[42:43]
	s_mov_b32 m0, s49
	s_nop 0
	global_load_lds_dwordx4 v132, s[42:43]
	s_waitcnt vmcnt(8)
	s_waitcnt lgkmcnt(0)
	s_setprio 1
	s_barrier
	v_mfma_f32_16x16x32_bf16 v[118:121], v[156:159], v[188:191], v[118:121]
	v_mfma_f32_16x16x32_bf16 v[114:117], v[164:167], v[188:191], v[114:117]
	v_mfma_f32_16x16x32_bf16 v[102:105], v[156:159], v[196:199], v[102:105]
	v_mfma_f32_16x16x32_bf16 v[98:101], v[164:167], v[196:199], v[98:101]
	v_mfma_f32_16x16x32_bf16 v[86:89], v[156:159], v[204:207], v[86:89]
	v_mfma_f32_16x16x32_bf16 v[82:85], v[164:167], v[204:207], v[82:85]
	v_mfma_f32_16x16x32_bf16 v[66:69], v[156:159], v[212:215], v[66:69]
	v_mfma_f32_16x16x32_bf16 v[62:65], v[164:167], v[212:215], v[62:65]
	v_mfma_f32_16x16x32_bf16 v[118:121], v[160:163], v[192:195], v[118:121]
	v_mfma_f32_16x16x32_bf16 v[114:117], v[168:171], v[192:195], v[114:117]
	v_mfma_f32_16x16x32_bf16 v[102:105], v[160:163], v[200:203], v[102:105]
	v_mfma_f32_16x16x32_bf16 v[98:101], v[168:171], v[200:203], v[98:101]
	v_mfma_f32_16x16x32_bf16 v[86:89], v[160:163], v[208:211], v[86:89]
	v_mfma_f32_16x16x32_bf16 v[82:85], v[168:171], v[208:211], v[82:85]
	v_mfma_f32_16x16x32_bf16 v[66:69], v[160:163], v[216:219], v[66:69]
	v_mfma_f32_16x16x32_bf16 v[62:65], v[168:171], v[216:219], v[62:65]
	s_setprio 0
	s_setprio 1
	v_mfma_f32_16x16x32_bf16 v[126:129], v[172:175], v[188:191], v[126:129]
	v_mfma_f32_16x16x32_bf16 v[122:125], v[180:183], v[188:191], v[122:125]
	v_mfma_f32_16x16x32_bf16 v[110:113], v[172:175], v[196:199], v[110:113]
	v_mfma_f32_16x16x32_bf16 v[106:109], v[180:183], v[196:199], v[106:109]
	v_mfma_f32_16x16x32_bf16 v[94:97], v[172:175], v[204:207], v[94:97]
	v_mfma_f32_16x16x32_bf16 v[90:93], v[180:183], v[204:207], v[90:93]
	v_mfma_f32_16x16x32_bf16 v[78:81], v[172:175], v[212:215], v[78:81]
	v_mfma_f32_16x16x32_bf16 v[74:77], v[180:183], v[212:215], v[74:77]
	v_mfma_f32_16x16x32_bf16 v[126:129], v[176:179], v[192:195], v[126:129]
	v_mfma_f32_16x16x32_bf16 v[122:125], v[184:187], v[192:195], v[122:125]
	v_mfma_f32_16x16x32_bf16 v[110:113], v[176:179], v[200:203], v[110:113]
	v_mfma_f32_16x16x32_bf16 v[106:109], v[184:187], v[200:203], v[106:109]
	v_mfma_f32_16x16x32_bf16 v[94:97], v[176:179], v[208:211], v[94:97]
	v_mfma_f32_16x16x32_bf16 v[90:93], v[184:187], v[208:211], v[90:93]
	v_mfma_f32_16x16x32_bf16 v[78:81], v[176:179], v[216:219], v[78:81]
	v_mfma_f32_16x16x32_bf16 v[74:77], v[184:187], v[216:219], v[74:77]
	s_barrier
	s_setprio 0
	s_mov_b32 m0, s46
	s_add_u32 s98, s98, 0x80
	s_addc_u32 s99, s99, 0
	s_add_u32 s100, s100, 0x80
	s_addc_u32 s101, s101, 0
	s_add_u32 s38, s38, 0x100080
	ds_read_b128 v[188:191], v152 offset:49152
	ds_read_b128 v[192:195], v152 offset:50176
	ds_read_b128 v[196:199], v152 offset:51200
	ds_read_b128 v[200:203], v152 offset:52224
	ds_read_b128 v[204:207], v152 offset:53248
	ds_read_b128 v[208:211], v152 offset:54272
	ds_read_b128 v[212:215], v152 offset:55296
	ds_read_b128 v[216:219], v152 offset:56320
	global_load_lds_dwordx4 v134, s[98:99]
	s_mov_b32 m0, s47
	s_addc_u32 s39, s39, 0
	global_load_lds_dwordx4 v130, s[98:99]
	s_mov_b32 m0, s56
	s_nop 0
	global_load_lds_dwordx4 v134, s[38:39]
	s_mov_b32 m0, s57
	s_nop 0
	global_load_lds_dwordx4 v130, s[38:39]
	s_mov_b32 m0, s50
	s_nop 0
	global_load_lds_dwordx4 v136, s[100:101]
	s_mov_b32 m0, s51
	s_nop 0
	global_load_lds_dwordx4 v132, s[100:101]
	s_waitcnt vmcnt(8)
	s_waitcnt lgkmcnt(0)
	s_setprio 1
	s_barrier
	v_mfma_f32_16x16x32_bf16 v[54:57], v[156:159], v[188:191], v[54:57]
	v_mfma_f32_16x16x32_bf16 v[50:53], v[164:167], v[188:191], v[50:53]
	v_mfma_f32_16x16x32_bf16 v[38:41], v[156:159], v[196:199], v[38:41]
	v_mfma_f32_16x16x32_bf16 v[34:37], v[164:167], v[196:199], v[34:37]
	v_mfma_f32_16x16x32_bf16 v[22:25], v[156:159], v[204:207], v[22:25]
	v_mfma_f32_16x16x32_bf16 v[18:21], v[164:167], v[204:207], v[18:21]
	v_mfma_f32_16x16x32_bf16 v[6:9], v[156:159], v[212:215], v[6:9]
	v_mfma_f32_16x16x32_bf16 v[2:5], v[164:167], v[212:215], v[2:5]
	v_mfma_f32_16x16x32_bf16 v[54:57], v[160:163], v[192:195], v[54:57]
	v_mfma_f32_16x16x32_bf16 v[50:53], v[168:171], v[192:195], v[50:53]
	v_mfma_f32_16x16x32_bf16 v[38:41], v[160:163], v[200:203], v[38:41]
	v_mfma_f32_16x16x32_bf16 v[34:37], v[168:171], v[200:203], v[34:37]
	v_mfma_f32_16x16x32_bf16 v[22:25], v[160:163], v[208:211], v[22:25]
	v_mfma_f32_16x16x32_bf16 v[18:21], v[168:171], v[208:211], v[18:21]
	v_mfma_f32_16x16x32_bf16 v[6:9], v[160:163], v[216:219], v[6:9]
	v_mfma_f32_16x16x32_bf16 v[2:5], v[168:171], v[216:219], v[2:5]
	s_setprio 0
	s_setprio 1
	v_mfma_f32_16x16x32_bf16 v[70:73], v[172:175], v[188:191], v[70:73]
	v_mfma_f32_16x16x32_bf16 v[58:61], v[180:183], v[188:191], v[58:61]
	v_mfma_f32_16x16x32_bf16 v[46:49], v[172:175], v[196:199], v[46:49]
	v_mfma_f32_16x16x32_bf16 v[42:45], v[180:183], v[196:199], v[42:45]
	v_mfma_f32_16x16x32_bf16 v[30:33], v[172:175], v[204:207], v[30:33]
	v_mfma_f32_16x16x32_bf16 v[26:29], v[180:183], v[204:207], v[26:29]
	v_mfma_f32_16x16x32_bf16 v[14:17], v[172:175], v[212:215], v[14:17]
	v_mfma_f32_16x16x32_bf16 v[10:13], v[180:183], v[212:215], v[10:13]
	v_mfma_f32_16x16x32_bf16 v[70:73], v[176:179], v[192:195], v[70:73]
	v_mfma_f32_16x16x32_bf16 v[58:61], v[184:187], v[192:195], v[58:61]
	v_mfma_f32_16x16x32_bf16 v[46:49], v[176:179], v[200:203], v[46:49]
	v_mfma_f32_16x16x32_bf16 v[42:45], v[184:187], v[200:203], v[42:45]
	v_mfma_f32_16x16x32_bf16 v[30:33], v[176:179], v[208:211], v[30:33]
	v_mfma_f32_16x16x32_bf16 v[26:29], v[184:187], v[208:211], v[26:29]
	v_mfma_f32_16x16x32_bf16 v[14:17], v[176:179], v[216:219], v[14:17]
	v_mfma_f32_16x16x32_bf16 v[10:13], v[184:187], v[216:219], v[10:13]
	s_barrier
	s_setprio 0
	s_add_i32 s68, s68, 2
	s_add_u32 s40, s40, 0x100
	s_addc_u32 s41, s41, 0
	s_add_u32 s26, s26, 0x100
	s_addc_u32 s27, s27, 0
	s_cmp_gt_u32 s68, 61
	s_cbranch_scc0 .LBB0_1345
	s_and_b64 vcc, exec, s[18:19]
	s_cbranch_vccz .LBB0_1348
	s_barrier

;     __host__ __device__ bool next(int i, Unit& u) const { if (!StaticOrder::next(i >> 1, u)) return false; u.seg = i & 1; return true; }
;     ...
;         const bool has_next = S.next(ui + 1, nxt);
;         const char* nA = has_next ? PG8_APTR(nxt) : cA; const char* nB = has_next ? PG8_BPTR(nxt) : cB;
;         const char* pfc = PG8_PFPTR(cA, cB); const char* pfn = PG8_PFPTR(nA, nB);
;         PG8_KITER(0);
.LBB0_1424:
	ds_read_b128 v[2:5], v152
	ds_read_b128 v[6:9], v152 offset:1024
	ds_read_b128 v[10:13], v152 offset:2048
	ds_read_b128 v[14:17], v152 offset:3072
	ds_read_b128 v[18:21], v153
	ds_read_b128 v[22:25], v153 offset:1024
	ds_read_b128 v[26:29], v153 offset:2048
	ds_read_b128 v[30:33], v153 offset:3072
	s_add_u32 s22, s18, 0x2b0080
	s_addc_u32 s23, s19, 0
	s_add_i32 s49, s28, 0xc000
	v_lshl_add_u64 v[66:67], s[22:23], 0, v[130:131]
	s_mov_b32 m0, s49
	s_add_i32 s50, s28, 0xe000
	ds_read_b128 v[34:37], v154
	ds_read_b128 v[38:41], v154 offset:1024
	ds_read_b128 v[42:45], v154 offset:2048
	ds_read_b128 v[46:49], v154 offset:3072
	ds_read_b128 v[50:53], v154 offset:4096
	ds_read_b128 v[54:57], v154 offset:5120
	ds_read_b128 v[58:61], v154 offset:6144
	ds_read_b128 v[62:65], v154 offset:7168
	global_load_lds_dwordx4 v[66:67], off
	v_lshl_add_u64 v[66:67], s[22:23], 0, v[134:135]
	s_mov_b32 m0, s50
	s_nop 0
	global_load_lds_dwordx4 v[66:67], off
	s_waitcnt vmcnt(8)
	s_waitcnt lgkmcnt(0)
	s_setprio 1
	s_barrier
	v_mfma_f32_16x16x32_bf16 v[90:93], v[2:5], v[58:61], 0
	v_mfma_f32_16x16x32_bf16 v[66:69], v[2:5], v[34:37], 0
	v_mfma_f32_16x16x32_bf16 v[70:73], v[10:13], v[34:37], 0
	v_mfma_f32_16x16x32_bf16 v[74:77], v[2:5], v[42:45], 0
	v_mfma_f32_16x16x32_bf16 v[78:81], v[10:13], v[42:45], 0
	v_mfma_f32_16x16x32_bf16 v[82:85], v[2:5], v[50:53], 0
	v_mfma_f32_16x16x32_bf16 v[86:89], v[10:13], v[50:53], 0
	v_mfma_f32_16x16x32_bf16 v[98:101], v[6:9], v[62:65], v[90:93]
	v_mfma_f32_16x16x32_bf16 v[90:93], v[10:13], v[58:61], 0
	v_mfma_f32_16x16x32_bf16 v[66:69], v[6:9], v[38:41], v[66:69]
	v_mfma_f32_16x16x32_bf16 v[70:73], v[14:17], v[38:41], v[70:73]
	v_mfma_f32_16x16x32_bf16 v[74:77], v[6:9], v[46:49], v[74:77]
	v_mfma_f32_16x16x32_bf16 v[78:81], v[14:17], v[46:49], v[78:81]
	v_mfma_f32_16x16x32_bf16 v[82:85], v[6:9], v[54:57], v[82:85]
	v_mfma_f32_16x16x32_bf16 v[86:89], v[14:17], v[54:57], v[86:89]
	v_mfma_f32_16x16x32_bf16 v[102:105], v[14:17], v[62:65], v[90:93]
	s_setprio 0
	s_setprio 1
	v_mfma_f32_16x16x32_bf16 v[90:93], v[18:21], v[34:37], 0
	v_mfma_f32_16x16x32_bf16 v[34:37], v[26:29], v[34:37], 0
	v_mfma_f32_16x16x32_bf16 v[114:117], v[22:25], v[38:41], v[90:93]
	v_mfma_f32_16x16x32_bf16 v[34:37], v[30:33], v[38:41], v[34:37]
	v_mfma_f32_16x16x32_bf16 v[38:41], v[18:21], v[42:45], 0
	v_mfma_f32_16x16x32_bf16 v[42:45], v[26:29], v[42:45], 0
	v_mfma_f32_16x16x32_bf16 v[38:41], v[22:25], v[46:49], v[38:41]
	v_mfma_f32_16x16x32_bf16 v[42:45], v[30:33], v[46:49], v[42:45]
	v_mfma_f32_16x16x32_bf16 v[46:49], v[18:21], v[50:53], 0
	v_mfma_f32_16x16x32_bf16 v[50:53], v[26:29], v[50:53], 0
	v_mfma_f32_16x16x32_bf16 v[46:49], v[22:25], v[54:57], v[46:49]
	v_mfma_f32_16x16x32_bf16 v[50:53], v[30:33], v[54:57], v[50:53]
	v_mfma_f32_16x16x32_bf16 v[54:57], v[18:21], v[58:61], 0
	v_mfma_f32_16x16x32_bf16 v[58:61], v[26:29], v[58:61], 0
	v_mfma_f32_16x16x32_bf16 v[54:57], v[22:25], v[62:65], v[54:57]
	v_mfma_f32_16x16x32_bf16 v[58:61], v[30:33], v[62:65], v[58:61]
	s_barrier
	s_setprio 0
	s_add_i32 s51, s39, s25
	v_lshl_add_u64 v[248:249], s[20:21], 0, v[132:133]
	s_add_i32 s52, s51, 0x2000
	v_lshl_add_u64 v[146:147], v[248:249], 0, s[12:13]
	s_mov_b32 m0, s51
	v_lshl_add_u64 v[250:251], s[20:21], 0, v[136:137]
	s_add_u32 s22, s20, 0x2b0100
	ds_read_b128 v[62:65], v154 offset:16384
	ds_read_b128 v[90:93], v154 offset:17408
	ds_read_b128 v[94:97], v154 offset:18432
	ds_read_b128 v[106:109], v154 offset:19456
	ds_read_b128 v[110:113], v154 offset:20480
	ds_read_b128 v[118:121], v154 offset:21504
	ds_read_b128 v[122:125], v154 offset:22528
	ds_read_b128 v[126:129], v154 offset:23552
	global_load_lds_dwordx4 v[146:147], off
	v_lshl_add_u64 v[146:147], v[250:251], 0, s[12:13]
	s_mov_b32 m0, s52
	s_addc_u32 s23, s21, 0
	s_add_i32 s46, s40, s25
	global_load_lds_dwordx4 v[146:147], off
	v_lshl_add_u64 v[146:147], s[22:23], 0, v[132:133]
	s_mov_b32 m0, s46
	s_add_i32 s47, s46, 0x2000
	global_load_lds_dwordx4 v[146:147], off
	v_lshl_add_u64 v[146:147], s[22:23], 0, v[136:137]
	s_mov_b32 m0, s47
	v_lshl_add_u64 v[252:253], s[18:19], 0, v[130:131]
	global_load_lds_dwordx4 v[146:147], off
	v_lshl_add_u64 v[146:147], v[252:253], 0, s[12:13]
	s_mov_b32 m0, s28
	v_lshl_add_u64 v[142:143], s[18:19], 0, v[134:135]
	global_load_lds_dwordx4 v[146:147], off
	v_lshl_add_u64 v[146:147], v[142:143], 0, s[12:13]
	s_mov_b32 m0, s29
	s_nop 0
	global_load_lds_dwordx4 v[146:147], off
	s_waitcnt vmcnt(8)
	s_waitcnt lgkmcnt(0)
	s_setprio 1
	s_barrier
	v_mfma_f32_16x16x32_bf16 v[146:149], v[2:5], v[62:65], 0
	v_mfma_f32_16x16x32_bf16 v[160:163], v[2:5], v[94:97], 0
	v_mfma_f32_16x16x32_bf16 v[168:171], v[2:5], v[110:113], 0
	v_mfma_f32_16x16x32_bf16 v[2:5], v[2:5], v[122:125], 0
	v_mfma_f32_16x16x32_bf16 v[148:151], v[6:9], v[90:93], v[146:149]
	v_mfma_f32_16x16x32_bf16 v[160:163], v[6:9], v[106:109], v[160:163]
	v_mfma_f32_16x16x32_bf16 v[168:171], v[6:9], v[118:121], v[168:171]
	v_mfma_f32_16x16x32_bf16 v[2:5], v[6:9], v[126:129], v[2:5]
	v_mfma_f32_16x16x32_bf16 v[6:9], v[10:13], v[122:125], 0
	v_mfma_f32_16x16x32_bf16 v[156:159], v[10:13], v[62:65], 0
	v_mfma_f32_16x16x32_bf16 v[164:167], v[10:13], v[94:97], 0
	v_mfma_f32_16x16x32_bf16 v[172:175], v[10:13], v[110:113], 0
	v_mfma_f32_16x16x32_bf16 v[6:9], v[14:17], v[126:129], v[6:9]
	v_mfma_f32_16x16x32_bf16 v[156:159], v[14:17], v[90:93], v[156:159]
	v_mfma_f32_16x16x32_bf16 v[164:167], v[14:17], v[106:109], v[164:167]
	v_mfma_f32_16x16x32_bf16 v[172:175], v[14:17], v[118:121], v[172:175]
	s_setprio 0
	s_setprio 1
	v_mfma_f32_16x16x32_bf16 v[10:13], v[18:21], v[62:65], 0
	v_mfma_f32_16x16x32_bf16 v[176:179], v[22:25], v[90:93], v[10:13]
	v_mfma_f32_16x16x32_bf16 v[10:13], v[26:29], v[62:65], 0
	v_mfma_f32_16x16x32_bf16 v[180:183], v[30:33], v[90:93], v[10:13]
	v_mfma_f32_16x16x32_bf16 v[10:13], v[18:21], v[94:97], 0
	v_mfma_f32_16x16x32_bf16 v[184:187], v[22:25], v[106:109], v[10:13]
	v_mfma_f32_16x16x32_bf16 v[10:13], v[26:29], v[94:97], 0
	v_mfma_f32_16x16x32_bf16 v[188:191], v[30:33], v[106:109], v[10:13]
	v_mfma_f32_16x16x32_bf16 v[10:13], v[18:21], v[110:113], 0
	v_mfma_f32_16x16x32_bf16 v[192:195], v[22:25], v[118:121], v[10:13]
	v_mfma_f32_16x16x32_bf16 v[10:13], v[26:29], v[110:113], 0
	v_mfma_f32_16x16x32_bf16 v[196:199], v[30:33], v[118:121], v[10:13]
	v_mfma_f32_16x16x32_bf16 v[10:13], v[18:21], v[122:125], 0
	v_mfma_f32_16x16x32_bf16 v[200:203], v[22:25], v[126:129], v[10:13]
	v_mfma_f32_16x16x32_bf16 v[10:13], v[26:29], v[122:125], 0
	v_mfma_f32_16x16x32_bf16 v[204:207], v[30:33], v[126:129], v[10:13]
	s_barrier
	s_setprio 0
	s_add_i32 s53, 0, 0x18000
	s_add_i32 s55, 0, 0x1c000
	v_add_u32_e32 v146, s53, v1
	v_add_u32_e32 v147, s55, v1
	s_nop 0
	ds_read_b128 v[10:13], v146
	ds_read_b128 v[14:17], v146 offset:1024
	ds_read_b128 v[18:21], v146 offset:2048
	ds_read_b128 v[22:25], v146 offset:3072
	ds_read_b128 v[208:211], v147
	ds_read_b128 v[212:215], v147 offset:1024
	ds_read_b128 v[216:219], v147 offset:2048
	ds_read_b128 v[220:223], v147 offset:3072
	s_add_u32 s22, s18, 0x2b0100
	s_addc_u32 s23, s19, 0
	s_mov_b32 m0, s30
	v_lshl_add_u64 v[90:91], s[22:23], 0, v[130:131]
	ds_read_b128 v[26:29], v154 offset:32768
	ds_read_b128 v[30:33], v154 offset:33792
	ds_read_b128 v[62:65], v154 offset:34816
	ds_read_b128 v[224:227], v154 offset:35840
	ds_read_b128 v[228:231], v154 offset:36864
	ds_read_b128 v[232:235], v154 offset:37888
	ds_read_b128 v[236:239], v154 offset:38912
	ds_read_b128 v[240:243], v154 offset:39936
	global_load_lds_dwordx4 v[90:91], off
	v_lshl_add_u64 v[90:91], s[22:23], 0, v[134:135]
	s_mov_b32 m0, s31
	s_nop 0
	global_load_lds_dwordx4 v[90:91], off
	s_waitcnt vmcnt(8)
	s_waitcnt lgkmcnt(0)
	s_setprio 1
	s_barrier
	v_mfma_f32_16x16x32_bf16 v[66:69], v[10:13], v[26:29], v[66:69]
	v_mfma_f32_16x16x32_bf16 v[126:129], v[14:17], v[30:33], v[66:69]
	v_mfma_f32_16x16x32_bf16 v[66:69], v[18:21], v[26:29], v[70:73]
	v_mfma_f32_16x16x32_bf16 v[122:125], v[22:25], v[30:33], v[66:69]
	v_mfma_f32_16x16x32_bf16 v[66:69], v[10:13], v[62:65], v[74:77]
	v_mfma_f32_16x16x32_bf16 v[110:113], v[14:17], v[224:227], v[66:69]
	v_mfma_f32_16x16x32_bf16 v[66:69], v[18:21], v[62:65], v[78:81]
	v_mfma_f32_16x16x32_bf16 v[106:109], v[22:25], v[224:227], v[66:69]
	v_mfma_f32_16x16x32_bf16 v[66:69], v[10:13], v[228:231], v[82:85]
	v_mfma_f32_16x16x32_bf16 v[94:97], v[14:17], v[232:235], v[66:69]
	v_mfma_f32_16x16x32_bf16 v[66:69], v[18:21], v[228:231], v[86:89]
	v_mfma_f32_16x16x32_bf16 v[90:93], v[22:25], v[232:235], v[66:69]
	v_mfma_f32_16x16x32_bf16 v[66:69], v[10:13], v[236:239], v[98:101]
	v_mfma_f32_16x16x32_bf16 v[78:81], v[14:17], v[240:243], v[66:69]
	v_mfma_f32_16x16x32_bf16 v[66:69], v[18:21], v[236:239], v[102:105]
	v_mfma_f32_16x16x32_bf16 v[74:77], v[22:25], v[240:243], v[66:69]
	s_setprio 0
	s_setprio 1
	v_mfma_f32_16x16x32_bf16 v[66:69], v[208:211], v[26:29], v[114:117]
	v_mfma_f32_16x16x32_bf16 v[26:29], v[216:219], v[26:29], v[34:37]
	v_mfma_f32_16x16x32_bf16 v[114:117], v[220:223], v[30:33], v[26:29]
	v_mfma_f32_16x16x32_bf16 v[26:29], v[208:211], v[62:65], v[38:41]
	v_mfma_f32_16x16x32_bf16 v[102:105], v[212:215], v[224:227], v[26:29]
	v_mfma_f32_16x16x32_bf16 v[26:29], v[216:219], v[62:65], v[42:45]
	v_mfma_f32_16x16x32_bf16 v[98:101], v[220:223], v[224:227], v[26:29]
	v_mfma_f32_16x16x32_bf16 v[26:29], v[208:211], v[228:231], v[46:49]
	v_mfma_f32_16x16x32_bf16 v[86:89], v[212:215], v[232:235], v[26:29]
	v_mfma_f32_16x16x32_bf16 v[26:29], v[216:219], v[228:231], v[50:53]
	v_mfma_f32_16x16x32_bf16 v[82:85], v[220:223], v[232:235], v[26:29]
	v_mfma_f32_16x16x32_bf16 v[26:29], v[208:211], v[236:239], v[54:57]
	v_mfma_f32_16x16x32_bf16 v[70:73], v[212:215], v[240:243], v[26:29]
	v_mfma_f32_16x16x32_bf16 v[26:29], v[216:219], v[236:239], v[58:61]
	v_mfma_f32_16x16x32_bf16 v[118:121], v[212:215], v[30:33], v[66:69]
	v_mfma_f32_16x16x32_bf16 v[66:69], v[220:223], v[240:243], v[26:29]
	s_barrier
	s_setprio 0
	s_add_i32 s53, s53, s25
	s_add_i32 s54, s53, 0x2000
	s_nop 1
	v_lshl_add_u64 v[26:27], v[248:249], 0, s[14:15]
	s_mov_b32 m0, s53
	s_add_u32 s22, s20, 0x2b0180
	ds_read_b128 v[34:37], v154 offset:49152
	ds_read_b128 v[38:41], v154 offset:50176
	ds_read_b128 v[224:227], v154 offset:51200
	ds_read_b128 v[228:231], v154 offset:52224
	ds_read_b128 v[232:235], v154 offset:53248
	ds_read_b128 v[236:239], v154 offset:54272
	ds_read_b128 v[240:243], v154 offset:55296
	ds_read_b128 v[244:247], v154 offset:56320
	global_load_lds_dwordx4 v[26:27], off
	v_lshl_add_u64 v[26:27], v[250:251], 0, s[14:15]
	s_mov_b32 m0, s54
	s_addc_u32 s23, s21, 0
	s_add_i32 s55, s55, s25
	global_load_lds_dwordx4 v[26:27], off
	v_lshl_add_u64 v[26:27], s[22:23], 0, v[132:133]
	s_mov_b32 m0, s55
	s_add_i32 s56, s55, 0x2000
	global_load_lds_dwordx4 v[26:27], off
	v_lshl_add_u64 v[26:27], s[22:23], 0, v[136:137]
	s_mov_b32 m0, s56
	s_nop 0
	global_load_lds_dwordx4 v[26:27], off
	v_lshl_add_u64 v[26:27], v[252:253], 0, s[14:15]
	s_mov_b32 m0, s34
	s_nop 0
	global_load_lds_dwordx4 v[26:27], off
	v_lshl_add_u64 v[26:27], v[142:143], 0, s[14:15]
	s_mov_b32 m0, s35
	s_nop 0
	global_load_lds_dwordx4 v[26:27], off
	s_waitcnt vmcnt(8)
	s_waitcnt lgkmcnt(0)
	s_setprio 1
	s_barrier
	v_mfma_f32_16x16x32_bf16 v[26:29], v[10:13], v[34:37], v[148:151]
	v_mfma_f32_16x16x32_bf16 v[62:65], v[14:17], v[38:41], v[26:29]
	v_mfma_f32_16x16x32_bf16 v[26:29], v[18:21], v[34:37], v[156:159]
	v_mfma_f32_16x16x32_bf16 v[58:61], v[22:25], v[38:41], v[26:29]
	v_mfma_f32_16x16x32_bf16 v[26:29], v[10:13], v[224:227], v[160:163]
	v_mfma_f32_16x16x32_bf16 v[46:49], v[14:17], v[228:231], v[26:29]
	v_mfma_f32_16x16x32_bf16 v[26:29], v[18:21], v[224:227], v[164:167]
	v_mfma_f32_16x16x32_bf16 v[42:45], v[22:25], v[228:231], v[26:29]
	v_mfma_f32_16x16x32_bf16 v[26:29], v[10:13], v[232:235], v[168:171]
	v_mfma_f32_16x16x32_bf16 v[2:5], v[10:13], v[240:243], v[2:5]
	v_mfma_f32_16x16x32_bf16 v[30:33], v[14:17], v[236:239], v[26:29]
	v_mfma_f32_16x16x32_bf16 v[26:29], v[18:21], v[232:235], v[172:175]
	v_mfma_f32_16x16x32_bf16 v[14:17], v[14:17], v[244:247], v[2:5]
	v_mfma_f32_16x16x32_bf16 v[2:5], v[18:21], v[240:243], v[6:9]
	v_mfma_f32_16x16x32_bf16 v[26:29], v[22:25], v[236:239], v[26:29]
	v_mfma_f32_16x16x32_bf16 v[10:13], v[22:25], v[244:247], v[2:5]
	s_setprio 0
	s_setprio 1
	v_mfma_f32_16x16x32_bf16 v[2:5], v[208:211], v[34:37], v[176:179]
	v_mfma_f32_16x16x32_bf16 v[54:57], v[212:215], v[38:41], v[2:5]
	v_mfma_f32_16x16x32_bf16 v[2:5], v[216:219], v[34:37], v[180:183]
	v_mfma_f32_16x16x32_bf16 v[50:53], v[220:223], v[38:41], v[2:5]
	v_mfma_f32_16x16x32_bf16 v[2:5], v[208:211], v[224:227], v[184:187]
	v_mfma_f32_16x16x32_bf16 v[38:41], v[212:215], v[228:231], v[2:5]
	v_mfma_f32_16x16x32_bf16 v[2:5], v[216:219], v[224:227], v[188:191]
	v_mfma_f32_16x16x32_bf16 v[34:37], v[220:223], v[228:231], v[2:5]
	v_mfma_f32_16x16x32_bf16 v[2:5], v[208:211], v[232:235], v[192:195]
	v_mfma_f32_16x16x32_bf16 v[22:25], v[212:215], v[236:239], v[2:5]
	v_mfma_f32_16x16x32_bf16 v[2:5], v[216:219], v[232:235], v[196:199]
	v_mfma_f32_16x16x32_bf16 v[18:21], v[220:223], v[236:239], v[2:5]
	v_mfma_f32_16x16x32_bf16 v[2:5], v[208:211], v[240:243], v[200:203]
	v_mfma_f32_16x16x32_bf16 v[6:9], v[212:215], v[244:247], v[2:5]
	v_mfma_f32_16x16x32_bf16 v[2:5], v[216:219], v[240:243], v[204:207]
	v_mfma_f32_16x16x32_bf16 v[2:5], v[220:223], v[244:247], v[2:5]
	s_barrier
	s_setprio 0
	s_add_u32 s26, s20, 0x200
	s_addc_u32 s27, s21, 0
	s_mov_b32 s57, 0
.LBB0_1425:
	ds_read_b128 v[148:151], v152
	ds_read_b128 v[156:159], v152 offset:1024
	ds_read_b128 v[160:163], v152 offset:2048
	ds_read_b128 v[164:167], v152 offset:3072
	ds_read_b128 v[168:171], v153
	ds_read_b128 v[172:175], v153 offset:1024
	ds_read_b128 v[176:179], v153 offset:2048
	ds_read_b128 v[180:183], v153 offset:3072
	s_add_u32 s20, s18, 0x200
	s_addc_u32 s21, s19, 0
	s_cmpk_eq_i32 s57, 0xa8
	s_cselect_b32 s23, s5, s21
	s_cselect_b32 s22, s4, s20
	s_cselect_b32 s21, s17, s27
	s_cselect_b32 s20, s16, s26
	s_mov_b32 m0, s49
	ds_read_b128 v[184:187], v154
	ds_read_b128 v[188:191], v154 offset:1024
	ds_read_b128 v[192:195], v154 offset:2048
	ds_read_b128 v[196:199], v154 offset:3072
	ds_read_b128 v[200:203], v154 offset:4096
	ds_read_b128 v[204:207], v154 offset:5120
	ds_read_b128 v[208:211], v154 offset:6144
	ds_read_b128 v[212:215], v154 offset:7168
	global_load_lds_dwordx4 v138, s[18:19]
	s_mov_b32 m0, s50
	s_nop 0
	global_load_lds_dwordx4 v140, s[18:19]
	s_waitcnt vmcnt(8)
	s_waitcnt lgkmcnt(0)
	s_setprio 1
	s_barrier
	v_mfma_f32_16x16x32_bf16 v[126:129], v[148:151], v[184:187], v[126:129]
	v_mfma_f32_16x16x32_bf16 v[122:125], v[160:163], v[184:187], v[122:125]
	v_mfma_f32_16x16x32_bf16 v[110:113], v[148:151], v[192:195], v[110:113]
	v_mfma_f32_16x16x32_bf16 v[106:109], v[160:163], v[192:195], v[106:109]
	v_mfma_f32_16x16x32_bf16 v[94:97], v[148:151], v[200:203], v[94:97]
	v_mfma_f32_16x16x32_bf16 v[90:93], v[160:163], v[200:203], v[90:93]
	v_mfma_f32_16x16x32_bf16 v[78:81], v[148:151], v[208:211], v[78:81]
	v_mfma_f32_16x16x32_bf16 v[74:77], v[160:163], v[208:211], v[74:77]
	v_mfma_f32_16x16x32_bf16 v[126:129], v[156:159], v[188:191], v[126:129]
	v_mfma_f32_16x16x32_bf16 v[122:125], v[164:167], v[188:191], v[122:125]
	v_mfma_f32_16x16x32_bf16 v[110:113], v[156:159], v[196:199], v[110:113]
	v_mfma_f32_16x16x32_bf16 v[106:109], v[164:167], v[196:199], v[106:109]
	v_mfma_f32_16x16x32_bf16 v[94:97], v[156:159], v[204:207], v[94:97]
	v_mfma_f32_16x16x32_bf16 v[90:93], v[164:167], v[204:207], v[90:93]
	v_mfma_f32_16x16x32_bf16 v[78:81], v[156:159], v[212:215], v[78:81]
	v_mfma_f32_16x16x32_bf16 v[74:77], v[164:167], v[212:215], v[74:77]
	s_setprio 0
	s_setprio 1
	v_mfma_f32_16x16x32_bf16 v[118:121], v[168:171], v[184:187], v[118:121]
	v_mfma_f32_16x16x32_bf16 v[114:117], v[176:179], v[184:187], v[114:117]
	v_mfma_f32_16x16x32_bf16 v[102:105], v[168:171], v[192:195], v[102:105]
	v_mfma_f32_16x16x32_bf16 v[98:101], v[176:179], v[192:195], v[98:101]
	v_mfma_f32_16x16x32_bf16 v[86:89], v[168:171], v[200:203], v[86:89]
	v_mfma_f32_16x16x32_bf16 v[82:85], v[176:179], v[200:203], v[82:85]
	v_mfma_f32_16x16x32_bf16 v[70:73], v[168:171], v[208:211], v[70:73]
	v_mfma_f32_16x16x32_bf16 v[66:69], v[176:179], v[208:211], v[66:69]
	v_mfma_f32_16x16x32_bf16 v[118:121], v[172:175], v[188:191], v[118:121]
	v_mfma_f32_16x16x32_bf16 v[114:117], v[180:183], v[188:191], v[114:117]
	v_mfma_f32_16x16x32_bf16 v[102:105], v[172:175], v[196:199], v[102:105]
	v_mfma_f32_16x16x32_bf16 v[98:101], v[180:183], v[196:199], v[98:101]
	v_mfma_f32_16x16x32_bf16 v[86:89], v[172:175], v[204:207], v[86:89]
	v_mfma_f32_16x16x32_bf16 v[82:85], v[180:183], v[204:207], v[82:85]
	v_mfma_f32_16x16x32_bf16 v[70:73], v[172:175], v[212:215], v[70:73]
	v_mfma_f32_16x16x32_bf16 v[66:69], v[180:183], v[212:215], v[66:69]
	s_barrier
	s_setprio 0
	s_mov_b32 m0, s51
	s_mov_b64 s[98:99], s[20:21]
	s_add_u32 s58, s20, 0x2b0000
	ds_read_b128 v[184:187], v154 offset:16384
	ds_read_b128 v[188:191], v154 offset:17408
	ds_read_b128 v[192:195], v154 offset:18432
	ds_read_b128 v[196:199], v154 offset:19456
	ds_read_b128 v[200:203], v154 offset:20480
	ds_read_b128 v[204:207], v154 offset:21504
	ds_read_b128 v[208:211], v154 offset:22528
	ds_read_b128 v[212:215], v154 offset:23552
	global_load_lds_dwordx4 v132, s[20:21]
	s_mov_b32 m0, s52
	s_addc_u32 s59, s21, 0
	global_load_lds_dwordx4 v136, s[20:21]
	s_mov_b32 m0, s46
	s_mov_b64 s[100:101], s[22:23]
	global_load_lds_dwordx4 v132, s[58:59]
	s_mov_b32 m0, s47
	s_nop 0
	global_load_lds_dwordx4 v136, s[58:59]
	s_mov_b32 m0, s28
	s_nop 0
	global_load_lds_dwordx4 v130, s[22:23]
	s_mov_b32 m0, s29
	s_nop 0
	global_load_lds_dwordx4 v134, s[22:23]
	s_waitcnt vmcnt(8)
	s_waitcnt lgkmcnt(0)
	s_setprio 1
	s_barrier
	v_mfma_f32_16x16x32_bf16 v[62:65], v[148:151], v[184:187], v[62:65]
	v_mfma_f32_16x16x32_bf16 v[58:61], v[160:163], v[184:187], v[58:61]
	v_mfma_f32_16x16x32_bf16 v[46:49], v[148:151], v[192:195], v[46:49]
	v_mfma_f32_16x16x32_bf16 v[42:45], v[160:163], v[192:195], v[42:45]
	v_mfma_f32_16x16x32_bf16 v[30:33], v[148:151], v[200:203], v[30:33]
	v_mfma_f32_16x16x32_bf16 v[26:29], v[160:163], v[200:203], v[26:29]
	v_mfma_f32_16x16x32_bf16 v[14:17], v[148:151], v[208:211], v[14:17]
	v_mfma_f32_16x16x32_bf16 v[10:13], v[160:163], v[208:211], v[10:13]
	v_mfma_f32_16x16x32_bf16 v[62:65], v[156:159], v[188:191], v[62:65]
	v_mfma_f32_16x16x32_bf16 v[58:61], v[164:167], v[188:191], v[58:61]
	v_mfma_f32_16x16x32_bf16 v[46:49], v[156:159], v[196:199], v[46:49]
	v_mfma_f32_16x16x32_bf16 v[42:45], v[164:167], v[196:199], v[42:45]
	v_mfma_f32_16x16x32_bf16 v[30:33], v[156:159], v[204:207], v[30:33]
	v_mfma_f32_16x16x32_bf16 v[26:29], v[164:167], v[204:207], v[26:29]
	v_mfma_f32_16x16x32_bf16 v[14:17], v[156:159], v[212:215], v[14:17]
	v_mfma_f32_16x16x32_bf16 v[10:13], v[164:167], v[212:215], v[10:13]
	s_setprio 0
	s_setprio 1
	v_mfma_f32_16x16x32_bf16 v[54:57], v[168:171], v[184:187], v[54:57]
	v_mfma_f32_16x16x32_bf16 v[50:53], v[176:179], v[184:187], v[50:53]
	v_mfma_f32_16x16x32_bf16 v[38:41], v[168:171], v[192:195], v[38:41]
	v_mfma_f32_16x16x32_bf16 v[34:37], v[176:179], v[192:195], v[34:37]
	v_mfma_f32_16x16x32_bf16 v[22:25], v[168:171], v[200:203], v[22:25]
	v_mfma_f32_16x16x32_bf16 v[18:21], v[176:179], v[200:203], v[18:21]
	v_mfma_f32_16x16x32_bf16 v[6:9], v[168:171], v[208:211], v[6:9]
	v_mfma_f32_16x16x32_bf16 v[2:5], v[176:179], v[208:211], v[2:5]
	v_mfma_f32_16x16x32_bf16 v[54:57], v[172:175], v[188:191], v[54:57]
	v_mfma_f32_16x16x32_bf16 v[50:53], v[180:183], v[188:191], v[50:53]
	v_mfma_f32_16x16x32_bf16 v[38:41], v[172:175], v[196:199], v[38:41]
	v_mfma_f32_16x16x32_bf16 v[34:37], v[180:183], v[196:199], v[34:37]
	v_mfma_f32_16x16x32_bf16 v[22:25], v[172:175], v[204:207], v[22:25]
	v_mfma_f32_16x16x32_bf16 v[18:21], v[180:183], v[204:207], v[18:21]
	v_mfma_f32_16x16x32_bf16 v[6:9], v[172:175], v[212:215], v[6:9]
	v_mfma_f32_16x16x32_bf16 v[2:5], v[180:183], v[212:215], v[2:5]
	s_barrier
; #define PG8_BAR __builtin_amdgcn_s_barrier()
;     ...
;         for (int t = 2; t < nt; t += 2) PG8_KITER(t);
;         if constexpr (ALIGN_EPI) { if (wr == 0) PG8_BAR; }
	s_setprio 0
	ds_read_b128 v[148:151], v146
	ds_read_b128 v[156:159], v146 offset:1024
	ds_read_b128 v[160:163], v146 offset:2048
	ds_read_b128 v[164:167], v146 offset:3072
	ds_read_b128 v[168:171], v147
	ds_read_b128 v[172:175], v147 offset:1024
	ds_read_b128 v[176:179], v147 offset:2048
	ds_read_b128 v[180:183], v147 offset:3072
	s_add_u32 s22, s22, 0x2b0000
	s_addc_u32 s23, s23, 0
	s_mov_b32 m0, s30
	ds_read_b128 v[184:187], v154 offset:32768
	ds_read_b128 v[188:191], v154 offset:33792
	ds_read_b128 v[192:195], v154 offset:34816
	ds_read_b128 v[196:199], v154 offset:35840
	ds_read_b128 v[200:203], v154 offset:36864
	ds_read_b128 v[204:207], v154 offset:37888
	ds_read_b128 v[208:211], v154 offset:38912
	ds_read_b128 v[212:215], v154 offset:39936
	global_load_lds_dwordx4 v130, s[22:23]
	s_mov_b32 m0, s31
	s_nop 0
	global_load_lds_dwordx4 v134, s[22:23]
	s_waitcnt vmcnt(8)
	s_waitcnt lgkmcnt(0)
	s_setprio 1
	s_barrier
	v_mfma_f32_16x16x32_bf16 v[126:129], v[148:151], v[184:187], v[126:129]
	v_mfma_f32_16x16x32_bf16 v[122:125], v[160:163], v[184:187], v[122:125]
	v_mfma_f32_16x16x32_bf16 v[110:113], v[148:151], v[192:195], v[110:113]
	v_mfma_f32_16x16x32_bf16 v[106:109], v[160:163], v[192:195], v[106:109]
	v_mfma_f32_16x16x32_bf16 v[94:97], v[148:151], v[200:203], v[94:97]
	v_mfma_f32_16x16x32_bf16 v[90:93], v[160:163], v[200:203], v[90:93]
	v_mfma_f32_16x16x32_bf16 v[78:81], v[148:151], v[208:211], v[78:81]
	v_mfma_f32_16x16x32_bf16 v[74:77], v[160:163], v[208:211], v[74:77]
	v_mfma_f32_16x16x32_bf16 v[126:129], v[156:159], v[188:191], v[126:129]
	v_mfma_f32_16x16x32_bf16 v[122:125], v[164:167], v[188:191], v[122:125]
	v_mfma_f32_16x16x32_bf16 v[110:113], v[156:159], v[196:199], v[110:113]
	v_mfma_f32_16x16x32_bf16 v[106:109], v[164:167], v[196:199], v[106:109]
	v_mfma_f32_16x16x32_bf16 v[94:97], v[156:159], v[204:207], v[94:97]
	v_mfma_f32_16x16x32_bf16 v[90:93], v[164:167], v[204:207], v[90:93]
	v_mfma_f32_16x16x32_bf16 v[78:81], v[156:159], v[212:215], v[78:81]
	v_mfma_f32_16x16x32_bf16 v[74:77], v[164:167], v[212:215], v[74:77]
	s_setprio 0
	s_setprio 1
	v_mfma_f32_16x16x32_bf16 v[118:121], v[168:171], v[184:187], v[118:121]
	v_mfma_f32_16x16x32_bf16 v[114:117], v[176:179], v[184:187], v[114:117]
	v_mfma_f32_16x16x32_bf16 v[102:105], v[168:171], v[192:195], v[102:105]
	v_mfma_f32_16x16x32_bf16 v[98:101], v[176:179], v[192:195], v[98:101]
	v_mfma_f32_16x16x32_bf16 v[86:89], v[168:171], v[200:203], v[86:89]
	v_mfma_f32_16x16x32_bf16 v[82:85], v[176:179], v[200:203], v[82:85]
	v_mfma_f32_16x16x32_bf16 v[70:73], v[168:171], v[208:211], v[70:73]
	v_mfma_f32_16x16x32_bf16 v[66:69], v[176:179], v[208:211], v[66:69]
	v_mfma_f32_16x16x32_bf16 v[118:121], v[172:175], v[188:191], v[118:121]
	v_mfma_f32_16x16x32_bf16 v[114:117], v[180:183], v[188:191], v[114:117]
	v_mfma_f32_16x16x32_bf16 v[102:105], v[172:175], v[196:199], v[102:105]
	v_mfma_f32_16x16x32_bf16 v[98:101], v[180:183], v[196:199], v[98:101]
	v_mfma_f32_16x16x32_bf16 v[86:89], v[172:175], v[204:207], v[86:89]
	v_mfma_f32_16x16x32_bf16 v[82:85], v[180:183], v[204:207], v[82:85]
	v_mfma_f32_16x16x32_bf16 v[70:73], v[172:175], v[212:215], v[70:73]
	v_mfma_f32_16x16x32_bf16 v[66:69], v[180:183], v[212:215], v[66:69]
	s_barrier
	s_setprio 0
	s_mov_b32 m0, s53
	s_add_u32 s98, s98, 0x80
	s_addc_u32 s99, s99, 0
	s_add_u32 s100, s100, 0x80
	s_addc_u32 s101, s101, 0
	s_add_u32 s20, s20, 0x2b0080
	ds_read_b128 v[184:187], v154 offset:49152
	ds_read_b128 v[188:191], v154 offset:50176
	ds_read_b128 v[192:195], v154 offset:51200
	ds_read_b128 v[196:199], v154 offset:52224
	ds_read_b128 v[200:203], v154 offset:53248
	ds_read_b128 v[204:207], v154 offset:54272
	ds_read_b128 v[208:211], v154 offset:55296
	ds_read_b128 v[212:215], v154 offset:56320
	global_load_lds_dwordx4 v132, s[98:99]
	s_mov_b32 m0, s54
	s_addc_u32 s21, s21, 0
	global_load_lds_dwordx4 v136, s[98:99]
	s_mov_b32 m0, s55
	s_nop 0
	global_load_lds_dwordx4 v132, s[20:21]
	s_mov_b32 m0, s56
	s_nop 0
	global_load_lds_dwordx4 v136, s[20:21]
	s_mov_b32 m0, s34
	s_nop 0
	global_load_lds_dwordx4 v130, s[100:101]
	s_mov_b32 m0, s35
	s_nop 0
	global_load_lds_dwordx4 v134, s[100:101]
	s_waitcnt vmcnt(8)
	s_waitcnt lgkmcnt(0)
	s_setprio 1
	s_barrier
	v_mfma_f32_16x16x32_bf16 v[62:65], v[148:151], v[184:187], v[62:65]
	v_mfma_f32_16x16x32_bf16 v[58:61], v[160:163], v[184:187], v[58:61]
	v_mfma_f32_16x16x32_bf16 v[46:49], v[148:151], v[192:195], v[46:49]
	v_mfma_f32_16x16x32_bf16 v[42:45], v[160:163], v[192:195], v[42:45]
	v_mfma_f32_16x16x32_bf16 v[30:33], v[148:151], v[200:203], v[30:33]
	v_mfma_f32_16x16x32_bf16 v[26:29], v[160:163], v[200:203], v[26:29]
	v_mfma_f32_16x16x32_bf16 v[14:17], v[148:151], v[208:211], v[14:17]
	v_mfma_f32_16x16x32_bf16 v[10:13], v[160:163], v[208:211], v[10:13]
	v_mfma_f32_16x16x32_bf16 v[62:65], v[156:159], v[188:191], v[62:65]
	v_mfma_f32_16x16x32_bf16 v[58:61], v[164:167], v[188:191], v[58:61]
	v_mfma_f32_16x16x32_bf16 v[46:49], v[156:159], v[196:199], v[46:49]
	v_mfma_f32_16x16x32_bf16 v[42:45], v[164:167], v[196:199], v[42:45]
	v_mfma_f32_16x16x32_bf16 v[30:33], v[156:159], v[204:207], v[30:33]
	v_mfma_f32_16x16x32_bf16 v[26:29], v[164:167], v[204:207], v[26:29]
	v_mfma_f32_16x16x32_bf16 v[14:17], v[156:159], v[212:215], v[14:17]
	v_mfma_f32_16x16x32_bf16 v[10:13], v[164:167], v[212:215], v[10:13]
	s_setprio 0
	s_setprio 1
	v_mfma_f32_16x16x32_bf16 v[54:57], v[168:171], v[184:187], v[54:57]
	v_mfma_f32_16x16x32_bf16 v[50:53], v[176:179], v[184:187], v[50:53]
	v_mfma_f32_16x16x32_bf16 v[38:41], v[168:171], v[192:195], v[38:41]
	v_mfma_f32_16x16x32_bf16 v[34:37], v[176:179], v[192:195], v[34:37]
	v_mfma_f32_16x16x32_bf16 v[22:25], v[168:171], v[200:203], v[22:25]
	v_mfma_f32_16x16x32_bf16 v[18:21], v[176:179], v[200:203], v[18:21]
	v_mfma_f32_16x16x32_bf16 v[6:9], v[168:171], v[208:211], v[6:9]
	v_mfma_f32_16x16x32_bf16 v[2:5], v[176:179], v[208:211], v[2:5]
	v_mfma_f32_16x16x32_bf16 v[54:57], v[172:175], v[188:191], v[54:57]
	v_mfma_f32_16x16x32_bf16 v[50:53], v[180:183], v[188:191], v[50:53]
	v_mfma_f32_16x16x32_bf16 v[38:41], v[172:175], v[196:199], v[38:41]
	v_mfma_f32_16x16x32_bf16 v[34:37], v[180:183], v[196:199], v[34:37]
	v_mfma_f32_16x16x32_bf16 v[22:25], v[172:175], v[204:207], v[22:25]
	v_mfma_f32_16x16x32_bf16 v[18:21], v[180:183], v[204:207], v[18:21]
	v_mfma_f32_16x16x32_bf16 v[6:9], v[172:175], v[212:215], v[6:9]
	v_mfma_f32_16x16x32_bf16 v[2:5], v[180:183], v[212:215], v[2:5]
	s_barrier
	s_setprio 0
	s_add_i32 s57, s57, 2
	s_add_u32 s18, s18, 0x100
	s_addc_u32 s19, s19, 0
	s_add_u32 s26, s26, 0x100
	s_addc_u32 s27, s27, 0
	s_cmpk_gt_u32 s57, 0xa9
	s_cbranch_scc0 .LBB0_1425
	s_and_b64 vcc, exec, s[10:11]
	s_cbranch_vccz .LBB0_1428
	s_barrier
